# layer-1 modulation GEMV moved from phase 0 into the mixers(L0) hook on blocks>=128 (first needed in phase 11)
# baseline (speedup 1.0000x reference)
.LBB0_74:
.LBB0_75:
	s_cmp_ge_u32 s96, 128
	s_cbranch_scc1 .Lp0_skipmod
	s_load_dwordx2 s[0:1], s[92:93], 0x28
	s_load_dwordx2 s[2:3], s[92:93], 0x30
	s_load_dwordx2 s[4:5], s[92:93], 0x18
	s_load_dwordx2 s[6:7], s[92:93], 0x20
	v_lshlrev_b32_e32 v1, 2, v154
	s_waitcnt lgkmcnt(0)
	s_add_u32 s12, s4, 0x0
	s_addc_u32 s13, s5, 0
	global_load_dword v32, v1, s[12:13]
	s_add_u32 s12, s4, 0x800
	s_addc_u32 s13, s5, 0
	global_load_dword v33, v1, s[12:13]
	s_add_u32 s12, s4, 0x1000
	s_addc_u32 s13, s5, 0
	global_load_dword v34, v1, s[12:13]
	s_add_u32 s12, s4, 0x1800
	s_addc_u32 s13, s5, 0
	global_load_dword v35, v1, s[12:13]
	s_add_u32 s12, s4, 0x2000
	s_addc_u32 s13, s5, 0
	global_load_dword v36, v1, s[12:13]
	s_add_u32 s12, s4, 0x2800
	s_addc_u32 s13, s5, 0
	global_load_dword v37, v1, s[12:13]
	s_add_u32 s12, s4, 0x3000
	s_addc_u32 s13, s5, 0
	global_load_dword v38, v1, s[12:13]
	s_add_u32 s12, s4, 0x3800
	s_addc_u32 s13, s5, 0
	global_load_dword v39, v1, s[12:13]
	s_add_u32 s12, s4, 0x4000
	s_addc_u32 s13, s5, 0
	global_load_dword v40, v1, s[12:13]
	s_add_u32 s12, s4, 0x4800
	s_addc_u32 s13, s5, 0
	global_load_dword v41, v1, s[12:13]
	s_add_u32 s12, s4, 0x5000
	s_addc_u32 s13, s5, 0
	global_load_dword v42, v1, s[12:13]
	s_add_u32 s12, s4, 0x5800
	s_addc_u32 s13, s5, 0
	global_load_dword v43, v1, s[12:13]
	s_add_u32 s12, s4, 0x6000
	s_addc_u32 s13, s5, 0
	global_load_dword v44, v1, s[12:13]
	s_add_u32 s12, s4, 0x6800
	s_addc_u32 s13, s5, 0
	global_load_dword v45, v1, s[12:13]
	s_add_u32 s12, s4, 0x7000
	s_addc_u32 s13, s5, 0
	global_load_dword v46, v1, s[12:13]
	s_add_u32 s12, s4, 0x7800
	s_addc_u32 s13, s5, 0
	global_load_dword v47, v1, s[12:13]
	s_add_u32 s12, s6, 0x0
	s_addc_u32 s13, s7, 0
	global_load_dword v48, v1, s[12:13]
	s_add_u32 s12, s6, 0x800
	s_addc_u32 s13, s7, 0
	global_load_dword v49, v1, s[12:13]
	s_add_u32 s12, s6, 0x1000
	s_addc_u32 s13, s7, 0
	global_load_dword v50, v1, s[12:13]
	s_add_u32 s12, s6, 0x1800
	s_addc_u32 s13, s7, 0
	global_load_dword v51, v1, s[12:13]
	v_mov_b32_e32 v2, 0xbfb8aa3b
	s_waitcnt vmcnt(0)
	v_mul_f32_e32 v3, v2, v32
	v_exp_f32_e32 v3, v3
	s_nop 0
	v_add_f32_e32 v3, 1.0, v3
	v_rcp_f32_e32 v3, v3
	s_nop 0
	v_mul_f32_e32 v3, v3, v32
	ds_write_b32 v1, v3 offset:0
	v_mul_f32_e32 v3, v2, v33
	v_exp_f32_e32 v3, v3
	s_nop 0
	v_add_f32_e32 v3, 1.0, v3
	v_rcp_f32_e32 v3, v3
	s_nop 0
	v_mul_f32_e32 v3, v3, v33
	ds_write_b32 v1, v3 offset:2048
	v_mul_f32_e32 v3, v2, v34
	v_exp_f32_e32 v3, v3
	s_nop 0
	v_add_f32_e32 v3, 1.0, v3
	v_rcp_f32_e32 v3, v3
	s_nop 0
	v_mul_f32_e32 v3, v3, v34
	ds_write_b32 v1, v3 offset:4096
	v_mul_f32_e32 v3, v2, v35
	v_exp_f32_e32 v3, v3
	s_nop 0
	v_add_f32_e32 v3, 1.0, v3
	v_rcp_f32_e32 v3, v3
	s_nop 0
	v_mul_f32_e32 v3, v3, v35
	ds_write_b32 v1, v3 offset:6144
	v_mul_f32_e32 v3, v2, v36
	v_exp_f32_e32 v3, v3
	s_nop 0
	v_add_f32_e32 v3, 1.0, v3
	v_rcp_f32_e32 v3, v3
	s_nop 0
	v_mul_f32_e32 v3, v3, v36
	ds_write_b32 v1, v3 offset:8192
	v_mul_f32_e32 v3, v2, v37
	v_exp_f32_e32 v3, v3
	s_nop 0
	v_add_f32_e32 v3, 1.0, v3
	v_rcp_f32_e32 v3, v3
	s_nop 0
	v_mul_f32_e32 v3, v3, v37
	ds_write_b32 v1, v3 offset:10240
	v_mul_f32_e32 v3, v2, v38
	v_exp_f32_e32 v3, v3
	s_nop 0
	v_add_f32_e32 v3, 1.0, v3
	v_rcp_f32_e32 v3, v3
	s_nop 0
	v_mul_f32_e32 v3, v3, v38
	ds_write_b32 v1, v3 offset:12288
	v_mul_f32_e32 v3, v2, v39
	v_exp_f32_e32 v3, v3
	s_nop 0
	v_add_f32_e32 v3, 1.0, v3
	v_rcp_f32_e32 v3, v3
	s_nop 0
	v_mul_f32_e32 v3, v3, v39
	ds_write_b32 v1, v3 offset:14336
	v_mul_f32_e32 v3, v2, v40
	v_exp_f32_e32 v3, v3
	s_nop 0
	v_add_f32_e32 v3, 1.0, v3
	v_rcp_f32_e32 v3, v3
	s_nop 0
	v_mul_f32_e32 v3, v3, v40
	ds_write_b32 v1, v3 offset:16384
	v_mul_f32_e32 v3, v2, v41
	v_exp_f32_e32 v3, v3
	s_nop 0
	v_add_f32_e32 v3, 1.0, v3
	v_rcp_f32_e32 v3, v3
	s_nop 0
	v_mul_f32_e32 v3, v3, v41
	ds_write_b32 v1, v3 offset:18432
	v_mul_f32_e32 v3, v2, v42
	v_exp_f32_e32 v3, v3
	s_nop 0
	v_add_f32_e32 v3, 1.0, v3
	v_rcp_f32_e32 v3, v3
	s_nop 0
	v_mul_f32_e32 v3, v3, v42
	ds_write_b32 v1, v3 offset:20480
	v_mul_f32_e32 v3, v2, v43
	v_exp_f32_e32 v3, v3
	s_nop 0
	v_add_f32_e32 v3, 1.0, v3
	v_rcp_f32_e32 v3, v3
	s_nop 0
	v_mul_f32_e32 v3, v3, v43
	ds_write_b32 v1, v3 offset:22528
	v_mul_f32_e32 v3, v2, v44
	v_exp_f32_e32 v3, v3
	s_nop 0
	v_add_f32_e32 v3, 1.0, v3
	v_rcp_f32_e32 v3, v3
	s_nop 0
	v_mul_f32_e32 v3, v3, v44
	ds_write_b32 v1, v3 offset:24576
	v_mul_f32_e32 v3, v2, v45
	v_exp_f32_e32 v3, v3
	s_nop 0
	v_add_f32_e32 v3, 1.0, v3
	v_rcp_f32_e32 v3, v3
	s_nop 0
	v_mul_f32_e32 v3, v3, v45
	ds_write_b32 v1, v3 offset:26624
	v_mul_f32_e32 v3, v2, v46
	v_exp_f32_e32 v3, v3
	s_nop 0
	v_add_f32_e32 v3, 1.0, v3
	v_rcp_f32_e32 v3, v3
	s_nop 0
	v_mul_f32_e32 v3, v3, v46
	ds_write_b32 v1, v3 offset:28672
	v_mul_f32_e32 v3, v2, v47
	v_exp_f32_e32 v3, v3
	s_nop 0
	v_add_f32_e32 v3, 1.0, v3
	v_rcp_f32_e32 v3, v3
	s_nop 0
	v_mul_f32_e32 v3, v3, v47
	ds_write_b32 v1, v3 offset:30720
	v_mul_f32_e32 v3, v2, v48
	v_exp_f32_e32 v3, v3
	s_nop 0
	v_add_f32_e32 v3, 1.0, v3
	v_rcp_f32_e32 v3, v3
	s_nop 0
	v_mul_f32_e32 v3, v3, v48
	ds_write_b32 v1, v3 offset:32768
	v_mul_f32_e32 v3, v2, v49
	v_exp_f32_e32 v3, v3
	s_nop 0
	v_add_f32_e32 v3, 1.0, v3
	v_rcp_f32_e32 v3, v3
	s_nop 0
	v_mul_f32_e32 v3, v3, v49
	ds_write_b32 v1, v3 offset:34816
	v_mul_f32_e32 v3, v2, v50
	v_exp_f32_e32 v3, v3
	s_nop 0
	v_add_f32_e32 v3, 1.0, v3
	v_rcp_f32_e32 v3, v3
	s_nop 0
	v_mul_f32_e32 v3, v3, v50
	ds_write_b32 v1, v3 offset:36864
	v_mul_f32_e32 v3, v2, v51
	v_exp_f32_e32 v3, v3
	s_nop 0
	v_add_f32_e32 v3, 1.0, v3
	v_rcp_f32_e32 v3, v3
	s_nop 0
	v_mul_f32_e32 v3, v3, v51
	ds_write_b32 v1, v3 offset:38912
	s_waitcnt lgkmcnt(0)
	s_barrier
	s_lshr_b32 s8, s96, 7
	s_and_b32 s9, s96, 127
	s_mul_i32 s9, s9, 96
	v_and_b32_e32 v1, 63, v154
	v_cmp_lt_u32_e32 vcc, 23, v1
	s_nop 1
	v_cndmask_b32_e64 v2, 0, 1, vcc
	v_mul_u32_u24_e32 v3, 24, v2
	v_sub_u32_e32 v3, v1, v3
	v_lshrrev_b32_e32 v4, 6, v154
	v_lshl_add_u32 v10, v4, 8, v2
	v_lshlrev_b32_e32 v10, 2, v10
	v_mul_u32_u24_e32 v11, 0xc000, v2
	v_lshl_add_u32 v11, v3, 4, v11
	v_readfirstlane_b32 s12, v4
	s_lshl_b32 s12, s12, 8
	s_lshl_b32 s13, s8, 11
	s_add_u32 s12, s12, s13
	s_mul_hi_u32 s14, s12, 0xc000
	s_mul_i32 s12, s12, 0xc000
	s_lshl_b32 s13, s9, 2
	s_add_u32 s12, s12, s13
	s_addc_u32 s14, s14, 0
	s_add_u32 s10, s0, s12
	s_addc_u32 s11, s1, s14
	v_mov_b32_e32 v12, 0
	v_mov_b32_e32 v13, 0
	v_mov_b32_e32 v14, 0
	v_mov_b32_e32 v15, 0
	v_mov_b32_e32 v16, 0
	v_mov_b32_e32 v17, 0
	v_mov_b32_e32 v18, 0
	v_mov_b32_e32 v19, 0
	v_mov_b32_e32 v20, 0
	v_mov_b32_e32 v21, 0
	v_mov_b32_e32 v22, 0
	v_mov_b32_e32 v23, 0
	v_mov_b32_e32 v24, 0
	v_mov_b32_e32 v25, 0
	v_mov_b32_e32 v26, 0
	v_mov_b32_e32 v27, 0
	v_mov_b32_e32 v28, 0
	v_mov_b32_e32 v29, 0
	v_mov_b32_e32 v30, 0
	v_mov_b32_e32 v31, 0
	s_mov_b64 s[20:21], exec
	s_mov_b32 exec_lo, -1
	s_mov_b32 exec_hi, 0xffff
	global_load_dwordx4 v[32:35], v11, s[10:11]
	s_add_u32 s10, s10, 0x18000
	s_addc_u32 s11, s11, 0
	global_load_dwordx4 v[36:39], v11, s[10:11]
	s_add_u32 s10, s10, 0x18000
	s_addc_u32 s11, s11, 0
	global_load_dwordx4 v[40:43], v11, s[10:11]
	s_add_u32 s10, s10, 0x18000
	s_addc_u32 s11, s11, 0
	global_load_dwordx4 v[44:47], v11, s[10:11]
	s_add_u32 s10, s10, 0x18000
	s_addc_u32 s11, s11, 0
	global_load_dwordx4 v[48:51], v11, s[10:11]
	s_add_u32 s10, s10, 0x18000
	s_addc_u32 s11, s11, 0
	global_load_dwordx4 v[52:55], v11, s[10:11]
	s_add_u32 s10, s10, 0x18000
	s_addc_u32 s11, s11, 0
	global_load_dwordx4 v[56:59], v11, s[10:11]
	s_add_u32 s10, s10, 0x18000
	s_addc_u32 s11, s11, 0
	global_load_dwordx4 v[60:63], v11, s[10:11]
	s_add_u32 s10, s10, 0x18000
	s_addc_u32 s11, s11, 0
	global_load_dwordx4 v[64:67], v11, s[10:11]
	s_add_u32 s10, s10, 0x18000
	s_addc_u32 s11, s11, 0
	global_load_dwordx4 v[68:71], v11, s[10:11]
	s_add_u32 s10, s10, 0x18000
	s_addc_u32 s11, s11, 0
	global_load_dwordx4 v[72:75], v11, s[10:11]
	s_add_u32 s10, s10, 0x18000
	s_addc_u32 s11, s11, 0
	global_load_dwordx4 v[76:79], v11, s[10:11]
	s_add_u32 s10, s10, 0x18000
	s_addc_u32 s11, s11, 0
	global_load_dwordx4 v[80:83], v11, s[10:11]
	s_add_u32 s10, s10, 0x18000
	s_addc_u32 s11, s11, 0
	global_load_dwordx4 v[84:87], v11, s[10:11]
	s_add_u32 s10, s10, 0x18000
	s_addc_u32 s11, s11, 0
	global_load_dwordx4 v[88:91], v11, s[10:11]
	s_add_u32 s10, s10, 0x18000
	s_addc_u32 s11, s11, 0
	global_load_dwordx4 v[92:95], v11, s[10:11]
	s_add_u32 s10, s10, 0x18000
	s_addc_u32 s11, s11, 0
	ds_read_b32 v96, v10 offset:0
	ds_read_b32 v97, v10 offset:8192
	ds_read_b32 v98, v10 offset:16384
	ds_read_b32 v99, v10 offset:24576
	ds_read_b32 v100, v10 offset:32768
	s_waitcnt vmcnt(15) lgkmcnt(0)
	v_fmac_f32_e32 v12, v96, v32
	v_fmac_f32_e32 v13, v96, v33
	v_fmac_f32_e32 v14, v96, v34
	v_fmac_f32_e32 v15, v96, v35
	v_fmac_f32_e32 v16, v97, v32
	v_fmac_f32_e32 v17, v97, v33
	v_fmac_f32_e32 v18, v97, v34
	v_fmac_f32_e32 v19, v97, v35
	v_fmac_f32_e32 v20, v98, v32
	v_fmac_f32_e32 v21, v98, v33
	v_fmac_f32_e32 v22, v98, v34
	v_fmac_f32_e32 v23, v98, v35
	v_fmac_f32_e32 v24, v99, v32
	v_fmac_f32_e32 v25, v99, v33
	v_fmac_f32_e32 v26, v99, v34
	v_fmac_f32_e32 v27, v99, v35
	v_fmac_f32_e32 v28, v100, v32
	v_fmac_f32_e32 v29, v100, v33
	v_fmac_f32_e32 v30, v100, v34
	v_fmac_f32_e32 v31, v100, v35
	global_load_dwordx4 v[32:35], v11, s[10:11]
	s_add_u32 s10, s10, 0x18000
	s_addc_u32 s11, s11, 0
	ds_read_b32 v96, v10 offset:8
	ds_read_b32 v97, v10 offset:8200
	ds_read_b32 v98, v10 offset:16392
	ds_read_b32 v99, v10 offset:24584
	ds_read_b32 v100, v10 offset:32776
	s_waitcnt vmcnt(15) lgkmcnt(0)
	v_fmac_f32_e32 v12, v96, v36
	v_fmac_f32_e32 v13, v96, v37
	v_fmac_f32_e32 v14, v96, v38
	v_fmac_f32_e32 v15, v96, v39
	v_fmac_f32_e32 v16, v97, v36
	v_fmac_f32_e32 v17, v97, v37
	v_fmac_f32_e32 v18, v97, v38
	v_fmac_f32_e32 v19, v97, v39
	v_fmac_f32_e32 v20, v98, v36
	v_fmac_f32_e32 v21, v98, v37
	v_fmac_f32_e32 v22, v98, v38
	v_fmac_f32_e32 v23, v98, v39
	v_fmac_f32_e32 v24, v99, v36
	v_fmac_f32_e32 v25, v99, v37
	v_fmac_f32_e32 v26, v99, v38
	v_fmac_f32_e32 v27, v99, v39
	v_fmac_f32_e32 v28, v100, v36
	v_fmac_f32_e32 v29, v100, v37
	v_fmac_f32_e32 v30, v100, v38
	v_fmac_f32_e32 v31, v100, v39
	global_load_dwordx4 v[36:39], v11, s[10:11]
	s_add_u32 s10, s10, 0x18000
	s_addc_u32 s11, s11, 0
	ds_read_b32 v96, v10 offset:16
	ds_read_b32 v97, v10 offset:8208
	ds_read_b32 v98, v10 offset:16400
	ds_read_b32 v99, v10 offset:24592
	ds_read_b32 v100, v10 offset:32784
	s_waitcnt vmcnt(15) lgkmcnt(0)
	v_fmac_f32_e32 v12, v96, v40
	v_fmac_f32_e32 v13, v96, v41
	v_fmac_f32_e32 v14, v96, v42
	v_fmac_f32_e32 v15, v96, v43
	v_fmac_f32_e32 v16, v97, v40
	v_fmac_f32_e32 v17, v97, v41
	v_fmac_f32_e32 v18, v97, v42
	v_fmac_f32_e32 v19, v97, v43
	v_fmac_f32_e32 v20, v98, v40
	v_fmac_f32_e32 v21, v98, v41
	v_fmac_f32_e32 v22, v98, v42
	v_fmac_f32_e32 v23, v98, v43
	v_fmac_f32_e32 v24, v99, v40
	v_fmac_f32_e32 v25, v99, v41
	v_fmac_f32_e32 v26, v99, v42
	v_fmac_f32_e32 v27, v99, v43
	v_fmac_f32_e32 v28, v100, v40
	v_fmac_f32_e32 v29, v100, v41
	v_fmac_f32_e32 v30, v100, v42
	v_fmac_f32_e32 v31, v100, v43
	global_load_dwordx4 v[40:43], v11, s[10:11]
	s_add_u32 s10, s10, 0x18000
	s_addc_u32 s11, s11, 0
	ds_read_b32 v96, v10 offset:24
	ds_read_b32 v97, v10 offset:8216
	ds_read_b32 v98, v10 offset:16408
	ds_read_b32 v99, v10 offset:24600
	ds_read_b32 v100, v10 offset:32792
	s_waitcnt vmcnt(15) lgkmcnt(0)
	v_fmac_f32_e32 v12, v96, v44
	v_fmac_f32_e32 v13, v96, v45
	v_fmac_f32_e32 v14, v96, v46
	v_fmac_f32_e32 v15, v96, v47
	v_fmac_f32_e32 v16, v97, v44
	v_fmac_f32_e32 v17, v97, v45
	v_fmac_f32_e32 v18, v97, v46
	v_fmac_f32_e32 v19, v97, v47
	v_fmac_f32_e32 v20, v98, v44
	v_fmac_f32_e32 v21, v98, v45
	v_fmac_f32_e32 v22, v98, v46
	v_fmac_f32_e32 v23, v98, v47
	v_fmac_f32_e32 v24, v99, v44
	v_fmac_f32_e32 v25, v99, v45
	v_fmac_f32_e32 v26, v99, v46
	v_fmac_f32_e32 v27, v99, v47
	v_fmac_f32_e32 v28, v100, v44
	v_fmac_f32_e32 v29, v100, v45
	v_fmac_f32_e32 v30, v100, v46
	v_fmac_f32_e32 v31, v100, v47
	global_load_dwordx4 v[44:47], v11, s[10:11]
	s_add_u32 s10, s10, 0x18000
	s_addc_u32 s11, s11, 0
	ds_read_b32 v96, v10 offset:32
	ds_read_b32 v97, v10 offset:8224
	ds_read_b32 v98, v10 offset:16416
	ds_read_b32 v99, v10 offset:24608
	ds_read_b32 v100, v10 offset:32800
	s_waitcnt vmcnt(15) lgkmcnt(0)
	v_fmac_f32_e32 v12, v96, v48
	v_fmac_f32_e32 v13, v96, v49
	v_fmac_f32_e32 v14, v96, v50
	v_fmac_f32_e32 v15, v96, v51
	v_fmac_f32_e32 v16, v97, v48
	v_fmac_f32_e32 v17, v97, v49
	v_fmac_f32_e32 v18, v97, v50
	v_fmac_f32_e32 v19, v97, v51
	v_fmac_f32_e32 v20, v98, v48
	v_fmac_f32_e32 v21, v98, v49
	v_fmac_f32_e32 v22, v98, v50
	v_fmac_f32_e32 v23, v98, v51
	v_fmac_f32_e32 v24, v99, v48
	v_fmac_f32_e32 v25, v99, v49
	v_fmac_f32_e32 v26, v99, v50
	v_fmac_f32_e32 v27, v99, v51
	v_fmac_f32_e32 v28, v100, v48
	v_fmac_f32_e32 v29, v100, v49
	v_fmac_f32_e32 v30, v100, v50
	v_fmac_f32_e32 v31, v100, v51
	global_load_dwordx4 v[48:51], v11, s[10:11]
	s_add_u32 s10, s10, 0x18000
	s_addc_u32 s11, s11, 0
	ds_read_b32 v96, v10 offset:40
	ds_read_b32 v97, v10 offset:8232
	ds_read_b32 v98, v10 offset:16424
	ds_read_b32 v99, v10 offset:24616
	ds_read_b32 v100, v10 offset:32808
	s_waitcnt vmcnt(15) lgkmcnt(0)
	v_fmac_f32_e32 v12, v96, v52
	v_fmac_f32_e32 v13, v96, v53
	v_fmac_f32_e32 v14, v96, v54
	v_fmac_f32_e32 v15, v96, v55
	v_fmac_f32_e32 v16, v97, v52
	v_fmac_f32_e32 v17, v97, v53
	v_fmac_f32_e32 v18, v97, v54
	v_fmac_f32_e32 v19, v97, v55
	v_fmac_f32_e32 v20, v98, v52
	v_fmac_f32_e32 v21, v98, v53
	v_fmac_f32_e32 v22, v98, v54
	v_fmac_f32_e32 v23, v98, v55
	v_fmac_f32_e32 v24, v99, v52
	v_fmac_f32_e32 v25, v99, v53
	v_fmac_f32_e32 v26, v99, v54
	v_fmac_f32_e32 v27, v99, v55
	v_fmac_f32_e32 v28, v100, v52
	v_fmac_f32_e32 v29, v100, v53
	v_fmac_f32_e32 v30, v100, v54
	v_fmac_f32_e32 v31, v100, v55
	global_load_dwordx4 v[52:55], v11, s[10:11]
	s_add_u32 s10, s10, 0x18000
	s_addc_u32 s11, s11, 0
	ds_read_b32 v96, v10 offset:48
	ds_read_b32 v97, v10 offset:8240
	ds_read_b32 v98, v10 offset:16432
	ds_read_b32 v99, v10 offset:24624
	ds_read_b32 v100, v10 offset:32816
	s_waitcnt vmcnt(15) lgkmcnt(0)
	v_fmac_f32_e32 v12, v96, v56
	v_fmac_f32_e32 v13, v96, v57
	v_fmac_f32_e32 v14, v96, v58
	v_fmac_f32_e32 v15, v96, v59
	v_fmac_f32_e32 v16, v97, v56
	v_fmac_f32_e32 v17, v97, v57
	v_fmac_f32_e32 v18, v97, v58
	v_fmac_f32_e32 v19, v97, v59
	v_fmac_f32_e32 v20, v98, v56
	v_fmac_f32_e32 v21, v98, v57
	v_fmac_f32_e32 v22, v98, v58
	v_fmac_f32_e32 v23, v98, v59
	v_fmac_f32_e32 v24, v99, v56
	v_fmac_f32_e32 v25, v99, v57
	v_fmac_f32_e32 v26, v99, v58
	v_fmac_f32_e32 v27, v99, v59
	v_fmac_f32_e32 v28, v100, v56
	v_fmac_f32_e32 v29, v100, v57
	v_fmac_f32_e32 v30, v100, v58
	v_fmac_f32_e32 v31, v100, v59
	global_load_dwordx4 v[56:59], v11, s[10:11]
	s_add_u32 s10, s10, 0x18000
	s_addc_u32 s11, s11, 0
	ds_read_b32 v96, v10 offset:56
	ds_read_b32 v97, v10 offset:8248
	ds_read_b32 v98, v10 offset:16440
	ds_read_b32 v99, v10 offset:24632
	ds_read_b32 v100, v10 offset:32824
	s_waitcnt vmcnt(15) lgkmcnt(0)
	v_fmac_f32_e32 v12, v96, v60
	v_fmac_f32_e32 v13, v96, v61
	v_fmac_f32_e32 v14, v96, v62
	v_fmac_f32_e32 v15, v96, v63
	v_fmac_f32_e32 v16, v97, v60
	v_fmac_f32_e32 v17, v97, v61
	v_fmac_f32_e32 v18, v97, v62
	v_fmac_f32_e32 v19, v97, v63
	v_fmac_f32_e32 v20, v98, v60
	v_fmac_f32_e32 v21, v98, v61
	v_fmac_f32_e32 v22, v98, v62
	v_fmac_f32_e32 v23, v98, v63
	v_fmac_f32_e32 v24, v99, v60
	v_fmac_f32_e32 v25, v99, v61
	v_fmac_f32_e32 v26, v99, v62
	v_fmac_f32_e32 v27, v99, v63
	v_fmac_f32_e32 v28, v100, v60
	v_fmac_f32_e32 v29, v100, v61
	v_fmac_f32_e32 v30, v100, v62
	v_fmac_f32_e32 v31, v100, v63
	global_load_dwordx4 v[60:63], v11, s[10:11]
	s_add_u32 s10, s10, 0x18000
	s_addc_u32 s11, s11, 0
	ds_read_b32 v96, v10 offset:64
	ds_read_b32 v97, v10 offset:8256
	ds_read_b32 v98, v10 offset:16448
	ds_read_b32 v99, v10 offset:24640
	ds_read_b32 v100, v10 offset:32832
	s_waitcnt vmcnt(15) lgkmcnt(0)
	v_fmac_f32_e32 v12, v96, v64
	v_fmac_f32_e32 v13, v96, v65
	v_fmac_f32_e32 v14, v96, v66
	v_fmac_f32_e32 v15, v96, v67
	v_fmac_f32_e32 v16, v97, v64
	v_fmac_f32_e32 v17, v97, v65
	v_fmac_f32_e32 v18, v97, v66
	v_fmac_f32_e32 v19, v97, v67
	v_fmac_f32_e32 v20, v98, v64
	v_fmac_f32_e32 v21, v98, v65
	v_fmac_f32_e32 v22, v98, v66
	v_fmac_f32_e32 v23, v98, v67
	v_fmac_f32_e32 v24, v99, v64
	v_fmac_f32_e32 v25, v99, v65
	v_fmac_f32_e32 v26, v99, v66
	v_fmac_f32_e32 v27, v99, v67
	v_fmac_f32_e32 v28, v100, v64
	v_fmac_f32_e32 v29, v100, v65
	v_fmac_f32_e32 v30, v100, v66
	v_fmac_f32_e32 v31, v100, v67
	global_load_dwordx4 v[64:67], v11, s[10:11]
	s_add_u32 s10, s10, 0x18000
	s_addc_u32 s11, s11, 0
	ds_read_b32 v96, v10 offset:72
	ds_read_b32 v97, v10 offset:8264
	ds_read_b32 v98, v10 offset:16456
	ds_read_b32 v99, v10 offset:24648
	ds_read_b32 v100, v10 offset:32840
	s_waitcnt vmcnt(15) lgkmcnt(0)
	v_fmac_f32_e32 v12, v96, v68
	v_fmac_f32_e32 v13, v96, v69
	v_fmac_f32_e32 v14, v96, v70
	v_fmac_f32_e32 v15, v96, v71
	v_fmac_f32_e32 v16, v97, v68
	v_fmac_f32_e32 v17, v97, v69
	v_fmac_f32_e32 v18, v97, v70
	v_fmac_f32_e32 v19, v97, v71
	v_fmac_f32_e32 v20, v98, v68
	v_fmac_f32_e32 v21, v98, v69
	v_fmac_f32_e32 v22, v98, v70
	v_fmac_f32_e32 v23, v98, v71
	v_fmac_f32_e32 v24, v99, v68
	v_fmac_f32_e32 v25, v99, v69
	v_fmac_f32_e32 v26, v99, v70
	v_fmac_f32_e32 v27, v99, v71
	v_fmac_f32_e32 v28, v100, v68
	v_fmac_f32_e32 v29, v100, v69
	v_fmac_f32_e32 v30, v100, v70
	v_fmac_f32_e32 v31, v100, v71
	global_load_dwordx4 v[68:71], v11, s[10:11]
	s_add_u32 s10, s10, 0x18000
	s_addc_u32 s11, s11, 0
	ds_read_b32 v96, v10 offset:80
	ds_read_b32 v97, v10 offset:8272
	ds_read_b32 v98, v10 offset:16464
	ds_read_b32 v99, v10 offset:24656
	ds_read_b32 v100, v10 offset:32848
	s_waitcnt vmcnt(15) lgkmcnt(0)
	v_fmac_f32_e32 v12, v96, v72
	v_fmac_f32_e32 v13, v96, v73
	v_fmac_f32_e32 v14, v96, v74
	v_fmac_f32_e32 v15, v96, v75
	v_fmac_f32_e32 v16, v97, v72
	v_fmac_f32_e32 v17, v97, v73
	v_fmac_f32_e32 v18, v97, v74
	v_fmac_f32_e32 v19, v97, v75
	v_fmac_f32_e32 v20, v98, v72
	v_fmac_f32_e32 v21, v98, v73
	v_fmac_f32_e32 v22, v98, v74
	v_fmac_f32_e32 v23, v98, v75
	v_fmac_f32_e32 v24, v99, v72
	v_fmac_f32_e32 v25, v99, v73
	v_fmac_f32_e32 v26, v99, v74
	v_fmac_f32_e32 v27, v99, v75
	v_fmac_f32_e32 v28, v100, v72
	v_fmac_f32_e32 v29, v100, v73
	v_fmac_f32_e32 v30, v100, v74
	v_fmac_f32_e32 v31, v100, v75
	global_load_dwordx4 v[72:75], v11, s[10:11]
	s_add_u32 s10, s10, 0x18000
	s_addc_u32 s11, s11, 0
	ds_read_b32 v96, v10 offset:88
	ds_read_b32 v97, v10 offset:8280
	ds_read_b32 v98, v10 offset:16472
	ds_read_b32 v99, v10 offset:24664
	ds_read_b32 v100, v10 offset:32856
	s_waitcnt vmcnt(15) lgkmcnt(0)
	v_fmac_f32_e32 v12, v96, v76
	v_fmac_f32_e32 v13, v96, v77
	v_fmac_f32_e32 v14, v96, v78
	v_fmac_f32_e32 v15, v96, v79
	v_fmac_f32_e32 v16, v97, v76
	v_fmac_f32_e32 v17, v97, v77
	v_fmac_f32_e32 v18, v97, v78
	v_fmac_f32_e32 v19, v97, v79
	v_fmac_f32_e32 v20, v98, v76
	v_fmac_f32_e32 v21, v98, v77
	v_fmac_f32_e32 v22, v98, v78
	v_fmac_f32_e32 v23, v98, v79
	v_fmac_f32_e32 v24, v99, v76
	v_fmac_f32_e32 v25, v99, v77
	v_fmac_f32_e32 v26, v99, v78
	v_fmac_f32_e32 v27, v99, v79
	v_fmac_f32_e32 v28, v100, v76
	v_fmac_f32_e32 v29, v100, v77
	v_fmac_f32_e32 v30, v100, v78
	v_fmac_f32_e32 v31, v100, v79
	global_load_dwordx4 v[76:79], v11, s[10:11]
	s_add_u32 s10, s10, 0x18000
	s_addc_u32 s11, s11, 0
	ds_read_b32 v96, v10 offset:96
	ds_read_b32 v97, v10 offset:8288
	ds_read_b32 v98, v10 offset:16480
	ds_read_b32 v99, v10 offset:24672
	ds_read_b32 v100, v10 offset:32864
	s_waitcnt vmcnt(15) lgkmcnt(0)
	v_fmac_f32_e32 v12, v96, v80
	v_fmac_f32_e32 v13, v96, v81
	v_fmac_f32_e32 v14, v96, v82
	v_fmac_f32_e32 v15, v96, v83
	v_fmac_f32_e32 v16, v97, v80
	v_fmac_f32_e32 v17, v97, v81
	v_fmac_f32_e32 v18, v97, v82
	v_fmac_f32_e32 v19, v97, v83
	v_fmac_f32_e32 v20, v98, v80
	v_fmac_f32_e32 v21, v98, v81
	v_fmac_f32_e32 v22, v98, v82
	v_fmac_f32_e32 v23, v98, v83
	v_fmac_f32_e32 v24, v99, v80
	v_fmac_f32_e32 v25, v99, v81
	v_fmac_f32_e32 v26, v99, v82
	v_fmac_f32_e32 v27, v99, v83
	v_fmac_f32_e32 v28, v100, v80
	v_fmac_f32_e32 v29, v100, v81
	v_fmac_f32_e32 v30, v100, v82
	v_fmac_f32_e32 v31, v100, v83
	global_load_dwordx4 v[80:83], v11, s[10:11]
	s_add_u32 s10, s10, 0x18000
	s_addc_u32 s11, s11, 0
	ds_read_b32 v96, v10 offset:104
	ds_read_b32 v97, v10 offset:8296
	ds_read_b32 v98, v10 offset:16488
	ds_read_b32 v99, v10 offset:24680
	ds_read_b32 v100, v10 offset:32872
	s_waitcnt vmcnt(15) lgkmcnt(0)
	v_fmac_f32_e32 v12, v96, v84
	v_fmac_f32_e32 v13, v96, v85
	v_fmac_f32_e32 v14, v96, v86
	v_fmac_f32_e32 v15, v96, v87
	v_fmac_f32_e32 v16, v97, v84
	v_fmac_f32_e32 v17, v97, v85
	v_fmac_f32_e32 v18, v97, v86
	v_fmac_f32_e32 v19, v97, v87
	v_fmac_f32_e32 v20, v98, v84
	v_fmac_f32_e32 v21, v98, v85
	v_fmac_f32_e32 v22, v98, v86
	v_fmac_f32_e32 v23, v98, v87
	v_fmac_f32_e32 v24, v99, v84
	v_fmac_f32_e32 v25, v99, v85
	v_fmac_f32_e32 v26, v99, v86
	v_fmac_f32_e32 v27, v99, v87
	v_fmac_f32_e32 v28, v100, v84
	v_fmac_f32_e32 v29, v100, v85
	v_fmac_f32_e32 v30, v100, v86
	v_fmac_f32_e32 v31, v100, v87
	global_load_dwordx4 v[84:87], v11, s[10:11]
	s_add_u32 s10, s10, 0x18000
	s_addc_u32 s11, s11, 0
	ds_read_b32 v96, v10 offset:112
	ds_read_b32 v97, v10 offset:8304
	ds_read_b32 v98, v10 offset:16496
	ds_read_b32 v99, v10 offset:24688
	ds_read_b32 v100, v10 offset:32880
	s_waitcnt vmcnt(15) lgkmcnt(0)
	v_fmac_f32_e32 v12, v96, v88
	v_fmac_f32_e32 v13, v96, v89
	v_fmac_f32_e32 v14, v96, v90
	v_fmac_f32_e32 v15, v96, v91
	v_fmac_f32_e32 v16, v97, v88
	v_fmac_f32_e32 v17, v97, v89
	v_fmac_f32_e32 v18, v97, v90
	v_fmac_f32_e32 v19, v97, v91
	v_fmac_f32_e32 v20, v98, v88
	v_fmac_f32_e32 v21, v98, v89
	v_fmac_f32_e32 v22, v98, v90
	v_fmac_f32_e32 v23, v98, v91
	v_fmac_f32_e32 v24, v99, v88
	v_fmac_f32_e32 v25, v99, v89
	v_fmac_f32_e32 v26, v99, v90
	v_fmac_f32_e32 v27, v99, v91
	v_fmac_f32_e32 v28, v100, v88
	v_fmac_f32_e32 v29, v100, v89
	v_fmac_f32_e32 v30, v100, v90
	v_fmac_f32_e32 v31, v100, v91
	global_load_dwordx4 v[88:91], v11, s[10:11]
	s_add_u32 s10, s10, 0x18000
	s_addc_u32 s11, s11, 0
	ds_read_b32 v96, v10 offset:120
	ds_read_b32 v97, v10 offset:8312
	ds_read_b32 v98, v10 offset:16504
	ds_read_b32 v99, v10 offset:24696
	ds_read_b32 v100, v10 offset:32888
	s_waitcnt vmcnt(15) lgkmcnt(0)
	v_fmac_f32_e32 v12, v96, v92
	v_fmac_f32_e32 v13, v96, v93
	v_fmac_f32_e32 v14, v96, v94
	v_fmac_f32_e32 v15, v96, v95
	v_fmac_f32_e32 v16, v97, v92
	v_fmac_f32_e32 v17, v97, v93
	v_fmac_f32_e32 v18, v97, v94
	v_fmac_f32_e32 v19, v97, v95
	v_fmac_f32_e32 v20, v98, v92
	v_fmac_f32_e32 v21, v98, v93
	v_fmac_f32_e32 v22, v98, v94
	v_fmac_f32_e32 v23, v98, v95
	v_fmac_f32_e32 v24, v99, v92
	v_fmac_f32_e32 v25, v99, v93
	v_fmac_f32_e32 v26, v99, v94
	v_fmac_f32_e32 v27, v99, v95
	v_fmac_f32_e32 v28, v100, v92
	v_fmac_f32_e32 v29, v100, v93
	v_fmac_f32_e32 v30, v100, v94
	v_fmac_f32_e32 v31, v100, v95
	global_load_dwordx4 v[92:95], v11, s[10:11]
	s_add_u32 s10, s10, 0x18000
	s_addc_u32 s11, s11, 0
	ds_read_b32 v96, v10 offset:128
	ds_read_b32 v97, v10 offset:8320
	ds_read_b32 v98, v10 offset:16512
	ds_read_b32 v99, v10 offset:24704
	ds_read_b32 v100, v10 offset:32896
	s_waitcnt vmcnt(15) lgkmcnt(0)
	v_fmac_f32_e32 v12, v96, v32
	v_fmac_f32_e32 v13, v96, v33
	v_fmac_f32_e32 v14, v96, v34
	v_fmac_f32_e32 v15, v96, v35
	v_fmac_f32_e32 v16, v97, v32
	v_fmac_f32_e32 v17, v97, v33
	v_fmac_f32_e32 v18, v97, v34
	v_fmac_f32_e32 v19, v97, v35
	v_fmac_f32_e32 v20, v98, v32
	v_fmac_f32_e32 v21, v98, v33
	v_fmac_f32_e32 v22, v98, v34
	v_fmac_f32_e32 v23, v98, v35
	v_fmac_f32_e32 v24, v99, v32
	v_fmac_f32_e32 v25, v99, v33
	v_fmac_f32_e32 v26, v99, v34
	v_fmac_f32_e32 v27, v99, v35
	v_fmac_f32_e32 v28, v100, v32
	v_fmac_f32_e32 v29, v100, v33
	v_fmac_f32_e32 v30, v100, v34
	v_fmac_f32_e32 v31, v100, v35
	global_load_dwordx4 v[32:35], v11, s[10:11]
	s_add_u32 s10, s10, 0x18000
	s_addc_u32 s11, s11, 0
	ds_read_b32 v96, v10 offset:136
	ds_read_b32 v97, v10 offset:8328
	ds_read_b32 v98, v10 offset:16520
	ds_read_b32 v99, v10 offset:24712
	ds_read_b32 v100, v10 offset:32904
	s_waitcnt vmcnt(15) lgkmcnt(0)
	v_fmac_f32_e32 v12, v96, v36
	v_fmac_f32_e32 v13, v96, v37
	v_fmac_f32_e32 v14, v96, v38
	v_fmac_f32_e32 v15, v96, v39
	v_fmac_f32_e32 v16, v97, v36
	v_fmac_f32_e32 v17, v97, v37
	v_fmac_f32_e32 v18, v97, v38
	v_fmac_f32_e32 v19, v97, v39
	v_fmac_f32_e32 v20, v98, v36
	v_fmac_f32_e32 v21, v98, v37
	v_fmac_f32_e32 v22, v98, v38
	v_fmac_f32_e32 v23, v98, v39
	v_fmac_f32_e32 v24, v99, v36
	v_fmac_f32_e32 v25, v99, v37
	v_fmac_f32_e32 v26, v99, v38
	v_fmac_f32_e32 v27, v99, v39
	v_fmac_f32_e32 v28, v100, v36
	v_fmac_f32_e32 v29, v100, v37
	v_fmac_f32_e32 v30, v100, v38
	v_fmac_f32_e32 v31, v100, v39
	global_load_dwordx4 v[36:39], v11, s[10:11]
	s_add_u32 s10, s10, 0x18000
	s_addc_u32 s11, s11, 0
	ds_read_b32 v96, v10 offset:144
	ds_read_b32 v97, v10 offset:8336
	ds_read_b32 v98, v10 offset:16528
	ds_read_b32 v99, v10 offset:24720
	ds_read_b32 v100, v10 offset:32912
	s_waitcnt vmcnt(15) lgkmcnt(0)
	v_fmac_f32_e32 v12, v96, v40
	v_fmac_f32_e32 v13, v96, v41
	v_fmac_f32_e32 v14, v96, v42
	v_fmac_f32_e32 v15, v96, v43
	v_fmac_f32_e32 v16, v97, v40
	v_fmac_f32_e32 v17, v97, v41
	v_fmac_f32_e32 v18, v97, v42
	v_fmac_f32_e32 v19, v97, v43
	v_fmac_f32_e32 v20, v98, v40
	v_fmac_f32_e32 v21, v98, v41
	v_fmac_f32_e32 v22, v98, v42
	v_fmac_f32_e32 v23, v98, v43
	v_fmac_f32_e32 v24, v99, v40
	v_fmac_f32_e32 v25, v99, v41
	v_fmac_f32_e32 v26, v99, v42
	v_fmac_f32_e32 v27, v99, v43
	v_fmac_f32_e32 v28, v100, v40
	v_fmac_f32_e32 v29, v100, v41
	v_fmac_f32_e32 v30, v100, v42
	v_fmac_f32_e32 v31, v100, v43
	global_load_dwordx4 v[40:43], v11, s[10:11]
	s_add_u32 s10, s10, 0x18000
	s_addc_u32 s11, s11, 0
	ds_read_b32 v96, v10 offset:152
	ds_read_b32 v97, v10 offset:8344
	ds_read_b32 v98, v10 offset:16536
	ds_read_b32 v99, v10 offset:24728
	ds_read_b32 v100, v10 offset:32920
	s_waitcnt vmcnt(15) lgkmcnt(0)
	v_fmac_f32_e32 v12, v96, v44
	v_fmac_f32_e32 v13, v96, v45
	v_fmac_f32_e32 v14, v96, v46
	v_fmac_f32_e32 v15, v96, v47
	v_fmac_f32_e32 v16, v97, v44
	v_fmac_f32_e32 v17, v97, v45
	v_fmac_f32_e32 v18, v97, v46
	v_fmac_f32_e32 v19, v97, v47
	v_fmac_f32_e32 v20, v98, v44
	v_fmac_f32_e32 v21, v98, v45
	v_fmac_f32_e32 v22, v98, v46
	v_fmac_f32_e32 v23, v98, v47
	v_fmac_f32_e32 v24, v99, v44
	v_fmac_f32_e32 v25, v99, v45
	v_fmac_f32_e32 v26, v99, v46
	v_fmac_f32_e32 v27, v99, v47
	v_fmac_f32_e32 v28, v100, v44
	v_fmac_f32_e32 v29, v100, v45
	v_fmac_f32_e32 v30, v100, v46
	v_fmac_f32_e32 v31, v100, v47
	global_load_dwordx4 v[44:47], v11, s[10:11]
	s_add_u32 s10, s10, 0x18000
	s_addc_u32 s11, s11, 0
	ds_read_b32 v96, v10 offset:160
	ds_read_b32 v97, v10 offset:8352
	ds_read_b32 v98, v10 offset:16544
	ds_read_b32 v99, v10 offset:24736
	ds_read_b32 v100, v10 offset:32928
	s_waitcnt vmcnt(15) lgkmcnt(0)
	v_fmac_f32_e32 v12, v96, v48
	v_fmac_f32_e32 v13, v96, v49
	v_fmac_f32_e32 v14, v96, v50
	v_fmac_f32_e32 v15, v96, v51
	v_fmac_f32_e32 v16, v97, v48
	v_fmac_f32_e32 v17, v97, v49
	v_fmac_f32_e32 v18, v97, v50
	v_fmac_f32_e32 v19, v97, v51
	v_fmac_f32_e32 v20, v98, v48
	v_fmac_f32_e32 v21, v98, v49
	v_fmac_f32_e32 v22, v98, v50
	v_fmac_f32_e32 v23, v98, v51
	v_fmac_f32_e32 v24, v99, v48
	v_fmac_f32_e32 v25, v99, v49
	v_fmac_f32_e32 v26, v99, v50
	v_fmac_f32_e32 v27, v99, v51
	v_fmac_f32_e32 v28, v100, v48
	v_fmac_f32_e32 v29, v100, v49
	v_fmac_f32_e32 v30, v100, v50
	v_fmac_f32_e32 v31, v100, v51
	global_load_dwordx4 v[48:51], v11, s[10:11]
	s_add_u32 s10, s10, 0x18000
	s_addc_u32 s11, s11, 0
	ds_read_b32 v96, v10 offset:168
	ds_read_b32 v97, v10 offset:8360
	ds_read_b32 v98, v10 offset:16552
	ds_read_b32 v99, v10 offset:24744
	ds_read_b32 v100, v10 offset:32936
	s_waitcnt vmcnt(15) lgkmcnt(0)
	v_fmac_f32_e32 v12, v96, v52
	v_fmac_f32_e32 v13, v96, v53
	v_fmac_f32_e32 v14, v96, v54
	v_fmac_f32_e32 v15, v96, v55
	v_fmac_f32_e32 v16, v97, v52
	v_fmac_f32_e32 v17, v97, v53
	v_fmac_f32_e32 v18, v97, v54
	v_fmac_f32_e32 v19, v97, v55
	v_fmac_f32_e32 v20, v98, v52
	v_fmac_f32_e32 v21, v98, v53
	v_fmac_f32_e32 v22, v98, v54
	v_fmac_f32_e32 v23, v98, v55
	v_fmac_f32_e32 v24, v99, v52
	v_fmac_f32_e32 v25, v99, v53
	v_fmac_f32_e32 v26, v99, v54
	v_fmac_f32_e32 v27, v99, v55
	v_fmac_f32_e32 v28, v100, v52
	v_fmac_f32_e32 v29, v100, v53
	v_fmac_f32_e32 v30, v100, v54
	v_fmac_f32_e32 v31, v100, v55
	global_load_dwordx4 v[52:55], v11, s[10:11]
	s_add_u32 s10, s10, 0x18000
	s_addc_u32 s11, s11, 0
	ds_read_b32 v96, v10 offset:176
	ds_read_b32 v97, v10 offset:8368
	ds_read_b32 v98, v10 offset:16560
	ds_read_b32 v99, v10 offset:24752
	ds_read_b32 v100, v10 offset:32944
	s_waitcnt vmcnt(15) lgkmcnt(0)
	v_fmac_f32_e32 v12, v96, v56
	v_fmac_f32_e32 v13, v96, v57
	v_fmac_f32_e32 v14, v96, v58
	v_fmac_f32_e32 v15, v96, v59
	v_fmac_f32_e32 v16, v97, v56
	v_fmac_f32_e32 v17, v97, v57
	v_fmac_f32_e32 v18, v97, v58
	v_fmac_f32_e32 v19, v97, v59
	v_fmac_f32_e32 v20, v98, v56
	v_fmac_f32_e32 v21, v98, v57
	v_fmac_f32_e32 v22, v98, v58
	v_fmac_f32_e32 v23, v98, v59
	v_fmac_f32_e32 v24, v99, v56
	v_fmac_f32_e32 v25, v99, v57
	v_fmac_f32_e32 v26, v99, v58
	v_fmac_f32_e32 v27, v99, v59
	v_fmac_f32_e32 v28, v100, v56
	v_fmac_f32_e32 v29, v100, v57
	v_fmac_f32_e32 v30, v100, v58
	v_fmac_f32_e32 v31, v100, v59
	global_load_dwordx4 v[56:59], v11, s[10:11]
	s_add_u32 s10, s10, 0x18000
	s_addc_u32 s11, s11, 0
	ds_read_b32 v96, v10 offset:184
	ds_read_b32 v97, v10 offset:8376
	ds_read_b32 v98, v10 offset:16568
	ds_read_b32 v99, v10 offset:24760
	ds_read_b32 v100, v10 offset:32952
	s_waitcnt vmcnt(15) lgkmcnt(0)
	v_fmac_f32_e32 v12, v96, v60
	v_fmac_f32_e32 v13, v96, v61
	v_fmac_f32_e32 v14, v96, v62
	v_fmac_f32_e32 v15, v96, v63
	v_fmac_f32_e32 v16, v97, v60
	v_fmac_f32_e32 v17, v97, v61
	v_fmac_f32_e32 v18, v97, v62
	v_fmac_f32_e32 v19, v97, v63
	v_fmac_f32_e32 v20, v98, v60
	v_fmac_f32_e32 v21, v98, v61
	v_fmac_f32_e32 v22, v98, v62
	v_fmac_f32_e32 v23, v98, v63
	v_fmac_f32_e32 v24, v99, v60
	v_fmac_f32_e32 v25, v99, v61
	v_fmac_f32_e32 v26, v99, v62
	v_fmac_f32_e32 v27, v99, v63
	v_fmac_f32_e32 v28, v100, v60
	v_fmac_f32_e32 v29, v100, v61
	v_fmac_f32_e32 v30, v100, v62
	v_fmac_f32_e32 v31, v100, v63
	global_load_dwordx4 v[60:63], v11, s[10:11]
	s_add_u32 s10, s10, 0x18000
	s_addc_u32 s11, s11, 0
	ds_read_b32 v96, v10 offset:192
	ds_read_b32 v97, v10 offset:8384
	ds_read_b32 v98, v10 offset:16576
	ds_read_b32 v99, v10 offset:24768
	ds_read_b32 v100, v10 offset:32960
	s_waitcnt vmcnt(15) lgkmcnt(0)
	v_fmac_f32_e32 v12, v96, v64
	v_fmac_f32_e32 v13, v96, v65
	v_fmac_f32_e32 v14, v96, v66
	v_fmac_f32_e32 v15, v96, v67
	v_fmac_f32_e32 v16, v97, v64
	v_fmac_f32_e32 v17, v97, v65
	v_fmac_f32_e32 v18, v97, v66
	v_fmac_f32_e32 v19, v97, v67
	v_fmac_f32_e32 v20, v98, v64
	v_fmac_f32_e32 v21, v98, v65
	v_fmac_f32_e32 v22, v98, v66
	v_fmac_f32_e32 v23, v98, v67
	v_fmac_f32_e32 v24, v99, v64
	v_fmac_f32_e32 v25, v99, v65
	v_fmac_f32_e32 v26, v99, v66
	v_fmac_f32_e32 v27, v99, v67
	v_fmac_f32_e32 v28, v100, v64
	v_fmac_f32_e32 v29, v100, v65
	v_fmac_f32_e32 v30, v100, v66
	v_fmac_f32_e32 v31, v100, v67
	global_load_dwordx4 v[64:67], v11, s[10:11]
	s_add_u32 s10, s10, 0x18000
	s_addc_u32 s11, s11, 0
	ds_read_b32 v96, v10 offset:200
	ds_read_b32 v97, v10 offset:8392
	ds_read_b32 v98, v10 offset:16584
	ds_read_b32 v99, v10 offset:24776
	ds_read_b32 v100, v10 offset:32968
	s_waitcnt vmcnt(15) lgkmcnt(0)
	v_fmac_f32_e32 v12, v96, v68
	v_fmac_f32_e32 v13, v96, v69
	v_fmac_f32_e32 v14, v96, v70
	v_fmac_f32_e32 v15, v96, v71
	v_fmac_f32_e32 v16, v97, v68
	v_fmac_f32_e32 v17, v97, v69
	v_fmac_f32_e32 v18, v97, v70
	v_fmac_f32_e32 v19, v97, v71
	v_fmac_f32_e32 v20, v98, v68
	v_fmac_f32_e32 v21, v98, v69
	v_fmac_f32_e32 v22, v98, v70
	v_fmac_f32_e32 v23, v98, v71
	v_fmac_f32_e32 v24, v99, v68
	v_fmac_f32_e32 v25, v99, v69
	v_fmac_f32_e32 v26, v99, v70
	v_fmac_f32_e32 v27, v99, v71
	v_fmac_f32_e32 v28, v100, v68
	v_fmac_f32_e32 v29, v100, v69
	v_fmac_f32_e32 v30, v100, v70
	v_fmac_f32_e32 v31, v100, v71
	global_load_dwordx4 v[68:71], v11, s[10:11]
	s_add_u32 s10, s10, 0x18000
	s_addc_u32 s11, s11, 0
	ds_read_b32 v96, v10 offset:208
	ds_read_b32 v97, v10 offset:8400
	ds_read_b32 v98, v10 offset:16592
	ds_read_b32 v99, v10 offset:24784
	ds_read_b32 v100, v10 offset:32976
	s_waitcnt vmcnt(15) lgkmcnt(0)
	v_fmac_f32_e32 v12, v96, v72
	v_fmac_f32_e32 v13, v96, v73
	v_fmac_f32_e32 v14, v96, v74
	v_fmac_f32_e32 v15, v96, v75
	v_fmac_f32_e32 v16, v97, v72
	v_fmac_f32_e32 v17, v97, v73
	v_fmac_f32_e32 v18, v97, v74
	v_fmac_f32_e32 v19, v97, v75
	v_fmac_f32_e32 v20, v98, v72
	v_fmac_f32_e32 v21, v98, v73
	v_fmac_f32_e32 v22, v98, v74
	v_fmac_f32_e32 v23, v98, v75
	v_fmac_f32_e32 v24, v99, v72
	v_fmac_f32_e32 v25, v99, v73
	v_fmac_f32_e32 v26, v99, v74
	v_fmac_f32_e32 v27, v99, v75
	v_fmac_f32_e32 v28, v100, v72
	v_fmac_f32_e32 v29, v100, v73
	v_fmac_f32_e32 v30, v100, v74
	v_fmac_f32_e32 v31, v100, v75
	global_load_dwordx4 v[72:75], v11, s[10:11]
	s_add_u32 s10, s10, 0x18000
	s_addc_u32 s11, s11, 0
	ds_read_b32 v96, v10 offset:216
	ds_read_b32 v97, v10 offset:8408
	ds_read_b32 v98, v10 offset:16600
	ds_read_b32 v99, v10 offset:24792
	ds_read_b32 v100, v10 offset:32984
	s_waitcnt vmcnt(15) lgkmcnt(0)
	v_fmac_f32_e32 v12, v96, v76
	v_fmac_f32_e32 v13, v96, v77
	v_fmac_f32_e32 v14, v96, v78
	v_fmac_f32_e32 v15, v96, v79
	v_fmac_f32_e32 v16, v97, v76
	v_fmac_f32_e32 v17, v97, v77
	v_fmac_f32_e32 v18, v97, v78
	v_fmac_f32_e32 v19, v97, v79
	v_fmac_f32_e32 v20, v98, v76
	v_fmac_f32_e32 v21, v98, v77
	v_fmac_f32_e32 v22, v98, v78
	v_fmac_f32_e32 v23, v98, v79
	v_fmac_f32_e32 v24, v99, v76
	v_fmac_f32_e32 v25, v99, v77
	v_fmac_f32_e32 v26, v99, v78
	v_fmac_f32_e32 v27, v99, v79
	v_fmac_f32_e32 v28, v100, v76
	v_fmac_f32_e32 v29, v100, v77
	v_fmac_f32_e32 v30, v100, v78
	v_fmac_f32_e32 v31, v100, v79
	global_load_dwordx4 v[76:79], v11, s[10:11]
	s_add_u32 s10, s10, 0x18000
	s_addc_u32 s11, s11, 0
	ds_read_b32 v96, v10 offset:224
	ds_read_b32 v97, v10 offset:8416
	ds_read_b32 v98, v10 offset:16608
	ds_read_b32 v99, v10 offset:24800
	ds_read_b32 v100, v10 offset:32992
	s_waitcnt vmcnt(15) lgkmcnt(0)
	v_fmac_f32_e32 v12, v96, v80
	v_fmac_f32_e32 v13, v96, v81
	v_fmac_f32_e32 v14, v96, v82
	v_fmac_f32_e32 v15, v96, v83
	v_fmac_f32_e32 v16, v97, v80
	v_fmac_f32_e32 v17, v97, v81
	v_fmac_f32_e32 v18, v97, v82
	v_fmac_f32_e32 v19, v97, v83
	v_fmac_f32_e32 v20, v98, v80
	v_fmac_f32_e32 v21, v98, v81
	v_fmac_f32_e32 v22, v98, v82
	v_fmac_f32_e32 v23, v98, v83
	v_fmac_f32_e32 v24, v99, v80
	v_fmac_f32_e32 v25, v99, v81
	v_fmac_f32_e32 v26, v99, v82
	v_fmac_f32_e32 v27, v99, v83
	v_fmac_f32_e32 v28, v100, v80
	v_fmac_f32_e32 v29, v100, v81
	v_fmac_f32_e32 v30, v100, v82
	v_fmac_f32_e32 v31, v100, v83
	global_load_dwordx4 v[80:83], v11, s[10:11]
	s_add_u32 s10, s10, 0x18000
	s_addc_u32 s11, s11, 0
	ds_read_b32 v96, v10 offset:232
	ds_read_b32 v97, v10 offset:8424
	ds_read_b32 v98, v10 offset:16616
	ds_read_b32 v99, v10 offset:24808
	ds_read_b32 v100, v10 offset:33000
	s_waitcnt vmcnt(15) lgkmcnt(0)
	v_fmac_f32_e32 v12, v96, v84
	v_fmac_f32_e32 v13, v96, v85
	v_fmac_f32_e32 v14, v96, v86
	v_fmac_f32_e32 v15, v96, v87
	v_fmac_f32_e32 v16, v97, v84
	v_fmac_f32_e32 v17, v97, v85
	v_fmac_f32_e32 v18, v97, v86
	v_fmac_f32_e32 v19, v97, v87
	v_fmac_f32_e32 v20, v98, v84
	v_fmac_f32_e32 v21, v98, v85
	v_fmac_f32_e32 v22, v98, v86
	v_fmac_f32_e32 v23, v98, v87
	v_fmac_f32_e32 v24, v99, v84
	v_fmac_f32_e32 v25, v99, v85
	v_fmac_f32_e32 v26, v99, v86
	v_fmac_f32_e32 v27, v99, v87
	v_fmac_f32_e32 v28, v100, v84
	v_fmac_f32_e32 v29, v100, v85
	v_fmac_f32_e32 v30, v100, v86
	v_fmac_f32_e32 v31, v100, v87
	global_load_dwordx4 v[84:87], v11, s[10:11]
	s_add_u32 s10, s10, 0x18000
	s_addc_u32 s11, s11, 0
	ds_read_b32 v96, v10 offset:240
	ds_read_b32 v97, v10 offset:8432
	ds_read_b32 v98, v10 offset:16624
	ds_read_b32 v99, v10 offset:24816
	ds_read_b32 v100, v10 offset:33008
	s_waitcnt vmcnt(15) lgkmcnt(0)
	v_fmac_f32_e32 v12, v96, v88
	v_fmac_f32_e32 v13, v96, v89
	v_fmac_f32_e32 v14, v96, v90
	v_fmac_f32_e32 v15, v96, v91
	v_fmac_f32_e32 v16, v97, v88
	v_fmac_f32_e32 v17, v97, v89
	v_fmac_f32_e32 v18, v97, v90
	v_fmac_f32_e32 v19, v97, v91
	v_fmac_f32_e32 v20, v98, v88
	v_fmac_f32_e32 v21, v98, v89
	v_fmac_f32_e32 v22, v98, v90
	v_fmac_f32_e32 v23, v98, v91
	v_fmac_f32_e32 v24, v99, v88
	v_fmac_f32_e32 v25, v99, v89
	v_fmac_f32_e32 v26, v99, v90
	v_fmac_f32_e32 v27, v99, v91
	v_fmac_f32_e32 v28, v100, v88
	v_fmac_f32_e32 v29, v100, v89
	v_fmac_f32_e32 v30, v100, v90
	v_fmac_f32_e32 v31, v100, v91
	global_load_dwordx4 v[88:91], v11, s[10:11]
	s_add_u32 s10, s10, 0x18000
	s_addc_u32 s11, s11, 0
	ds_read_b32 v96, v10 offset:248
	ds_read_b32 v97, v10 offset:8440
	ds_read_b32 v98, v10 offset:16632
	ds_read_b32 v99, v10 offset:24824
	ds_read_b32 v100, v10 offset:33016
	s_waitcnt vmcnt(15) lgkmcnt(0)
	v_fmac_f32_e32 v12, v96, v92
	v_fmac_f32_e32 v13, v96, v93
	v_fmac_f32_e32 v14, v96, v94
	v_fmac_f32_e32 v15, v96, v95
	v_fmac_f32_e32 v16, v97, v92
	v_fmac_f32_e32 v17, v97, v93
	v_fmac_f32_e32 v18, v97, v94
	v_fmac_f32_e32 v19, v97, v95
	v_fmac_f32_e32 v20, v98, v92
	v_fmac_f32_e32 v21, v98, v93
	v_fmac_f32_e32 v22, v98, v94
	v_fmac_f32_e32 v23, v98, v95
	v_fmac_f32_e32 v24, v99, v92
	v_fmac_f32_e32 v25, v99, v93
	v_fmac_f32_e32 v26, v99, v94
	v_fmac_f32_e32 v27, v99, v95
	v_fmac_f32_e32 v28, v100, v92
	v_fmac_f32_e32 v29, v100, v93
	v_fmac_f32_e32 v30, v100, v94
	v_fmac_f32_e32 v31, v100, v95
	global_load_dwordx4 v[92:95], v11, s[10:11]
	s_add_u32 s10, s10, 0x18000
	s_addc_u32 s11, s11, 0
	ds_read_b32 v96, v10 offset:256
	ds_read_b32 v97, v10 offset:8448
	ds_read_b32 v98, v10 offset:16640
	ds_read_b32 v99, v10 offset:24832
	ds_read_b32 v100, v10 offset:33024
	s_waitcnt vmcnt(15) lgkmcnt(0)
	v_fmac_f32_e32 v12, v96, v32
	v_fmac_f32_e32 v13, v96, v33
	v_fmac_f32_e32 v14, v96, v34
	v_fmac_f32_e32 v15, v96, v35
	v_fmac_f32_e32 v16, v97, v32
	v_fmac_f32_e32 v17, v97, v33
	v_fmac_f32_e32 v18, v97, v34
	v_fmac_f32_e32 v19, v97, v35
	v_fmac_f32_e32 v20, v98, v32
	v_fmac_f32_e32 v21, v98, v33
	v_fmac_f32_e32 v22, v98, v34
	v_fmac_f32_e32 v23, v98, v35
	v_fmac_f32_e32 v24, v99, v32
	v_fmac_f32_e32 v25, v99, v33
	v_fmac_f32_e32 v26, v99, v34
	v_fmac_f32_e32 v27, v99, v35
	v_fmac_f32_e32 v28, v100, v32
	v_fmac_f32_e32 v29, v100, v33
	v_fmac_f32_e32 v30, v100, v34
	v_fmac_f32_e32 v31, v100, v35
	global_load_dwordx4 v[32:35], v11, s[10:11]
	s_add_u32 s10, s10, 0x18000
	s_addc_u32 s11, s11, 0
	ds_read_b32 v96, v10 offset:264
	ds_read_b32 v97, v10 offset:8456
	ds_read_b32 v98, v10 offset:16648
	ds_read_b32 v99, v10 offset:24840
	ds_read_b32 v100, v10 offset:33032
	s_waitcnt vmcnt(15) lgkmcnt(0)
	v_fmac_f32_e32 v12, v96, v36
	v_fmac_f32_e32 v13, v96, v37
	v_fmac_f32_e32 v14, v96, v38
	v_fmac_f32_e32 v15, v96, v39
	v_fmac_f32_e32 v16, v97, v36
	v_fmac_f32_e32 v17, v97, v37
	v_fmac_f32_e32 v18, v97, v38
	v_fmac_f32_e32 v19, v97, v39
	v_fmac_f32_e32 v20, v98, v36
	v_fmac_f32_e32 v21, v98, v37
	v_fmac_f32_e32 v22, v98, v38
	v_fmac_f32_e32 v23, v98, v39
	v_fmac_f32_e32 v24, v99, v36
	v_fmac_f32_e32 v25, v99, v37
	v_fmac_f32_e32 v26, v99, v38
	v_fmac_f32_e32 v27, v99, v39
	v_fmac_f32_e32 v28, v100, v36
	v_fmac_f32_e32 v29, v100, v37
	v_fmac_f32_e32 v30, v100, v38
	v_fmac_f32_e32 v31, v100, v39
	global_load_dwordx4 v[36:39], v11, s[10:11]
	s_add_u32 s10, s10, 0x18000
	s_addc_u32 s11, s11, 0
	ds_read_b32 v96, v10 offset:272
	ds_read_b32 v97, v10 offset:8464
	ds_read_b32 v98, v10 offset:16656
	ds_read_b32 v99, v10 offset:24848
	ds_read_b32 v100, v10 offset:33040
	s_waitcnt vmcnt(15) lgkmcnt(0)
	v_fmac_f32_e32 v12, v96, v40
	v_fmac_f32_e32 v13, v96, v41
	v_fmac_f32_e32 v14, v96, v42
	v_fmac_f32_e32 v15, v96, v43
	v_fmac_f32_e32 v16, v97, v40
	v_fmac_f32_e32 v17, v97, v41
	v_fmac_f32_e32 v18, v97, v42
	v_fmac_f32_e32 v19, v97, v43
	v_fmac_f32_e32 v20, v98, v40
	v_fmac_f32_e32 v21, v98, v41
	v_fmac_f32_e32 v22, v98, v42
	v_fmac_f32_e32 v23, v98, v43
	v_fmac_f32_e32 v24, v99, v40
	v_fmac_f32_e32 v25, v99, v41
	v_fmac_f32_e32 v26, v99, v42
	v_fmac_f32_e32 v27, v99, v43
	v_fmac_f32_e32 v28, v100, v40
	v_fmac_f32_e32 v29, v100, v41
	v_fmac_f32_e32 v30, v100, v42
	v_fmac_f32_e32 v31, v100, v43
	global_load_dwordx4 v[40:43], v11, s[10:11]
	s_add_u32 s10, s10, 0x18000
	s_addc_u32 s11, s11, 0
	ds_read_b32 v96, v10 offset:280
	ds_read_b32 v97, v10 offset:8472
	ds_read_b32 v98, v10 offset:16664
	ds_read_b32 v99, v10 offset:24856
	ds_read_b32 v100, v10 offset:33048
	s_waitcnt vmcnt(15) lgkmcnt(0)
	v_fmac_f32_e32 v12, v96, v44
	v_fmac_f32_e32 v13, v96, v45
	v_fmac_f32_e32 v14, v96, v46
	v_fmac_f32_e32 v15, v96, v47
	v_fmac_f32_e32 v16, v97, v44
	v_fmac_f32_e32 v17, v97, v45
	v_fmac_f32_e32 v18, v97, v46
	v_fmac_f32_e32 v19, v97, v47
	v_fmac_f32_e32 v20, v98, v44
	v_fmac_f32_e32 v21, v98, v45
	v_fmac_f32_e32 v22, v98, v46
	v_fmac_f32_e32 v23, v98, v47
	v_fmac_f32_e32 v24, v99, v44
	v_fmac_f32_e32 v25, v99, v45
	v_fmac_f32_e32 v26, v99, v46
	v_fmac_f32_e32 v27, v99, v47
	v_fmac_f32_e32 v28, v100, v44
	v_fmac_f32_e32 v29, v100, v45
	v_fmac_f32_e32 v30, v100, v46
	v_fmac_f32_e32 v31, v100, v47
	global_load_dwordx4 v[44:47], v11, s[10:11]
	s_add_u32 s10, s10, 0x18000
	s_addc_u32 s11, s11, 0
	ds_read_b32 v96, v10 offset:288
	ds_read_b32 v97, v10 offset:8480
	ds_read_b32 v98, v10 offset:16672
	ds_read_b32 v99, v10 offset:24864
	ds_read_b32 v100, v10 offset:33056
	s_waitcnt vmcnt(15) lgkmcnt(0)
	v_fmac_f32_e32 v12, v96, v48
	v_fmac_f32_e32 v13, v96, v49
	v_fmac_f32_e32 v14, v96, v50
	v_fmac_f32_e32 v15, v96, v51
	v_fmac_f32_e32 v16, v97, v48
	v_fmac_f32_e32 v17, v97, v49
	v_fmac_f32_e32 v18, v97, v50
	v_fmac_f32_e32 v19, v97, v51
	v_fmac_f32_e32 v20, v98, v48
	v_fmac_f32_e32 v21, v98, v49
	v_fmac_f32_e32 v22, v98, v50
	v_fmac_f32_e32 v23, v98, v51
	v_fmac_f32_e32 v24, v99, v48
	v_fmac_f32_e32 v25, v99, v49
	v_fmac_f32_e32 v26, v99, v50
	v_fmac_f32_e32 v27, v99, v51
	v_fmac_f32_e32 v28, v100, v48
	v_fmac_f32_e32 v29, v100, v49
	v_fmac_f32_e32 v30, v100, v50
	v_fmac_f32_e32 v31, v100, v51
	global_load_dwordx4 v[48:51], v11, s[10:11]
	s_add_u32 s10, s10, 0x18000
	s_addc_u32 s11, s11, 0
	ds_read_b32 v96, v10 offset:296
	ds_read_b32 v97, v10 offset:8488
	ds_read_b32 v98, v10 offset:16680
	ds_read_b32 v99, v10 offset:24872
	ds_read_b32 v100, v10 offset:33064
	s_waitcnt vmcnt(15) lgkmcnt(0)
	v_fmac_f32_e32 v12, v96, v52
	v_fmac_f32_e32 v13, v96, v53
	v_fmac_f32_e32 v14, v96, v54
	v_fmac_f32_e32 v15, v96, v55
	v_fmac_f32_e32 v16, v97, v52
	v_fmac_f32_e32 v17, v97, v53
	v_fmac_f32_e32 v18, v97, v54
	v_fmac_f32_e32 v19, v97, v55
	v_fmac_f32_e32 v20, v98, v52
	v_fmac_f32_e32 v21, v98, v53
	v_fmac_f32_e32 v22, v98, v54
	v_fmac_f32_e32 v23, v98, v55
	v_fmac_f32_e32 v24, v99, v52
	v_fmac_f32_e32 v25, v99, v53
	v_fmac_f32_e32 v26, v99, v54
	v_fmac_f32_e32 v27, v99, v55
	v_fmac_f32_e32 v28, v100, v52
	v_fmac_f32_e32 v29, v100, v53
	v_fmac_f32_e32 v30, v100, v54
	v_fmac_f32_e32 v31, v100, v55
	global_load_dwordx4 v[52:55], v11, s[10:11]
	s_add_u32 s10, s10, 0x18000
	s_addc_u32 s11, s11, 0
	ds_read_b32 v96, v10 offset:304
	ds_read_b32 v97, v10 offset:8496
	ds_read_b32 v98, v10 offset:16688
	ds_read_b32 v99, v10 offset:24880
	ds_read_b32 v100, v10 offset:33072
	s_waitcnt vmcnt(15) lgkmcnt(0)
	v_fmac_f32_e32 v12, v96, v56
	v_fmac_f32_e32 v13, v96, v57
	v_fmac_f32_e32 v14, v96, v58
	v_fmac_f32_e32 v15, v96, v59
	v_fmac_f32_e32 v16, v97, v56
	v_fmac_f32_e32 v17, v97, v57
	v_fmac_f32_e32 v18, v97, v58
	v_fmac_f32_e32 v19, v97, v59
	v_fmac_f32_e32 v20, v98, v56
	v_fmac_f32_e32 v21, v98, v57
	v_fmac_f32_e32 v22, v98, v58
	v_fmac_f32_e32 v23, v98, v59
	v_fmac_f32_e32 v24, v99, v56
	v_fmac_f32_e32 v25, v99, v57
	v_fmac_f32_e32 v26, v99, v58
	v_fmac_f32_e32 v27, v99, v59
	v_fmac_f32_e32 v28, v100, v56
	v_fmac_f32_e32 v29, v100, v57
	v_fmac_f32_e32 v30, v100, v58
	v_fmac_f32_e32 v31, v100, v59
	global_load_dwordx4 v[56:59], v11, s[10:11]
	s_add_u32 s10, s10, 0x18000
	s_addc_u32 s11, s11, 0
	ds_read_b32 v96, v10 offset:312
	ds_read_b32 v97, v10 offset:8504
	ds_read_b32 v98, v10 offset:16696
	ds_read_b32 v99, v10 offset:24888
	ds_read_b32 v100, v10 offset:33080
	s_waitcnt vmcnt(15) lgkmcnt(0)
	v_fmac_f32_e32 v12, v96, v60
	v_fmac_f32_e32 v13, v96, v61
	v_fmac_f32_e32 v14, v96, v62
	v_fmac_f32_e32 v15, v96, v63
	v_fmac_f32_e32 v16, v97, v60
	v_fmac_f32_e32 v17, v97, v61
	v_fmac_f32_e32 v18, v97, v62
	v_fmac_f32_e32 v19, v97, v63
	v_fmac_f32_e32 v20, v98, v60
	v_fmac_f32_e32 v21, v98, v61
	v_fmac_f32_e32 v22, v98, v62
	v_fmac_f32_e32 v23, v98, v63
	v_fmac_f32_e32 v24, v99, v60
	v_fmac_f32_e32 v25, v99, v61
	v_fmac_f32_e32 v26, v99, v62
	v_fmac_f32_e32 v27, v99, v63
	v_fmac_f32_e32 v28, v100, v60
	v_fmac_f32_e32 v29, v100, v61
	v_fmac_f32_e32 v30, v100, v62
	v_fmac_f32_e32 v31, v100, v63
	global_load_dwordx4 v[60:63], v11, s[10:11]
	s_add_u32 s10, s10, 0x18000
	s_addc_u32 s11, s11, 0
	ds_read_b32 v96, v10 offset:320
	ds_read_b32 v97, v10 offset:8512
	ds_read_b32 v98, v10 offset:16704
	ds_read_b32 v99, v10 offset:24896
	ds_read_b32 v100, v10 offset:33088
	s_waitcnt vmcnt(15) lgkmcnt(0)
	v_fmac_f32_e32 v12, v96, v64
	v_fmac_f32_e32 v13, v96, v65
	v_fmac_f32_e32 v14, v96, v66
	v_fmac_f32_e32 v15, v96, v67
	v_fmac_f32_e32 v16, v97, v64
	v_fmac_f32_e32 v17, v97, v65
	v_fmac_f32_e32 v18, v97, v66
	v_fmac_f32_e32 v19, v97, v67
	v_fmac_f32_e32 v20, v98, v64
	v_fmac_f32_e32 v21, v98, v65
	v_fmac_f32_e32 v22, v98, v66
	v_fmac_f32_e32 v23, v98, v67
	v_fmac_f32_e32 v24, v99, v64
	v_fmac_f32_e32 v25, v99, v65
	v_fmac_f32_e32 v26, v99, v66
	v_fmac_f32_e32 v27, v99, v67
	v_fmac_f32_e32 v28, v100, v64
	v_fmac_f32_e32 v29, v100, v65
	v_fmac_f32_e32 v30, v100, v66
	v_fmac_f32_e32 v31, v100, v67
	global_load_dwordx4 v[64:67], v11, s[10:11]
	s_add_u32 s10, s10, 0x18000
	s_addc_u32 s11, s11, 0
	ds_read_b32 v96, v10 offset:328
	ds_read_b32 v97, v10 offset:8520
	ds_read_b32 v98, v10 offset:16712
	ds_read_b32 v99, v10 offset:24904
	ds_read_b32 v100, v10 offset:33096
	s_waitcnt vmcnt(15) lgkmcnt(0)
	v_fmac_f32_e32 v12, v96, v68
	v_fmac_f32_e32 v13, v96, v69
	v_fmac_f32_e32 v14, v96, v70
	v_fmac_f32_e32 v15, v96, v71
	v_fmac_f32_e32 v16, v97, v68
	v_fmac_f32_e32 v17, v97, v69
	v_fmac_f32_e32 v18, v97, v70
	v_fmac_f32_e32 v19, v97, v71
	v_fmac_f32_e32 v20, v98, v68
	v_fmac_f32_e32 v21, v98, v69
	v_fmac_f32_e32 v22, v98, v70
	v_fmac_f32_e32 v23, v98, v71
	v_fmac_f32_e32 v24, v99, v68
	v_fmac_f32_e32 v25, v99, v69
	v_fmac_f32_e32 v26, v99, v70
	v_fmac_f32_e32 v27, v99, v71
	v_fmac_f32_e32 v28, v100, v68
	v_fmac_f32_e32 v29, v100, v69
	v_fmac_f32_e32 v30, v100, v70
	v_fmac_f32_e32 v31, v100, v71
	global_load_dwordx4 v[68:71], v11, s[10:11]
	s_add_u32 s10, s10, 0x18000
	s_addc_u32 s11, s11, 0
	ds_read_b32 v96, v10 offset:336
	ds_read_b32 v97, v10 offset:8528
	ds_read_b32 v98, v10 offset:16720
	ds_read_b32 v99, v10 offset:24912
	ds_read_b32 v100, v10 offset:33104
	s_waitcnt vmcnt(15) lgkmcnt(0)
	v_fmac_f32_e32 v12, v96, v72
	v_fmac_f32_e32 v13, v96, v73
	v_fmac_f32_e32 v14, v96, v74
	v_fmac_f32_e32 v15, v96, v75
	v_fmac_f32_e32 v16, v97, v72
	v_fmac_f32_e32 v17, v97, v73
	v_fmac_f32_e32 v18, v97, v74
	v_fmac_f32_e32 v19, v97, v75
	v_fmac_f32_e32 v20, v98, v72
	v_fmac_f32_e32 v21, v98, v73
	v_fmac_f32_e32 v22, v98, v74
	v_fmac_f32_e32 v23, v98, v75
	v_fmac_f32_e32 v24, v99, v72
	v_fmac_f32_e32 v25, v99, v73
	v_fmac_f32_e32 v26, v99, v74
	v_fmac_f32_e32 v27, v99, v75
	v_fmac_f32_e32 v28, v100, v72
	v_fmac_f32_e32 v29, v100, v73
	v_fmac_f32_e32 v30, v100, v74
	v_fmac_f32_e32 v31, v100, v75
	global_load_dwordx4 v[72:75], v11, s[10:11]
	s_add_u32 s10, s10, 0x18000
	s_addc_u32 s11, s11, 0
	ds_read_b32 v96, v10 offset:344
	ds_read_b32 v97, v10 offset:8536
	ds_read_b32 v98, v10 offset:16728
	ds_read_b32 v99, v10 offset:24920
	ds_read_b32 v100, v10 offset:33112
	s_waitcnt vmcnt(15) lgkmcnt(0)
	v_fmac_f32_e32 v12, v96, v76
	v_fmac_f32_e32 v13, v96, v77
	v_fmac_f32_e32 v14, v96, v78
	v_fmac_f32_e32 v15, v96, v79
	v_fmac_f32_e32 v16, v97, v76
	v_fmac_f32_e32 v17, v97, v77
	v_fmac_f32_e32 v18, v97, v78
	v_fmac_f32_e32 v19, v97, v79
	v_fmac_f32_e32 v20, v98, v76
	v_fmac_f32_e32 v21, v98, v77
	v_fmac_f32_e32 v22, v98, v78
	v_fmac_f32_e32 v23, v98, v79
	v_fmac_f32_e32 v24, v99, v76
	v_fmac_f32_e32 v25, v99, v77
	v_fmac_f32_e32 v26, v99, v78
	v_fmac_f32_e32 v27, v99, v79
	v_fmac_f32_e32 v28, v100, v76
	v_fmac_f32_e32 v29, v100, v77
	v_fmac_f32_e32 v30, v100, v78
	v_fmac_f32_e32 v31, v100, v79
	global_load_dwordx4 v[76:79], v11, s[10:11]
	s_add_u32 s10, s10, 0x18000
	s_addc_u32 s11, s11, 0
	ds_read_b32 v96, v10 offset:352
	ds_read_b32 v97, v10 offset:8544
	ds_read_b32 v98, v10 offset:16736
	ds_read_b32 v99, v10 offset:24928
	ds_read_b32 v100, v10 offset:33120
	s_waitcnt vmcnt(15) lgkmcnt(0)
	v_fmac_f32_e32 v12, v96, v80
	v_fmac_f32_e32 v13, v96, v81
	v_fmac_f32_e32 v14, v96, v82
	v_fmac_f32_e32 v15, v96, v83
	v_fmac_f32_e32 v16, v97, v80
	v_fmac_f32_e32 v17, v97, v81
	v_fmac_f32_e32 v18, v97, v82
	v_fmac_f32_e32 v19, v97, v83
	v_fmac_f32_e32 v20, v98, v80
	v_fmac_f32_e32 v21, v98, v81
	v_fmac_f32_e32 v22, v98, v82
	v_fmac_f32_e32 v23, v98, v83
	v_fmac_f32_e32 v24, v99, v80
	v_fmac_f32_e32 v25, v99, v81
	v_fmac_f32_e32 v26, v99, v82
	v_fmac_f32_e32 v27, v99, v83
	v_fmac_f32_e32 v28, v100, v80
	v_fmac_f32_e32 v29, v100, v81
	v_fmac_f32_e32 v30, v100, v82
	v_fmac_f32_e32 v31, v100, v83
	global_load_dwordx4 v[80:83], v11, s[10:11]
	s_add_u32 s10, s10, 0x18000
	s_addc_u32 s11, s11, 0
	ds_read_b32 v96, v10 offset:360
	ds_read_b32 v97, v10 offset:8552
	ds_read_b32 v98, v10 offset:16744
	ds_read_b32 v99, v10 offset:24936
	ds_read_b32 v100, v10 offset:33128
	s_waitcnt vmcnt(15) lgkmcnt(0)
	v_fmac_f32_e32 v12, v96, v84
	v_fmac_f32_e32 v13, v96, v85
	v_fmac_f32_e32 v14, v96, v86
	v_fmac_f32_e32 v15, v96, v87
	v_fmac_f32_e32 v16, v97, v84
	v_fmac_f32_e32 v17, v97, v85
	v_fmac_f32_e32 v18, v97, v86
	v_fmac_f32_e32 v19, v97, v87
	v_fmac_f32_e32 v20, v98, v84
	v_fmac_f32_e32 v21, v98, v85
	v_fmac_f32_e32 v22, v98, v86
	v_fmac_f32_e32 v23, v98, v87
	v_fmac_f32_e32 v24, v99, v84
	v_fmac_f32_e32 v25, v99, v85
	v_fmac_f32_e32 v26, v99, v86
	v_fmac_f32_e32 v27, v99, v87
	v_fmac_f32_e32 v28, v100, v84
	v_fmac_f32_e32 v29, v100, v85
	v_fmac_f32_e32 v30, v100, v86
	v_fmac_f32_e32 v31, v100, v87
	global_load_dwordx4 v[84:87], v11, s[10:11]
	s_add_u32 s10, s10, 0x18000
	s_addc_u32 s11, s11, 0
	ds_read_b32 v96, v10 offset:368
	ds_read_b32 v97, v10 offset:8560
	ds_read_b32 v98, v10 offset:16752
	ds_read_b32 v99, v10 offset:24944
	ds_read_b32 v100, v10 offset:33136
	s_waitcnt vmcnt(15) lgkmcnt(0)
	v_fmac_f32_e32 v12, v96, v88
	v_fmac_f32_e32 v13, v96, v89
	v_fmac_f32_e32 v14, v96, v90
	v_fmac_f32_e32 v15, v96, v91
	v_fmac_f32_e32 v16, v97, v88
	v_fmac_f32_e32 v17, v97, v89
	v_fmac_f32_e32 v18, v97, v90
	v_fmac_f32_e32 v19, v97, v91
	v_fmac_f32_e32 v20, v98, v88
	v_fmac_f32_e32 v21, v98, v89
	v_fmac_f32_e32 v22, v98, v90
	v_fmac_f32_e32 v23, v98, v91
	v_fmac_f32_e32 v24, v99, v88
	v_fmac_f32_e32 v25, v99, v89
	v_fmac_f32_e32 v26, v99, v90
	v_fmac_f32_e32 v27, v99, v91
	v_fmac_f32_e32 v28, v100, v88
	v_fmac_f32_e32 v29, v100, v89
	v_fmac_f32_e32 v30, v100, v90
	v_fmac_f32_e32 v31, v100, v91
	global_load_dwordx4 v[88:91], v11, s[10:11]
	s_add_u32 s10, s10, 0x18000
	s_addc_u32 s11, s11, 0
	ds_read_b32 v96, v10 offset:376
	ds_read_b32 v97, v10 offset:8568
	ds_read_b32 v98, v10 offset:16760
	ds_read_b32 v99, v10 offset:24952
	ds_read_b32 v100, v10 offset:33144
	s_waitcnt vmcnt(15) lgkmcnt(0)
	v_fmac_f32_e32 v12, v96, v92
	v_fmac_f32_e32 v13, v96, v93
	v_fmac_f32_e32 v14, v96, v94
	v_fmac_f32_e32 v15, v96, v95
	v_fmac_f32_e32 v16, v97, v92
	v_fmac_f32_e32 v17, v97, v93
	v_fmac_f32_e32 v18, v97, v94
	v_fmac_f32_e32 v19, v97, v95
	v_fmac_f32_e32 v20, v98, v92
	v_fmac_f32_e32 v21, v98, v93
	v_fmac_f32_e32 v22, v98, v94
	v_fmac_f32_e32 v23, v98, v95
	v_fmac_f32_e32 v24, v99, v92
	v_fmac_f32_e32 v25, v99, v93
	v_fmac_f32_e32 v26, v99, v94
	v_fmac_f32_e32 v27, v99, v95
	v_fmac_f32_e32 v28, v100, v92
	v_fmac_f32_e32 v29, v100, v93
	v_fmac_f32_e32 v30, v100, v94
	v_fmac_f32_e32 v31, v100, v95
	global_load_dwordx4 v[92:95], v11, s[10:11]
	s_add_u32 s10, s10, 0x18000
	s_addc_u32 s11, s11, 0
	ds_read_b32 v96, v10 offset:384
	ds_read_b32 v97, v10 offset:8576
	ds_read_b32 v98, v10 offset:16768
	ds_read_b32 v99, v10 offset:24960
	ds_read_b32 v100, v10 offset:33152
	s_waitcnt vmcnt(15) lgkmcnt(0)
	v_fmac_f32_e32 v12, v96, v32
	v_fmac_f32_e32 v13, v96, v33
	v_fmac_f32_e32 v14, v96, v34
	v_fmac_f32_e32 v15, v96, v35
	v_fmac_f32_e32 v16, v97, v32
	v_fmac_f32_e32 v17, v97, v33
	v_fmac_f32_e32 v18, v97, v34
	v_fmac_f32_e32 v19, v97, v35
	v_fmac_f32_e32 v20, v98, v32
	v_fmac_f32_e32 v21, v98, v33
	v_fmac_f32_e32 v22, v98, v34
	v_fmac_f32_e32 v23, v98, v35
	v_fmac_f32_e32 v24, v99, v32
	v_fmac_f32_e32 v25, v99, v33
	v_fmac_f32_e32 v26, v99, v34
	v_fmac_f32_e32 v27, v99, v35
	v_fmac_f32_e32 v28, v100, v32
	v_fmac_f32_e32 v29, v100, v33
	v_fmac_f32_e32 v30, v100, v34
	v_fmac_f32_e32 v31, v100, v35
	global_load_dwordx4 v[32:35], v11, s[10:11]
	s_add_u32 s10, s10, 0x18000
	s_addc_u32 s11, s11, 0
	ds_read_b32 v96, v10 offset:392
	ds_read_b32 v97, v10 offset:8584
	ds_read_b32 v98, v10 offset:16776
	ds_read_b32 v99, v10 offset:24968
	ds_read_b32 v100, v10 offset:33160
	s_waitcnt vmcnt(15) lgkmcnt(0)
	v_fmac_f32_e32 v12, v96, v36
	v_fmac_f32_e32 v13, v96, v37
	v_fmac_f32_e32 v14, v96, v38
	v_fmac_f32_e32 v15, v96, v39
	v_fmac_f32_e32 v16, v97, v36
	v_fmac_f32_e32 v17, v97, v37
	v_fmac_f32_e32 v18, v97, v38
	v_fmac_f32_e32 v19, v97, v39
	v_fmac_f32_e32 v20, v98, v36
	v_fmac_f32_e32 v21, v98, v37
	v_fmac_f32_e32 v22, v98, v38
	v_fmac_f32_e32 v23, v98, v39
	v_fmac_f32_e32 v24, v99, v36
	v_fmac_f32_e32 v25, v99, v37
	v_fmac_f32_e32 v26, v99, v38
	v_fmac_f32_e32 v27, v99, v39
	v_fmac_f32_e32 v28, v100, v36
	v_fmac_f32_e32 v29, v100, v37
	v_fmac_f32_e32 v30, v100, v38
	v_fmac_f32_e32 v31, v100, v39
	global_load_dwordx4 v[36:39], v11, s[10:11]
	s_add_u32 s10, s10, 0x18000
	s_addc_u32 s11, s11, 0
	ds_read_b32 v96, v10 offset:400
	ds_read_b32 v97, v10 offset:8592
	ds_read_b32 v98, v10 offset:16784
	ds_read_b32 v99, v10 offset:24976
	ds_read_b32 v100, v10 offset:33168
	s_waitcnt vmcnt(15) lgkmcnt(0)
	v_fmac_f32_e32 v12, v96, v40
	v_fmac_f32_e32 v13, v96, v41
	v_fmac_f32_e32 v14, v96, v42
	v_fmac_f32_e32 v15, v96, v43
	v_fmac_f32_e32 v16, v97, v40
	v_fmac_f32_e32 v17, v97, v41
	v_fmac_f32_e32 v18, v97, v42
	v_fmac_f32_e32 v19, v97, v43
	v_fmac_f32_e32 v20, v98, v40
	v_fmac_f32_e32 v21, v98, v41
	v_fmac_f32_e32 v22, v98, v42
	v_fmac_f32_e32 v23, v98, v43
	v_fmac_f32_e32 v24, v99, v40
	v_fmac_f32_e32 v25, v99, v41
	v_fmac_f32_e32 v26, v99, v42
	v_fmac_f32_e32 v27, v99, v43
	v_fmac_f32_e32 v28, v100, v40
	v_fmac_f32_e32 v29, v100, v41
	v_fmac_f32_e32 v30, v100, v42
	v_fmac_f32_e32 v31, v100, v43
	global_load_dwordx4 v[40:43], v11, s[10:11]
	s_add_u32 s10, s10, 0x18000
	s_addc_u32 s11, s11, 0
	ds_read_b32 v96, v10 offset:408
	ds_read_b32 v97, v10 offset:8600
	ds_read_b32 v98, v10 offset:16792
	ds_read_b32 v99, v10 offset:24984
	ds_read_b32 v100, v10 offset:33176
	s_waitcnt vmcnt(15) lgkmcnt(0)
	v_fmac_f32_e32 v12, v96, v44
	v_fmac_f32_e32 v13, v96, v45
	v_fmac_f32_e32 v14, v96, v46
	v_fmac_f32_e32 v15, v96, v47
	v_fmac_f32_e32 v16, v97, v44
	v_fmac_f32_e32 v17, v97, v45
	v_fmac_f32_e32 v18, v97, v46
	v_fmac_f32_e32 v19, v97, v47
	v_fmac_f32_e32 v20, v98, v44
	v_fmac_f32_e32 v21, v98, v45
	v_fmac_f32_e32 v22, v98, v46
	v_fmac_f32_e32 v23, v98, v47
	v_fmac_f32_e32 v24, v99, v44
	v_fmac_f32_e32 v25, v99, v45
	v_fmac_f32_e32 v26, v99, v46
	v_fmac_f32_e32 v27, v99, v47
	v_fmac_f32_e32 v28, v100, v44
	v_fmac_f32_e32 v29, v100, v45
	v_fmac_f32_e32 v30, v100, v46
	v_fmac_f32_e32 v31, v100, v47
	global_load_dwordx4 v[44:47], v11, s[10:11]
	s_add_u32 s10, s10, 0x18000
	s_addc_u32 s11, s11, 0
	ds_read_b32 v96, v10 offset:416
	ds_read_b32 v97, v10 offset:8608
	ds_read_b32 v98, v10 offset:16800
	ds_read_b32 v99, v10 offset:24992
	ds_read_b32 v100, v10 offset:33184
	s_waitcnt vmcnt(15) lgkmcnt(0)
	v_fmac_f32_e32 v12, v96, v48
	v_fmac_f32_e32 v13, v96, v49
	v_fmac_f32_e32 v14, v96, v50
	v_fmac_f32_e32 v15, v96, v51
	v_fmac_f32_e32 v16, v97, v48
	v_fmac_f32_e32 v17, v97, v49
	v_fmac_f32_e32 v18, v97, v50
	v_fmac_f32_e32 v19, v97, v51
	v_fmac_f32_e32 v20, v98, v48
	v_fmac_f32_e32 v21, v98, v49
	v_fmac_f32_e32 v22, v98, v50
	v_fmac_f32_e32 v23, v98, v51
	v_fmac_f32_e32 v24, v99, v48
	v_fmac_f32_e32 v25, v99, v49
	v_fmac_f32_e32 v26, v99, v50
	v_fmac_f32_e32 v27, v99, v51
	v_fmac_f32_e32 v28, v100, v48
	v_fmac_f32_e32 v29, v100, v49
	v_fmac_f32_e32 v30, v100, v50
	v_fmac_f32_e32 v31, v100, v51
	global_load_dwordx4 v[48:51], v11, s[10:11]
	s_add_u32 s10, s10, 0x18000
	s_addc_u32 s11, s11, 0
	ds_read_b32 v96, v10 offset:424
	ds_read_b32 v97, v10 offset:8616
	ds_read_b32 v98, v10 offset:16808
	ds_read_b32 v99, v10 offset:25000
	ds_read_b32 v100, v10 offset:33192
	s_waitcnt vmcnt(15) lgkmcnt(0)
	v_fmac_f32_e32 v12, v96, v52
	v_fmac_f32_e32 v13, v96, v53
	v_fmac_f32_e32 v14, v96, v54
	v_fmac_f32_e32 v15, v96, v55
	v_fmac_f32_e32 v16, v97, v52
	v_fmac_f32_e32 v17, v97, v53
	v_fmac_f32_e32 v18, v97, v54
	v_fmac_f32_e32 v19, v97, v55
	v_fmac_f32_e32 v20, v98, v52
	v_fmac_f32_e32 v21, v98, v53
	v_fmac_f32_e32 v22, v98, v54
	v_fmac_f32_e32 v23, v98, v55
	v_fmac_f32_e32 v24, v99, v52
	v_fmac_f32_e32 v25, v99, v53
	v_fmac_f32_e32 v26, v99, v54
	v_fmac_f32_e32 v27, v99, v55
	v_fmac_f32_e32 v28, v100, v52
	v_fmac_f32_e32 v29, v100, v53
	v_fmac_f32_e32 v30, v100, v54
	v_fmac_f32_e32 v31, v100, v55
	global_load_dwordx4 v[52:55], v11, s[10:11]
	s_add_u32 s10, s10, 0x18000
	s_addc_u32 s11, s11, 0
	ds_read_b32 v96, v10 offset:432
	ds_read_b32 v97, v10 offset:8624
	ds_read_b32 v98, v10 offset:16816
	ds_read_b32 v99, v10 offset:25008
	ds_read_b32 v100, v10 offset:33200
	s_waitcnt vmcnt(15) lgkmcnt(0)
	v_fmac_f32_e32 v12, v96, v56
	v_fmac_f32_e32 v13, v96, v57
	v_fmac_f32_e32 v14, v96, v58
	v_fmac_f32_e32 v15, v96, v59
	v_fmac_f32_e32 v16, v97, v56
	v_fmac_f32_e32 v17, v97, v57
	v_fmac_f32_e32 v18, v97, v58
	v_fmac_f32_e32 v19, v97, v59
	v_fmac_f32_e32 v20, v98, v56
	v_fmac_f32_e32 v21, v98, v57
	v_fmac_f32_e32 v22, v98, v58
	v_fmac_f32_e32 v23, v98, v59
	v_fmac_f32_e32 v24, v99, v56
	v_fmac_f32_e32 v25, v99, v57
	v_fmac_f32_e32 v26, v99, v58
	v_fmac_f32_e32 v27, v99, v59
	v_fmac_f32_e32 v28, v100, v56
	v_fmac_f32_e32 v29, v100, v57
	v_fmac_f32_e32 v30, v100, v58
	v_fmac_f32_e32 v31, v100, v59
	global_load_dwordx4 v[56:59], v11, s[10:11]
	s_add_u32 s10, s10, 0x18000
	s_addc_u32 s11, s11, 0
	ds_read_b32 v96, v10 offset:440
	ds_read_b32 v97, v10 offset:8632
	ds_read_b32 v98, v10 offset:16824
	ds_read_b32 v99, v10 offset:25016
	ds_read_b32 v100, v10 offset:33208
	s_waitcnt vmcnt(15) lgkmcnt(0)
	v_fmac_f32_e32 v12, v96, v60
	v_fmac_f32_e32 v13, v96, v61
	v_fmac_f32_e32 v14, v96, v62
	v_fmac_f32_e32 v15, v96, v63
	v_fmac_f32_e32 v16, v97, v60
	v_fmac_f32_e32 v17, v97, v61
	v_fmac_f32_e32 v18, v97, v62
	v_fmac_f32_e32 v19, v97, v63
	v_fmac_f32_e32 v20, v98, v60
	v_fmac_f32_e32 v21, v98, v61
	v_fmac_f32_e32 v22, v98, v62
	v_fmac_f32_e32 v23, v98, v63
	v_fmac_f32_e32 v24, v99, v60
	v_fmac_f32_e32 v25, v99, v61
	v_fmac_f32_e32 v26, v99, v62
	v_fmac_f32_e32 v27, v99, v63
	v_fmac_f32_e32 v28, v100, v60
	v_fmac_f32_e32 v29, v100, v61
	v_fmac_f32_e32 v30, v100, v62
	v_fmac_f32_e32 v31, v100, v63
	global_load_dwordx4 v[60:63], v11, s[10:11]
	s_add_u32 s10, s10, 0x18000
	s_addc_u32 s11, s11, 0
	ds_read_b32 v96, v10 offset:448
	ds_read_b32 v97, v10 offset:8640
	ds_read_b32 v98, v10 offset:16832
	ds_read_b32 v99, v10 offset:25024
	ds_read_b32 v100, v10 offset:33216
	s_waitcnt vmcnt(15) lgkmcnt(0)
	v_fmac_f32_e32 v12, v96, v64
	v_fmac_f32_e32 v13, v96, v65
	v_fmac_f32_e32 v14, v96, v66
	v_fmac_f32_e32 v15, v96, v67
	v_fmac_f32_e32 v16, v97, v64
	v_fmac_f32_e32 v17, v97, v65
	v_fmac_f32_e32 v18, v97, v66
	v_fmac_f32_e32 v19, v97, v67
	v_fmac_f32_e32 v20, v98, v64
	v_fmac_f32_e32 v21, v98, v65
	v_fmac_f32_e32 v22, v98, v66
	v_fmac_f32_e32 v23, v98, v67
	v_fmac_f32_e32 v24, v99, v64
	v_fmac_f32_e32 v25, v99, v65
	v_fmac_f32_e32 v26, v99, v66
	v_fmac_f32_e32 v27, v99, v67
	v_fmac_f32_e32 v28, v100, v64
	v_fmac_f32_e32 v29, v100, v65
	v_fmac_f32_e32 v30, v100, v66
	v_fmac_f32_e32 v31, v100, v67
	global_load_dwordx4 v[64:67], v11, s[10:11]
	s_add_u32 s10, s10, 0x18000
	s_addc_u32 s11, s11, 0
	ds_read_b32 v96, v10 offset:456
	ds_read_b32 v97, v10 offset:8648
	ds_read_b32 v98, v10 offset:16840
	ds_read_b32 v99, v10 offset:25032
	ds_read_b32 v100, v10 offset:33224
	s_waitcnt vmcnt(15) lgkmcnt(0)
	v_fmac_f32_e32 v12, v96, v68
	v_fmac_f32_e32 v13, v96, v69
	v_fmac_f32_e32 v14, v96, v70
	v_fmac_f32_e32 v15, v96, v71
	v_fmac_f32_e32 v16, v97, v68
	v_fmac_f32_e32 v17, v97, v69
	v_fmac_f32_e32 v18, v97, v70
	v_fmac_f32_e32 v19, v97, v71
	v_fmac_f32_e32 v20, v98, v68
	v_fmac_f32_e32 v21, v98, v69
	v_fmac_f32_e32 v22, v98, v70
	v_fmac_f32_e32 v23, v98, v71
	v_fmac_f32_e32 v24, v99, v68
	v_fmac_f32_e32 v25, v99, v69
	v_fmac_f32_e32 v26, v99, v70
	v_fmac_f32_e32 v27, v99, v71
	v_fmac_f32_e32 v28, v100, v68
	v_fmac_f32_e32 v29, v100, v69
	v_fmac_f32_e32 v30, v100, v70
	v_fmac_f32_e32 v31, v100, v71
	global_load_dwordx4 v[68:71], v11, s[10:11]
	s_add_u32 s10, s10, 0x18000
	s_addc_u32 s11, s11, 0
	ds_read_b32 v96, v10 offset:464
	ds_read_b32 v97, v10 offset:8656
	ds_read_b32 v98, v10 offset:16848
	ds_read_b32 v99, v10 offset:25040
	ds_read_b32 v100, v10 offset:33232
	s_waitcnt vmcnt(15) lgkmcnt(0)
	v_fmac_f32_e32 v12, v96, v72
	v_fmac_f32_e32 v13, v96, v73
	v_fmac_f32_e32 v14, v96, v74
	v_fmac_f32_e32 v15, v96, v75
	v_fmac_f32_e32 v16, v97, v72
	v_fmac_f32_e32 v17, v97, v73
	v_fmac_f32_e32 v18, v97, v74
	v_fmac_f32_e32 v19, v97, v75
	v_fmac_f32_e32 v20, v98, v72
	v_fmac_f32_e32 v21, v98, v73
	v_fmac_f32_e32 v22, v98, v74
	v_fmac_f32_e32 v23, v98, v75
	v_fmac_f32_e32 v24, v99, v72
	v_fmac_f32_e32 v25, v99, v73
	v_fmac_f32_e32 v26, v99, v74
	v_fmac_f32_e32 v27, v99, v75
	v_fmac_f32_e32 v28, v100, v72
	v_fmac_f32_e32 v29, v100, v73
	v_fmac_f32_e32 v30, v100, v74
	v_fmac_f32_e32 v31, v100, v75
	global_load_dwordx4 v[72:75], v11, s[10:11]
	s_add_u32 s10, s10, 0x18000
	s_addc_u32 s11, s11, 0
	ds_read_b32 v96, v10 offset:472
	ds_read_b32 v97, v10 offset:8664
	ds_read_b32 v98, v10 offset:16856
	ds_read_b32 v99, v10 offset:25048
	ds_read_b32 v100, v10 offset:33240
	s_waitcnt vmcnt(15) lgkmcnt(0)
	v_fmac_f32_e32 v12, v96, v76
	v_fmac_f32_e32 v13, v96, v77
	v_fmac_f32_e32 v14, v96, v78
	v_fmac_f32_e32 v15, v96, v79
	v_fmac_f32_e32 v16, v97, v76
	v_fmac_f32_e32 v17, v97, v77
	v_fmac_f32_e32 v18, v97, v78
	v_fmac_f32_e32 v19, v97, v79
	v_fmac_f32_e32 v20, v98, v76
	v_fmac_f32_e32 v21, v98, v77
	v_fmac_f32_e32 v22, v98, v78
	v_fmac_f32_e32 v23, v98, v79
	v_fmac_f32_e32 v24, v99, v76
	v_fmac_f32_e32 v25, v99, v77
	v_fmac_f32_e32 v26, v99, v78
	v_fmac_f32_e32 v27, v99, v79
	v_fmac_f32_e32 v28, v100, v76
	v_fmac_f32_e32 v29, v100, v77
	v_fmac_f32_e32 v30, v100, v78
	v_fmac_f32_e32 v31, v100, v79
	global_load_dwordx4 v[76:79], v11, s[10:11]
	s_add_u32 s10, s10, 0x18000
	s_addc_u32 s11, s11, 0
	ds_read_b32 v96, v10 offset:480
	ds_read_b32 v97, v10 offset:8672
	ds_read_b32 v98, v10 offset:16864
	ds_read_b32 v99, v10 offset:25056
	ds_read_b32 v100, v10 offset:33248
	s_waitcnt vmcnt(15) lgkmcnt(0)
	v_fmac_f32_e32 v12, v96, v80
	v_fmac_f32_e32 v13, v96, v81
	v_fmac_f32_e32 v14, v96, v82
	v_fmac_f32_e32 v15, v96, v83
	v_fmac_f32_e32 v16, v97, v80
	v_fmac_f32_e32 v17, v97, v81
	v_fmac_f32_e32 v18, v97, v82
	v_fmac_f32_e32 v19, v97, v83
	v_fmac_f32_e32 v20, v98, v80
	v_fmac_f32_e32 v21, v98, v81
	v_fmac_f32_e32 v22, v98, v82
	v_fmac_f32_e32 v23, v98, v83
	v_fmac_f32_e32 v24, v99, v80
	v_fmac_f32_e32 v25, v99, v81
	v_fmac_f32_e32 v26, v99, v82
	v_fmac_f32_e32 v27, v99, v83
	v_fmac_f32_e32 v28, v100, v80
	v_fmac_f32_e32 v29, v100, v81
	v_fmac_f32_e32 v30, v100, v82
	v_fmac_f32_e32 v31, v100, v83
	global_load_dwordx4 v[80:83], v11, s[10:11]
	s_add_u32 s10, s10, 0x18000
	s_addc_u32 s11, s11, 0
	ds_read_b32 v96, v10 offset:488
	ds_read_b32 v97, v10 offset:8680
	ds_read_b32 v98, v10 offset:16872
	ds_read_b32 v99, v10 offset:25064
	ds_read_b32 v100, v10 offset:33256
	s_waitcnt vmcnt(15) lgkmcnt(0)
	v_fmac_f32_e32 v12, v96, v84
	v_fmac_f32_e32 v13, v96, v85
	v_fmac_f32_e32 v14, v96, v86
	v_fmac_f32_e32 v15, v96, v87
	v_fmac_f32_e32 v16, v97, v84
	v_fmac_f32_e32 v17, v97, v85
	v_fmac_f32_e32 v18, v97, v86
	v_fmac_f32_e32 v19, v97, v87
	v_fmac_f32_e32 v20, v98, v84
	v_fmac_f32_e32 v21, v98, v85
	v_fmac_f32_e32 v22, v98, v86
	v_fmac_f32_e32 v23, v98, v87
	v_fmac_f32_e32 v24, v99, v84
	v_fmac_f32_e32 v25, v99, v85
	v_fmac_f32_e32 v26, v99, v86
	v_fmac_f32_e32 v27, v99, v87
	v_fmac_f32_e32 v28, v100, v84
	v_fmac_f32_e32 v29, v100, v85
	v_fmac_f32_e32 v30, v100, v86
	v_fmac_f32_e32 v31, v100, v87
	global_load_dwordx4 v[84:87], v11, s[10:11]
	s_add_u32 s10, s10, 0x18000
	s_addc_u32 s11, s11, 0
	ds_read_b32 v96, v10 offset:496
	ds_read_b32 v97, v10 offset:8688
	ds_read_b32 v98, v10 offset:16880
	ds_read_b32 v99, v10 offset:25072
	ds_read_b32 v100, v10 offset:33264
	s_waitcnt vmcnt(15) lgkmcnt(0)
	v_fmac_f32_e32 v12, v96, v88
	v_fmac_f32_e32 v13, v96, v89
	v_fmac_f32_e32 v14, v96, v90
	v_fmac_f32_e32 v15, v96, v91
	v_fmac_f32_e32 v16, v97, v88
	v_fmac_f32_e32 v17, v97, v89
	v_fmac_f32_e32 v18, v97, v90
	v_fmac_f32_e32 v19, v97, v91
	v_fmac_f32_e32 v20, v98, v88
	v_fmac_f32_e32 v21, v98, v89
	v_fmac_f32_e32 v22, v98, v90
	v_fmac_f32_e32 v23, v98, v91
	v_fmac_f32_e32 v24, v99, v88
	v_fmac_f32_e32 v25, v99, v89
	v_fmac_f32_e32 v26, v99, v90
	v_fmac_f32_e32 v27, v99, v91
	v_fmac_f32_e32 v28, v100, v88
	v_fmac_f32_e32 v29, v100, v89
	v_fmac_f32_e32 v30, v100, v90
	v_fmac_f32_e32 v31, v100, v91
	global_load_dwordx4 v[88:91], v11, s[10:11]
	s_add_u32 s10, s10, 0x18000
	s_addc_u32 s11, s11, 0
	ds_read_b32 v96, v10 offset:504
	ds_read_b32 v97, v10 offset:8696
	ds_read_b32 v98, v10 offset:16888
	ds_read_b32 v99, v10 offset:25080
	ds_read_b32 v100, v10 offset:33272
	s_waitcnt vmcnt(15) lgkmcnt(0)
	v_fmac_f32_e32 v12, v96, v92
	v_fmac_f32_e32 v13, v96, v93
	v_fmac_f32_e32 v14, v96, v94
	v_fmac_f32_e32 v15, v96, v95
	v_fmac_f32_e32 v16, v97, v92
	v_fmac_f32_e32 v17, v97, v93
	v_fmac_f32_e32 v18, v97, v94
	v_fmac_f32_e32 v19, v97, v95
	v_fmac_f32_e32 v20, v98, v92
	v_fmac_f32_e32 v21, v98, v93
	v_fmac_f32_e32 v22, v98, v94
	v_fmac_f32_e32 v23, v98, v95
	v_fmac_f32_e32 v24, v99, v92
	v_fmac_f32_e32 v25, v99, v93
	v_fmac_f32_e32 v26, v99, v94
	v_fmac_f32_e32 v27, v99, v95
	v_fmac_f32_e32 v28, v100, v92
	v_fmac_f32_e32 v29, v100, v93
	v_fmac_f32_e32 v30, v100, v94
	v_fmac_f32_e32 v31, v100, v95
	global_load_dwordx4 v[92:95], v11, s[10:11]
	s_add_u32 s10, s10, 0x18000
	s_addc_u32 s11, s11, 0
	ds_read_b32 v96, v10 offset:512
	ds_read_b32 v97, v10 offset:8704
	ds_read_b32 v98, v10 offset:16896
	ds_read_b32 v99, v10 offset:25088
	ds_read_b32 v100, v10 offset:33280
	s_waitcnt vmcnt(15) lgkmcnt(0)
	v_fmac_f32_e32 v12, v96, v32
	v_fmac_f32_e32 v13, v96, v33
	v_fmac_f32_e32 v14, v96, v34
	v_fmac_f32_e32 v15, v96, v35
	v_fmac_f32_e32 v16, v97, v32
	v_fmac_f32_e32 v17, v97, v33
	v_fmac_f32_e32 v18, v97, v34
	v_fmac_f32_e32 v19, v97, v35
	v_fmac_f32_e32 v20, v98, v32
	v_fmac_f32_e32 v21, v98, v33
	v_fmac_f32_e32 v22, v98, v34
	v_fmac_f32_e32 v23, v98, v35
	v_fmac_f32_e32 v24, v99, v32
	v_fmac_f32_e32 v25, v99, v33
	v_fmac_f32_e32 v26, v99, v34
	v_fmac_f32_e32 v27, v99, v35
	v_fmac_f32_e32 v28, v100, v32
	v_fmac_f32_e32 v29, v100, v33
	v_fmac_f32_e32 v30, v100, v34
	v_fmac_f32_e32 v31, v100, v35
	global_load_dwordx4 v[32:35], v11, s[10:11]
	s_add_u32 s10, s10, 0x18000
	s_addc_u32 s11, s11, 0
	ds_read_b32 v96, v10 offset:520
	ds_read_b32 v97, v10 offset:8712
	ds_read_b32 v98, v10 offset:16904
	ds_read_b32 v99, v10 offset:25096
	ds_read_b32 v100, v10 offset:33288
	s_waitcnt vmcnt(15) lgkmcnt(0)
	v_fmac_f32_e32 v12, v96, v36
	v_fmac_f32_e32 v13, v96, v37
	v_fmac_f32_e32 v14, v96, v38
	v_fmac_f32_e32 v15, v96, v39
	v_fmac_f32_e32 v16, v97, v36
	v_fmac_f32_e32 v17, v97, v37
	v_fmac_f32_e32 v18, v97, v38
	v_fmac_f32_e32 v19, v97, v39
	v_fmac_f32_e32 v20, v98, v36
	v_fmac_f32_e32 v21, v98, v37
	v_fmac_f32_e32 v22, v98, v38
	v_fmac_f32_e32 v23, v98, v39
	v_fmac_f32_e32 v24, v99, v36
	v_fmac_f32_e32 v25, v99, v37
	v_fmac_f32_e32 v26, v99, v38
	v_fmac_f32_e32 v27, v99, v39
	v_fmac_f32_e32 v28, v100, v36
	v_fmac_f32_e32 v29, v100, v37
	v_fmac_f32_e32 v30, v100, v38
	v_fmac_f32_e32 v31, v100, v39
	global_load_dwordx4 v[36:39], v11, s[10:11]
	s_add_u32 s10, s10, 0x18000
	s_addc_u32 s11, s11, 0
	ds_read_b32 v96, v10 offset:528
	ds_read_b32 v97, v10 offset:8720
	ds_read_b32 v98, v10 offset:16912
	ds_read_b32 v99, v10 offset:25104
	ds_read_b32 v100, v10 offset:33296
	s_waitcnt vmcnt(15) lgkmcnt(0)
	v_fmac_f32_e32 v12, v96, v40
	v_fmac_f32_e32 v13, v96, v41
	v_fmac_f32_e32 v14, v96, v42
	v_fmac_f32_e32 v15, v96, v43
	v_fmac_f32_e32 v16, v97, v40
	v_fmac_f32_e32 v17, v97, v41
	v_fmac_f32_e32 v18, v97, v42
	v_fmac_f32_e32 v19, v97, v43
	v_fmac_f32_e32 v20, v98, v40
	v_fmac_f32_e32 v21, v98, v41
	v_fmac_f32_e32 v22, v98, v42
	v_fmac_f32_e32 v23, v98, v43
	v_fmac_f32_e32 v24, v99, v40
	v_fmac_f32_e32 v25, v99, v41
	v_fmac_f32_e32 v26, v99, v42
	v_fmac_f32_e32 v27, v99, v43
	v_fmac_f32_e32 v28, v100, v40
	v_fmac_f32_e32 v29, v100, v41
	v_fmac_f32_e32 v30, v100, v42
	v_fmac_f32_e32 v31, v100, v43
	global_load_dwordx4 v[40:43], v11, s[10:11]
	s_add_u32 s10, s10, 0x18000
	s_addc_u32 s11, s11, 0
	ds_read_b32 v96, v10 offset:536
	ds_read_b32 v97, v10 offset:8728
	ds_read_b32 v98, v10 offset:16920
	ds_read_b32 v99, v10 offset:25112
	ds_read_b32 v100, v10 offset:33304
	s_waitcnt vmcnt(15) lgkmcnt(0)
	v_fmac_f32_e32 v12, v96, v44
	v_fmac_f32_e32 v13, v96, v45
	v_fmac_f32_e32 v14, v96, v46
	v_fmac_f32_e32 v15, v96, v47
	v_fmac_f32_e32 v16, v97, v44
	v_fmac_f32_e32 v17, v97, v45
	v_fmac_f32_e32 v18, v97, v46
	v_fmac_f32_e32 v19, v97, v47
	v_fmac_f32_e32 v20, v98, v44
	v_fmac_f32_e32 v21, v98, v45
	v_fmac_f32_e32 v22, v98, v46
	v_fmac_f32_e32 v23, v98, v47
	v_fmac_f32_e32 v24, v99, v44
	v_fmac_f32_e32 v25, v99, v45
	v_fmac_f32_e32 v26, v99, v46
	v_fmac_f32_e32 v27, v99, v47
	v_fmac_f32_e32 v28, v100, v44
	v_fmac_f32_e32 v29, v100, v45
	v_fmac_f32_e32 v30, v100, v46
	v_fmac_f32_e32 v31, v100, v47
	global_load_dwordx4 v[44:47], v11, s[10:11]
	s_add_u32 s10, s10, 0x18000
	s_addc_u32 s11, s11, 0
	ds_read_b32 v96, v10 offset:544
	ds_read_b32 v97, v10 offset:8736
	ds_read_b32 v98, v10 offset:16928
	ds_read_b32 v99, v10 offset:25120
	ds_read_b32 v100, v10 offset:33312
	s_waitcnt vmcnt(15) lgkmcnt(0)
	v_fmac_f32_e32 v12, v96, v48
	v_fmac_f32_e32 v13, v96, v49
	v_fmac_f32_e32 v14, v96, v50
	v_fmac_f32_e32 v15, v96, v51
	v_fmac_f32_e32 v16, v97, v48
	v_fmac_f32_e32 v17, v97, v49
	v_fmac_f32_e32 v18, v97, v50
	v_fmac_f32_e32 v19, v97, v51
	v_fmac_f32_e32 v20, v98, v48
	v_fmac_f32_e32 v21, v98, v49
	v_fmac_f32_e32 v22, v98, v50
	v_fmac_f32_e32 v23, v98, v51
	v_fmac_f32_e32 v24, v99, v48
	v_fmac_f32_e32 v25, v99, v49
	v_fmac_f32_e32 v26, v99, v50
	v_fmac_f32_e32 v27, v99, v51
	v_fmac_f32_e32 v28, v100, v48
	v_fmac_f32_e32 v29, v100, v49
	v_fmac_f32_e32 v30, v100, v50
	v_fmac_f32_e32 v31, v100, v51
	global_load_dwordx4 v[48:51], v11, s[10:11]
	s_add_u32 s10, s10, 0x18000
	s_addc_u32 s11, s11, 0
	ds_read_b32 v96, v10 offset:552
	ds_read_b32 v97, v10 offset:8744
	ds_read_b32 v98, v10 offset:16936
	ds_read_b32 v99, v10 offset:25128
	ds_read_b32 v100, v10 offset:33320
	s_waitcnt vmcnt(15) lgkmcnt(0)
	v_fmac_f32_e32 v12, v96, v52
	v_fmac_f32_e32 v13, v96, v53
	v_fmac_f32_e32 v14, v96, v54
	v_fmac_f32_e32 v15, v96, v55
	v_fmac_f32_e32 v16, v97, v52
	v_fmac_f32_e32 v17, v97, v53
	v_fmac_f32_e32 v18, v97, v54
	v_fmac_f32_e32 v19, v97, v55
	v_fmac_f32_e32 v20, v98, v52
	v_fmac_f32_e32 v21, v98, v53
	v_fmac_f32_e32 v22, v98, v54
	v_fmac_f32_e32 v23, v98, v55
	v_fmac_f32_e32 v24, v99, v52
	v_fmac_f32_e32 v25, v99, v53
	v_fmac_f32_e32 v26, v99, v54
	v_fmac_f32_e32 v27, v99, v55
	v_fmac_f32_e32 v28, v100, v52
	v_fmac_f32_e32 v29, v100, v53
	v_fmac_f32_e32 v30, v100, v54
	v_fmac_f32_e32 v31, v100, v55
	global_load_dwordx4 v[52:55], v11, s[10:11]
	s_add_u32 s10, s10, 0x18000
	s_addc_u32 s11, s11, 0
	ds_read_b32 v96, v10 offset:560
	ds_read_b32 v97, v10 offset:8752
	ds_read_b32 v98, v10 offset:16944
	ds_read_b32 v99, v10 offset:25136
	ds_read_b32 v100, v10 offset:33328
	s_waitcnt vmcnt(15) lgkmcnt(0)
	v_fmac_f32_e32 v12, v96, v56
	v_fmac_f32_e32 v13, v96, v57
	v_fmac_f32_e32 v14, v96, v58
	v_fmac_f32_e32 v15, v96, v59
	v_fmac_f32_e32 v16, v97, v56
	v_fmac_f32_e32 v17, v97, v57
	v_fmac_f32_e32 v18, v97, v58
	v_fmac_f32_e32 v19, v97, v59
	v_fmac_f32_e32 v20, v98, v56
	v_fmac_f32_e32 v21, v98, v57
	v_fmac_f32_e32 v22, v98, v58
	v_fmac_f32_e32 v23, v98, v59
	v_fmac_f32_e32 v24, v99, v56
	v_fmac_f32_e32 v25, v99, v57
	v_fmac_f32_e32 v26, v99, v58
	v_fmac_f32_e32 v27, v99, v59
	v_fmac_f32_e32 v28, v100, v56
	v_fmac_f32_e32 v29, v100, v57
	v_fmac_f32_e32 v30, v100, v58
	v_fmac_f32_e32 v31, v100, v59
	global_load_dwordx4 v[56:59], v11, s[10:11]
	s_add_u32 s10, s10, 0x18000
	s_addc_u32 s11, s11, 0
	ds_read_b32 v96, v10 offset:568
	ds_read_b32 v97, v10 offset:8760
	ds_read_b32 v98, v10 offset:16952
	ds_read_b32 v99, v10 offset:25144
	ds_read_b32 v100, v10 offset:33336
	s_waitcnt vmcnt(15) lgkmcnt(0)
	v_fmac_f32_e32 v12, v96, v60
	v_fmac_f32_e32 v13, v96, v61
	v_fmac_f32_e32 v14, v96, v62
	v_fmac_f32_e32 v15, v96, v63
	v_fmac_f32_e32 v16, v97, v60
	v_fmac_f32_e32 v17, v97, v61
	v_fmac_f32_e32 v18, v97, v62
	v_fmac_f32_e32 v19, v97, v63
	v_fmac_f32_e32 v20, v98, v60
	v_fmac_f32_e32 v21, v98, v61
	v_fmac_f32_e32 v22, v98, v62
	v_fmac_f32_e32 v23, v98, v63
	v_fmac_f32_e32 v24, v99, v60
	v_fmac_f32_e32 v25, v99, v61
	v_fmac_f32_e32 v26, v99, v62
	v_fmac_f32_e32 v27, v99, v63
	v_fmac_f32_e32 v28, v100, v60
	v_fmac_f32_e32 v29, v100, v61
	v_fmac_f32_e32 v30, v100, v62
	v_fmac_f32_e32 v31, v100, v63
	global_load_dwordx4 v[60:63], v11, s[10:11]
	s_add_u32 s10, s10, 0x18000
	s_addc_u32 s11, s11, 0
	ds_read_b32 v96, v10 offset:576
	ds_read_b32 v97, v10 offset:8768
	ds_read_b32 v98, v10 offset:16960
	ds_read_b32 v99, v10 offset:25152
	ds_read_b32 v100, v10 offset:33344
	s_waitcnt vmcnt(15) lgkmcnt(0)
	v_fmac_f32_e32 v12, v96, v64
	v_fmac_f32_e32 v13, v96, v65
	v_fmac_f32_e32 v14, v96, v66
	v_fmac_f32_e32 v15, v96, v67
	v_fmac_f32_e32 v16, v97, v64
	v_fmac_f32_e32 v17, v97, v65
	v_fmac_f32_e32 v18, v97, v66
	v_fmac_f32_e32 v19, v97, v67
	v_fmac_f32_e32 v20, v98, v64
	v_fmac_f32_e32 v21, v98, v65
	v_fmac_f32_e32 v22, v98, v66
	v_fmac_f32_e32 v23, v98, v67
	v_fmac_f32_e32 v24, v99, v64
	v_fmac_f32_e32 v25, v99, v65
	v_fmac_f32_e32 v26, v99, v66
	v_fmac_f32_e32 v27, v99, v67
	v_fmac_f32_e32 v28, v100, v64
	v_fmac_f32_e32 v29, v100, v65
	v_fmac_f32_e32 v30, v100, v66
	v_fmac_f32_e32 v31, v100, v67
	global_load_dwordx4 v[64:67], v11, s[10:11]
	s_add_u32 s10, s10, 0x18000
	s_addc_u32 s11, s11, 0
	ds_read_b32 v96, v10 offset:584
	ds_read_b32 v97, v10 offset:8776
	ds_read_b32 v98, v10 offset:16968
	ds_read_b32 v99, v10 offset:25160
	ds_read_b32 v100, v10 offset:33352
	s_waitcnt vmcnt(15) lgkmcnt(0)
	v_fmac_f32_e32 v12, v96, v68
	v_fmac_f32_e32 v13, v96, v69
	v_fmac_f32_e32 v14, v96, v70
	v_fmac_f32_e32 v15, v96, v71
	v_fmac_f32_e32 v16, v97, v68
	v_fmac_f32_e32 v17, v97, v69
	v_fmac_f32_e32 v18, v97, v70
	v_fmac_f32_e32 v19, v97, v71
	v_fmac_f32_e32 v20, v98, v68
	v_fmac_f32_e32 v21, v98, v69
	v_fmac_f32_e32 v22, v98, v70
	v_fmac_f32_e32 v23, v98, v71
	v_fmac_f32_e32 v24, v99, v68
	v_fmac_f32_e32 v25, v99, v69
	v_fmac_f32_e32 v26, v99, v70
	v_fmac_f32_e32 v27, v99, v71
	v_fmac_f32_e32 v28, v100, v68
	v_fmac_f32_e32 v29, v100, v69
	v_fmac_f32_e32 v30, v100, v70
	v_fmac_f32_e32 v31, v100, v71
	global_load_dwordx4 v[68:71], v11, s[10:11]
	s_add_u32 s10, s10, 0x18000
	s_addc_u32 s11, s11, 0
	ds_read_b32 v96, v10 offset:592
	ds_read_b32 v97, v10 offset:8784
	ds_read_b32 v98, v10 offset:16976
	ds_read_b32 v99, v10 offset:25168
	ds_read_b32 v100, v10 offset:33360
	s_waitcnt vmcnt(15) lgkmcnt(0)
	v_fmac_f32_e32 v12, v96, v72
	v_fmac_f32_e32 v13, v96, v73
	v_fmac_f32_e32 v14, v96, v74
	v_fmac_f32_e32 v15, v96, v75
	v_fmac_f32_e32 v16, v97, v72
	v_fmac_f32_e32 v17, v97, v73
	v_fmac_f32_e32 v18, v97, v74
	v_fmac_f32_e32 v19, v97, v75
	v_fmac_f32_e32 v20, v98, v72
	v_fmac_f32_e32 v21, v98, v73
	v_fmac_f32_e32 v22, v98, v74
	v_fmac_f32_e32 v23, v98, v75
	v_fmac_f32_e32 v24, v99, v72
	v_fmac_f32_e32 v25, v99, v73
	v_fmac_f32_e32 v26, v99, v74
	v_fmac_f32_e32 v27, v99, v75
	v_fmac_f32_e32 v28, v100, v72
	v_fmac_f32_e32 v29, v100, v73
	v_fmac_f32_e32 v30, v100, v74
	v_fmac_f32_e32 v31, v100, v75
	global_load_dwordx4 v[72:75], v11, s[10:11]
	s_add_u32 s10, s10, 0x18000
	s_addc_u32 s11, s11, 0
	ds_read_b32 v96, v10 offset:600
	ds_read_b32 v97, v10 offset:8792
	ds_read_b32 v98, v10 offset:16984
	ds_read_b32 v99, v10 offset:25176
	ds_read_b32 v100, v10 offset:33368
	s_waitcnt vmcnt(15) lgkmcnt(0)
	v_fmac_f32_e32 v12, v96, v76
	v_fmac_f32_e32 v13, v96, v77
	v_fmac_f32_e32 v14, v96, v78
	v_fmac_f32_e32 v15, v96, v79
	v_fmac_f32_e32 v16, v97, v76
	v_fmac_f32_e32 v17, v97, v77
	v_fmac_f32_e32 v18, v97, v78
	v_fmac_f32_e32 v19, v97, v79
	v_fmac_f32_e32 v20, v98, v76
	v_fmac_f32_e32 v21, v98, v77
	v_fmac_f32_e32 v22, v98, v78
	v_fmac_f32_e32 v23, v98, v79
	v_fmac_f32_e32 v24, v99, v76
	v_fmac_f32_e32 v25, v99, v77
	v_fmac_f32_e32 v26, v99, v78
	v_fmac_f32_e32 v27, v99, v79
	v_fmac_f32_e32 v28, v100, v76
	v_fmac_f32_e32 v29, v100, v77
	v_fmac_f32_e32 v30, v100, v78
	v_fmac_f32_e32 v31, v100, v79
	global_load_dwordx4 v[76:79], v11, s[10:11]
	s_add_u32 s10, s10, 0x18000
	s_addc_u32 s11, s11, 0
	ds_read_b32 v96, v10 offset:608
	ds_read_b32 v97, v10 offset:8800
	ds_read_b32 v98, v10 offset:16992
	ds_read_b32 v99, v10 offset:25184
	ds_read_b32 v100, v10 offset:33376
	s_waitcnt vmcnt(15) lgkmcnt(0)
	v_fmac_f32_e32 v12, v96, v80
	v_fmac_f32_e32 v13, v96, v81
	v_fmac_f32_e32 v14, v96, v82
	v_fmac_f32_e32 v15, v96, v83
	v_fmac_f32_e32 v16, v97, v80
	v_fmac_f32_e32 v17, v97, v81
	v_fmac_f32_e32 v18, v97, v82
	v_fmac_f32_e32 v19, v97, v83
	v_fmac_f32_e32 v20, v98, v80
	v_fmac_f32_e32 v21, v98, v81
	v_fmac_f32_e32 v22, v98, v82
	v_fmac_f32_e32 v23, v98, v83
	v_fmac_f32_e32 v24, v99, v80
	v_fmac_f32_e32 v25, v99, v81
	v_fmac_f32_e32 v26, v99, v82
	v_fmac_f32_e32 v27, v99, v83
	v_fmac_f32_e32 v28, v100, v80
	v_fmac_f32_e32 v29, v100, v81
	v_fmac_f32_e32 v30, v100, v82
	v_fmac_f32_e32 v31, v100, v83
	global_load_dwordx4 v[80:83], v11, s[10:11]
	s_add_u32 s10, s10, 0x18000
	s_addc_u32 s11, s11, 0
	ds_read_b32 v96, v10 offset:616
	ds_read_b32 v97, v10 offset:8808
	ds_read_b32 v98, v10 offset:17000
	ds_read_b32 v99, v10 offset:25192
	ds_read_b32 v100, v10 offset:33384
	s_waitcnt vmcnt(15) lgkmcnt(0)
	v_fmac_f32_e32 v12, v96, v84
	v_fmac_f32_e32 v13, v96, v85
	v_fmac_f32_e32 v14, v96, v86
	v_fmac_f32_e32 v15, v96, v87
	v_fmac_f32_e32 v16, v97, v84
	v_fmac_f32_e32 v17, v97, v85
	v_fmac_f32_e32 v18, v97, v86
	v_fmac_f32_e32 v19, v97, v87
	v_fmac_f32_e32 v20, v98, v84
	v_fmac_f32_e32 v21, v98, v85
	v_fmac_f32_e32 v22, v98, v86
	v_fmac_f32_e32 v23, v98, v87
	v_fmac_f32_e32 v24, v99, v84
	v_fmac_f32_e32 v25, v99, v85
	v_fmac_f32_e32 v26, v99, v86
	v_fmac_f32_e32 v27, v99, v87
	v_fmac_f32_e32 v28, v100, v84
	v_fmac_f32_e32 v29, v100, v85
	v_fmac_f32_e32 v30, v100, v86
	v_fmac_f32_e32 v31, v100, v87
	global_load_dwordx4 v[84:87], v11, s[10:11]
	s_add_u32 s10, s10, 0x18000
	s_addc_u32 s11, s11, 0
	ds_read_b32 v96, v10 offset:624
	ds_read_b32 v97, v10 offset:8816
	ds_read_b32 v98, v10 offset:17008
	ds_read_b32 v99, v10 offset:25200
	ds_read_b32 v100, v10 offset:33392
	s_waitcnt vmcnt(15) lgkmcnt(0)
	v_fmac_f32_e32 v12, v96, v88
	v_fmac_f32_e32 v13, v96, v89
	v_fmac_f32_e32 v14, v96, v90
	v_fmac_f32_e32 v15, v96, v91
	v_fmac_f32_e32 v16, v97, v88
	v_fmac_f32_e32 v17, v97, v89
	v_fmac_f32_e32 v18, v97, v90
	v_fmac_f32_e32 v19, v97, v91
	v_fmac_f32_e32 v20, v98, v88
	v_fmac_f32_e32 v21, v98, v89
	v_fmac_f32_e32 v22, v98, v90
	v_fmac_f32_e32 v23, v98, v91
	v_fmac_f32_e32 v24, v99, v88
	v_fmac_f32_e32 v25, v99, v89
	v_fmac_f32_e32 v26, v99, v90
	v_fmac_f32_e32 v27, v99, v91
	v_fmac_f32_e32 v28, v100, v88
	v_fmac_f32_e32 v29, v100, v89
	v_fmac_f32_e32 v30, v100, v90
	v_fmac_f32_e32 v31, v100, v91
	global_load_dwordx4 v[88:91], v11, s[10:11]
	s_add_u32 s10, s10, 0x18000
	s_addc_u32 s11, s11, 0
	ds_read_b32 v96, v10 offset:632
	ds_read_b32 v97, v10 offset:8824
	ds_read_b32 v98, v10 offset:17016
	ds_read_b32 v99, v10 offset:25208
	ds_read_b32 v100, v10 offset:33400
	s_waitcnt vmcnt(15) lgkmcnt(0)
	v_fmac_f32_e32 v12, v96, v92
	v_fmac_f32_e32 v13, v96, v93
	v_fmac_f32_e32 v14, v96, v94
	v_fmac_f32_e32 v15, v96, v95
	v_fmac_f32_e32 v16, v97, v92
	v_fmac_f32_e32 v17, v97, v93
	v_fmac_f32_e32 v18, v97, v94
	v_fmac_f32_e32 v19, v97, v95
	v_fmac_f32_e32 v20, v98, v92
	v_fmac_f32_e32 v21, v98, v93
	v_fmac_f32_e32 v22, v98, v94
	v_fmac_f32_e32 v23, v98, v95
	v_fmac_f32_e32 v24, v99, v92
	v_fmac_f32_e32 v25, v99, v93
	v_fmac_f32_e32 v26, v99, v94
	v_fmac_f32_e32 v27, v99, v95
	v_fmac_f32_e32 v28, v100, v92
	v_fmac_f32_e32 v29, v100, v93
	v_fmac_f32_e32 v30, v100, v94
	v_fmac_f32_e32 v31, v100, v95
	global_load_dwordx4 v[92:95], v11, s[10:11]
	s_add_u32 s10, s10, 0x18000
	s_addc_u32 s11, s11, 0
	ds_read_b32 v96, v10 offset:640
	ds_read_b32 v97, v10 offset:8832
	ds_read_b32 v98, v10 offset:17024
	ds_read_b32 v99, v10 offset:25216
	ds_read_b32 v100, v10 offset:33408
	s_waitcnt vmcnt(15) lgkmcnt(0)
	v_fmac_f32_e32 v12, v96, v32
	v_fmac_f32_e32 v13, v96, v33
	v_fmac_f32_e32 v14, v96, v34
	v_fmac_f32_e32 v15, v96, v35
	v_fmac_f32_e32 v16, v97, v32
	v_fmac_f32_e32 v17, v97, v33
	v_fmac_f32_e32 v18, v97, v34
	v_fmac_f32_e32 v19, v97, v35
	v_fmac_f32_e32 v20, v98, v32
	v_fmac_f32_e32 v21, v98, v33
	v_fmac_f32_e32 v22, v98, v34
	v_fmac_f32_e32 v23, v98, v35
	v_fmac_f32_e32 v24, v99, v32
	v_fmac_f32_e32 v25, v99, v33
	v_fmac_f32_e32 v26, v99, v34
	v_fmac_f32_e32 v27, v99, v35
	v_fmac_f32_e32 v28, v100, v32
	v_fmac_f32_e32 v29, v100, v33
	v_fmac_f32_e32 v30, v100, v34
	v_fmac_f32_e32 v31, v100, v35
	global_load_dwordx4 v[32:35], v11, s[10:11]
	s_add_u32 s10, s10, 0x18000
	s_addc_u32 s11, s11, 0
	ds_read_b32 v96, v10 offset:648
	ds_read_b32 v97, v10 offset:8840
	ds_read_b32 v98, v10 offset:17032
	ds_read_b32 v99, v10 offset:25224
	ds_read_b32 v100, v10 offset:33416
	s_waitcnt vmcnt(15) lgkmcnt(0)
	v_fmac_f32_e32 v12, v96, v36
	v_fmac_f32_e32 v13, v96, v37
	v_fmac_f32_e32 v14, v96, v38
	v_fmac_f32_e32 v15, v96, v39
	v_fmac_f32_e32 v16, v97, v36
	v_fmac_f32_e32 v17, v97, v37
	v_fmac_f32_e32 v18, v97, v38
	v_fmac_f32_e32 v19, v97, v39
	v_fmac_f32_e32 v20, v98, v36
	v_fmac_f32_e32 v21, v98, v37
	v_fmac_f32_e32 v22, v98, v38
	v_fmac_f32_e32 v23, v98, v39
	v_fmac_f32_e32 v24, v99, v36
	v_fmac_f32_e32 v25, v99, v37
	v_fmac_f32_e32 v26, v99, v38
	v_fmac_f32_e32 v27, v99, v39
	v_fmac_f32_e32 v28, v100, v36
	v_fmac_f32_e32 v29, v100, v37
	v_fmac_f32_e32 v30, v100, v38
	v_fmac_f32_e32 v31, v100, v39
	global_load_dwordx4 v[36:39], v11, s[10:11]
	s_add_u32 s10, s10, 0x18000
	s_addc_u32 s11, s11, 0
	ds_read_b32 v96, v10 offset:656
	ds_read_b32 v97, v10 offset:8848
	ds_read_b32 v98, v10 offset:17040
	ds_read_b32 v99, v10 offset:25232
	ds_read_b32 v100, v10 offset:33424
	s_waitcnt vmcnt(15) lgkmcnt(0)
	v_fmac_f32_e32 v12, v96, v40
	v_fmac_f32_e32 v13, v96, v41
	v_fmac_f32_e32 v14, v96, v42
	v_fmac_f32_e32 v15, v96, v43
	v_fmac_f32_e32 v16, v97, v40
	v_fmac_f32_e32 v17, v97, v41
	v_fmac_f32_e32 v18, v97, v42
	v_fmac_f32_e32 v19, v97, v43
	v_fmac_f32_e32 v20, v98, v40
	v_fmac_f32_e32 v21, v98, v41
	v_fmac_f32_e32 v22, v98, v42
	v_fmac_f32_e32 v23, v98, v43
	v_fmac_f32_e32 v24, v99, v40
	v_fmac_f32_e32 v25, v99, v41
	v_fmac_f32_e32 v26, v99, v42
	v_fmac_f32_e32 v27, v99, v43
	v_fmac_f32_e32 v28, v100, v40
	v_fmac_f32_e32 v29, v100, v41
	v_fmac_f32_e32 v30, v100, v42
	v_fmac_f32_e32 v31, v100, v43
	global_load_dwordx4 v[40:43], v11, s[10:11]
	s_add_u32 s10, s10, 0x18000
	s_addc_u32 s11, s11, 0
	ds_read_b32 v96, v10 offset:664
	ds_read_b32 v97, v10 offset:8856
	ds_read_b32 v98, v10 offset:17048
	ds_read_b32 v99, v10 offset:25240
	ds_read_b32 v100, v10 offset:33432
	s_waitcnt vmcnt(15) lgkmcnt(0)
	v_fmac_f32_e32 v12, v96, v44
	v_fmac_f32_e32 v13, v96, v45
	v_fmac_f32_e32 v14, v96, v46
	v_fmac_f32_e32 v15, v96, v47
	v_fmac_f32_e32 v16, v97, v44
	v_fmac_f32_e32 v17, v97, v45
	v_fmac_f32_e32 v18, v97, v46
	v_fmac_f32_e32 v19, v97, v47
	v_fmac_f32_e32 v20, v98, v44
	v_fmac_f32_e32 v21, v98, v45
	v_fmac_f32_e32 v22, v98, v46
	v_fmac_f32_e32 v23, v98, v47
	v_fmac_f32_e32 v24, v99, v44
	v_fmac_f32_e32 v25, v99, v45
	v_fmac_f32_e32 v26, v99, v46
	v_fmac_f32_e32 v27, v99, v47
	v_fmac_f32_e32 v28, v100, v44
	v_fmac_f32_e32 v29, v100, v45
	v_fmac_f32_e32 v30, v100, v46
	v_fmac_f32_e32 v31, v100, v47
	global_load_dwordx4 v[44:47], v11, s[10:11]
	s_add_u32 s10, s10, 0x18000
	s_addc_u32 s11, s11, 0
	ds_read_b32 v96, v10 offset:672
	ds_read_b32 v97, v10 offset:8864
	ds_read_b32 v98, v10 offset:17056
	ds_read_b32 v99, v10 offset:25248
	ds_read_b32 v100, v10 offset:33440
	s_waitcnt vmcnt(15) lgkmcnt(0)
	v_fmac_f32_e32 v12, v96, v48
	v_fmac_f32_e32 v13, v96, v49
	v_fmac_f32_e32 v14, v96, v50
	v_fmac_f32_e32 v15, v96, v51
	v_fmac_f32_e32 v16, v97, v48
	v_fmac_f32_e32 v17, v97, v49
	v_fmac_f32_e32 v18, v97, v50
	v_fmac_f32_e32 v19, v97, v51
	v_fmac_f32_e32 v20, v98, v48
	v_fmac_f32_e32 v21, v98, v49
	v_fmac_f32_e32 v22, v98, v50
	v_fmac_f32_e32 v23, v98, v51
	v_fmac_f32_e32 v24, v99, v48
	v_fmac_f32_e32 v25, v99, v49
	v_fmac_f32_e32 v26, v99, v50
	v_fmac_f32_e32 v27, v99, v51
	v_fmac_f32_e32 v28, v100, v48
	v_fmac_f32_e32 v29, v100, v49
	v_fmac_f32_e32 v30, v100, v50
	v_fmac_f32_e32 v31, v100, v51
	global_load_dwordx4 v[48:51], v11, s[10:11]
	s_add_u32 s10, s10, 0x18000
	s_addc_u32 s11, s11, 0
	ds_read_b32 v96, v10 offset:680
	ds_read_b32 v97, v10 offset:8872
	ds_read_b32 v98, v10 offset:17064
	ds_read_b32 v99, v10 offset:25256
	ds_read_b32 v100, v10 offset:33448
	s_waitcnt vmcnt(15) lgkmcnt(0)
	v_fmac_f32_e32 v12, v96, v52
	v_fmac_f32_e32 v13, v96, v53
	v_fmac_f32_e32 v14, v96, v54
	v_fmac_f32_e32 v15, v96, v55
	v_fmac_f32_e32 v16, v97, v52
	v_fmac_f32_e32 v17, v97, v53
	v_fmac_f32_e32 v18, v97, v54
	v_fmac_f32_e32 v19, v97, v55
	v_fmac_f32_e32 v20, v98, v52
	v_fmac_f32_e32 v21, v98, v53
	v_fmac_f32_e32 v22, v98, v54
	v_fmac_f32_e32 v23, v98, v55
	v_fmac_f32_e32 v24, v99, v52
	v_fmac_f32_e32 v25, v99, v53
	v_fmac_f32_e32 v26, v99, v54
	v_fmac_f32_e32 v27, v99, v55
	v_fmac_f32_e32 v28, v100, v52
	v_fmac_f32_e32 v29, v100, v53
	v_fmac_f32_e32 v30, v100, v54
	v_fmac_f32_e32 v31, v100, v55
	global_load_dwordx4 v[52:55], v11, s[10:11]
	s_add_u32 s10, s10, 0x18000
	s_addc_u32 s11, s11, 0
	ds_read_b32 v96, v10 offset:688
	ds_read_b32 v97, v10 offset:8880
	ds_read_b32 v98, v10 offset:17072
	ds_read_b32 v99, v10 offset:25264
	ds_read_b32 v100, v10 offset:33456
	s_waitcnt vmcnt(15) lgkmcnt(0)
	v_fmac_f32_e32 v12, v96, v56
	v_fmac_f32_e32 v13, v96, v57
	v_fmac_f32_e32 v14, v96, v58
	v_fmac_f32_e32 v15, v96, v59
	v_fmac_f32_e32 v16, v97, v56
	v_fmac_f32_e32 v17, v97, v57
	v_fmac_f32_e32 v18, v97, v58
	v_fmac_f32_e32 v19, v97, v59
	v_fmac_f32_e32 v20, v98, v56
	v_fmac_f32_e32 v21, v98, v57
	v_fmac_f32_e32 v22, v98, v58
	v_fmac_f32_e32 v23, v98, v59
	v_fmac_f32_e32 v24, v99, v56
	v_fmac_f32_e32 v25, v99, v57
	v_fmac_f32_e32 v26, v99, v58
	v_fmac_f32_e32 v27, v99, v59
	v_fmac_f32_e32 v28, v100, v56
	v_fmac_f32_e32 v29, v100, v57
	v_fmac_f32_e32 v30, v100, v58
	v_fmac_f32_e32 v31, v100, v59
	global_load_dwordx4 v[56:59], v11, s[10:11]
	s_add_u32 s10, s10, 0x18000
	s_addc_u32 s11, s11, 0
	ds_read_b32 v96, v10 offset:696
	ds_read_b32 v97, v10 offset:8888
	ds_read_b32 v98, v10 offset:17080
	ds_read_b32 v99, v10 offset:25272
	ds_read_b32 v100, v10 offset:33464
	s_waitcnt vmcnt(15) lgkmcnt(0)
	v_fmac_f32_e32 v12, v96, v60
	v_fmac_f32_e32 v13, v96, v61
	v_fmac_f32_e32 v14, v96, v62
	v_fmac_f32_e32 v15, v96, v63
	v_fmac_f32_e32 v16, v97, v60
	v_fmac_f32_e32 v17, v97, v61
	v_fmac_f32_e32 v18, v97, v62
	v_fmac_f32_e32 v19, v97, v63
	v_fmac_f32_e32 v20, v98, v60
	v_fmac_f32_e32 v21, v98, v61
	v_fmac_f32_e32 v22, v98, v62
	v_fmac_f32_e32 v23, v98, v63
	v_fmac_f32_e32 v24, v99, v60
	v_fmac_f32_e32 v25, v99, v61
	v_fmac_f32_e32 v26, v99, v62
	v_fmac_f32_e32 v27, v99, v63
	v_fmac_f32_e32 v28, v100, v60
	v_fmac_f32_e32 v29, v100, v61
	v_fmac_f32_e32 v30, v100, v62
	v_fmac_f32_e32 v31, v100, v63
	global_load_dwordx4 v[60:63], v11, s[10:11]
	s_add_u32 s10, s10, 0x18000
	s_addc_u32 s11, s11, 0
	ds_read_b32 v96, v10 offset:704
	ds_read_b32 v97, v10 offset:8896
	ds_read_b32 v98, v10 offset:17088
	ds_read_b32 v99, v10 offset:25280
	ds_read_b32 v100, v10 offset:33472
	s_waitcnt vmcnt(15) lgkmcnt(0)
	v_fmac_f32_e32 v12, v96, v64
	v_fmac_f32_e32 v13, v96, v65
	v_fmac_f32_e32 v14, v96, v66
	v_fmac_f32_e32 v15, v96, v67
	v_fmac_f32_e32 v16, v97, v64
	v_fmac_f32_e32 v17, v97, v65
	v_fmac_f32_e32 v18, v97, v66
	v_fmac_f32_e32 v19, v97, v67
	v_fmac_f32_e32 v20, v98, v64
	v_fmac_f32_e32 v21, v98, v65
	v_fmac_f32_e32 v22, v98, v66
	v_fmac_f32_e32 v23, v98, v67
	v_fmac_f32_e32 v24, v99, v64
	v_fmac_f32_e32 v25, v99, v65
	v_fmac_f32_e32 v26, v99, v66
	v_fmac_f32_e32 v27, v99, v67
	v_fmac_f32_e32 v28, v100, v64
	v_fmac_f32_e32 v29, v100, v65
	v_fmac_f32_e32 v30, v100, v66
	v_fmac_f32_e32 v31, v100, v67
	global_load_dwordx4 v[64:67], v11, s[10:11]
	s_add_u32 s10, s10, 0x18000
	s_addc_u32 s11, s11, 0
	ds_read_b32 v96, v10 offset:712
	ds_read_b32 v97, v10 offset:8904
	ds_read_b32 v98, v10 offset:17096
	ds_read_b32 v99, v10 offset:25288
	ds_read_b32 v100, v10 offset:33480
	s_waitcnt vmcnt(15) lgkmcnt(0)
	v_fmac_f32_e32 v12, v96, v68
	v_fmac_f32_e32 v13, v96, v69
	v_fmac_f32_e32 v14, v96, v70
	v_fmac_f32_e32 v15, v96, v71
	v_fmac_f32_e32 v16, v97, v68
	v_fmac_f32_e32 v17, v97, v69
	v_fmac_f32_e32 v18, v97, v70
	v_fmac_f32_e32 v19, v97, v71
	v_fmac_f32_e32 v20, v98, v68
	v_fmac_f32_e32 v21, v98, v69
	v_fmac_f32_e32 v22, v98, v70
	v_fmac_f32_e32 v23, v98, v71
	v_fmac_f32_e32 v24, v99, v68
	v_fmac_f32_e32 v25, v99, v69
	v_fmac_f32_e32 v26, v99, v70
	v_fmac_f32_e32 v27, v99, v71
	v_fmac_f32_e32 v28, v100, v68
	v_fmac_f32_e32 v29, v100, v69
	v_fmac_f32_e32 v30, v100, v70
	v_fmac_f32_e32 v31, v100, v71
	global_load_dwordx4 v[68:71], v11, s[10:11]
	s_add_u32 s10, s10, 0x18000
	s_addc_u32 s11, s11, 0
	ds_read_b32 v96, v10 offset:720
	ds_read_b32 v97, v10 offset:8912
	ds_read_b32 v98, v10 offset:17104
	ds_read_b32 v99, v10 offset:25296
	ds_read_b32 v100, v10 offset:33488
	s_waitcnt vmcnt(15) lgkmcnt(0)
	v_fmac_f32_e32 v12, v96, v72
	v_fmac_f32_e32 v13, v96, v73
	v_fmac_f32_e32 v14, v96, v74
	v_fmac_f32_e32 v15, v96, v75
	v_fmac_f32_e32 v16, v97, v72
	v_fmac_f32_e32 v17, v97, v73
	v_fmac_f32_e32 v18, v97, v74
	v_fmac_f32_e32 v19, v97, v75
	v_fmac_f32_e32 v20, v98, v72
	v_fmac_f32_e32 v21, v98, v73
	v_fmac_f32_e32 v22, v98, v74
	v_fmac_f32_e32 v23, v98, v75
	v_fmac_f32_e32 v24, v99, v72
	v_fmac_f32_e32 v25, v99, v73
	v_fmac_f32_e32 v26, v99, v74
	v_fmac_f32_e32 v27, v99, v75
	v_fmac_f32_e32 v28, v100, v72
	v_fmac_f32_e32 v29, v100, v73
	v_fmac_f32_e32 v30, v100, v74
	v_fmac_f32_e32 v31, v100, v75
	global_load_dwordx4 v[72:75], v11, s[10:11]
	s_add_u32 s10, s10, 0x18000
	s_addc_u32 s11, s11, 0
	ds_read_b32 v96, v10 offset:728
	ds_read_b32 v97, v10 offset:8920
	ds_read_b32 v98, v10 offset:17112
	ds_read_b32 v99, v10 offset:25304
	ds_read_b32 v100, v10 offset:33496
	s_waitcnt vmcnt(15) lgkmcnt(0)
	v_fmac_f32_e32 v12, v96, v76
	v_fmac_f32_e32 v13, v96, v77
	v_fmac_f32_e32 v14, v96, v78
	v_fmac_f32_e32 v15, v96, v79
	v_fmac_f32_e32 v16, v97, v76
	v_fmac_f32_e32 v17, v97, v77
	v_fmac_f32_e32 v18, v97, v78
	v_fmac_f32_e32 v19, v97, v79
	v_fmac_f32_e32 v20, v98, v76
	v_fmac_f32_e32 v21, v98, v77
	v_fmac_f32_e32 v22, v98, v78
	v_fmac_f32_e32 v23, v98, v79
	v_fmac_f32_e32 v24, v99, v76
	v_fmac_f32_e32 v25, v99, v77
	v_fmac_f32_e32 v26, v99, v78
	v_fmac_f32_e32 v27, v99, v79
	v_fmac_f32_e32 v28, v100, v76
	v_fmac_f32_e32 v29, v100, v77
	v_fmac_f32_e32 v30, v100, v78
	v_fmac_f32_e32 v31, v100, v79
	global_load_dwordx4 v[76:79], v11, s[10:11]
	s_add_u32 s10, s10, 0x18000
	s_addc_u32 s11, s11, 0
	ds_read_b32 v96, v10 offset:736
	ds_read_b32 v97, v10 offset:8928
	ds_read_b32 v98, v10 offset:17120
	ds_read_b32 v99, v10 offset:25312
	ds_read_b32 v100, v10 offset:33504
	s_waitcnt vmcnt(15) lgkmcnt(0)
	v_fmac_f32_e32 v12, v96, v80
	v_fmac_f32_e32 v13, v96, v81
	v_fmac_f32_e32 v14, v96, v82
	v_fmac_f32_e32 v15, v96, v83
	v_fmac_f32_e32 v16, v97, v80
	v_fmac_f32_e32 v17, v97, v81
	v_fmac_f32_e32 v18, v97, v82
	v_fmac_f32_e32 v19, v97, v83
	v_fmac_f32_e32 v20, v98, v80
	v_fmac_f32_e32 v21, v98, v81
	v_fmac_f32_e32 v22, v98, v82
	v_fmac_f32_e32 v23, v98, v83
	v_fmac_f32_e32 v24, v99, v80
	v_fmac_f32_e32 v25, v99, v81
	v_fmac_f32_e32 v26, v99, v82
	v_fmac_f32_e32 v27, v99, v83
	v_fmac_f32_e32 v28, v100, v80
	v_fmac_f32_e32 v29, v100, v81
	v_fmac_f32_e32 v30, v100, v82
	v_fmac_f32_e32 v31, v100, v83
	global_load_dwordx4 v[80:83], v11, s[10:11]
	s_add_u32 s10, s10, 0x18000
	s_addc_u32 s11, s11, 0
	ds_read_b32 v96, v10 offset:744
	ds_read_b32 v97, v10 offset:8936
	ds_read_b32 v98, v10 offset:17128
	ds_read_b32 v99, v10 offset:25320
	ds_read_b32 v100, v10 offset:33512
	s_waitcnt vmcnt(15) lgkmcnt(0)
	v_fmac_f32_e32 v12, v96, v84
	v_fmac_f32_e32 v13, v96, v85
	v_fmac_f32_e32 v14, v96, v86
	v_fmac_f32_e32 v15, v96, v87
	v_fmac_f32_e32 v16, v97, v84
	v_fmac_f32_e32 v17, v97, v85
	v_fmac_f32_e32 v18, v97, v86
	v_fmac_f32_e32 v19, v97, v87
	v_fmac_f32_e32 v20, v98, v84
	v_fmac_f32_e32 v21, v98, v85
	v_fmac_f32_e32 v22, v98, v86
	v_fmac_f32_e32 v23, v98, v87
	v_fmac_f32_e32 v24, v99, v84
	v_fmac_f32_e32 v25, v99, v85
	v_fmac_f32_e32 v26, v99, v86
	v_fmac_f32_e32 v27, v99, v87
	v_fmac_f32_e32 v28, v100, v84
	v_fmac_f32_e32 v29, v100, v85
	v_fmac_f32_e32 v30, v100, v86
	v_fmac_f32_e32 v31, v100, v87
	global_load_dwordx4 v[84:87], v11, s[10:11]
	s_add_u32 s10, s10, 0x18000
	s_addc_u32 s11, s11, 0
	ds_read_b32 v96, v10 offset:752
	ds_read_b32 v97, v10 offset:8944
	ds_read_b32 v98, v10 offset:17136
	ds_read_b32 v99, v10 offset:25328
	ds_read_b32 v100, v10 offset:33520
	s_waitcnt vmcnt(15) lgkmcnt(0)
	v_fmac_f32_e32 v12, v96, v88
	v_fmac_f32_e32 v13, v96, v89
	v_fmac_f32_e32 v14, v96, v90
	v_fmac_f32_e32 v15, v96, v91
	v_fmac_f32_e32 v16, v97, v88
	v_fmac_f32_e32 v17, v97, v89
	v_fmac_f32_e32 v18, v97, v90
	v_fmac_f32_e32 v19, v97, v91
	v_fmac_f32_e32 v20, v98, v88
	v_fmac_f32_e32 v21, v98, v89
	v_fmac_f32_e32 v22, v98, v90
	v_fmac_f32_e32 v23, v98, v91
	v_fmac_f32_e32 v24, v99, v88
	v_fmac_f32_e32 v25, v99, v89
	v_fmac_f32_e32 v26, v99, v90
	v_fmac_f32_e32 v27, v99, v91
	v_fmac_f32_e32 v28, v100, v88
	v_fmac_f32_e32 v29, v100, v89
	v_fmac_f32_e32 v30, v100, v90
	v_fmac_f32_e32 v31, v100, v91
	global_load_dwordx4 v[88:91], v11, s[10:11]
	s_add_u32 s10, s10, 0x18000
	s_addc_u32 s11, s11, 0
	ds_read_b32 v96, v10 offset:760
	ds_read_b32 v97, v10 offset:8952
	ds_read_b32 v98, v10 offset:17144
	ds_read_b32 v99, v10 offset:25336
	ds_read_b32 v100, v10 offset:33528
	s_waitcnt vmcnt(15) lgkmcnt(0)
	v_fmac_f32_e32 v12, v96, v92
	v_fmac_f32_e32 v13, v96, v93
	v_fmac_f32_e32 v14, v96, v94
	v_fmac_f32_e32 v15, v96, v95
	v_fmac_f32_e32 v16, v97, v92
	v_fmac_f32_e32 v17, v97, v93
	v_fmac_f32_e32 v18, v97, v94
	v_fmac_f32_e32 v19, v97, v95
	v_fmac_f32_e32 v20, v98, v92
	v_fmac_f32_e32 v21, v98, v93
	v_fmac_f32_e32 v22, v98, v94
	v_fmac_f32_e32 v23, v98, v95
	v_fmac_f32_e32 v24, v99, v92
	v_fmac_f32_e32 v25, v99, v93
	v_fmac_f32_e32 v26, v99, v94
	v_fmac_f32_e32 v27, v99, v95
	v_fmac_f32_e32 v28, v100, v92
	v_fmac_f32_e32 v29, v100, v93
	v_fmac_f32_e32 v30, v100, v94
	v_fmac_f32_e32 v31, v100, v95
	global_load_dwordx4 v[92:95], v11, s[10:11]
	s_add_u32 s10, s10, 0x18000
	s_addc_u32 s11, s11, 0
	ds_read_b32 v96, v10 offset:768
	ds_read_b32 v97, v10 offset:8960
	ds_read_b32 v98, v10 offset:17152
	ds_read_b32 v99, v10 offset:25344
	ds_read_b32 v100, v10 offset:33536
	s_waitcnt vmcnt(15) lgkmcnt(0)
	v_fmac_f32_e32 v12, v96, v32
	v_fmac_f32_e32 v13, v96, v33
	v_fmac_f32_e32 v14, v96, v34
	v_fmac_f32_e32 v15, v96, v35
	v_fmac_f32_e32 v16, v97, v32
	v_fmac_f32_e32 v17, v97, v33
	v_fmac_f32_e32 v18, v97, v34
	v_fmac_f32_e32 v19, v97, v35
	v_fmac_f32_e32 v20, v98, v32
	v_fmac_f32_e32 v21, v98, v33
	v_fmac_f32_e32 v22, v98, v34
	v_fmac_f32_e32 v23, v98, v35
	v_fmac_f32_e32 v24, v99, v32
	v_fmac_f32_e32 v25, v99, v33
	v_fmac_f32_e32 v26, v99, v34
	v_fmac_f32_e32 v27, v99, v35
	v_fmac_f32_e32 v28, v100, v32
	v_fmac_f32_e32 v29, v100, v33
	v_fmac_f32_e32 v30, v100, v34
	v_fmac_f32_e32 v31, v100, v35
	global_load_dwordx4 v[32:35], v11, s[10:11]
	s_add_u32 s10, s10, 0x18000
	s_addc_u32 s11, s11, 0
	ds_read_b32 v96, v10 offset:776
	ds_read_b32 v97, v10 offset:8968
	ds_read_b32 v98, v10 offset:17160
	ds_read_b32 v99, v10 offset:25352
	ds_read_b32 v100, v10 offset:33544
	s_waitcnt vmcnt(15) lgkmcnt(0)
	v_fmac_f32_e32 v12, v96, v36
	v_fmac_f32_e32 v13, v96, v37
	v_fmac_f32_e32 v14, v96, v38
	v_fmac_f32_e32 v15, v96, v39
	v_fmac_f32_e32 v16, v97, v36
	v_fmac_f32_e32 v17, v97, v37
	v_fmac_f32_e32 v18, v97, v38
	v_fmac_f32_e32 v19, v97, v39
	v_fmac_f32_e32 v20, v98, v36
	v_fmac_f32_e32 v21, v98, v37
	v_fmac_f32_e32 v22, v98, v38
	v_fmac_f32_e32 v23, v98, v39
	v_fmac_f32_e32 v24, v99, v36
	v_fmac_f32_e32 v25, v99, v37
	v_fmac_f32_e32 v26, v99, v38
	v_fmac_f32_e32 v27, v99, v39
	v_fmac_f32_e32 v28, v100, v36
	v_fmac_f32_e32 v29, v100, v37
	v_fmac_f32_e32 v30, v100, v38
	v_fmac_f32_e32 v31, v100, v39
	global_load_dwordx4 v[36:39], v11, s[10:11]
	s_add_u32 s10, s10, 0x18000
	s_addc_u32 s11, s11, 0
	ds_read_b32 v96, v10 offset:784
	ds_read_b32 v97, v10 offset:8976
	ds_read_b32 v98, v10 offset:17168
	ds_read_b32 v99, v10 offset:25360
	ds_read_b32 v100, v10 offset:33552
	s_waitcnt vmcnt(15) lgkmcnt(0)
	v_fmac_f32_e32 v12, v96, v40
	v_fmac_f32_e32 v13, v96, v41
	v_fmac_f32_e32 v14, v96, v42
	v_fmac_f32_e32 v15, v96, v43
	v_fmac_f32_e32 v16, v97, v40
	v_fmac_f32_e32 v17, v97, v41
	v_fmac_f32_e32 v18, v97, v42
	v_fmac_f32_e32 v19, v97, v43
	v_fmac_f32_e32 v20, v98, v40
	v_fmac_f32_e32 v21, v98, v41
	v_fmac_f32_e32 v22, v98, v42
	v_fmac_f32_e32 v23, v98, v43
	v_fmac_f32_e32 v24, v99, v40
	v_fmac_f32_e32 v25, v99, v41
	v_fmac_f32_e32 v26, v99, v42
	v_fmac_f32_e32 v27, v99, v43
	v_fmac_f32_e32 v28, v100, v40
	v_fmac_f32_e32 v29, v100, v41
	v_fmac_f32_e32 v30, v100, v42
	v_fmac_f32_e32 v31, v100, v43
	global_load_dwordx4 v[40:43], v11, s[10:11]
	s_add_u32 s10, s10, 0x18000
	s_addc_u32 s11, s11, 0
	ds_read_b32 v96, v10 offset:792
	ds_read_b32 v97, v10 offset:8984
	ds_read_b32 v98, v10 offset:17176
	ds_read_b32 v99, v10 offset:25368
	ds_read_b32 v100, v10 offset:33560
	s_waitcnt vmcnt(15) lgkmcnt(0)
	v_fmac_f32_e32 v12, v96, v44
	v_fmac_f32_e32 v13, v96, v45
	v_fmac_f32_e32 v14, v96, v46
	v_fmac_f32_e32 v15, v96, v47
	v_fmac_f32_e32 v16, v97, v44
	v_fmac_f32_e32 v17, v97, v45
	v_fmac_f32_e32 v18, v97, v46
	v_fmac_f32_e32 v19, v97, v47
	v_fmac_f32_e32 v20, v98, v44
	v_fmac_f32_e32 v21, v98, v45
	v_fmac_f32_e32 v22, v98, v46
	v_fmac_f32_e32 v23, v98, v47
	v_fmac_f32_e32 v24, v99, v44
	v_fmac_f32_e32 v25, v99, v45
	v_fmac_f32_e32 v26, v99, v46
	v_fmac_f32_e32 v27, v99, v47
	v_fmac_f32_e32 v28, v100, v44
	v_fmac_f32_e32 v29, v100, v45
	v_fmac_f32_e32 v30, v100, v46
	v_fmac_f32_e32 v31, v100, v47
	global_load_dwordx4 v[44:47], v11, s[10:11]
	s_add_u32 s10, s10, 0x18000
	s_addc_u32 s11, s11, 0
	ds_read_b32 v96, v10 offset:800
	ds_read_b32 v97, v10 offset:8992
	ds_read_b32 v98, v10 offset:17184
	ds_read_b32 v99, v10 offset:25376
	ds_read_b32 v100, v10 offset:33568
	s_waitcnt vmcnt(15) lgkmcnt(0)
	v_fmac_f32_e32 v12, v96, v48
	v_fmac_f32_e32 v13, v96, v49
	v_fmac_f32_e32 v14, v96, v50
	v_fmac_f32_e32 v15, v96, v51
	v_fmac_f32_e32 v16, v97, v48
	v_fmac_f32_e32 v17, v97, v49
	v_fmac_f32_e32 v18, v97, v50
	v_fmac_f32_e32 v19, v97, v51
	v_fmac_f32_e32 v20, v98, v48
	v_fmac_f32_e32 v21, v98, v49
	v_fmac_f32_e32 v22, v98, v50
	v_fmac_f32_e32 v23, v98, v51
	v_fmac_f32_e32 v24, v99, v48
	v_fmac_f32_e32 v25, v99, v49
	v_fmac_f32_e32 v26, v99, v50
	v_fmac_f32_e32 v27, v99, v51
	v_fmac_f32_e32 v28, v100, v48
	v_fmac_f32_e32 v29, v100, v49
	v_fmac_f32_e32 v30, v100, v50
	v_fmac_f32_e32 v31, v100, v51
	global_load_dwordx4 v[48:51], v11, s[10:11]
	s_add_u32 s10, s10, 0x18000
	s_addc_u32 s11, s11, 0
	ds_read_b32 v96, v10 offset:808
	ds_read_b32 v97, v10 offset:9000
	ds_read_b32 v98, v10 offset:17192
	ds_read_b32 v99, v10 offset:25384
	ds_read_b32 v100, v10 offset:33576
	s_waitcnt vmcnt(15) lgkmcnt(0)
	v_fmac_f32_e32 v12, v96, v52
	v_fmac_f32_e32 v13, v96, v53
	v_fmac_f32_e32 v14, v96, v54
	v_fmac_f32_e32 v15, v96, v55
	v_fmac_f32_e32 v16, v97, v52
	v_fmac_f32_e32 v17, v97, v53
	v_fmac_f32_e32 v18, v97, v54
	v_fmac_f32_e32 v19, v97, v55
	v_fmac_f32_e32 v20, v98, v52
	v_fmac_f32_e32 v21, v98, v53
	v_fmac_f32_e32 v22, v98, v54
	v_fmac_f32_e32 v23, v98, v55
	v_fmac_f32_e32 v24, v99, v52
	v_fmac_f32_e32 v25, v99, v53
	v_fmac_f32_e32 v26, v99, v54
	v_fmac_f32_e32 v27, v99, v55
	v_fmac_f32_e32 v28, v100, v52
	v_fmac_f32_e32 v29, v100, v53
	v_fmac_f32_e32 v30, v100, v54
	v_fmac_f32_e32 v31, v100, v55
	global_load_dwordx4 v[52:55], v11, s[10:11]
	s_add_u32 s10, s10, 0x18000
	s_addc_u32 s11, s11, 0
	ds_read_b32 v96, v10 offset:816
	ds_read_b32 v97, v10 offset:9008
	ds_read_b32 v98, v10 offset:17200
	ds_read_b32 v99, v10 offset:25392
	ds_read_b32 v100, v10 offset:33584
	s_waitcnt vmcnt(15) lgkmcnt(0)
	v_fmac_f32_e32 v12, v96, v56
	v_fmac_f32_e32 v13, v96, v57
	v_fmac_f32_e32 v14, v96, v58
	v_fmac_f32_e32 v15, v96, v59
	v_fmac_f32_e32 v16, v97, v56
	v_fmac_f32_e32 v17, v97, v57
	v_fmac_f32_e32 v18, v97, v58
	v_fmac_f32_e32 v19, v97, v59
	v_fmac_f32_e32 v20, v98, v56
	v_fmac_f32_e32 v21, v98, v57
	v_fmac_f32_e32 v22, v98, v58
	v_fmac_f32_e32 v23, v98, v59
	v_fmac_f32_e32 v24, v99, v56
	v_fmac_f32_e32 v25, v99, v57
	v_fmac_f32_e32 v26, v99, v58
	v_fmac_f32_e32 v27, v99, v59
	v_fmac_f32_e32 v28, v100, v56
	v_fmac_f32_e32 v29, v100, v57
	v_fmac_f32_e32 v30, v100, v58
	v_fmac_f32_e32 v31, v100, v59
	global_load_dwordx4 v[56:59], v11, s[10:11]
	s_add_u32 s10, s10, 0x18000
	s_addc_u32 s11, s11, 0
	ds_read_b32 v96, v10 offset:824
	ds_read_b32 v97, v10 offset:9016
	ds_read_b32 v98, v10 offset:17208
	ds_read_b32 v99, v10 offset:25400
	ds_read_b32 v100, v10 offset:33592
	s_waitcnt vmcnt(15) lgkmcnt(0)
	v_fmac_f32_e32 v12, v96, v60
	v_fmac_f32_e32 v13, v96, v61
	v_fmac_f32_e32 v14, v96, v62
	v_fmac_f32_e32 v15, v96, v63
	v_fmac_f32_e32 v16, v97, v60
	v_fmac_f32_e32 v17, v97, v61
	v_fmac_f32_e32 v18, v97, v62
	v_fmac_f32_e32 v19, v97, v63
	v_fmac_f32_e32 v20, v98, v60
	v_fmac_f32_e32 v21, v98, v61
	v_fmac_f32_e32 v22, v98, v62
	v_fmac_f32_e32 v23, v98, v63
	v_fmac_f32_e32 v24, v99, v60
	v_fmac_f32_e32 v25, v99, v61
	v_fmac_f32_e32 v26, v99, v62
	v_fmac_f32_e32 v27, v99, v63
	v_fmac_f32_e32 v28, v100, v60
	v_fmac_f32_e32 v29, v100, v61
	v_fmac_f32_e32 v30, v100, v62
	v_fmac_f32_e32 v31, v100, v63
	global_load_dwordx4 v[60:63], v11, s[10:11]
	s_add_u32 s10, s10, 0x18000
	s_addc_u32 s11, s11, 0
	ds_read_b32 v96, v10 offset:832
	ds_read_b32 v97, v10 offset:9024
	ds_read_b32 v98, v10 offset:17216
	ds_read_b32 v99, v10 offset:25408
	ds_read_b32 v100, v10 offset:33600
	s_waitcnt vmcnt(15) lgkmcnt(0)
	v_fmac_f32_e32 v12, v96, v64
	v_fmac_f32_e32 v13, v96, v65
	v_fmac_f32_e32 v14, v96, v66
	v_fmac_f32_e32 v15, v96, v67
	v_fmac_f32_e32 v16, v97, v64
	v_fmac_f32_e32 v17, v97, v65
	v_fmac_f32_e32 v18, v97, v66
	v_fmac_f32_e32 v19, v97, v67
	v_fmac_f32_e32 v20, v98, v64
	v_fmac_f32_e32 v21, v98, v65
	v_fmac_f32_e32 v22, v98, v66
	v_fmac_f32_e32 v23, v98, v67
	v_fmac_f32_e32 v24, v99, v64
	v_fmac_f32_e32 v25, v99, v65
	v_fmac_f32_e32 v26, v99, v66
	v_fmac_f32_e32 v27, v99, v67
	v_fmac_f32_e32 v28, v100, v64
	v_fmac_f32_e32 v29, v100, v65
	v_fmac_f32_e32 v30, v100, v66
	v_fmac_f32_e32 v31, v100, v67
	global_load_dwordx4 v[64:67], v11, s[10:11]
	s_add_u32 s10, s10, 0x18000
	s_addc_u32 s11, s11, 0
	ds_read_b32 v96, v10 offset:840
	ds_read_b32 v97, v10 offset:9032
	ds_read_b32 v98, v10 offset:17224
	ds_read_b32 v99, v10 offset:25416
	ds_read_b32 v100, v10 offset:33608
	s_waitcnt vmcnt(15) lgkmcnt(0)
	v_fmac_f32_e32 v12, v96, v68
	v_fmac_f32_e32 v13, v96, v69
	v_fmac_f32_e32 v14, v96, v70
	v_fmac_f32_e32 v15, v96, v71
	v_fmac_f32_e32 v16, v97, v68
	v_fmac_f32_e32 v17, v97, v69
	v_fmac_f32_e32 v18, v97, v70
	v_fmac_f32_e32 v19, v97, v71
	v_fmac_f32_e32 v20, v98, v68
	v_fmac_f32_e32 v21, v98, v69
	v_fmac_f32_e32 v22, v98, v70
	v_fmac_f32_e32 v23, v98, v71
	v_fmac_f32_e32 v24, v99, v68
	v_fmac_f32_e32 v25, v99, v69
	v_fmac_f32_e32 v26, v99, v70
	v_fmac_f32_e32 v27, v99, v71
	v_fmac_f32_e32 v28, v100, v68
	v_fmac_f32_e32 v29, v100, v69
	v_fmac_f32_e32 v30, v100, v70
	v_fmac_f32_e32 v31, v100, v71
	global_load_dwordx4 v[68:71], v11, s[10:11]
	s_add_u32 s10, s10, 0x18000
	s_addc_u32 s11, s11, 0
	ds_read_b32 v96, v10 offset:848
	ds_read_b32 v97, v10 offset:9040
	ds_read_b32 v98, v10 offset:17232
	ds_read_b32 v99, v10 offset:25424
	ds_read_b32 v100, v10 offset:33616
	s_waitcnt vmcnt(15) lgkmcnt(0)
	v_fmac_f32_e32 v12, v96, v72
	v_fmac_f32_e32 v13, v96, v73
	v_fmac_f32_e32 v14, v96, v74
	v_fmac_f32_e32 v15, v96, v75
	v_fmac_f32_e32 v16, v97, v72
	v_fmac_f32_e32 v17, v97, v73
	v_fmac_f32_e32 v18, v97, v74
	v_fmac_f32_e32 v19, v97, v75
	v_fmac_f32_e32 v20, v98, v72
	v_fmac_f32_e32 v21, v98, v73
	v_fmac_f32_e32 v22, v98, v74
	v_fmac_f32_e32 v23, v98, v75
	v_fmac_f32_e32 v24, v99, v72
	v_fmac_f32_e32 v25, v99, v73
	v_fmac_f32_e32 v26, v99, v74
	v_fmac_f32_e32 v27, v99, v75
	v_fmac_f32_e32 v28, v100, v72
	v_fmac_f32_e32 v29, v100, v73
	v_fmac_f32_e32 v30, v100, v74
	v_fmac_f32_e32 v31, v100, v75
	global_load_dwordx4 v[72:75], v11, s[10:11]
	s_add_u32 s10, s10, 0x18000
	s_addc_u32 s11, s11, 0
	ds_read_b32 v96, v10 offset:856
	ds_read_b32 v97, v10 offset:9048
	ds_read_b32 v98, v10 offset:17240
	ds_read_b32 v99, v10 offset:25432
	ds_read_b32 v100, v10 offset:33624
	s_waitcnt vmcnt(15) lgkmcnt(0)
	v_fmac_f32_e32 v12, v96, v76
	v_fmac_f32_e32 v13, v96, v77
	v_fmac_f32_e32 v14, v96, v78
	v_fmac_f32_e32 v15, v96, v79
	v_fmac_f32_e32 v16, v97, v76
	v_fmac_f32_e32 v17, v97, v77
	v_fmac_f32_e32 v18, v97, v78
	v_fmac_f32_e32 v19, v97, v79
	v_fmac_f32_e32 v20, v98, v76
	v_fmac_f32_e32 v21, v98, v77
	v_fmac_f32_e32 v22, v98, v78
	v_fmac_f32_e32 v23, v98, v79
	v_fmac_f32_e32 v24, v99, v76
	v_fmac_f32_e32 v25, v99, v77
	v_fmac_f32_e32 v26, v99, v78
	v_fmac_f32_e32 v27, v99, v79
	v_fmac_f32_e32 v28, v100, v76
	v_fmac_f32_e32 v29, v100, v77
	v_fmac_f32_e32 v30, v100, v78
	v_fmac_f32_e32 v31, v100, v79
	global_load_dwordx4 v[76:79], v11, s[10:11]
	s_add_u32 s10, s10, 0x18000
	s_addc_u32 s11, s11, 0
	ds_read_b32 v96, v10 offset:864
	ds_read_b32 v97, v10 offset:9056
	ds_read_b32 v98, v10 offset:17248
	ds_read_b32 v99, v10 offset:25440
	ds_read_b32 v100, v10 offset:33632
	s_waitcnt vmcnt(15) lgkmcnt(0)
	v_fmac_f32_e32 v12, v96, v80
	v_fmac_f32_e32 v13, v96, v81
	v_fmac_f32_e32 v14, v96, v82
	v_fmac_f32_e32 v15, v96, v83
	v_fmac_f32_e32 v16, v97, v80
	v_fmac_f32_e32 v17, v97, v81
	v_fmac_f32_e32 v18, v97, v82
	v_fmac_f32_e32 v19, v97, v83
	v_fmac_f32_e32 v20, v98, v80
	v_fmac_f32_e32 v21, v98, v81
	v_fmac_f32_e32 v22, v98, v82
	v_fmac_f32_e32 v23, v98, v83
	v_fmac_f32_e32 v24, v99, v80
	v_fmac_f32_e32 v25, v99, v81
	v_fmac_f32_e32 v26, v99, v82
	v_fmac_f32_e32 v27, v99, v83
	v_fmac_f32_e32 v28, v100, v80
	v_fmac_f32_e32 v29, v100, v81
	v_fmac_f32_e32 v30, v100, v82
	v_fmac_f32_e32 v31, v100, v83
	global_load_dwordx4 v[80:83], v11, s[10:11]
	s_add_u32 s10, s10, 0x18000
	s_addc_u32 s11, s11, 0
	ds_read_b32 v96, v10 offset:872
	ds_read_b32 v97, v10 offset:9064
	ds_read_b32 v98, v10 offset:17256
	ds_read_b32 v99, v10 offset:25448
	ds_read_b32 v100, v10 offset:33640
	s_waitcnt vmcnt(15) lgkmcnt(0)
	v_fmac_f32_e32 v12, v96, v84
	v_fmac_f32_e32 v13, v96, v85
	v_fmac_f32_e32 v14, v96, v86
	v_fmac_f32_e32 v15, v96, v87
	v_fmac_f32_e32 v16, v97, v84
	v_fmac_f32_e32 v17, v97, v85
	v_fmac_f32_e32 v18, v97, v86
	v_fmac_f32_e32 v19, v97, v87
	v_fmac_f32_e32 v20, v98, v84
	v_fmac_f32_e32 v21, v98, v85
	v_fmac_f32_e32 v22, v98, v86
	v_fmac_f32_e32 v23, v98, v87
	v_fmac_f32_e32 v24, v99, v84
	v_fmac_f32_e32 v25, v99, v85
	v_fmac_f32_e32 v26, v99, v86
	v_fmac_f32_e32 v27, v99, v87
	v_fmac_f32_e32 v28, v100, v84
	v_fmac_f32_e32 v29, v100, v85
	v_fmac_f32_e32 v30, v100, v86
	v_fmac_f32_e32 v31, v100, v87
	global_load_dwordx4 v[84:87], v11, s[10:11]
	s_add_u32 s10, s10, 0x18000
	s_addc_u32 s11, s11, 0
	ds_read_b32 v96, v10 offset:880
	ds_read_b32 v97, v10 offset:9072
	ds_read_b32 v98, v10 offset:17264
	ds_read_b32 v99, v10 offset:25456
	ds_read_b32 v100, v10 offset:33648
	s_waitcnt vmcnt(15) lgkmcnt(0)
	v_fmac_f32_e32 v12, v96, v88
	v_fmac_f32_e32 v13, v96, v89
	v_fmac_f32_e32 v14, v96, v90
	v_fmac_f32_e32 v15, v96, v91
	v_fmac_f32_e32 v16, v97, v88
	v_fmac_f32_e32 v17, v97, v89
	v_fmac_f32_e32 v18, v97, v90
	v_fmac_f32_e32 v19, v97, v91
	v_fmac_f32_e32 v20, v98, v88
	v_fmac_f32_e32 v21, v98, v89
	v_fmac_f32_e32 v22, v98, v90
	v_fmac_f32_e32 v23, v98, v91
	v_fmac_f32_e32 v24, v99, v88
	v_fmac_f32_e32 v25, v99, v89
	v_fmac_f32_e32 v26, v99, v90
	v_fmac_f32_e32 v27, v99, v91
	v_fmac_f32_e32 v28, v100, v88
	v_fmac_f32_e32 v29, v100, v89
	v_fmac_f32_e32 v30, v100, v90
	v_fmac_f32_e32 v31, v100, v91
	global_load_dwordx4 v[88:91], v11, s[10:11]
	s_add_u32 s10, s10, 0x18000
	s_addc_u32 s11, s11, 0
	ds_read_b32 v96, v10 offset:888
	ds_read_b32 v97, v10 offset:9080
	ds_read_b32 v98, v10 offset:17272
	ds_read_b32 v99, v10 offset:25464
	ds_read_b32 v100, v10 offset:33656
	s_waitcnt vmcnt(15) lgkmcnt(0)
	v_fmac_f32_e32 v12, v96, v92
	v_fmac_f32_e32 v13, v96, v93
	v_fmac_f32_e32 v14, v96, v94
	v_fmac_f32_e32 v15, v96, v95
	v_fmac_f32_e32 v16, v97, v92
	v_fmac_f32_e32 v17, v97, v93
	v_fmac_f32_e32 v18, v97, v94
	v_fmac_f32_e32 v19, v97, v95
	v_fmac_f32_e32 v20, v98, v92
	v_fmac_f32_e32 v21, v98, v93
	v_fmac_f32_e32 v22, v98, v94
	v_fmac_f32_e32 v23, v98, v95
	v_fmac_f32_e32 v24, v99, v92
	v_fmac_f32_e32 v25, v99, v93
	v_fmac_f32_e32 v26, v99, v94
	v_fmac_f32_e32 v27, v99, v95
	v_fmac_f32_e32 v28, v100, v92
	v_fmac_f32_e32 v29, v100, v93
	v_fmac_f32_e32 v30, v100, v94
	v_fmac_f32_e32 v31, v100, v95
	global_load_dwordx4 v[92:95], v11, s[10:11]
	s_add_u32 s10, s10, 0x18000
	s_addc_u32 s11, s11, 0
	ds_read_b32 v96, v10 offset:896
	ds_read_b32 v97, v10 offset:9088
	ds_read_b32 v98, v10 offset:17280
	ds_read_b32 v99, v10 offset:25472
	ds_read_b32 v100, v10 offset:33664
	s_waitcnt vmcnt(15) lgkmcnt(0)
	v_fmac_f32_e32 v12, v96, v32
	v_fmac_f32_e32 v13, v96, v33
	v_fmac_f32_e32 v14, v96, v34
	v_fmac_f32_e32 v15, v96, v35
	v_fmac_f32_e32 v16, v97, v32
	v_fmac_f32_e32 v17, v97, v33
	v_fmac_f32_e32 v18, v97, v34
	v_fmac_f32_e32 v19, v97, v35
	v_fmac_f32_e32 v20, v98, v32
	v_fmac_f32_e32 v21, v98, v33
	v_fmac_f32_e32 v22, v98, v34
	v_fmac_f32_e32 v23, v98, v35
	v_fmac_f32_e32 v24, v99, v32
	v_fmac_f32_e32 v25, v99, v33
	v_fmac_f32_e32 v26, v99, v34
	v_fmac_f32_e32 v27, v99, v35
	v_fmac_f32_e32 v28, v100, v32
	v_fmac_f32_e32 v29, v100, v33
	v_fmac_f32_e32 v30, v100, v34
	v_fmac_f32_e32 v31, v100, v35
	ds_read_b32 v96, v10 offset:904
	ds_read_b32 v97, v10 offset:9096
	ds_read_b32 v98, v10 offset:17288
	ds_read_b32 v99, v10 offset:25480
	ds_read_b32 v100, v10 offset:33672
	s_waitcnt vmcnt(14) lgkmcnt(0)
	v_fmac_f32_e32 v12, v96, v36
	v_fmac_f32_e32 v13, v96, v37
	v_fmac_f32_e32 v14, v96, v38
	v_fmac_f32_e32 v15, v96, v39
	v_fmac_f32_e32 v16, v97, v36
	v_fmac_f32_e32 v17, v97, v37
	v_fmac_f32_e32 v18, v97, v38
	v_fmac_f32_e32 v19, v97, v39
	v_fmac_f32_e32 v20, v98, v36
	v_fmac_f32_e32 v21, v98, v37
	v_fmac_f32_e32 v22, v98, v38
	v_fmac_f32_e32 v23, v98, v39
	v_fmac_f32_e32 v24, v99, v36
	v_fmac_f32_e32 v25, v99, v37
	v_fmac_f32_e32 v26, v99, v38
	v_fmac_f32_e32 v27, v99, v39
	v_fmac_f32_e32 v28, v100, v36
	v_fmac_f32_e32 v29, v100, v37
	v_fmac_f32_e32 v30, v100, v38
	v_fmac_f32_e32 v31, v100, v39
	ds_read_b32 v96, v10 offset:912
	ds_read_b32 v97, v10 offset:9104
	ds_read_b32 v98, v10 offset:17296
	ds_read_b32 v99, v10 offset:25488
	ds_read_b32 v100, v10 offset:33680
	s_waitcnt vmcnt(13) lgkmcnt(0)
	v_fmac_f32_e32 v12, v96, v40
	v_fmac_f32_e32 v13, v96, v41
	v_fmac_f32_e32 v14, v96, v42
	v_fmac_f32_e32 v15, v96, v43
	v_fmac_f32_e32 v16, v97, v40
	v_fmac_f32_e32 v17, v97, v41
	v_fmac_f32_e32 v18, v97, v42
	v_fmac_f32_e32 v19, v97, v43
	v_fmac_f32_e32 v20, v98, v40
	v_fmac_f32_e32 v21, v98, v41
	v_fmac_f32_e32 v22, v98, v42
	v_fmac_f32_e32 v23, v98, v43
	v_fmac_f32_e32 v24, v99, v40
	v_fmac_f32_e32 v25, v99, v41
	v_fmac_f32_e32 v26, v99, v42
	v_fmac_f32_e32 v27, v99, v43
	v_fmac_f32_e32 v28, v100, v40
	v_fmac_f32_e32 v29, v100, v41
	v_fmac_f32_e32 v30, v100, v42
	v_fmac_f32_e32 v31, v100, v43
	ds_read_b32 v96, v10 offset:920
	ds_read_b32 v97, v10 offset:9112
	ds_read_b32 v98, v10 offset:17304
	ds_read_b32 v99, v10 offset:25496
	ds_read_b32 v100, v10 offset:33688
	s_waitcnt vmcnt(12) lgkmcnt(0)
	v_fmac_f32_e32 v12, v96, v44
	v_fmac_f32_e32 v13, v96, v45
	v_fmac_f32_e32 v14, v96, v46
	v_fmac_f32_e32 v15, v96, v47
	v_fmac_f32_e32 v16, v97, v44
	v_fmac_f32_e32 v17, v97, v45
	v_fmac_f32_e32 v18, v97, v46
	v_fmac_f32_e32 v19, v97, v47
	v_fmac_f32_e32 v20, v98, v44
	v_fmac_f32_e32 v21, v98, v45
	v_fmac_f32_e32 v22, v98, v46
	v_fmac_f32_e32 v23, v98, v47
	v_fmac_f32_e32 v24, v99, v44
	v_fmac_f32_e32 v25, v99, v45
	v_fmac_f32_e32 v26, v99, v46
	v_fmac_f32_e32 v27, v99, v47
	v_fmac_f32_e32 v28, v100, v44
	v_fmac_f32_e32 v29, v100, v45
	v_fmac_f32_e32 v30, v100, v46
	v_fmac_f32_e32 v31, v100, v47
	ds_read_b32 v96, v10 offset:928
	ds_read_b32 v97, v10 offset:9120
	ds_read_b32 v98, v10 offset:17312
	ds_read_b32 v99, v10 offset:25504
	ds_read_b32 v100, v10 offset:33696
	s_waitcnt vmcnt(11) lgkmcnt(0)
	v_fmac_f32_e32 v12, v96, v48
	v_fmac_f32_e32 v13, v96, v49
	v_fmac_f32_e32 v14, v96, v50
	v_fmac_f32_e32 v15, v96, v51
	v_fmac_f32_e32 v16, v97, v48
	v_fmac_f32_e32 v17, v97, v49
	v_fmac_f32_e32 v18, v97, v50
	v_fmac_f32_e32 v19, v97, v51
	v_fmac_f32_e32 v20, v98, v48
	v_fmac_f32_e32 v21, v98, v49
	v_fmac_f32_e32 v22, v98, v50
	v_fmac_f32_e32 v23, v98, v51
	v_fmac_f32_e32 v24, v99, v48
	v_fmac_f32_e32 v25, v99, v49
	v_fmac_f32_e32 v26, v99, v50
	v_fmac_f32_e32 v27, v99, v51
	v_fmac_f32_e32 v28, v100, v48
	v_fmac_f32_e32 v29, v100, v49
	v_fmac_f32_e32 v30, v100, v50
	v_fmac_f32_e32 v31, v100, v51
	ds_read_b32 v96, v10 offset:936
	ds_read_b32 v97, v10 offset:9128
	ds_read_b32 v98, v10 offset:17320
	ds_read_b32 v99, v10 offset:25512
	ds_read_b32 v100, v10 offset:33704
	s_waitcnt vmcnt(10) lgkmcnt(0)
	v_fmac_f32_e32 v12, v96, v52
	v_fmac_f32_e32 v13, v96, v53
	v_fmac_f32_e32 v14, v96, v54
	v_fmac_f32_e32 v15, v96, v55
	v_fmac_f32_e32 v16, v97, v52
	v_fmac_f32_e32 v17, v97, v53
	v_fmac_f32_e32 v18, v97, v54
	v_fmac_f32_e32 v19, v97, v55
	v_fmac_f32_e32 v20, v98, v52
	v_fmac_f32_e32 v21, v98, v53
	v_fmac_f32_e32 v22, v98, v54
	v_fmac_f32_e32 v23, v98, v55
	v_fmac_f32_e32 v24, v99, v52
	v_fmac_f32_e32 v25, v99, v53
	v_fmac_f32_e32 v26, v99, v54
	v_fmac_f32_e32 v27, v99, v55
	v_fmac_f32_e32 v28, v100, v52
	v_fmac_f32_e32 v29, v100, v53
	v_fmac_f32_e32 v30, v100, v54
	v_fmac_f32_e32 v31, v100, v55
	ds_read_b32 v96, v10 offset:944
	ds_read_b32 v97, v10 offset:9136
	ds_read_b32 v98, v10 offset:17328
	ds_read_b32 v99, v10 offset:25520
	ds_read_b32 v100, v10 offset:33712
	s_waitcnt vmcnt(9) lgkmcnt(0)
	v_fmac_f32_e32 v12, v96, v56
	v_fmac_f32_e32 v13, v96, v57
	v_fmac_f32_e32 v14, v96, v58
	v_fmac_f32_e32 v15, v96, v59
	v_fmac_f32_e32 v16, v97, v56
	v_fmac_f32_e32 v17, v97, v57
	v_fmac_f32_e32 v18, v97, v58
	v_fmac_f32_e32 v19, v97, v59
	v_fmac_f32_e32 v20, v98, v56
	v_fmac_f32_e32 v21, v98, v57
	v_fmac_f32_e32 v22, v98, v58
	v_fmac_f32_e32 v23, v98, v59
	v_fmac_f32_e32 v24, v99, v56
	v_fmac_f32_e32 v25, v99, v57
	v_fmac_f32_e32 v26, v99, v58
	v_fmac_f32_e32 v27, v99, v59
	v_fmac_f32_e32 v28, v100, v56
	v_fmac_f32_e32 v29, v100, v57
	v_fmac_f32_e32 v30, v100, v58
	v_fmac_f32_e32 v31, v100, v59
	ds_read_b32 v96, v10 offset:952
	ds_read_b32 v97, v10 offset:9144
	ds_read_b32 v98, v10 offset:17336
	ds_read_b32 v99, v10 offset:25528
	ds_read_b32 v100, v10 offset:33720
	s_waitcnt vmcnt(8) lgkmcnt(0)
	v_fmac_f32_e32 v12, v96, v60
	v_fmac_f32_e32 v13, v96, v61
	v_fmac_f32_e32 v14, v96, v62
	v_fmac_f32_e32 v15, v96, v63
	v_fmac_f32_e32 v16, v97, v60
	v_fmac_f32_e32 v17, v97, v61
	v_fmac_f32_e32 v18, v97, v62
	v_fmac_f32_e32 v19, v97, v63
	v_fmac_f32_e32 v20, v98, v60
	v_fmac_f32_e32 v21, v98, v61
	v_fmac_f32_e32 v22, v98, v62
	v_fmac_f32_e32 v23, v98, v63
	v_fmac_f32_e32 v24, v99, v60
	v_fmac_f32_e32 v25, v99, v61
	v_fmac_f32_e32 v26, v99, v62
	v_fmac_f32_e32 v27, v99, v63
	v_fmac_f32_e32 v28, v100, v60
	v_fmac_f32_e32 v29, v100, v61
	v_fmac_f32_e32 v30, v100, v62
	v_fmac_f32_e32 v31, v100, v63
	ds_read_b32 v96, v10 offset:960
	ds_read_b32 v97, v10 offset:9152
	ds_read_b32 v98, v10 offset:17344
	ds_read_b32 v99, v10 offset:25536
	ds_read_b32 v100, v10 offset:33728
	s_waitcnt vmcnt(7) lgkmcnt(0)
	v_fmac_f32_e32 v12, v96, v64
	v_fmac_f32_e32 v13, v96, v65
	v_fmac_f32_e32 v14, v96, v66
	v_fmac_f32_e32 v15, v96, v67
	v_fmac_f32_e32 v16, v97, v64
	v_fmac_f32_e32 v17, v97, v65
	v_fmac_f32_e32 v18, v97, v66
	v_fmac_f32_e32 v19, v97, v67
	v_fmac_f32_e32 v20, v98, v64
	v_fmac_f32_e32 v21, v98, v65
	v_fmac_f32_e32 v22, v98, v66
	v_fmac_f32_e32 v23, v98, v67
	v_fmac_f32_e32 v24, v99, v64
	v_fmac_f32_e32 v25, v99, v65
	v_fmac_f32_e32 v26, v99, v66
	v_fmac_f32_e32 v27, v99, v67
	v_fmac_f32_e32 v28, v100, v64
	v_fmac_f32_e32 v29, v100, v65
	v_fmac_f32_e32 v30, v100, v66
	v_fmac_f32_e32 v31, v100, v67
	ds_read_b32 v96, v10 offset:968
	ds_read_b32 v97, v10 offset:9160
	ds_read_b32 v98, v10 offset:17352
	ds_read_b32 v99, v10 offset:25544
	ds_read_b32 v100, v10 offset:33736
	s_waitcnt vmcnt(6) lgkmcnt(0)
	v_fmac_f32_e32 v12, v96, v68
	v_fmac_f32_e32 v13, v96, v69
	v_fmac_f32_e32 v14, v96, v70
	v_fmac_f32_e32 v15, v96, v71
	v_fmac_f32_e32 v16, v97, v68
	v_fmac_f32_e32 v17, v97, v69
	v_fmac_f32_e32 v18, v97, v70
	v_fmac_f32_e32 v19, v97, v71
	v_fmac_f32_e32 v20, v98, v68
	v_fmac_f32_e32 v21, v98, v69
	v_fmac_f32_e32 v22, v98, v70
	v_fmac_f32_e32 v23, v98, v71
	v_fmac_f32_e32 v24, v99, v68
	v_fmac_f32_e32 v25, v99, v69
	v_fmac_f32_e32 v26, v99, v70
	v_fmac_f32_e32 v27, v99, v71
	v_fmac_f32_e32 v28, v100, v68
	v_fmac_f32_e32 v29, v100, v69
	v_fmac_f32_e32 v30, v100, v70
	v_fmac_f32_e32 v31, v100, v71
	ds_read_b32 v96, v10 offset:976
	ds_read_b32 v97, v10 offset:9168
	ds_read_b32 v98, v10 offset:17360
	ds_read_b32 v99, v10 offset:25552
	ds_read_b32 v100, v10 offset:33744
	s_waitcnt vmcnt(5) lgkmcnt(0)
	v_fmac_f32_e32 v12, v96, v72
	v_fmac_f32_e32 v13, v96, v73
	v_fmac_f32_e32 v14, v96, v74
	v_fmac_f32_e32 v15, v96, v75
	v_fmac_f32_e32 v16, v97, v72
	v_fmac_f32_e32 v17, v97, v73
	v_fmac_f32_e32 v18, v97, v74
	v_fmac_f32_e32 v19, v97, v75
	v_fmac_f32_e32 v20, v98, v72
	v_fmac_f32_e32 v21, v98, v73
	v_fmac_f32_e32 v22, v98, v74
	v_fmac_f32_e32 v23, v98, v75
	v_fmac_f32_e32 v24, v99, v72
	v_fmac_f32_e32 v25, v99, v73
	v_fmac_f32_e32 v26, v99, v74
	v_fmac_f32_e32 v27, v99, v75
	v_fmac_f32_e32 v28, v100, v72
	v_fmac_f32_e32 v29, v100, v73
	v_fmac_f32_e32 v30, v100, v74
	v_fmac_f32_e32 v31, v100, v75
	ds_read_b32 v96, v10 offset:984
	ds_read_b32 v97, v10 offset:9176
	ds_read_b32 v98, v10 offset:17368
	ds_read_b32 v99, v10 offset:25560
	ds_read_b32 v100, v10 offset:33752
	s_waitcnt vmcnt(4) lgkmcnt(0)
	v_fmac_f32_e32 v12, v96, v76
	v_fmac_f32_e32 v13, v96, v77
	v_fmac_f32_e32 v14, v96, v78
	v_fmac_f32_e32 v15, v96, v79
	v_fmac_f32_e32 v16, v97, v76
	v_fmac_f32_e32 v17, v97, v77
	v_fmac_f32_e32 v18, v97, v78
	v_fmac_f32_e32 v19, v97, v79
	v_fmac_f32_e32 v20, v98, v76
	v_fmac_f32_e32 v21, v98, v77
	v_fmac_f32_e32 v22, v98, v78
	v_fmac_f32_e32 v23, v98, v79
	v_fmac_f32_e32 v24, v99, v76
	v_fmac_f32_e32 v25, v99, v77
	v_fmac_f32_e32 v26, v99, v78
	v_fmac_f32_e32 v27, v99, v79
	v_fmac_f32_e32 v28, v100, v76
	v_fmac_f32_e32 v29, v100, v77
	v_fmac_f32_e32 v30, v100, v78
	v_fmac_f32_e32 v31, v100, v79
	ds_read_b32 v96, v10 offset:992
	ds_read_b32 v97, v10 offset:9184
	ds_read_b32 v98, v10 offset:17376
	ds_read_b32 v99, v10 offset:25568
	ds_read_b32 v100, v10 offset:33760
	s_waitcnt vmcnt(3) lgkmcnt(0)
	v_fmac_f32_e32 v12, v96, v80
	v_fmac_f32_e32 v13, v96, v81
	v_fmac_f32_e32 v14, v96, v82
	v_fmac_f32_e32 v15, v96, v83
	v_fmac_f32_e32 v16, v97, v80
	v_fmac_f32_e32 v17, v97, v81
	v_fmac_f32_e32 v18, v97, v82
	v_fmac_f32_e32 v19, v97, v83
	v_fmac_f32_e32 v20, v98, v80
	v_fmac_f32_e32 v21, v98, v81
	v_fmac_f32_e32 v22, v98, v82
	v_fmac_f32_e32 v23, v98, v83
	v_fmac_f32_e32 v24, v99, v80
	v_fmac_f32_e32 v25, v99, v81
	v_fmac_f32_e32 v26, v99, v82
	v_fmac_f32_e32 v27, v99, v83
	v_fmac_f32_e32 v28, v100, v80
	v_fmac_f32_e32 v29, v100, v81
	v_fmac_f32_e32 v30, v100, v82
	v_fmac_f32_e32 v31, v100, v83
	ds_read_b32 v96, v10 offset:1000
	ds_read_b32 v97, v10 offset:9192
	ds_read_b32 v98, v10 offset:17384
	ds_read_b32 v99, v10 offset:25576
	ds_read_b32 v100, v10 offset:33768
	s_waitcnt vmcnt(2) lgkmcnt(0)
	v_fmac_f32_e32 v12, v96, v84
	v_fmac_f32_e32 v13, v96, v85
	v_fmac_f32_e32 v14, v96, v86
	v_fmac_f32_e32 v15, v96, v87
	v_fmac_f32_e32 v16, v97, v84
	v_fmac_f32_e32 v17, v97, v85
	v_fmac_f32_e32 v18, v97, v86
	v_fmac_f32_e32 v19, v97, v87
	v_fmac_f32_e32 v20, v98, v84
	v_fmac_f32_e32 v21, v98, v85
	v_fmac_f32_e32 v22, v98, v86
	v_fmac_f32_e32 v23, v98, v87
	v_fmac_f32_e32 v24, v99, v84
	v_fmac_f32_e32 v25, v99, v85
	v_fmac_f32_e32 v26, v99, v86
	v_fmac_f32_e32 v27, v99, v87
	v_fmac_f32_e32 v28, v100, v84
	v_fmac_f32_e32 v29, v100, v85
	v_fmac_f32_e32 v30, v100, v86
	v_fmac_f32_e32 v31, v100, v87
	ds_read_b32 v96, v10 offset:1008
	ds_read_b32 v97, v10 offset:9200
	ds_read_b32 v98, v10 offset:17392
	ds_read_b32 v99, v10 offset:25584
	ds_read_b32 v100, v10 offset:33776
	s_waitcnt vmcnt(1) lgkmcnt(0)
	v_fmac_f32_e32 v12, v96, v88
	v_fmac_f32_e32 v13, v96, v89
	v_fmac_f32_e32 v14, v96, v90
	v_fmac_f32_e32 v15, v96, v91
	v_fmac_f32_e32 v16, v97, v88
	v_fmac_f32_e32 v17, v97, v89
	v_fmac_f32_e32 v18, v97, v90
	v_fmac_f32_e32 v19, v97, v91
	v_fmac_f32_e32 v20, v98, v88
	v_fmac_f32_e32 v21, v98, v89
	v_fmac_f32_e32 v22, v98, v90
	v_fmac_f32_e32 v23, v98, v91
	v_fmac_f32_e32 v24, v99, v88
	v_fmac_f32_e32 v25, v99, v89
	v_fmac_f32_e32 v26, v99, v90
	v_fmac_f32_e32 v27, v99, v91
	v_fmac_f32_e32 v28, v100, v88
	v_fmac_f32_e32 v29, v100, v89
	v_fmac_f32_e32 v30, v100, v90
	v_fmac_f32_e32 v31, v100, v91
	ds_read_b32 v96, v10 offset:1016
	ds_read_b32 v97, v10 offset:9208
	ds_read_b32 v98, v10 offset:17400
	ds_read_b32 v99, v10 offset:25592
	ds_read_b32 v100, v10 offset:33784
	s_waitcnt vmcnt(0) lgkmcnt(0)
	v_fmac_f32_e32 v12, v96, v92
	v_fmac_f32_e32 v13, v96, v93
	v_fmac_f32_e32 v14, v96, v94
	v_fmac_f32_e32 v15, v96, v95
	v_fmac_f32_e32 v16, v97, v92
	v_fmac_f32_e32 v17, v97, v93
	v_fmac_f32_e32 v18, v97, v94
	v_fmac_f32_e32 v19, v97, v95
	v_fmac_f32_e32 v20, v98, v92
	v_fmac_f32_e32 v21, v98, v93
	v_fmac_f32_e32 v22, v98, v94
	v_fmac_f32_e32 v23, v98, v95
	v_fmac_f32_e32 v24, v99, v92
	v_fmac_f32_e32 v25, v99, v93
	v_fmac_f32_e32 v26, v99, v94
	v_fmac_f32_e32 v27, v99, v95
	v_fmac_f32_e32 v28, v100, v92
	v_fmac_f32_e32 v29, v100, v93
	v_fmac_f32_e32 v30, v100, v94
	v_fmac_f32_e32 v31, v100, v95
	v_lshl_add_u32 v5, v4, 1, v2
	v_mul_u32_u24_e32 v5, 24, v5
	v_add_u32_e32 v5, v5, v3
	v_mul_u32_u24_e32 v5, 80, v5
	v_add_u32_e32 v5, 0xa000, v5
	ds_write_b128 v5, v[12:15] offset:0
	ds_write_b128 v5, v[16:19] offset:16
	ds_write_b128 v5, v[20:23] offset:32
	ds_write_b128 v5, v[24:27] offset:48
	ds_write_b128 v5, v[28:31] offset:64
	s_mov_b64 exec, s[20:21]
	s_waitcnt lgkmcnt(0)
	s_barrier
	v_cmp_gt_u32_e32 vcc, 480, v154
	s_and_saveexec_b64 s[20:21], vcc
	v_mul_u32_u24_e32 v1, 0xccd, v154
	v_lshrrev_b32_e32 v1, 16, v1
	v_mul_u32_u24_e32 v2, 20, v1
	v_sub_u32_e32 v2, v154, v2
	v_mul_u32_u24_e32 v3, 80, v1
	v_lshl_add_u32 v3, v2, 2, v3
	v_add_u32_e32 v3, 0xa000, v3
	ds_read_b32 v32, v3 offset:0
	ds_read_b32 v33, v3 offset:1920
	ds_read_b32 v34, v3 offset:3840
	ds_read_b32 v35, v3 offset:5760
	ds_read_b32 v36, v3 offset:7680
	ds_read_b32 v37, v3 offset:9600
	ds_read_b32 v38, v3 offset:11520
	ds_read_b32 v39, v3 offset:13440
	ds_read_b32 v40, v3 offset:15360
	ds_read_b32 v41, v3 offset:17280
	ds_read_b32 v42, v3 offset:19200
	ds_read_b32 v43, v3 offset:21120
	ds_read_b32 v44, v3 offset:23040
	ds_read_b32 v45, v3 offset:24960
	ds_read_b32 v46, v3 offset:26880
	ds_read_b32 v47, v3 offset:28800
	v_lshrrev_b32_e32 v4, 2, v2
	v_and_b32_e32 v5, 3, v2
	v_lshl_add_u32 v5, v1, 2, v5
	v_add_u32_e32 v5, s9, v5
	s_mul_i32 s12, s8, 12288
	v_add_u32_e32 v6, s12, v5
	v_lshlrev_b32_e32 v6, 2, v6
	global_load_dword v7, v6, s[2:3]
	s_mul_i32 s12, s8, 5
	v_add_u32_e32 v4, s12, v4
	v_mul_u32_u24_e32 v4, 12288, v4
	v_add_u32_e32 v4, v4, v5
	v_lshlrev_b32_e32 v4, 2, v4
	s_add_u32 s12, s90, 0x10400000
	s_addc_u32 s13, s91, 0
	s_waitcnt lgkmcnt(0)
	v_mov_b32_e32 v8, 0
	v_add_f32_e32 v8, v8, v32
	v_add_f32_e32 v8, v8, v33
	v_add_f32_e32 v8, v8, v34
	v_add_f32_e32 v8, v8, v35
	v_add_f32_e32 v8, v8, v36
	v_add_f32_e32 v8, v8, v37
	v_add_f32_e32 v8, v8, v38
	v_add_f32_e32 v8, v8, v39
	v_add_f32_e32 v8, v8, v40
	v_add_f32_e32 v8, v8, v41
	v_add_f32_e32 v8, v8, v42
	v_add_f32_e32 v8, v8, v43
	v_add_f32_e32 v8, v8, v44
	v_add_f32_e32 v8, v8, v45
	v_add_f32_e32 v8, v8, v46
	v_add_f32_e32 v8, v8, v47
	s_waitcnt vmcnt(0)
	v_add_f32_e32 v8, v8, v7
	global_store_dword v4, v8, s[12:13]
	s_or_b64 exec, exec, s[20:21]
	s_waitcnt vmcnt(0)
	s_barrier
	v_mov_b32_e32 v22, v154
	s_branch .LBB0_97
.Lp0_skipmod:
	v_mov_b32_e32 v22, v154

.LBB0_493:
	s_cmp_lt_u32 s96, 128
	s_cbranch_scc1 .Lmix0_skip
	s_load_dwordx2 s[0:1], s[92:93], 0x28
	s_load_dwordx2 s[2:3], s[92:93], 0x30
	s_load_dwordx2 s[4:5], s[92:93], 0x18
	s_load_dwordx2 s[6:7], s[92:93], 0x20
	v_lshlrev_b32_e32 v1, 2, v154
	s_waitcnt lgkmcnt(0)
	s_add_u32 s12, s4, 0x0
	s_addc_u32 s13, s5, 0
	global_load_dword v32, v1, s[12:13]
	s_add_u32 s12, s4, 0x800
	s_addc_u32 s13, s5, 0
	global_load_dword v33, v1, s[12:13]
	s_add_u32 s12, s4, 0x1000
	s_addc_u32 s13, s5, 0
	global_load_dword v34, v1, s[12:13]
	s_add_u32 s12, s4, 0x1800
	s_addc_u32 s13, s5, 0
	global_load_dword v35, v1, s[12:13]
	s_add_u32 s12, s4, 0x2000
	s_addc_u32 s13, s5, 0
	global_load_dword v36, v1, s[12:13]
	s_add_u32 s12, s4, 0x2800
	s_addc_u32 s13, s5, 0
	global_load_dword v37, v1, s[12:13]
	s_add_u32 s12, s4, 0x3000
	s_addc_u32 s13, s5, 0
	global_load_dword v38, v1, s[12:13]
	s_add_u32 s12, s4, 0x3800
	s_addc_u32 s13, s5, 0
	global_load_dword v39, v1, s[12:13]
	s_add_u32 s12, s4, 0x4000
	s_addc_u32 s13, s5, 0
	global_load_dword v40, v1, s[12:13]
	s_add_u32 s12, s4, 0x4800
	s_addc_u32 s13, s5, 0
	global_load_dword v41, v1, s[12:13]
	s_add_u32 s12, s4, 0x5000
	s_addc_u32 s13, s5, 0
	global_load_dword v42, v1, s[12:13]
	s_add_u32 s12, s4, 0x5800
	s_addc_u32 s13, s5, 0
	global_load_dword v43, v1, s[12:13]
	s_add_u32 s12, s4, 0x6000
	s_addc_u32 s13, s5, 0
	global_load_dword v44, v1, s[12:13]
	s_add_u32 s12, s4, 0x6800
	s_addc_u32 s13, s5, 0
	global_load_dword v45, v1, s[12:13]
	s_add_u32 s12, s4, 0x7000
	s_addc_u32 s13, s5, 0
	global_load_dword v46, v1, s[12:13]
	s_add_u32 s12, s4, 0x7800
	s_addc_u32 s13, s5, 0
	global_load_dword v47, v1, s[12:13]
	s_add_u32 s12, s6, 0x0
	s_addc_u32 s13, s7, 0
	global_load_dword v48, v1, s[12:13]
	s_add_u32 s12, s6, 0x800
	s_addc_u32 s13, s7, 0
	global_load_dword v49, v1, s[12:13]
	s_add_u32 s12, s6, 0x1000
	s_addc_u32 s13, s7, 0
	global_load_dword v50, v1, s[12:13]
	s_add_u32 s12, s6, 0x1800
	s_addc_u32 s13, s7, 0
	global_load_dword v51, v1, s[12:13]
	v_mov_b32_e32 v2, 0xbfb8aa3b
	s_waitcnt vmcnt(0)
	v_mul_f32_e32 v3, v2, v32
	v_exp_f32_e32 v3, v3
	s_nop 0
	v_add_f32_e32 v3, 1.0, v3
	v_rcp_f32_e32 v3, v3
	s_nop 0
	v_mul_f32_e32 v3, v3, v32
	ds_write_b32 v1, v3 offset:0
	v_mul_f32_e32 v3, v2, v33
	v_exp_f32_e32 v3, v3
	s_nop 0
	v_add_f32_e32 v3, 1.0, v3
	v_rcp_f32_e32 v3, v3
	s_nop 0
	v_mul_f32_e32 v3, v3, v33
	ds_write_b32 v1, v3 offset:2048
	v_mul_f32_e32 v3, v2, v34
	v_exp_f32_e32 v3, v3
	s_nop 0
	v_add_f32_e32 v3, 1.0, v3
	v_rcp_f32_e32 v3, v3
	s_nop 0
	v_mul_f32_e32 v3, v3, v34
	ds_write_b32 v1, v3 offset:4096
	v_mul_f32_e32 v3, v2, v35
	v_exp_f32_e32 v3, v3
	s_nop 0
	v_add_f32_e32 v3, 1.0, v3
	v_rcp_f32_e32 v3, v3
	s_nop 0
	v_mul_f32_e32 v3, v3, v35
	ds_write_b32 v1, v3 offset:6144
	v_mul_f32_e32 v3, v2, v36
	v_exp_f32_e32 v3, v3
	s_nop 0
	v_add_f32_e32 v3, 1.0, v3
	v_rcp_f32_e32 v3, v3
	s_nop 0
	v_mul_f32_e32 v3, v3, v36
	ds_write_b32 v1, v3 offset:8192
	v_mul_f32_e32 v3, v2, v37
	v_exp_f32_e32 v3, v3
	s_nop 0
	v_add_f32_e32 v3, 1.0, v3
	v_rcp_f32_e32 v3, v3
	s_nop 0
	v_mul_f32_e32 v3, v3, v37
	ds_write_b32 v1, v3 offset:10240
	v_mul_f32_e32 v3, v2, v38
	v_exp_f32_e32 v3, v3
	s_nop 0
	v_add_f32_e32 v3, 1.0, v3
	v_rcp_f32_e32 v3, v3
	s_nop 0
	v_mul_f32_e32 v3, v3, v38
	ds_write_b32 v1, v3 offset:12288
	v_mul_f32_e32 v3, v2, v39
	v_exp_f32_e32 v3, v3
	s_nop 0
	v_add_f32_e32 v3, 1.0, v3
	v_rcp_f32_e32 v3, v3
	s_nop 0
	v_mul_f32_e32 v3, v3, v39
	ds_write_b32 v1, v3 offset:14336
	v_mul_f32_e32 v3, v2, v40
	v_exp_f32_e32 v3, v3
	s_nop 0
	v_add_f32_e32 v3, 1.0, v3
	v_rcp_f32_e32 v3, v3
	s_nop 0
	v_mul_f32_e32 v3, v3, v40
	ds_write_b32 v1, v3 offset:16384
	v_mul_f32_e32 v3, v2, v41
	v_exp_f32_e32 v3, v3
	s_nop 0
	v_add_f32_e32 v3, 1.0, v3
	v_rcp_f32_e32 v3, v3
	s_nop 0
	v_mul_f32_e32 v3, v3, v41
	ds_write_b32 v1, v3 offset:18432
	v_mul_f32_e32 v3, v2, v42
	v_exp_f32_e32 v3, v3
	s_nop 0
	v_add_f32_e32 v3, 1.0, v3
	v_rcp_f32_e32 v3, v3
	s_nop 0
	v_mul_f32_e32 v3, v3, v42
	ds_write_b32 v1, v3 offset:20480
	v_mul_f32_e32 v3, v2, v43
	v_exp_f32_e32 v3, v3
	s_nop 0
	v_add_f32_e32 v3, 1.0, v3
	v_rcp_f32_e32 v3, v3
	s_nop 0
	v_mul_f32_e32 v3, v3, v43
	ds_write_b32 v1, v3 offset:22528
	v_mul_f32_e32 v3, v2, v44
	v_exp_f32_e32 v3, v3
	s_nop 0
	v_add_f32_e32 v3, 1.0, v3
	v_rcp_f32_e32 v3, v3
	s_nop 0
	v_mul_f32_e32 v3, v3, v44
	ds_write_b32 v1, v3 offset:24576
	v_mul_f32_e32 v3, v2, v45
	v_exp_f32_e32 v3, v3
	s_nop 0
	v_add_f32_e32 v3, 1.0, v3
	v_rcp_f32_e32 v3, v3
	s_nop 0
	v_mul_f32_e32 v3, v3, v45
	ds_write_b32 v1, v3 offset:26624
	v_mul_f32_e32 v3, v2, v46
	v_exp_f32_e32 v3, v3
	s_nop 0
	v_add_f32_e32 v3, 1.0, v3
	v_rcp_f32_e32 v3, v3
	s_nop 0
	v_mul_f32_e32 v3, v3, v46
	ds_write_b32 v1, v3 offset:28672
	v_mul_f32_e32 v3, v2, v47
	v_exp_f32_e32 v3, v3
	s_nop 0
	v_add_f32_e32 v3, 1.0, v3
	v_rcp_f32_e32 v3, v3
	s_nop 0
	v_mul_f32_e32 v3, v3, v47
	ds_write_b32 v1, v3 offset:30720
	v_mul_f32_e32 v3, v2, v48
	v_exp_f32_e32 v3, v3
	s_nop 0
	v_add_f32_e32 v3, 1.0, v3
	v_rcp_f32_e32 v3, v3
	s_nop 0
	v_mul_f32_e32 v3, v3, v48
	ds_write_b32 v1, v3 offset:32768
	v_mul_f32_e32 v3, v2, v49
	v_exp_f32_e32 v3, v3
	s_nop 0
	v_add_f32_e32 v3, 1.0, v3
	v_rcp_f32_e32 v3, v3
	s_nop 0
	v_mul_f32_e32 v3, v3, v49
	ds_write_b32 v1, v3 offset:34816
	v_mul_f32_e32 v3, v2, v50
	v_exp_f32_e32 v3, v3
	s_nop 0
	v_add_f32_e32 v3, 1.0, v3
	v_rcp_f32_e32 v3, v3
	s_nop 0
	v_mul_f32_e32 v3, v3, v50
	ds_write_b32 v1, v3 offset:36864
	v_mul_f32_e32 v3, v2, v51
	v_exp_f32_e32 v3, v3
	s_nop 0
	v_add_f32_e32 v3, 1.0, v3
	v_rcp_f32_e32 v3, v3
	s_nop 0
	v_mul_f32_e32 v3, v3, v51
	ds_write_b32 v1, v3 offset:38912
	s_waitcnt lgkmcnt(0)
	s_barrier
	s_lshr_b32 s8, s96, 7
	s_and_b32 s9, s96, 127
	s_mul_i32 s9, s9, 96
	v_and_b32_e32 v1, 63, v154
	v_cmp_lt_u32_e32 vcc, 23, v1
	s_nop 1
	v_cndmask_b32_e64 v2, 0, 1, vcc
	v_mul_u32_u24_e32 v3, 24, v2
	v_sub_u32_e32 v3, v1, v3
	v_lshrrev_b32_e32 v4, 6, v154
	v_lshl_add_u32 v10, v4, 8, v2
	v_lshlrev_b32_e32 v10, 2, v10
	v_mul_u32_u24_e32 v11, 0xc000, v2
	v_lshl_add_u32 v11, v3, 4, v11
	v_readfirstlane_b32 s12, v4
	s_lshl_b32 s12, s12, 8
	s_lshl_b32 s13, s8, 11
	s_add_u32 s12, s12, s13
	s_mul_hi_u32 s14, s12, 0xc000
	s_mul_i32 s12, s12, 0xc000
	s_lshl_b32 s13, s9, 2
	s_add_u32 s12, s12, s13
	s_addc_u32 s14, s14, 0
	s_add_u32 s10, s0, s12
	s_addc_u32 s11, s1, s14
	v_mov_b32_e32 v12, 0
	v_mov_b32_e32 v13, 0
	v_mov_b32_e32 v14, 0
	v_mov_b32_e32 v15, 0
	v_mov_b32_e32 v16, 0
	v_mov_b32_e32 v17, 0
	v_mov_b32_e32 v18, 0
	v_mov_b32_e32 v19, 0
	v_mov_b32_e32 v20, 0
	v_mov_b32_e32 v21, 0
	v_mov_b32_e32 v22, 0
	v_mov_b32_e32 v23, 0
	v_mov_b32_e32 v24, 0
	v_mov_b32_e32 v25, 0
	v_mov_b32_e32 v26, 0
	v_mov_b32_e32 v27, 0
	v_mov_b32_e32 v28, 0
	v_mov_b32_e32 v29, 0
	v_mov_b32_e32 v30, 0
	v_mov_b32_e32 v31, 0
	s_mov_b64 s[20:21], exec
	s_mov_b32 exec_lo, -1
	s_mov_b32 exec_hi, 0xffff
	global_load_dwordx4 v[32:35], v11, s[10:11]
	s_add_u32 s10, s10, 0x18000
	s_addc_u32 s11, s11, 0
	global_load_dwordx4 v[36:39], v11, s[10:11]
	s_add_u32 s10, s10, 0x18000
	s_addc_u32 s11, s11, 0
	global_load_dwordx4 v[40:43], v11, s[10:11]
	s_add_u32 s10, s10, 0x18000
	s_addc_u32 s11, s11, 0
	global_load_dwordx4 v[44:47], v11, s[10:11]
	s_add_u32 s10, s10, 0x18000
	s_addc_u32 s11, s11, 0
	global_load_dwordx4 v[48:51], v11, s[10:11]
	s_add_u32 s10, s10, 0x18000
	s_addc_u32 s11, s11, 0
	global_load_dwordx4 v[52:55], v11, s[10:11]
	s_add_u32 s10, s10, 0x18000
	s_addc_u32 s11, s11, 0
	global_load_dwordx4 v[56:59], v11, s[10:11]
	s_add_u32 s10, s10, 0x18000
	s_addc_u32 s11, s11, 0
	global_load_dwordx4 v[60:63], v11, s[10:11]
	s_add_u32 s10, s10, 0x18000
	s_addc_u32 s11, s11, 0
	global_load_dwordx4 v[64:67], v11, s[10:11]
	s_add_u32 s10, s10, 0x18000
	s_addc_u32 s11, s11, 0
	global_load_dwordx4 v[68:71], v11, s[10:11]
	s_add_u32 s10, s10, 0x18000
	s_addc_u32 s11, s11, 0
	global_load_dwordx4 v[72:75], v11, s[10:11]
	s_add_u32 s10, s10, 0x18000
	s_addc_u32 s11, s11, 0
	global_load_dwordx4 v[76:79], v11, s[10:11]
	s_add_u32 s10, s10, 0x18000
	s_addc_u32 s11, s11, 0
	global_load_dwordx4 v[80:83], v11, s[10:11]
	s_add_u32 s10, s10, 0x18000
	s_addc_u32 s11, s11, 0
	global_load_dwordx4 v[84:87], v11, s[10:11]
	s_add_u32 s10, s10, 0x18000
	s_addc_u32 s11, s11, 0
	global_load_dwordx4 v[88:91], v11, s[10:11]
	s_add_u32 s10, s10, 0x18000
	s_addc_u32 s11, s11, 0
	global_load_dwordx4 v[92:95], v11, s[10:11]
	s_add_u32 s10, s10, 0x18000
	s_addc_u32 s11, s11, 0
	ds_read_b32 v96, v10 offset:0
	ds_read_b32 v97, v10 offset:8192
	ds_read_b32 v98, v10 offset:16384
	ds_read_b32 v99, v10 offset:24576
	ds_read_b32 v100, v10 offset:32768
	s_waitcnt vmcnt(15) lgkmcnt(0)
	v_fmac_f32_e32 v12, v96, v32
	v_fmac_f32_e32 v13, v96, v33
	v_fmac_f32_e32 v14, v96, v34
	v_fmac_f32_e32 v15, v96, v35
	v_fmac_f32_e32 v16, v97, v32
	v_fmac_f32_e32 v17, v97, v33
	v_fmac_f32_e32 v18, v97, v34
	v_fmac_f32_e32 v19, v97, v35
	v_fmac_f32_e32 v20, v98, v32
	v_fmac_f32_e32 v21, v98, v33
	v_fmac_f32_e32 v22, v98, v34
	v_fmac_f32_e32 v23, v98, v35
	v_fmac_f32_e32 v24, v99, v32
	v_fmac_f32_e32 v25, v99, v33
	v_fmac_f32_e32 v26, v99, v34
	v_fmac_f32_e32 v27, v99, v35
	v_fmac_f32_e32 v28, v100, v32
	v_fmac_f32_e32 v29, v100, v33
	v_fmac_f32_e32 v30, v100, v34
	v_fmac_f32_e32 v31, v100, v35
	global_load_dwordx4 v[32:35], v11, s[10:11]
	s_add_u32 s10, s10, 0x18000
	s_addc_u32 s11, s11, 0
	ds_read_b32 v96, v10 offset:8
	ds_read_b32 v97, v10 offset:8200
	ds_read_b32 v98, v10 offset:16392
	ds_read_b32 v99, v10 offset:24584
	ds_read_b32 v100, v10 offset:32776
	s_waitcnt vmcnt(15) lgkmcnt(0)
	v_fmac_f32_e32 v12, v96, v36
	v_fmac_f32_e32 v13, v96, v37
	v_fmac_f32_e32 v14, v96, v38
	v_fmac_f32_e32 v15, v96, v39
	v_fmac_f32_e32 v16, v97, v36
	v_fmac_f32_e32 v17, v97, v37
	v_fmac_f32_e32 v18, v97, v38
	v_fmac_f32_e32 v19, v97, v39
	v_fmac_f32_e32 v20, v98, v36
	v_fmac_f32_e32 v21, v98, v37
	v_fmac_f32_e32 v22, v98, v38
	v_fmac_f32_e32 v23, v98, v39
	v_fmac_f32_e32 v24, v99, v36
	v_fmac_f32_e32 v25, v99, v37
	v_fmac_f32_e32 v26, v99, v38
	v_fmac_f32_e32 v27, v99, v39
	v_fmac_f32_e32 v28, v100, v36
	v_fmac_f32_e32 v29, v100, v37
	v_fmac_f32_e32 v30, v100, v38
	v_fmac_f32_e32 v31, v100, v39
	global_load_dwordx4 v[36:39], v11, s[10:11]
	s_add_u32 s10, s10, 0x18000
	s_addc_u32 s11, s11, 0
	ds_read_b32 v96, v10 offset:16
	ds_read_b32 v97, v10 offset:8208
	ds_read_b32 v98, v10 offset:16400
	ds_read_b32 v99, v10 offset:24592
	ds_read_b32 v100, v10 offset:32784
	s_waitcnt vmcnt(15) lgkmcnt(0)
	v_fmac_f32_e32 v12, v96, v40
	v_fmac_f32_e32 v13, v96, v41
	v_fmac_f32_e32 v14, v96, v42
	v_fmac_f32_e32 v15, v96, v43
	v_fmac_f32_e32 v16, v97, v40
	v_fmac_f32_e32 v17, v97, v41
	v_fmac_f32_e32 v18, v97, v42
	v_fmac_f32_e32 v19, v97, v43
	v_fmac_f32_e32 v20, v98, v40
	v_fmac_f32_e32 v21, v98, v41
	v_fmac_f32_e32 v22, v98, v42
	v_fmac_f32_e32 v23, v98, v43
	v_fmac_f32_e32 v24, v99, v40
	v_fmac_f32_e32 v25, v99, v41
	v_fmac_f32_e32 v26, v99, v42
	v_fmac_f32_e32 v27, v99, v43
	v_fmac_f32_e32 v28, v100, v40
	v_fmac_f32_e32 v29, v100, v41
	v_fmac_f32_e32 v30, v100, v42
	v_fmac_f32_e32 v31, v100, v43
	global_load_dwordx4 v[40:43], v11, s[10:11]
	s_add_u32 s10, s10, 0x18000
	s_addc_u32 s11, s11, 0
	ds_read_b32 v96, v10 offset:24
	ds_read_b32 v97, v10 offset:8216
	ds_read_b32 v98, v10 offset:16408
	ds_read_b32 v99, v10 offset:24600
	ds_read_b32 v100, v10 offset:32792
	s_waitcnt vmcnt(15) lgkmcnt(0)
	v_fmac_f32_e32 v12, v96, v44
	v_fmac_f32_e32 v13, v96, v45
	v_fmac_f32_e32 v14, v96, v46
	v_fmac_f32_e32 v15, v96, v47
	v_fmac_f32_e32 v16, v97, v44
	v_fmac_f32_e32 v17, v97, v45
	v_fmac_f32_e32 v18, v97, v46
	v_fmac_f32_e32 v19, v97, v47
	v_fmac_f32_e32 v20, v98, v44
	v_fmac_f32_e32 v21, v98, v45
	v_fmac_f32_e32 v22, v98, v46
	v_fmac_f32_e32 v23, v98, v47
	v_fmac_f32_e32 v24, v99, v44
	v_fmac_f32_e32 v25, v99, v45
	v_fmac_f32_e32 v26, v99, v46
	v_fmac_f32_e32 v27, v99, v47
	v_fmac_f32_e32 v28, v100, v44
	v_fmac_f32_e32 v29, v100, v45
	v_fmac_f32_e32 v30, v100, v46
	v_fmac_f32_e32 v31, v100, v47
	global_load_dwordx4 v[44:47], v11, s[10:11]
	s_add_u32 s10, s10, 0x18000
	s_addc_u32 s11, s11, 0
	ds_read_b32 v96, v10 offset:32
	ds_read_b32 v97, v10 offset:8224
	ds_read_b32 v98, v10 offset:16416
	ds_read_b32 v99, v10 offset:24608
	ds_read_b32 v100, v10 offset:32800
	s_waitcnt vmcnt(15) lgkmcnt(0)
	v_fmac_f32_e32 v12, v96, v48
	v_fmac_f32_e32 v13, v96, v49
	v_fmac_f32_e32 v14, v96, v50
	v_fmac_f32_e32 v15, v96, v51
	v_fmac_f32_e32 v16, v97, v48
	v_fmac_f32_e32 v17, v97, v49
	v_fmac_f32_e32 v18, v97, v50
	v_fmac_f32_e32 v19, v97, v51
	v_fmac_f32_e32 v20, v98, v48
	v_fmac_f32_e32 v21, v98, v49
	v_fmac_f32_e32 v22, v98, v50
	v_fmac_f32_e32 v23, v98, v51
	v_fmac_f32_e32 v24, v99, v48
	v_fmac_f32_e32 v25, v99, v49
	v_fmac_f32_e32 v26, v99, v50
	v_fmac_f32_e32 v27, v99, v51
	v_fmac_f32_e32 v28, v100, v48
	v_fmac_f32_e32 v29, v100, v49
	v_fmac_f32_e32 v30, v100, v50
	v_fmac_f32_e32 v31, v100, v51
	global_load_dwordx4 v[48:51], v11, s[10:11]
	s_add_u32 s10, s10, 0x18000
	s_addc_u32 s11, s11, 0
	ds_read_b32 v96, v10 offset:40
	ds_read_b32 v97, v10 offset:8232
	ds_read_b32 v98, v10 offset:16424
	ds_read_b32 v99, v10 offset:24616
	ds_read_b32 v100, v10 offset:32808
	s_waitcnt vmcnt(15) lgkmcnt(0)
	v_fmac_f32_e32 v12, v96, v52
	v_fmac_f32_e32 v13, v96, v53
	v_fmac_f32_e32 v14, v96, v54
	v_fmac_f32_e32 v15, v96, v55
	v_fmac_f32_e32 v16, v97, v52
	v_fmac_f32_e32 v17, v97, v53
	v_fmac_f32_e32 v18, v97, v54
	v_fmac_f32_e32 v19, v97, v55
	v_fmac_f32_e32 v20, v98, v52
	v_fmac_f32_e32 v21, v98, v53
	v_fmac_f32_e32 v22, v98, v54
	v_fmac_f32_e32 v23, v98, v55
	v_fmac_f32_e32 v24, v99, v52
	v_fmac_f32_e32 v25, v99, v53
	v_fmac_f32_e32 v26, v99, v54
	v_fmac_f32_e32 v27, v99, v55
	v_fmac_f32_e32 v28, v100, v52
	v_fmac_f32_e32 v29, v100, v53
	v_fmac_f32_e32 v30, v100, v54
	v_fmac_f32_e32 v31, v100, v55
	global_load_dwordx4 v[52:55], v11, s[10:11]
	s_add_u32 s10, s10, 0x18000
	s_addc_u32 s11, s11, 0
	ds_read_b32 v96, v10 offset:48
	ds_read_b32 v97, v10 offset:8240
	ds_read_b32 v98, v10 offset:16432
	ds_read_b32 v99, v10 offset:24624
	ds_read_b32 v100, v10 offset:32816
	s_waitcnt vmcnt(15) lgkmcnt(0)
	v_fmac_f32_e32 v12, v96, v56
	v_fmac_f32_e32 v13, v96, v57
	v_fmac_f32_e32 v14, v96, v58
	v_fmac_f32_e32 v15, v96, v59
	v_fmac_f32_e32 v16, v97, v56
	v_fmac_f32_e32 v17, v97, v57
	v_fmac_f32_e32 v18, v97, v58
	v_fmac_f32_e32 v19, v97, v59
	v_fmac_f32_e32 v20, v98, v56
	v_fmac_f32_e32 v21, v98, v57
	v_fmac_f32_e32 v22, v98, v58
	v_fmac_f32_e32 v23, v98, v59
	v_fmac_f32_e32 v24, v99, v56
	v_fmac_f32_e32 v25, v99, v57
	v_fmac_f32_e32 v26, v99, v58
	v_fmac_f32_e32 v27, v99, v59
	v_fmac_f32_e32 v28, v100, v56
	v_fmac_f32_e32 v29, v100, v57
	v_fmac_f32_e32 v30, v100, v58
	v_fmac_f32_e32 v31, v100, v59
	global_load_dwordx4 v[56:59], v11, s[10:11]
	s_add_u32 s10, s10, 0x18000
	s_addc_u32 s11, s11, 0
	ds_read_b32 v96, v10 offset:56
	ds_read_b32 v97, v10 offset:8248
	ds_read_b32 v98, v10 offset:16440
	ds_read_b32 v99, v10 offset:24632
	ds_read_b32 v100, v10 offset:32824
	s_waitcnt vmcnt(15) lgkmcnt(0)
	v_fmac_f32_e32 v12, v96, v60
	v_fmac_f32_e32 v13, v96, v61
	v_fmac_f32_e32 v14, v96, v62
	v_fmac_f32_e32 v15, v96, v63
	v_fmac_f32_e32 v16, v97, v60
	v_fmac_f32_e32 v17, v97, v61
	v_fmac_f32_e32 v18, v97, v62
	v_fmac_f32_e32 v19, v97, v63
	v_fmac_f32_e32 v20, v98, v60
	v_fmac_f32_e32 v21, v98, v61
	v_fmac_f32_e32 v22, v98, v62
	v_fmac_f32_e32 v23, v98, v63
	v_fmac_f32_e32 v24, v99, v60
	v_fmac_f32_e32 v25, v99, v61
	v_fmac_f32_e32 v26, v99, v62
	v_fmac_f32_e32 v27, v99, v63
	v_fmac_f32_e32 v28, v100, v60
	v_fmac_f32_e32 v29, v100, v61
	v_fmac_f32_e32 v30, v100, v62
	v_fmac_f32_e32 v31, v100, v63
	global_load_dwordx4 v[60:63], v11, s[10:11]
	s_add_u32 s10, s10, 0x18000
	s_addc_u32 s11, s11, 0
	ds_read_b32 v96, v10 offset:64
	ds_read_b32 v97, v10 offset:8256
	ds_read_b32 v98, v10 offset:16448
	ds_read_b32 v99, v10 offset:24640
	ds_read_b32 v100, v10 offset:32832
	s_waitcnt vmcnt(15) lgkmcnt(0)
	v_fmac_f32_e32 v12, v96, v64
	v_fmac_f32_e32 v13, v96, v65
	v_fmac_f32_e32 v14, v96, v66
	v_fmac_f32_e32 v15, v96, v67
	v_fmac_f32_e32 v16, v97, v64
	v_fmac_f32_e32 v17, v97, v65
	v_fmac_f32_e32 v18, v97, v66
	v_fmac_f32_e32 v19, v97, v67
	v_fmac_f32_e32 v20, v98, v64
	v_fmac_f32_e32 v21, v98, v65
	v_fmac_f32_e32 v22, v98, v66
	v_fmac_f32_e32 v23, v98, v67
	v_fmac_f32_e32 v24, v99, v64
	v_fmac_f32_e32 v25, v99, v65
	v_fmac_f32_e32 v26, v99, v66
	v_fmac_f32_e32 v27, v99, v67
	v_fmac_f32_e32 v28, v100, v64
	v_fmac_f32_e32 v29, v100, v65
	v_fmac_f32_e32 v30, v100, v66
	v_fmac_f32_e32 v31, v100, v67
	global_load_dwordx4 v[64:67], v11, s[10:11]
	s_add_u32 s10, s10, 0x18000
	s_addc_u32 s11, s11, 0
	ds_read_b32 v96, v10 offset:72
	ds_read_b32 v97, v10 offset:8264
	ds_read_b32 v98, v10 offset:16456
	ds_read_b32 v99, v10 offset:24648
	ds_read_b32 v100, v10 offset:32840
	s_waitcnt vmcnt(15) lgkmcnt(0)
	v_fmac_f32_e32 v12, v96, v68
	v_fmac_f32_e32 v13, v96, v69
	v_fmac_f32_e32 v14, v96, v70
	v_fmac_f32_e32 v15, v96, v71
	v_fmac_f32_e32 v16, v97, v68
	v_fmac_f32_e32 v17, v97, v69
	v_fmac_f32_e32 v18, v97, v70
	v_fmac_f32_e32 v19, v97, v71
	v_fmac_f32_e32 v20, v98, v68
	v_fmac_f32_e32 v21, v98, v69
	v_fmac_f32_e32 v22, v98, v70
	v_fmac_f32_e32 v23, v98, v71
	v_fmac_f32_e32 v24, v99, v68
	v_fmac_f32_e32 v25, v99, v69
	v_fmac_f32_e32 v26, v99, v70
	v_fmac_f32_e32 v27, v99, v71
	v_fmac_f32_e32 v28, v100, v68
	v_fmac_f32_e32 v29, v100, v69
	v_fmac_f32_e32 v30, v100, v70
	v_fmac_f32_e32 v31, v100, v71
	global_load_dwordx4 v[68:71], v11, s[10:11]
	s_add_u32 s10, s10, 0x18000
	s_addc_u32 s11, s11, 0
	ds_read_b32 v96, v10 offset:80
	ds_read_b32 v97, v10 offset:8272
	ds_read_b32 v98, v10 offset:16464
	ds_read_b32 v99, v10 offset:24656
	ds_read_b32 v100, v10 offset:32848
	s_waitcnt vmcnt(15) lgkmcnt(0)
	v_fmac_f32_e32 v12, v96, v72
	v_fmac_f32_e32 v13, v96, v73
	v_fmac_f32_e32 v14, v96, v74
	v_fmac_f32_e32 v15, v96, v75
	v_fmac_f32_e32 v16, v97, v72
	v_fmac_f32_e32 v17, v97, v73
	v_fmac_f32_e32 v18, v97, v74
	v_fmac_f32_e32 v19, v97, v75
	v_fmac_f32_e32 v20, v98, v72
	v_fmac_f32_e32 v21, v98, v73
	v_fmac_f32_e32 v22, v98, v74
	v_fmac_f32_e32 v23, v98, v75
	v_fmac_f32_e32 v24, v99, v72
	v_fmac_f32_e32 v25, v99, v73
	v_fmac_f32_e32 v26, v99, v74
	v_fmac_f32_e32 v27, v99, v75
	v_fmac_f32_e32 v28, v100, v72
	v_fmac_f32_e32 v29, v100, v73
	v_fmac_f32_e32 v30, v100, v74
	v_fmac_f32_e32 v31, v100, v75
	global_load_dwordx4 v[72:75], v11, s[10:11]
	s_add_u32 s10, s10, 0x18000
	s_addc_u32 s11, s11, 0
	ds_read_b32 v96, v10 offset:88
	ds_read_b32 v97, v10 offset:8280
	ds_read_b32 v98, v10 offset:16472
	ds_read_b32 v99, v10 offset:24664
	ds_read_b32 v100, v10 offset:32856
	s_waitcnt vmcnt(15) lgkmcnt(0)
	v_fmac_f32_e32 v12, v96, v76
	v_fmac_f32_e32 v13, v96, v77
	v_fmac_f32_e32 v14, v96, v78
	v_fmac_f32_e32 v15, v96, v79
	v_fmac_f32_e32 v16, v97, v76
	v_fmac_f32_e32 v17, v97, v77
	v_fmac_f32_e32 v18, v97, v78
	v_fmac_f32_e32 v19, v97, v79
	v_fmac_f32_e32 v20, v98, v76
	v_fmac_f32_e32 v21, v98, v77
	v_fmac_f32_e32 v22, v98, v78
	v_fmac_f32_e32 v23, v98, v79
	v_fmac_f32_e32 v24, v99, v76
	v_fmac_f32_e32 v25, v99, v77
	v_fmac_f32_e32 v26, v99, v78
	v_fmac_f32_e32 v27, v99, v79
	v_fmac_f32_e32 v28, v100, v76
	v_fmac_f32_e32 v29, v100, v77
	v_fmac_f32_e32 v30, v100, v78
	v_fmac_f32_e32 v31, v100, v79
	global_load_dwordx4 v[76:79], v11, s[10:11]
	s_add_u32 s10, s10, 0x18000
	s_addc_u32 s11, s11, 0
	ds_read_b32 v96, v10 offset:96
	ds_read_b32 v97, v10 offset:8288
	ds_read_b32 v98, v10 offset:16480
	ds_read_b32 v99, v10 offset:24672
	ds_read_b32 v100, v10 offset:32864
	s_waitcnt vmcnt(15) lgkmcnt(0)
	v_fmac_f32_e32 v12, v96, v80
	v_fmac_f32_e32 v13, v96, v81
	v_fmac_f32_e32 v14, v96, v82
	v_fmac_f32_e32 v15, v96, v83
	v_fmac_f32_e32 v16, v97, v80
	v_fmac_f32_e32 v17, v97, v81
	v_fmac_f32_e32 v18, v97, v82
	v_fmac_f32_e32 v19, v97, v83
	v_fmac_f32_e32 v20, v98, v80
	v_fmac_f32_e32 v21, v98, v81
	v_fmac_f32_e32 v22, v98, v82
	v_fmac_f32_e32 v23, v98, v83
	v_fmac_f32_e32 v24, v99, v80
	v_fmac_f32_e32 v25, v99, v81
	v_fmac_f32_e32 v26, v99, v82
	v_fmac_f32_e32 v27, v99, v83
	v_fmac_f32_e32 v28, v100, v80
	v_fmac_f32_e32 v29, v100, v81
	v_fmac_f32_e32 v30, v100, v82
	v_fmac_f32_e32 v31, v100, v83
	global_load_dwordx4 v[80:83], v11, s[10:11]
	s_add_u32 s10, s10, 0x18000
	s_addc_u32 s11, s11, 0
	ds_read_b32 v96, v10 offset:104
	ds_read_b32 v97, v10 offset:8296
	ds_read_b32 v98, v10 offset:16488
	ds_read_b32 v99, v10 offset:24680
	ds_read_b32 v100, v10 offset:32872
	s_waitcnt vmcnt(15) lgkmcnt(0)
	v_fmac_f32_e32 v12, v96, v84
	v_fmac_f32_e32 v13, v96, v85
	v_fmac_f32_e32 v14, v96, v86
	v_fmac_f32_e32 v15, v96, v87
	v_fmac_f32_e32 v16, v97, v84
	v_fmac_f32_e32 v17, v97, v85
	v_fmac_f32_e32 v18, v97, v86
	v_fmac_f32_e32 v19, v97, v87
	v_fmac_f32_e32 v20, v98, v84
	v_fmac_f32_e32 v21, v98, v85
	v_fmac_f32_e32 v22, v98, v86
	v_fmac_f32_e32 v23, v98, v87
	v_fmac_f32_e32 v24, v99, v84
	v_fmac_f32_e32 v25, v99, v85
	v_fmac_f32_e32 v26, v99, v86
	v_fmac_f32_e32 v27, v99, v87
	v_fmac_f32_e32 v28, v100, v84
	v_fmac_f32_e32 v29, v100, v85
	v_fmac_f32_e32 v30, v100, v86
	v_fmac_f32_e32 v31, v100, v87
	global_load_dwordx4 v[84:87], v11, s[10:11]
	s_add_u32 s10, s10, 0x18000
	s_addc_u32 s11, s11, 0
	ds_read_b32 v96, v10 offset:112
	ds_read_b32 v97, v10 offset:8304
	ds_read_b32 v98, v10 offset:16496
	ds_read_b32 v99, v10 offset:24688
	ds_read_b32 v100, v10 offset:32880
	s_waitcnt vmcnt(15) lgkmcnt(0)
	v_fmac_f32_e32 v12, v96, v88
	v_fmac_f32_e32 v13, v96, v89
	v_fmac_f32_e32 v14, v96, v90
	v_fmac_f32_e32 v15, v96, v91
	v_fmac_f32_e32 v16, v97, v88
	v_fmac_f32_e32 v17, v97, v89
	v_fmac_f32_e32 v18, v97, v90
	v_fmac_f32_e32 v19, v97, v91
	v_fmac_f32_e32 v20, v98, v88
	v_fmac_f32_e32 v21, v98, v89
	v_fmac_f32_e32 v22, v98, v90
	v_fmac_f32_e32 v23, v98, v91
	v_fmac_f32_e32 v24, v99, v88
	v_fmac_f32_e32 v25, v99, v89
	v_fmac_f32_e32 v26, v99, v90
	v_fmac_f32_e32 v27, v99, v91
	v_fmac_f32_e32 v28, v100, v88
	v_fmac_f32_e32 v29, v100, v89
	v_fmac_f32_e32 v30, v100, v90
	v_fmac_f32_e32 v31, v100, v91
	global_load_dwordx4 v[88:91], v11, s[10:11]
	s_add_u32 s10, s10, 0x18000
	s_addc_u32 s11, s11, 0
	ds_read_b32 v96, v10 offset:120
	ds_read_b32 v97, v10 offset:8312
	ds_read_b32 v98, v10 offset:16504
	ds_read_b32 v99, v10 offset:24696
	ds_read_b32 v100, v10 offset:32888
	s_waitcnt vmcnt(15) lgkmcnt(0)
	v_fmac_f32_e32 v12, v96, v92
	v_fmac_f32_e32 v13, v96, v93
	v_fmac_f32_e32 v14, v96, v94
	v_fmac_f32_e32 v15, v96, v95
	v_fmac_f32_e32 v16, v97, v92
	v_fmac_f32_e32 v17, v97, v93
	v_fmac_f32_e32 v18, v97, v94
	v_fmac_f32_e32 v19, v97, v95
	v_fmac_f32_e32 v20, v98, v92
	v_fmac_f32_e32 v21, v98, v93
	v_fmac_f32_e32 v22, v98, v94
	v_fmac_f32_e32 v23, v98, v95
	v_fmac_f32_e32 v24, v99, v92
	v_fmac_f32_e32 v25, v99, v93
	v_fmac_f32_e32 v26, v99, v94
	v_fmac_f32_e32 v27, v99, v95
	v_fmac_f32_e32 v28, v100, v92
	v_fmac_f32_e32 v29, v100, v93
	v_fmac_f32_e32 v30, v100, v94
	v_fmac_f32_e32 v31, v100, v95
	global_load_dwordx4 v[92:95], v11, s[10:11]
	s_add_u32 s10, s10, 0x18000
	s_addc_u32 s11, s11, 0
	ds_read_b32 v96, v10 offset:128
	ds_read_b32 v97, v10 offset:8320
	ds_read_b32 v98, v10 offset:16512
	ds_read_b32 v99, v10 offset:24704
	ds_read_b32 v100, v10 offset:32896
	s_waitcnt vmcnt(15) lgkmcnt(0)
	v_fmac_f32_e32 v12, v96, v32
	v_fmac_f32_e32 v13, v96, v33
	v_fmac_f32_e32 v14, v96, v34
	v_fmac_f32_e32 v15, v96, v35
	v_fmac_f32_e32 v16, v97, v32
	v_fmac_f32_e32 v17, v97, v33
	v_fmac_f32_e32 v18, v97, v34
	v_fmac_f32_e32 v19, v97, v35
	v_fmac_f32_e32 v20, v98, v32
	v_fmac_f32_e32 v21, v98, v33
	v_fmac_f32_e32 v22, v98, v34
	v_fmac_f32_e32 v23, v98, v35
	v_fmac_f32_e32 v24, v99, v32
	v_fmac_f32_e32 v25, v99, v33
	v_fmac_f32_e32 v26, v99, v34
	v_fmac_f32_e32 v27, v99, v35
	v_fmac_f32_e32 v28, v100, v32
	v_fmac_f32_e32 v29, v100, v33
	v_fmac_f32_e32 v30, v100, v34
	v_fmac_f32_e32 v31, v100, v35
	global_load_dwordx4 v[32:35], v11, s[10:11]
	s_add_u32 s10, s10, 0x18000
	s_addc_u32 s11, s11, 0
	ds_read_b32 v96, v10 offset:136
	ds_read_b32 v97, v10 offset:8328
	ds_read_b32 v98, v10 offset:16520
	ds_read_b32 v99, v10 offset:24712
	ds_read_b32 v100, v10 offset:32904
	s_waitcnt vmcnt(15) lgkmcnt(0)
	v_fmac_f32_e32 v12, v96, v36
	v_fmac_f32_e32 v13, v96, v37
	v_fmac_f32_e32 v14, v96, v38
	v_fmac_f32_e32 v15, v96, v39
	v_fmac_f32_e32 v16, v97, v36
	v_fmac_f32_e32 v17, v97, v37
	v_fmac_f32_e32 v18, v97, v38
	v_fmac_f32_e32 v19, v97, v39
	v_fmac_f32_e32 v20, v98, v36
	v_fmac_f32_e32 v21, v98, v37
	v_fmac_f32_e32 v22, v98, v38
	v_fmac_f32_e32 v23, v98, v39
	v_fmac_f32_e32 v24, v99, v36
	v_fmac_f32_e32 v25, v99, v37
	v_fmac_f32_e32 v26, v99, v38
	v_fmac_f32_e32 v27, v99, v39
	v_fmac_f32_e32 v28, v100, v36
	v_fmac_f32_e32 v29, v100, v37
	v_fmac_f32_e32 v30, v100, v38
	v_fmac_f32_e32 v31, v100, v39
	global_load_dwordx4 v[36:39], v11, s[10:11]
	s_add_u32 s10, s10, 0x18000
	s_addc_u32 s11, s11, 0
	ds_read_b32 v96, v10 offset:144
	ds_read_b32 v97, v10 offset:8336
	ds_read_b32 v98, v10 offset:16528
	ds_read_b32 v99, v10 offset:24720
	ds_read_b32 v100, v10 offset:32912
	s_waitcnt vmcnt(15) lgkmcnt(0)
	v_fmac_f32_e32 v12, v96, v40
	v_fmac_f32_e32 v13, v96, v41
	v_fmac_f32_e32 v14, v96, v42
	v_fmac_f32_e32 v15, v96, v43
	v_fmac_f32_e32 v16, v97, v40
	v_fmac_f32_e32 v17, v97, v41
	v_fmac_f32_e32 v18, v97, v42
	v_fmac_f32_e32 v19, v97, v43
	v_fmac_f32_e32 v20, v98, v40
	v_fmac_f32_e32 v21, v98, v41
	v_fmac_f32_e32 v22, v98, v42
	v_fmac_f32_e32 v23, v98, v43
	v_fmac_f32_e32 v24, v99, v40
	v_fmac_f32_e32 v25, v99, v41
	v_fmac_f32_e32 v26, v99, v42
	v_fmac_f32_e32 v27, v99, v43
	v_fmac_f32_e32 v28, v100, v40
	v_fmac_f32_e32 v29, v100, v41
	v_fmac_f32_e32 v30, v100, v42
	v_fmac_f32_e32 v31, v100, v43
	global_load_dwordx4 v[40:43], v11, s[10:11]
	s_add_u32 s10, s10, 0x18000
	s_addc_u32 s11, s11, 0
	ds_read_b32 v96, v10 offset:152
	ds_read_b32 v97, v10 offset:8344
	ds_read_b32 v98, v10 offset:16536
	ds_read_b32 v99, v10 offset:24728
	ds_read_b32 v100, v10 offset:32920
	s_waitcnt vmcnt(15) lgkmcnt(0)
	v_fmac_f32_e32 v12, v96, v44
	v_fmac_f32_e32 v13, v96, v45
	v_fmac_f32_e32 v14, v96, v46
	v_fmac_f32_e32 v15, v96, v47
	v_fmac_f32_e32 v16, v97, v44
	v_fmac_f32_e32 v17, v97, v45
	v_fmac_f32_e32 v18, v97, v46
	v_fmac_f32_e32 v19, v97, v47
	v_fmac_f32_e32 v20, v98, v44
	v_fmac_f32_e32 v21, v98, v45
	v_fmac_f32_e32 v22, v98, v46
	v_fmac_f32_e32 v23, v98, v47
	v_fmac_f32_e32 v24, v99, v44
	v_fmac_f32_e32 v25, v99, v45
	v_fmac_f32_e32 v26, v99, v46
	v_fmac_f32_e32 v27, v99, v47
	v_fmac_f32_e32 v28, v100, v44
	v_fmac_f32_e32 v29, v100, v45
	v_fmac_f32_e32 v30, v100, v46
	v_fmac_f32_e32 v31, v100, v47
	global_load_dwordx4 v[44:47], v11, s[10:11]
	s_add_u32 s10, s10, 0x18000
	s_addc_u32 s11, s11, 0
	ds_read_b32 v96, v10 offset:160
	ds_read_b32 v97, v10 offset:8352
	ds_read_b32 v98, v10 offset:16544
	ds_read_b32 v99, v10 offset:24736
	ds_read_b32 v100, v10 offset:32928
	s_waitcnt vmcnt(15) lgkmcnt(0)
	v_fmac_f32_e32 v12, v96, v48
	v_fmac_f32_e32 v13, v96, v49
	v_fmac_f32_e32 v14, v96, v50
	v_fmac_f32_e32 v15, v96, v51
	v_fmac_f32_e32 v16, v97, v48
	v_fmac_f32_e32 v17, v97, v49
	v_fmac_f32_e32 v18, v97, v50
	v_fmac_f32_e32 v19, v97, v51
	v_fmac_f32_e32 v20, v98, v48
	v_fmac_f32_e32 v21, v98, v49
	v_fmac_f32_e32 v22, v98, v50
	v_fmac_f32_e32 v23, v98, v51
	v_fmac_f32_e32 v24, v99, v48
	v_fmac_f32_e32 v25, v99, v49
	v_fmac_f32_e32 v26, v99, v50
	v_fmac_f32_e32 v27, v99, v51
	v_fmac_f32_e32 v28, v100, v48
	v_fmac_f32_e32 v29, v100, v49
	v_fmac_f32_e32 v30, v100, v50
	v_fmac_f32_e32 v31, v100, v51
	global_load_dwordx4 v[48:51], v11, s[10:11]
	s_add_u32 s10, s10, 0x18000
	s_addc_u32 s11, s11, 0
	ds_read_b32 v96, v10 offset:168
	ds_read_b32 v97, v10 offset:8360
	ds_read_b32 v98, v10 offset:16552
	ds_read_b32 v99, v10 offset:24744
	ds_read_b32 v100, v10 offset:32936
	s_waitcnt vmcnt(15) lgkmcnt(0)
	v_fmac_f32_e32 v12, v96, v52
	v_fmac_f32_e32 v13, v96, v53
	v_fmac_f32_e32 v14, v96, v54
	v_fmac_f32_e32 v15, v96, v55
	v_fmac_f32_e32 v16, v97, v52
	v_fmac_f32_e32 v17, v97, v53
	v_fmac_f32_e32 v18, v97, v54
	v_fmac_f32_e32 v19, v97, v55
	v_fmac_f32_e32 v20, v98, v52
	v_fmac_f32_e32 v21, v98, v53
	v_fmac_f32_e32 v22, v98, v54
	v_fmac_f32_e32 v23, v98, v55
	v_fmac_f32_e32 v24, v99, v52
	v_fmac_f32_e32 v25, v99, v53
	v_fmac_f32_e32 v26, v99, v54
	v_fmac_f32_e32 v27, v99, v55
	v_fmac_f32_e32 v28, v100, v52
	v_fmac_f32_e32 v29, v100, v53
	v_fmac_f32_e32 v30, v100, v54
	v_fmac_f32_e32 v31, v100, v55
	global_load_dwordx4 v[52:55], v11, s[10:11]
	s_add_u32 s10, s10, 0x18000
	s_addc_u32 s11, s11, 0
	ds_read_b32 v96, v10 offset:176
	ds_read_b32 v97, v10 offset:8368
	ds_read_b32 v98, v10 offset:16560
	ds_read_b32 v99, v10 offset:24752
	ds_read_b32 v100, v10 offset:32944
	s_waitcnt vmcnt(15) lgkmcnt(0)
	v_fmac_f32_e32 v12, v96, v56
	v_fmac_f32_e32 v13, v96, v57
	v_fmac_f32_e32 v14, v96, v58
	v_fmac_f32_e32 v15, v96, v59
	v_fmac_f32_e32 v16, v97, v56
	v_fmac_f32_e32 v17, v97, v57
	v_fmac_f32_e32 v18, v97, v58
	v_fmac_f32_e32 v19, v97, v59
	v_fmac_f32_e32 v20, v98, v56
	v_fmac_f32_e32 v21, v98, v57
	v_fmac_f32_e32 v22, v98, v58
	v_fmac_f32_e32 v23, v98, v59
	v_fmac_f32_e32 v24, v99, v56
	v_fmac_f32_e32 v25, v99, v57
	v_fmac_f32_e32 v26, v99, v58
	v_fmac_f32_e32 v27, v99, v59
	v_fmac_f32_e32 v28, v100, v56
	v_fmac_f32_e32 v29, v100, v57
	v_fmac_f32_e32 v30, v100, v58
	v_fmac_f32_e32 v31, v100, v59
	global_load_dwordx4 v[56:59], v11, s[10:11]
	s_add_u32 s10, s10, 0x18000
	s_addc_u32 s11, s11, 0
	ds_read_b32 v96, v10 offset:184
	ds_read_b32 v97, v10 offset:8376
	ds_read_b32 v98, v10 offset:16568
	ds_read_b32 v99, v10 offset:24760
	ds_read_b32 v100, v10 offset:32952
	s_waitcnt vmcnt(15) lgkmcnt(0)
	v_fmac_f32_e32 v12, v96, v60
	v_fmac_f32_e32 v13, v96, v61
	v_fmac_f32_e32 v14, v96, v62
	v_fmac_f32_e32 v15, v96, v63
	v_fmac_f32_e32 v16, v97, v60
	v_fmac_f32_e32 v17, v97, v61
	v_fmac_f32_e32 v18, v97, v62
	v_fmac_f32_e32 v19, v97, v63
	v_fmac_f32_e32 v20, v98, v60
	v_fmac_f32_e32 v21, v98, v61
	v_fmac_f32_e32 v22, v98, v62
	v_fmac_f32_e32 v23, v98, v63
	v_fmac_f32_e32 v24, v99, v60
	v_fmac_f32_e32 v25, v99, v61
	v_fmac_f32_e32 v26, v99, v62
	v_fmac_f32_e32 v27, v99, v63
	v_fmac_f32_e32 v28, v100, v60
	v_fmac_f32_e32 v29, v100, v61
	v_fmac_f32_e32 v30, v100, v62
	v_fmac_f32_e32 v31, v100, v63
	global_load_dwordx4 v[60:63], v11, s[10:11]
	s_add_u32 s10, s10, 0x18000
	s_addc_u32 s11, s11, 0
	ds_read_b32 v96, v10 offset:192
	ds_read_b32 v97, v10 offset:8384
	ds_read_b32 v98, v10 offset:16576
	ds_read_b32 v99, v10 offset:24768
	ds_read_b32 v100, v10 offset:32960
	s_waitcnt vmcnt(15) lgkmcnt(0)
	v_fmac_f32_e32 v12, v96, v64
	v_fmac_f32_e32 v13, v96, v65
	v_fmac_f32_e32 v14, v96, v66
	v_fmac_f32_e32 v15, v96, v67
	v_fmac_f32_e32 v16, v97, v64
	v_fmac_f32_e32 v17, v97, v65
	v_fmac_f32_e32 v18, v97, v66
	v_fmac_f32_e32 v19, v97, v67
	v_fmac_f32_e32 v20, v98, v64
	v_fmac_f32_e32 v21, v98, v65
	v_fmac_f32_e32 v22, v98, v66
	v_fmac_f32_e32 v23, v98, v67
	v_fmac_f32_e32 v24, v99, v64
	v_fmac_f32_e32 v25, v99, v65
	v_fmac_f32_e32 v26, v99, v66
	v_fmac_f32_e32 v27, v99, v67
	v_fmac_f32_e32 v28, v100, v64
	v_fmac_f32_e32 v29, v100, v65
	v_fmac_f32_e32 v30, v100, v66
	v_fmac_f32_e32 v31, v100, v67
	global_load_dwordx4 v[64:67], v11, s[10:11]
	s_add_u32 s10, s10, 0x18000
	s_addc_u32 s11, s11, 0
	ds_read_b32 v96, v10 offset:200
	ds_read_b32 v97, v10 offset:8392
	ds_read_b32 v98, v10 offset:16584
	ds_read_b32 v99, v10 offset:24776
	ds_read_b32 v100, v10 offset:32968
	s_waitcnt vmcnt(15) lgkmcnt(0)
	v_fmac_f32_e32 v12, v96, v68
	v_fmac_f32_e32 v13, v96, v69
	v_fmac_f32_e32 v14, v96, v70
	v_fmac_f32_e32 v15, v96, v71
	v_fmac_f32_e32 v16, v97, v68
	v_fmac_f32_e32 v17, v97, v69
	v_fmac_f32_e32 v18, v97, v70
	v_fmac_f32_e32 v19, v97, v71
	v_fmac_f32_e32 v20, v98, v68
	v_fmac_f32_e32 v21, v98, v69
	v_fmac_f32_e32 v22, v98, v70
	v_fmac_f32_e32 v23, v98, v71
	v_fmac_f32_e32 v24, v99, v68
	v_fmac_f32_e32 v25, v99, v69
	v_fmac_f32_e32 v26, v99, v70
	v_fmac_f32_e32 v27, v99, v71
	v_fmac_f32_e32 v28, v100, v68
	v_fmac_f32_e32 v29, v100, v69
	v_fmac_f32_e32 v30, v100, v70
	v_fmac_f32_e32 v31, v100, v71
	global_load_dwordx4 v[68:71], v11, s[10:11]
	s_add_u32 s10, s10, 0x18000
	s_addc_u32 s11, s11, 0
	ds_read_b32 v96, v10 offset:208
	ds_read_b32 v97, v10 offset:8400
	ds_read_b32 v98, v10 offset:16592
	ds_read_b32 v99, v10 offset:24784
	ds_read_b32 v100, v10 offset:32976
	s_waitcnt vmcnt(15) lgkmcnt(0)
	v_fmac_f32_e32 v12, v96, v72
	v_fmac_f32_e32 v13, v96, v73
	v_fmac_f32_e32 v14, v96, v74
	v_fmac_f32_e32 v15, v96, v75
	v_fmac_f32_e32 v16, v97, v72
	v_fmac_f32_e32 v17, v97, v73
	v_fmac_f32_e32 v18, v97, v74
	v_fmac_f32_e32 v19, v97, v75
	v_fmac_f32_e32 v20, v98, v72
	v_fmac_f32_e32 v21, v98, v73
	v_fmac_f32_e32 v22, v98, v74
	v_fmac_f32_e32 v23, v98, v75
	v_fmac_f32_e32 v24, v99, v72
	v_fmac_f32_e32 v25, v99, v73
	v_fmac_f32_e32 v26, v99, v74
	v_fmac_f32_e32 v27, v99, v75
	v_fmac_f32_e32 v28, v100, v72
	v_fmac_f32_e32 v29, v100, v73
	v_fmac_f32_e32 v30, v100, v74
	v_fmac_f32_e32 v31, v100, v75
	global_load_dwordx4 v[72:75], v11, s[10:11]
	s_add_u32 s10, s10, 0x18000
	s_addc_u32 s11, s11, 0
	ds_read_b32 v96, v10 offset:216
	ds_read_b32 v97, v10 offset:8408
	ds_read_b32 v98, v10 offset:16600
	ds_read_b32 v99, v10 offset:24792
	ds_read_b32 v100, v10 offset:32984
	s_waitcnt vmcnt(15) lgkmcnt(0)
	v_fmac_f32_e32 v12, v96, v76
	v_fmac_f32_e32 v13, v96, v77
	v_fmac_f32_e32 v14, v96, v78
	v_fmac_f32_e32 v15, v96, v79
	v_fmac_f32_e32 v16, v97, v76
	v_fmac_f32_e32 v17, v97, v77
	v_fmac_f32_e32 v18, v97, v78
	v_fmac_f32_e32 v19, v97, v79
	v_fmac_f32_e32 v20, v98, v76
	v_fmac_f32_e32 v21, v98, v77
	v_fmac_f32_e32 v22, v98, v78
	v_fmac_f32_e32 v23, v98, v79
	v_fmac_f32_e32 v24, v99, v76
	v_fmac_f32_e32 v25, v99, v77
	v_fmac_f32_e32 v26, v99, v78
	v_fmac_f32_e32 v27, v99, v79
	v_fmac_f32_e32 v28, v100, v76
	v_fmac_f32_e32 v29, v100, v77
	v_fmac_f32_e32 v30, v100, v78
	v_fmac_f32_e32 v31, v100, v79
	global_load_dwordx4 v[76:79], v11, s[10:11]
	s_add_u32 s10, s10, 0x18000
	s_addc_u32 s11, s11, 0
	ds_read_b32 v96, v10 offset:224
	ds_read_b32 v97, v10 offset:8416
	ds_read_b32 v98, v10 offset:16608
	ds_read_b32 v99, v10 offset:24800
	ds_read_b32 v100, v10 offset:32992
	s_waitcnt vmcnt(15) lgkmcnt(0)
	v_fmac_f32_e32 v12, v96, v80
	v_fmac_f32_e32 v13, v96, v81
	v_fmac_f32_e32 v14, v96, v82
	v_fmac_f32_e32 v15, v96, v83
	v_fmac_f32_e32 v16, v97, v80
	v_fmac_f32_e32 v17, v97, v81
	v_fmac_f32_e32 v18, v97, v82
	v_fmac_f32_e32 v19, v97, v83
	v_fmac_f32_e32 v20, v98, v80
	v_fmac_f32_e32 v21, v98, v81
	v_fmac_f32_e32 v22, v98, v82
	v_fmac_f32_e32 v23, v98, v83
	v_fmac_f32_e32 v24, v99, v80
	v_fmac_f32_e32 v25, v99, v81
	v_fmac_f32_e32 v26, v99, v82
	v_fmac_f32_e32 v27, v99, v83
	v_fmac_f32_e32 v28, v100, v80
	v_fmac_f32_e32 v29, v100, v81
	v_fmac_f32_e32 v30, v100, v82
	v_fmac_f32_e32 v31, v100, v83
	global_load_dwordx4 v[80:83], v11, s[10:11]
	s_add_u32 s10, s10, 0x18000
	s_addc_u32 s11, s11, 0
	ds_read_b32 v96, v10 offset:232
	ds_read_b32 v97, v10 offset:8424
	ds_read_b32 v98, v10 offset:16616
	ds_read_b32 v99, v10 offset:24808
	ds_read_b32 v100, v10 offset:33000
	s_waitcnt vmcnt(15) lgkmcnt(0)
	v_fmac_f32_e32 v12, v96, v84
	v_fmac_f32_e32 v13, v96, v85
	v_fmac_f32_e32 v14, v96, v86
	v_fmac_f32_e32 v15, v96, v87
	v_fmac_f32_e32 v16, v97, v84
	v_fmac_f32_e32 v17, v97, v85
	v_fmac_f32_e32 v18, v97, v86
	v_fmac_f32_e32 v19, v97, v87
	v_fmac_f32_e32 v20, v98, v84
	v_fmac_f32_e32 v21, v98, v85
	v_fmac_f32_e32 v22, v98, v86
	v_fmac_f32_e32 v23, v98, v87
	v_fmac_f32_e32 v24, v99, v84
	v_fmac_f32_e32 v25, v99, v85
	v_fmac_f32_e32 v26, v99, v86
	v_fmac_f32_e32 v27, v99, v87
	v_fmac_f32_e32 v28, v100, v84
	v_fmac_f32_e32 v29, v100, v85
	v_fmac_f32_e32 v30, v100, v86
	v_fmac_f32_e32 v31, v100, v87
	global_load_dwordx4 v[84:87], v11, s[10:11]
	s_add_u32 s10, s10, 0x18000
	s_addc_u32 s11, s11, 0
	ds_read_b32 v96, v10 offset:240
	ds_read_b32 v97, v10 offset:8432
	ds_read_b32 v98, v10 offset:16624
	ds_read_b32 v99, v10 offset:24816
	ds_read_b32 v100, v10 offset:33008
	s_waitcnt vmcnt(15) lgkmcnt(0)
	v_fmac_f32_e32 v12, v96, v88
	v_fmac_f32_e32 v13, v96, v89
	v_fmac_f32_e32 v14, v96, v90
	v_fmac_f32_e32 v15, v96, v91
	v_fmac_f32_e32 v16, v97, v88
	v_fmac_f32_e32 v17, v97, v89
	v_fmac_f32_e32 v18, v97, v90
	v_fmac_f32_e32 v19, v97, v91
	v_fmac_f32_e32 v20, v98, v88
	v_fmac_f32_e32 v21, v98, v89
	v_fmac_f32_e32 v22, v98, v90
	v_fmac_f32_e32 v23, v98, v91
	v_fmac_f32_e32 v24, v99, v88
	v_fmac_f32_e32 v25, v99, v89
	v_fmac_f32_e32 v26, v99, v90
	v_fmac_f32_e32 v27, v99, v91
	v_fmac_f32_e32 v28, v100, v88
	v_fmac_f32_e32 v29, v100, v89
	v_fmac_f32_e32 v30, v100, v90
	v_fmac_f32_e32 v31, v100, v91
	global_load_dwordx4 v[88:91], v11, s[10:11]
	s_add_u32 s10, s10, 0x18000
	s_addc_u32 s11, s11, 0
	ds_read_b32 v96, v10 offset:248
	ds_read_b32 v97, v10 offset:8440
	ds_read_b32 v98, v10 offset:16632
	ds_read_b32 v99, v10 offset:24824
	ds_read_b32 v100, v10 offset:33016
	s_waitcnt vmcnt(15) lgkmcnt(0)
	v_fmac_f32_e32 v12, v96, v92
	v_fmac_f32_e32 v13, v96, v93
	v_fmac_f32_e32 v14, v96, v94
	v_fmac_f32_e32 v15, v96, v95
	v_fmac_f32_e32 v16, v97, v92
	v_fmac_f32_e32 v17, v97, v93
	v_fmac_f32_e32 v18, v97, v94
	v_fmac_f32_e32 v19, v97, v95
	v_fmac_f32_e32 v20, v98, v92
	v_fmac_f32_e32 v21, v98, v93
	v_fmac_f32_e32 v22, v98, v94
	v_fmac_f32_e32 v23, v98, v95
	v_fmac_f32_e32 v24, v99, v92
	v_fmac_f32_e32 v25, v99, v93
	v_fmac_f32_e32 v26, v99, v94
	v_fmac_f32_e32 v27, v99, v95
	v_fmac_f32_e32 v28, v100, v92
	v_fmac_f32_e32 v29, v100, v93
	v_fmac_f32_e32 v30, v100, v94
	v_fmac_f32_e32 v31, v100, v95
	global_load_dwordx4 v[92:95], v11, s[10:11]
	s_add_u32 s10, s10, 0x18000
	s_addc_u32 s11, s11, 0
	ds_read_b32 v96, v10 offset:256
	ds_read_b32 v97, v10 offset:8448
	ds_read_b32 v98, v10 offset:16640
	ds_read_b32 v99, v10 offset:24832
	ds_read_b32 v100, v10 offset:33024
	s_waitcnt vmcnt(15) lgkmcnt(0)
	v_fmac_f32_e32 v12, v96, v32
	v_fmac_f32_e32 v13, v96, v33
	v_fmac_f32_e32 v14, v96, v34
	v_fmac_f32_e32 v15, v96, v35
	v_fmac_f32_e32 v16, v97, v32
	v_fmac_f32_e32 v17, v97, v33
	v_fmac_f32_e32 v18, v97, v34
	v_fmac_f32_e32 v19, v97, v35
	v_fmac_f32_e32 v20, v98, v32
	v_fmac_f32_e32 v21, v98, v33
	v_fmac_f32_e32 v22, v98, v34
	v_fmac_f32_e32 v23, v98, v35
	v_fmac_f32_e32 v24, v99, v32
	v_fmac_f32_e32 v25, v99, v33
	v_fmac_f32_e32 v26, v99, v34
	v_fmac_f32_e32 v27, v99, v35
	v_fmac_f32_e32 v28, v100, v32
	v_fmac_f32_e32 v29, v100, v33
	v_fmac_f32_e32 v30, v100, v34
	v_fmac_f32_e32 v31, v100, v35
	global_load_dwordx4 v[32:35], v11, s[10:11]
	s_add_u32 s10, s10, 0x18000
	s_addc_u32 s11, s11, 0
	ds_read_b32 v96, v10 offset:264
	ds_read_b32 v97, v10 offset:8456
	ds_read_b32 v98, v10 offset:16648
	ds_read_b32 v99, v10 offset:24840
	ds_read_b32 v100, v10 offset:33032
	s_waitcnt vmcnt(15) lgkmcnt(0)
	v_fmac_f32_e32 v12, v96, v36
	v_fmac_f32_e32 v13, v96, v37
	v_fmac_f32_e32 v14, v96, v38
	v_fmac_f32_e32 v15, v96, v39
	v_fmac_f32_e32 v16, v97, v36
	v_fmac_f32_e32 v17, v97, v37
	v_fmac_f32_e32 v18, v97, v38
	v_fmac_f32_e32 v19, v97, v39
	v_fmac_f32_e32 v20, v98, v36
	v_fmac_f32_e32 v21, v98, v37
	v_fmac_f32_e32 v22, v98, v38
	v_fmac_f32_e32 v23, v98, v39
	v_fmac_f32_e32 v24, v99, v36
	v_fmac_f32_e32 v25, v99, v37
	v_fmac_f32_e32 v26, v99, v38
	v_fmac_f32_e32 v27, v99, v39
	v_fmac_f32_e32 v28, v100, v36
	v_fmac_f32_e32 v29, v100, v37
	v_fmac_f32_e32 v30, v100, v38
	v_fmac_f32_e32 v31, v100, v39
	global_load_dwordx4 v[36:39], v11, s[10:11]
	s_add_u32 s10, s10, 0x18000
	s_addc_u32 s11, s11, 0
	ds_read_b32 v96, v10 offset:272
	ds_read_b32 v97, v10 offset:8464
	ds_read_b32 v98, v10 offset:16656
	ds_read_b32 v99, v10 offset:24848
	ds_read_b32 v100, v10 offset:33040
	s_waitcnt vmcnt(15) lgkmcnt(0)
	v_fmac_f32_e32 v12, v96, v40
	v_fmac_f32_e32 v13, v96, v41
	v_fmac_f32_e32 v14, v96, v42
	v_fmac_f32_e32 v15, v96, v43
	v_fmac_f32_e32 v16, v97, v40
	v_fmac_f32_e32 v17, v97, v41
	v_fmac_f32_e32 v18, v97, v42
	v_fmac_f32_e32 v19, v97, v43
	v_fmac_f32_e32 v20, v98, v40
	v_fmac_f32_e32 v21, v98, v41
	v_fmac_f32_e32 v22, v98, v42
	v_fmac_f32_e32 v23, v98, v43
	v_fmac_f32_e32 v24, v99, v40
	v_fmac_f32_e32 v25, v99, v41
	v_fmac_f32_e32 v26, v99, v42
	v_fmac_f32_e32 v27, v99, v43
	v_fmac_f32_e32 v28, v100, v40
	v_fmac_f32_e32 v29, v100, v41
	v_fmac_f32_e32 v30, v100, v42
	v_fmac_f32_e32 v31, v100, v43
	global_load_dwordx4 v[40:43], v11, s[10:11]
	s_add_u32 s10, s10, 0x18000
	s_addc_u32 s11, s11, 0
	ds_read_b32 v96, v10 offset:280
	ds_read_b32 v97, v10 offset:8472
	ds_read_b32 v98, v10 offset:16664
	ds_read_b32 v99, v10 offset:24856
	ds_read_b32 v100, v10 offset:33048
	s_waitcnt vmcnt(15) lgkmcnt(0)
	v_fmac_f32_e32 v12, v96, v44
	v_fmac_f32_e32 v13, v96, v45
	v_fmac_f32_e32 v14, v96, v46
	v_fmac_f32_e32 v15, v96, v47
	v_fmac_f32_e32 v16, v97, v44
	v_fmac_f32_e32 v17, v97, v45
	v_fmac_f32_e32 v18, v97, v46
	v_fmac_f32_e32 v19, v97, v47
	v_fmac_f32_e32 v20, v98, v44
	v_fmac_f32_e32 v21, v98, v45
	v_fmac_f32_e32 v22, v98, v46
	v_fmac_f32_e32 v23, v98, v47
	v_fmac_f32_e32 v24, v99, v44
	v_fmac_f32_e32 v25, v99, v45
	v_fmac_f32_e32 v26, v99, v46
	v_fmac_f32_e32 v27, v99, v47
	v_fmac_f32_e32 v28, v100, v44
	v_fmac_f32_e32 v29, v100, v45
	v_fmac_f32_e32 v30, v100, v46
	v_fmac_f32_e32 v31, v100, v47
	global_load_dwordx4 v[44:47], v11, s[10:11]
	s_add_u32 s10, s10, 0x18000
	s_addc_u32 s11, s11, 0
	ds_read_b32 v96, v10 offset:288
	ds_read_b32 v97, v10 offset:8480
	ds_read_b32 v98, v10 offset:16672
	ds_read_b32 v99, v10 offset:24864
	ds_read_b32 v100, v10 offset:33056
	s_waitcnt vmcnt(15) lgkmcnt(0)
	v_fmac_f32_e32 v12, v96, v48
	v_fmac_f32_e32 v13, v96, v49
	v_fmac_f32_e32 v14, v96, v50
	v_fmac_f32_e32 v15, v96, v51
	v_fmac_f32_e32 v16, v97, v48
	v_fmac_f32_e32 v17, v97, v49
	v_fmac_f32_e32 v18, v97, v50
	v_fmac_f32_e32 v19, v97, v51
	v_fmac_f32_e32 v20, v98, v48
	v_fmac_f32_e32 v21, v98, v49
	v_fmac_f32_e32 v22, v98, v50
	v_fmac_f32_e32 v23, v98, v51
	v_fmac_f32_e32 v24, v99, v48
	v_fmac_f32_e32 v25, v99, v49
	v_fmac_f32_e32 v26, v99, v50
	v_fmac_f32_e32 v27, v99, v51
	v_fmac_f32_e32 v28, v100, v48
	v_fmac_f32_e32 v29, v100, v49
	v_fmac_f32_e32 v30, v100, v50
	v_fmac_f32_e32 v31, v100, v51
	global_load_dwordx4 v[48:51], v11, s[10:11]
	s_add_u32 s10, s10, 0x18000
	s_addc_u32 s11, s11, 0
	ds_read_b32 v96, v10 offset:296
	ds_read_b32 v97, v10 offset:8488
	ds_read_b32 v98, v10 offset:16680
	ds_read_b32 v99, v10 offset:24872
	ds_read_b32 v100, v10 offset:33064
	s_waitcnt vmcnt(15) lgkmcnt(0)
	v_fmac_f32_e32 v12, v96, v52
	v_fmac_f32_e32 v13, v96, v53
	v_fmac_f32_e32 v14, v96, v54
	v_fmac_f32_e32 v15, v96, v55
	v_fmac_f32_e32 v16, v97, v52
	v_fmac_f32_e32 v17, v97, v53
	v_fmac_f32_e32 v18, v97, v54
	v_fmac_f32_e32 v19, v97, v55
	v_fmac_f32_e32 v20, v98, v52
	v_fmac_f32_e32 v21, v98, v53
	v_fmac_f32_e32 v22, v98, v54
	v_fmac_f32_e32 v23, v98, v55
	v_fmac_f32_e32 v24, v99, v52
	v_fmac_f32_e32 v25, v99, v53
	v_fmac_f32_e32 v26, v99, v54
	v_fmac_f32_e32 v27, v99, v55
	v_fmac_f32_e32 v28, v100, v52
	v_fmac_f32_e32 v29, v100, v53
	v_fmac_f32_e32 v30, v100, v54
	v_fmac_f32_e32 v31, v100, v55
	global_load_dwordx4 v[52:55], v11, s[10:11]
	s_add_u32 s10, s10, 0x18000
	s_addc_u32 s11, s11, 0
	ds_read_b32 v96, v10 offset:304
	ds_read_b32 v97, v10 offset:8496
	ds_read_b32 v98, v10 offset:16688
	ds_read_b32 v99, v10 offset:24880
	ds_read_b32 v100, v10 offset:33072
	s_waitcnt vmcnt(15) lgkmcnt(0)
	v_fmac_f32_e32 v12, v96, v56
	v_fmac_f32_e32 v13, v96, v57
	v_fmac_f32_e32 v14, v96, v58
	v_fmac_f32_e32 v15, v96, v59
	v_fmac_f32_e32 v16, v97, v56
	v_fmac_f32_e32 v17, v97, v57
	v_fmac_f32_e32 v18, v97, v58
	v_fmac_f32_e32 v19, v97, v59
	v_fmac_f32_e32 v20, v98, v56
	v_fmac_f32_e32 v21, v98, v57
	v_fmac_f32_e32 v22, v98, v58
	v_fmac_f32_e32 v23, v98, v59
	v_fmac_f32_e32 v24, v99, v56
	v_fmac_f32_e32 v25, v99, v57
	v_fmac_f32_e32 v26, v99, v58
	v_fmac_f32_e32 v27, v99, v59
	v_fmac_f32_e32 v28, v100, v56
	v_fmac_f32_e32 v29, v100, v57
	v_fmac_f32_e32 v30, v100, v58
	v_fmac_f32_e32 v31, v100, v59
	global_load_dwordx4 v[56:59], v11, s[10:11]
	s_add_u32 s10, s10, 0x18000
	s_addc_u32 s11, s11, 0
	ds_read_b32 v96, v10 offset:312
	ds_read_b32 v97, v10 offset:8504
	ds_read_b32 v98, v10 offset:16696
	ds_read_b32 v99, v10 offset:24888
	ds_read_b32 v100, v10 offset:33080
	s_waitcnt vmcnt(15) lgkmcnt(0)
	v_fmac_f32_e32 v12, v96, v60
	v_fmac_f32_e32 v13, v96, v61
	v_fmac_f32_e32 v14, v96, v62
	v_fmac_f32_e32 v15, v96, v63
	v_fmac_f32_e32 v16, v97, v60
	v_fmac_f32_e32 v17, v97, v61
	v_fmac_f32_e32 v18, v97, v62
	v_fmac_f32_e32 v19, v97, v63
	v_fmac_f32_e32 v20, v98, v60
	v_fmac_f32_e32 v21, v98, v61
	v_fmac_f32_e32 v22, v98, v62
	v_fmac_f32_e32 v23, v98, v63
	v_fmac_f32_e32 v24, v99, v60
	v_fmac_f32_e32 v25, v99, v61
	v_fmac_f32_e32 v26, v99, v62
	v_fmac_f32_e32 v27, v99, v63
	v_fmac_f32_e32 v28, v100, v60
	v_fmac_f32_e32 v29, v100, v61
	v_fmac_f32_e32 v30, v100, v62
	v_fmac_f32_e32 v31, v100, v63
	global_load_dwordx4 v[60:63], v11, s[10:11]
	s_add_u32 s10, s10, 0x18000
	s_addc_u32 s11, s11, 0
	ds_read_b32 v96, v10 offset:320
	ds_read_b32 v97, v10 offset:8512
	ds_read_b32 v98, v10 offset:16704
	ds_read_b32 v99, v10 offset:24896
	ds_read_b32 v100, v10 offset:33088
	s_waitcnt vmcnt(15) lgkmcnt(0)
	v_fmac_f32_e32 v12, v96, v64
	v_fmac_f32_e32 v13, v96, v65
	v_fmac_f32_e32 v14, v96, v66
	v_fmac_f32_e32 v15, v96, v67
	v_fmac_f32_e32 v16, v97, v64
	v_fmac_f32_e32 v17, v97, v65
	v_fmac_f32_e32 v18, v97, v66
	v_fmac_f32_e32 v19, v97, v67
	v_fmac_f32_e32 v20, v98, v64
	v_fmac_f32_e32 v21, v98, v65
	v_fmac_f32_e32 v22, v98, v66
	v_fmac_f32_e32 v23, v98, v67
	v_fmac_f32_e32 v24, v99, v64
	v_fmac_f32_e32 v25, v99, v65
	v_fmac_f32_e32 v26, v99, v66
	v_fmac_f32_e32 v27, v99, v67
	v_fmac_f32_e32 v28, v100, v64
	v_fmac_f32_e32 v29, v100, v65
	v_fmac_f32_e32 v30, v100, v66
	v_fmac_f32_e32 v31, v100, v67
	global_load_dwordx4 v[64:67], v11, s[10:11]
	s_add_u32 s10, s10, 0x18000
	s_addc_u32 s11, s11, 0
	ds_read_b32 v96, v10 offset:328
	ds_read_b32 v97, v10 offset:8520
	ds_read_b32 v98, v10 offset:16712
	ds_read_b32 v99, v10 offset:24904
	ds_read_b32 v100, v10 offset:33096
	s_waitcnt vmcnt(15) lgkmcnt(0)
	v_fmac_f32_e32 v12, v96, v68
	v_fmac_f32_e32 v13, v96, v69
	v_fmac_f32_e32 v14, v96, v70
	v_fmac_f32_e32 v15, v96, v71
	v_fmac_f32_e32 v16, v97, v68
	v_fmac_f32_e32 v17, v97, v69
	v_fmac_f32_e32 v18, v97, v70
	v_fmac_f32_e32 v19, v97, v71
	v_fmac_f32_e32 v20, v98, v68
	v_fmac_f32_e32 v21, v98, v69
	v_fmac_f32_e32 v22, v98, v70
	v_fmac_f32_e32 v23, v98, v71
	v_fmac_f32_e32 v24, v99, v68
	v_fmac_f32_e32 v25, v99, v69
	v_fmac_f32_e32 v26, v99, v70
	v_fmac_f32_e32 v27, v99, v71
	v_fmac_f32_e32 v28, v100, v68
	v_fmac_f32_e32 v29, v100, v69
	v_fmac_f32_e32 v30, v100, v70
	v_fmac_f32_e32 v31, v100, v71
	global_load_dwordx4 v[68:71], v11, s[10:11]
	s_add_u32 s10, s10, 0x18000
	s_addc_u32 s11, s11, 0
	ds_read_b32 v96, v10 offset:336
	ds_read_b32 v97, v10 offset:8528
	ds_read_b32 v98, v10 offset:16720
	ds_read_b32 v99, v10 offset:24912
	ds_read_b32 v100, v10 offset:33104
	s_waitcnt vmcnt(15) lgkmcnt(0)
	v_fmac_f32_e32 v12, v96, v72
	v_fmac_f32_e32 v13, v96, v73
	v_fmac_f32_e32 v14, v96, v74
	v_fmac_f32_e32 v15, v96, v75
	v_fmac_f32_e32 v16, v97, v72
	v_fmac_f32_e32 v17, v97, v73
	v_fmac_f32_e32 v18, v97, v74
	v_fmac_f32_e32 v19, v97, v75
	v_fmac_f32_e32 v20, v98, v72
	v_fmac_f32_e32 v21, v98, v73
	v_fmac_f32_e32 v22, v98, v74
	v_fmac_f32_e32 v23, v98, v75
	v_fmac_f32_e32 v24, v99, v72
	v_fmac_f32_e32 v25, v99, v73
	v_fmac_f32_e32 v26, v99, v74
	v_fmac_f32_e32 v27, v99, v75
	v_fmac_f32_e32 v28, v100, v72
	v_fmac_f32_e32 v29, v100, v73
	v_fmac_f32_e32 v30, v100, v74
	v_fmac_f32_e32 v31, v100, v75
	global_load_dwordx4 v[72:75], v11, s[10:11]
	s_add_u32 s10, s10, 0x18000
	s_addc_u32 s11, s11, 0
	ds_read_b32 v96, v10 offset:344
	ds_read_b32 v97, v10 offset:8536
	ds_read_b32 v98, v10 offset:16728
	ds_read_b32 v99, v10 offset:24920
	ds_read_b32 v100, v10 offset:33112
	s_waitcnt vmcnt(15) lgkmcnt(0)
	v_fmac_f32_e32 v12, v96, v76
	v_fmac_f32_e32 v13, v96, v77
	v_fmac_f32_e32 v14, v96, v78
	v_fmac_f32_e32 v15, v96, v79
	v_fmac_f32_e32 v16, v97, v76
	v_fmac_f32_e32 v17, v97, v77
	v_fmac_f32_e32 v18, v97, v78
	v_fmac_f32_e32 v19, v97, v79
	v_fmac_f32_e32 v20, v98, v76
	v_fmac_f32_e32 v21, v98, v77
	v_fmac_f32_e32 v22, v98, v78
	v_fmac_f32_e32 v23, v98, v79
	v_fmac_f32_e32 v24, v99, v76
	v_fmac_f32_e32 v25, v99, v77
	v_fmac_f32_e32 v26, v99, v78
	v_fmac_f32_e32 v27, v99, v79
	v_fmac_f32_e32 v28, v100, v76
	v_fmac_f32_e32 v29, v100, v77
	v_fmac_f32_e32 v30, v100, v78
	v_fmac_f32_e32 v31, v100, v79
	global_load_dwordx4 v[76:79], v11, s[10:11]
	s_add_u32 s10, s10, 0x18000
	s_addc_u32 s11, s11, 0
	ds_read_b32 v96, v10 offset:352
	ds_read_b32 v97, v10 offset:8544
	ds_read_b32 v98, v10 offset:16736
	ds_read_b32 v99, v10 offset:24928
	ds_read_b32 v100, v10 offset:33120
	s_waitcnt vmcnt(15) lgkmcnt(0)
	v_fmac_f32_e32 v12, v96, v80
	v_fmac_f32_e32 v13, v96, v81
	v_fmac_f32_e32 v14, v96, v82
	v_fmac_f32_e32 v15, v96, v83
	v_fmac_f32_e32 v16, v97, v80
	v_fmac_f32_e32 v17, v97, v81
	v_fmac_f32_e32 v18, v97, v82
	v_fmac_f32_e32 v19, v97, v83
	v_fmac_f32_e32 v20, v98, v80
	v_fmac_f32_e32 v21, v98, v81
	v_fmac_f32_e32 v22, v98, v82
	v_fmac_f32_e32 v23, v98, v83
	v_fmac_f32_e32 v24, v99, v80
	v_fmac_f32_e32 v25, v99, v81
	v_fmac_f32_e32 v26, v99, v82
	v_fmac_f32_e32 v27, v99, v83
	v_fmac_f32_e32 v28, v100, v80
	v_fmac_f32_e32 v29, v100, v81
	v_fmac_f32_e32 v30, v100, v82
	v_fmac_f32_e32 v31, v100, v83
	global_load_dwordx4 v[80:83], v11, s[10:11]
	s_add_u32 s10, s10, 0x18000
	s_addc_u32 s11, s11, 0
	ds_read_b32 v96, v10 offset:360
	ds_read_b32 v97, v10 offset:8552
	ds_read_b32 v98, v10 offset:16744
	ds_read_b32 v99, v10 offset:24936
	ds_read_b32 v100, v10 offset:33128
	s_waitcnt vmcnt(15) lgkmcnt(0)
	v_fmac_f32_e32 v12, v96, v84
	v_fmac_f32_e32 v13, v96, v85
	v_fmac_f32_e32 v14, v96, v86
	v_fmac_f32_e32 v15, v96, v87
	v_fmac_f32_e32 v16, v97, v84
	v_fmac_f32_e32 v17, v97, v85
	v_fmac_f32_e32 v18, v97, v86
	v_fmac_f32_e32 v19, v97, v87
	v_fmac_f32_e32 v20, v98, v84
	v_fmac_f32_e32 v21, v98, v85
	v_fmac_f32_e32 v22, v98, v86
	v_fmac_f32_e32 v23, v98, v87
	v_fmac_f32_e32 v24, v99, v84
	v_fmac_f32_e32 v25, v99, v85
	v_fmac_f32_e32 v26, v99, v86
	v_fmac_f32_e32 v27, v99, v87
	v_fmac_f32_e32 v28, v100, v84
	v_fmac_f32_e32 v29, v100, v85
	v_fmac_f32_e32 v30, v100, v86
	v_fmac_f32_e32 v31, v100, v87
	global_load_dwordx4 v[84:87], v11, s[10:11]
	s_add_u32 s10, s10, 0x18000
	s_addc_u32 s11, s11, 0
	ds_read_b32 v96, v10 offset:368
	ds_read_b32 v97, v10 offset:8560
	ds_read_b32 v98, v10 offset:16752
	ds_read_b32 v99, v10 offset:24944
	ds_read_b32 v100, v10 offset:33136
	s_waitcnt vmcnt(15) lgkmcnt(0)
	v_fmac_f32_e32 v12, v96, v88
	v_fmac_f32_e32 v13, v96, v89
	v_fmac_f32_e32 v14, v96, v90
	v_fmac_f32_e32 v15, v96, v91
	v_fmac_f32_e32 v16, v97, v88
	v_fmac_f32_e32 v17, v97, v89
	v_fmac_f32_e32 v18, v97, v90
	v_fmac_f32_e32 v19, v97, v91
	v_fmac_f32_e32 v20, v98, v88
	v_fmac_f32_e32 v21, v98, v89
	v_fmac_f32_e32 v22, v98, v90
	v_fmac_f32_e32 v23, v98, v91
	v_fmac_f32_e32 v24, v99, v88
	v_fmac_f32_e32 v25, v99, v89
	v_fmac_f32_e32 v26, v99, v90
	v_fmac_f32_e32 v27, v99, v91
	v_fmac_f32_e32 v28, v100, v88
	v_fmac_f32_e32 v29, v100, v89
	v_fmac_f32_e32 v30, v100, v90
	v_fmac_f32_e32 v31, v100, v91
	global_load_dwordx4 v[88:91], v11, s[10:11]
	s_add_u32 s10, s10, 0x18000
	s_addc_u32 s11, s11, 0
	ds_read_b32 v96, v10 offset:376
	ds_read_b32 v97, v10 offset:8568
	ds_read_b32 v98, v10 offset:16760
	ds_read_b32 v99, v10 offset:24952
	ds_read_b32 v100, v10 offset:33144
	s_waitcnt vmcnt(15) lgkmcnt(0)
	v_fmac_f32_e32 v12, v96, v92
	v_fmac_f32_e32 v13, v96, v93
	v_fmac_f32_e32 v14, v96, v94
	v_fmac_f32_e32 v15, v96, v95
	v_fmac_f32_e32 v16, v97, v92
	v_fmac_f32_e32 v17, v97, v93
	v_fmac_f32_e32 v18, v97, v94
	v_fmac_f32_e32 v19, v97, v95
	v_fmac_f32_e32 v20, v98, v92
	v_fmac_f32_e32 v21, v98, v93
	v_fmac_f32_e32 v22, v98, v94
	v_fmac_f32_e32 v23, v98, v95
	v_fmac_f32_e32 v24, v99, v92
	v_fmac_f32_e32 v25, v99, v93
	v_fmac_f32_e32 v26, v99, v94
	v_fmac_f32_e32 v27, v99, v95
	v_fmac_f32_e32 v28, v100, v92
	v_fmac_f32_e32 v29, v100, v93
	v_fmac_f32_e32 v30, v100, v94
	v_fmac_f32_e32 v31, v100, v95
	global_load_dwordx4 v[92:95], v11, s[10:11]
	s_add_u32 s10, s10, 0x18000
	s_addc_u32 s11, s11, 0
	ds_read_b32 v96, v10 offset:384
	ds_read_b32 v97, v10 offset:8576
	ds_read_b32 v98, v10 offset:16768
	ds_read_b32 v99, v10 offset:24960
	ds_read_b32 v100, v10 offset:33152
	s_waitcnt vmcnt(15) lgkmcnt(0)
	v_fmac_f32_e32 v12, v96, v32
	v_fmac_f32_e32 v13, v96, v33
	v_fmac_f32_e32 v14, v96, v34
	v_fmac_f32_e32 v15, v96, v35
	v_fmac_f32_e32 v16, v97, v32
	v_fmac_f32_e32 v17, v97, v33
	v_fmac_f32_e32 v18, v97, v34
	v_fmac_f32_e32 v19, v97, v35
	v_fmac_f32_e32 v20, v98, v32
	v_fmac_f32_e32 v21, v98, v33
	v_fmac_f32_e32 v22, v98, v34
	v_fmac_f32_e32 v23, v98, v35
	v_fmac_f32_e32 v24, v99, v32
	v_fmac_f32_e32 v25, v99, v33
	v_fmac_f32_e32 v26, v99, v34
	v_fmac_f32_e32 v27, v99, v35
	v_fmac_f32_e32 v28, v100, v32
	v_fmac_f32_e32 v29, v100, v33
	v_fmac_f32_e32 v30, v100, v34
	v_fmac_f32_e32 v31, v100, v35
	global_load_dwordx4 v[32:35], v11, s[10:11]
	s_add_u32 s10, s10, 0x18000
	s_addc_u32 s11, s11, 0
	ds_read_b32 v96, v10 offset:392
	ds_read_b32 v97, v10 offset:8584
	ds_read_b32 v98, v10 offset:16776
	ds_read_b32 v99, v10 offset:24968
	ds_read_b32 v100, v10 offset:33160
	s_waitcnt vmcnt(15) lgkmcnt(0)
	v_fmac_f32_e32 v12, v96, v36
	v_fmac_f32_e32 v13, v96, v37
	v_fmac_f32_e32 v14, v96, v38
	v_fmac_f32_e32 v15, v96, v39
	v_fmac_f32_e32 v16, v97, v36
	v_fmac_f32_e32 v17, v97, v37
	v_fmac_f32_e32 v18, v97, v38
	v_fmac_f32_e32 v19, v97, v39
	v_fmac_f32_e32 v20, v98, v36
	v_fmac_f32_e32 v21, v98, v37
	v_fmac_f32_e32 v22, v98, v38
	v_fmac_f32_e32 v23, v98, v39
	v_fmac_f32_e32 v24, v99, v36
	v_fmac_f32_e32 v25, v99, v37
	v_fmac_f32_e32 v26, v99, v38
	v_fmac_f32_e32 v27, v99, v39
	v_fmac_f32_e32 v28, v100, v36
	v_fmac_f32_e32 v29, v100, v37
	v_fmac_f32_e32 v30, v100, v38
	v_fmac_f32_e32 v31, v100, v39
	global_load_dwordx4 v[36:39], v11, s[10:11]
	s_add_u32 s10, s10, 0x18000
	s_addc_u32 s11, s11, 0
	ds_read_b32 v96, v10 offset:400
	ds_read_b32 v97, v10 offset:8592
	ds_read_b32 v98, v10 offset:16784
	ds_read_b32 v99, v10 offset:24976
	ds_read_b32 v100, v10 offset:33168
	s_waitcnt vmcnt(15) lgkmcnt(0)
	v_fmac_f32_e32 v12, v96, v40
	v_fmac_f32_e32 v13, v96, v41
	v_fmac_f32_e32 v14, v96, v42
	v_fmac_f32_e32 v15, v96, v43
	v_fmac_f32_e32 v16, v97, v40
	v_fmac_f32_e32 v17, v97, v41
	v_fmac_f32_e32 v18, v97, v42
	v_fmac_f32_e32 v19, v97, v43
	v_fmac_f32_e32 v20, v98, v40
	v_fmac_f32_e32 v21, v98, v41
	v_fmac_f32_e32 v22, v98, v42
	v_fmac_f32_e32 v23, v98, v43
	v_fmac_f32_e32 v24, v99, v40
	v_fmac_f32_e32 v25, v99, v41
	v_fmac_f32_e32 v26, v99, v42
	v_fmac_f32_e32 v27, v99, v43
	v_fmac_f32_e32 v28, v100, v40
	v_fmac_f32_e32 v29, v100, v41
	v_fmac_f32_e32 v30, v100, v42
	v_fmac_f32_e32 v31, v100, v43
	global_load_dwordx4 v[40:43], v11, s[10:11]
	s_add_u32 s10, s10, 0x18000
	s_addc_u32 s11, s11, 0
	ds_read_b32 v96, v10 offset:408
	ds_read_b32 v97, v10 offset:8600
	ds_read_b32 v98, v10 offset:16792
	ds_read_b32 v99, v10 offset:24984
	ds_read_b32 v100, v10 offset:33176
	s_waitcnt vmcnt(15) lgkmcnt(0)
	v_fmac_f32_e32 v12, v96, v44
	v_fmac_f32_e32 v13, v96, v45
	v_fmac_f32_e32 v14, v96, v46
	v_fmac_f32_e32 v15, v96, v47
	v_fmac_f32_e32 v16, v97, v44
	v_fmac_f32_e32 v17, v97, v45
	v_fmac_f32_e32 v18, v97, v46
	v_fmac_f32_e32 v19, v97, v47
	v_fmac_f32_e32 v20, v98, v44
	v_fmac_f32_e32 v21, v98, v45
	v_fmac_f32_e32 v22, v98, v46
	v_fmac_f32_e32 v23, v98, v47
	v_fmac_f32_e32 v24, v99, v44
	v_fmac_f32_e32 v25, v99, v45
	v_fmac_f32_e32 v26, v99, v46
	v_fmac_f32_e32 v27, v99, v47
	v_fmac_f32_e32 v28, v100, v44
	v_fmac_f32_e32 v29, v100, v45
	v_fmac_f32_e32 v30, v100, v46
	v_fmac_f32_e32 v31, v100, v47
	global_load_dwordx4 v[44:47], v11, s[10:11]
	s_add_u32 s10, s10, 0x18000
	s_addc_u32 s11, s11, 0
	ds_read_b32 v96, v10 offset:416
	ds_read_b32 v97, v10 offset:8608
	ds_read_b32 v98, v10 offset:16800
	ds_read_b32 v99, v10 offset:24992
	ds_read_b32 v100, v10 offset:33184
	s_waitcnt vmcnt(15) lgkmcnt(0)
	v_fmac_f32_e32 v12, v96, v48
	v_fmac_f32_e32 v13, v96, v49
	v_fmac_f32_e32 v14, v96, v50
	v_fmac_f32_e32 v15, v96, v51
	v_fmac_f32_e32 v16, v97, v48
	v_fmac_f32_e32 v17, v97, v49
	v_fmac_f32_e32 v18, v97, v50
	v_fmac_f32_e32 v19, v97, v51
	v_fmac_f32_e32 v20, v98, v48
	v_fmac_f32_e32 v21, v98, v49
	v_fmac_f32_e32 v22, v98, v50
	v_fmac_f32_e32 v23, v98, v51
	v_fmac_f32_e32 v24, v99, v48
	v_fmac_f32_e32 v25, v99, v49
	v_fmac_f32_e32 v26, v99, v50
	v_fmac_f32_e32 v27, v99, v51
	v_fmac_f32_e32 v28, v100, v48
	v_fmac_f32_e32 v29, v100, v49
	v_fmac_f32_e32 v30, v100, v50
	v_fmac_f32_e32 v31, v100, v51
	global_load_dwordx4 v[48:51], v11, s[10:11]
	s_add_u32 s10, s10, 0x18000
	s_addc_u32 s11, s11, 0
	ds_read_b32 v96, v10 offset:424
	ds_read_b32 v97, v10 offset:8616
	ds_read_b32 v98, v10 offset:16808
	ds_read_b32 v99, v10 offset:25000
	ds_read_b32 v100, v10 offset:33192
	s_waitcnt vmcnt(15) lgkmcnt(0)
	v_fmac_f32_e32 v12, v96, v52
	v_fmac_f32_e32 v13, v96, v53
	v_fmac_f32_e32 v14, v96, v54
	v_fmac_f32_e32 v15, v96, v55
	v_fmac_f32_e32 v16, v97, v52
	v_fmac_f32_e32 v17, v97, v53
	v_fmac_f32_e32 v18, v97, v54
	v_fmac_f32_e32 v19, v97, v55
	v_fmac_f32_e32 v20, v98, v52
	v_fmac_f32_e32 v21, v98, v53
	v_fmac_f32_e32 v22, v98, v54
	v_fmac_f32_e32 v23, v98, v55
	v_fmac_f32_e32 v24, v99, v52
	v_fmac_f32_e32 v25, v99, v53
	v_fmac_f32_e32 v26, v99, v54
	v_fmac_f32_e32 v27, v99, v55
	v_fmac_f32_e32 v28, v100, v52
	v_fmac_f32_e32 v29, v100, v53
	v_fmac_f32_e32 v30, v100, v54
	v_fmac_f32_e32 v31, v100, v55
	global_load_dwordx4 v[52:55], v11, s[10:11]
	s_add_u32 s10, s10, 0x18000
	s_addc_u32 s11, s11, 0
	ds_read_b32 v96, v10 offset:432
	ds_read_b32 v97, v10 offset:8624
	ds_read_b32 v98, v10 offset:16816
	ds_read_b32 v99, v10 offset:25008
	ds_read_b32 v100, v10 offset:33200
	s_waitcnt vmcnt(15) lgkmcnt(0)
	v_fmac_f32_e32 v12, v96, v56
	v_fmac_f32_e32 v13, v96, v57
	v_fmac_f32_e32 v14, v96, v58
	v_fmac_f32_e32 v15, v96, v59
	v_fmac_f32_e32 v16, v97, v56
	v_fmac_f32_e32 v17, v97, v57
	v_fmac_f32_e32 v18, v97, v58
	v_fmac_f32_e32 v19, v97, v59
	v_fmac_f32_e32 v20, v98, v56
	v_fmac_f32_e32 v21, v98, v57
	v_fmac_f32_e32 v22, v98, v58
	v_fmac_f32_e32 v23, v98, v59
	v_fmac_f32_e32 v24, v99, v56
	v_fmac_f32_e32 v25, v99, v57
	v_fmac_f32_e32 v26, v99, v58
	v_fmac_f32_e32 v27, v99, v59
	v_fmac_f32_e32 v28, v100, v56
	v_fmac_f32_e32 v29, v100, v57
	v_fmac_f32_e32 v30, v100, v58
	v_fmac_f32_e32 v31, v100, v59
	global_load_dwordx4 v[56:59], v11, s[10:11]
	s_add_u32 s10, s10, 0x18000
	s_addc_u32 s11, s11, 0
	ds_read_b32 v96, v10 offset:440
	ds_read_b32 v97, v10 offset:8632
	ds_read_b32 v98, v10 offset:16824
	ds_read_b32 v99, v10 offset:25016
	ds_read_b32 v100, v10 offset:33208
	s_waitcnt vmcnt(15) lgkmcnt(0)
	v_fmac_f32_e32 v12, v96, v60
	v_fmac_f32_e32 v13, v96, v61
	v_fmac_f32_e32 v14, v96, v62
	v_fmac_f32_e32 v15, v96, v63
	v_fmac_f32_e32 v16, v97, v60
	v_fmac_f32_e32 v17, v97, v61
	v_fmac_f32_e32 v18, v97, v62
	v_fmac_f32_e32 v19, v97, v63
	v_fmac_f32_e32 v20, v98, v60
	v_fmac_f32_e32 v21, v98, v61
	v_fmac_f32_e32 v22, v98, v62
	v_fmac_f32_e32 v23, v98, v63
	v_fmac_f32_e32 v24, v99, v60
	v_fmac_f32_e32 v25, v99, v61
	v_fmac_f32_e32 v26, v99, v62
	v_fmac_f32_e32 v27, v99, v63
	v_fmac_f32_e32 v28, v100, v60
	v_fmac_f32_e32 v29, v100, v61
	v_fmac_f32_e32 v30, v100, v62
	v_fmac_f32_e32 v31, v100, v63
	global_load_dwordx4 v[60:63], v11, s[10:11]
	s_add_u32 s10, s10, 0x18000
	s_addc_u32 s11, s11, 0
	ds_read_b32 v96, v10 offset:448
	ds_read_b32 v97, v10 offset:8640
	ds_read_b32 v98, v10 offset:16832
	ds_read_b32 v99, v10 offset:25024
	ds_read_b32 v100, v10 offset:33216
	s_waitcnt vmcnt(15) lgkmcnt(0)
	v_fmac_f32_e32 v12, v96, v64
	v_fmac_f32_e32 v13, v96, v65
	v_fmac_f32_e32 v14, v96, v66
	v_fmac_f32_e32 v15, v96, v67
	v_fmac_f32_e32 v16, v97, v64
	v_fmac_f32_e32 v17, v97, v65
	v_fmac_f32_e32 v18, v97, v66
	v_fmac_f32_e32 v19, v97, v67
	v_fmac_f32_e32 v20, v98, v64
	v_fmac_f32_e32 v21, v98, v65
	v_fmac_f32_e32 v22, v98, v66
	v_fmac_f32_e32 v23, v98, v67
	v_fmac_f32_e32 v24, v99, v64
	v_fmac_f32_e32 v25, v99, v65
	v_fmac_f32_e32 v26, v99, v66
	v_fmac_f32_e32 v27, v99, v67
	v_fmac_f32_e32 v28, v100, v64
	v_fmac_f32_e32 v29, v100, v65
	v_fmac_f32_e32 v30, v100, v66
	v_fmac_f32_e32 v31, v100, v67
	global_load_dwordx4 v[64:67], v11, s[10:11]
	s_add_u32 s10, s10, 0x18000
	s_addc_u32 s11, s11, 0
	ds_read_b32 v96, v10 offset:456
	ds_read_b32 v97, v10 offset:8648
	ds_read_b32 v98, v10 offset:16840
	ds_read_b32 v99, v10 offset:25032
	ds_read_b32 v100, v10 offset:33224
	s_waitcnt vmcnt(15) lgkmcnt(0)
	v_fmac_f32_e32 v12, v96, v68
	v_fmac_f32_e32 v13, v96, v69
	v_fmac_f32_e32 v14, v96, v70
	v_fmac_f32_e32 v15, v96, v71
	v_fmac_f32_e32 v16, v97, v68
	v_fmac_f32_e32 v17, v97, v69
	v_fmac_f32_e32 v18, v97, v70
	v_fmac_f32_e32 v19, v97, v71
	v_fmac_f32_e32 v20, v98, v68
	v_fmac_f32_e32 v21, v98, v69
	v_fmac_f32_e32 v22, v98, v70
	v_fmac_f32_e32 v23, v98, v71
	v_fmac_f32_e32 v24, v99, v68
	v_fmac_f32_e32 v25, v99, v69
	v_fmac_f32_e32 v26, v99, v70
	v_fmac_f32_e32 v27, v99, v71
	v_fmac_f32_e32 v28, v100, v68
	v_fmac_f32_e32 v29, v100, v69
	v_fmac_f32_e32 v30, v100, v70
	v_fmac_f32_e32 v31, v100, v71
	global_load_dwordx4 v[68:71], v11, s[10:11]
	s_add_u32 s10, s10, 0x18000
	s_addc_u32 s11, s11, 0
	ds_read_b32 v96, v10 offset:464
	ds_read_b32 v97, v10 offset:8656
	ds_read_b32 v98, v10 offset:16848
	ds_read_b32 v99, v10 offset:25040
	ds_read_b32 v100, v10 offset:33232
	s_waitcnt vmcnt(15) lgkmcnt(0)
	v_fmac_f32_e32 v12, v96, v72
	v_fmac_f32_e32 v13, v96, v73
	v_fmac_f32_e32 v14, v96, v74
	v_fmac_f32_e32 v15, v96, v75
	v_fmac_f32_e32 v16, v97, v72
	v_fmac_f32_e32 v17, v97, v73
	v_fmac_f32_e32 v18, v97, v74
	v_fmac_f32_e32 v19, v97, v75
	v_fmac_f32_e32 v20, v98, v72
	v_fmac_f32_e32 v21, v98, v73
	v_fmac_f32_e32 v22, v98, v74
	v_fmac_f32_e32 v23, v98, v75
	v_fmac_f32_e32 v24, v99, v72
	v_fmac_f32_e32 v25, v99, v73
	v_fmac_f32_e32 v26, v99, v74
	v_fmac_f32_e32 v27, v99, v75
	v_fmac_f32_e32 v28, v100, v72
	v_fmac_f32_e32 v29, v100, v73
	v_fmac_f32_e32 v30, v100, v74
	v_fmac_f32_e32 v31, v100, v75
	global_load_dwordx4 v[72:75], v11, s[10:11]
	s_add_u32 s10, s10, 0x18000
	s_addc_u32 s11, s11, 0
	ds_read_b32 v96, v10 offset:472
	ds_read_b32 v97, v10 offset:8664
	ds_read_b32 v98, v10 offset:16856
	ds_read_b32 v99, v10 offset:25048
	ds_read_b32 v100, v10 offset:33240
	s_waitcnt vmcnt(15) lgkmcnt(0)
	v_fmac_f32_e32 v12, v96, v76
	v_fmac_f32_e32 v13, v96, v77
	v_fmac_f32_e32 v14, v96, v78
	v_fmac_f32_e32 v15, v96, v79
	v_fmac_f32_e32 v16, v97, v76
	v_fmac_f32_e32 v17, v97, v77
	v_fmac_f32_e32 v18, v97, v78
	v_fmac_f32_e32 v19, v97, v79
	v_fmac_f32_e32 v20, v98, v76
	v_fmac_f32_e32 v21, v98, v77
	v_fmac_f32_e32 v22, v98, v78
	v_fmac_f32_e32 v23, v98, v79
	v_fmac_f32_e32 v24, v99, v76
	v_fmac_f32_e32 v25, v99, v77
	v_fmac_f32_e32 v26, v99, v78
	v_fmac_f32_e32 v27, v99, v79
	v_fmac_f32_e32 v28, v100, v76
	v_fmac_f32_e32 v29, v100, v77
	v_fmac_f32_e32 v30, v100, v78
	v_fmac_f32_e32 v31, v100, v79
	global_load_dwordx4 v[76:79], v11, s[10:11]
	s_add_u32 s10, s10, 0x18000
	s_addc_u32 s11, s11, 0
	ds_read_b32 v96, v10 offset:480
	ds_read_b32 v97, v10 offset:8672
	ds_read_b32 v98, v10 offset:16864
	ds_read_b32 v99, v10 offset:25056
	ds_read_b32 v100, v10 offset:33248
	s_waitcnt vmcnt(15) lgkmcnt(0)
	v_fmac_f32_e32 v12, v96, v80
	v_fmac_f32_e32 v13, v96, v81
	v_fmac_f32_e32 v14, v96, v82
	v_fmac_f32_e32 v15, v96, v83
	v_fmac_f32_e32 v16, v97, v80
	v_fmac_f32_e32 v17, v97, v81
	v_fmac_f32_e32 v18, v97, v82
	v_fmac_f32_e32 v19, v97, v83
	v_fmac_f32_e32 v20, v98, v80
	v_fmac_f32_e32 v21, v98, v81
	v_fmac_f32_e32 v22, v98, v82
	v_fmac_f32_e32 v23, v98, v83
	v_fmac_f32_e32 v24, v99, v80
	v_fmac_f32_e32 v25, v99, v81
	v_fmac_f32_e32 v26, v99, v82
	v_fmac_f32_e32 v27, v99, v83
	v_fmac_f32_e32 v28, v100, v80
	v_fmac_f32_e32 v29, v100, v81
	v_fmac_f32_e32 v30, v100, v82
	v_fmac_f32_e32 v31, v100, v83
	global_load_dwordx4 v[80:83], v11, s[10:11]
	s_add_u32 s10, s10, 0x18000
	s_addc_u32 s11, s11, 0
	ds_read_b32 v96, v10 offset:488
	ds_read_b32 v97, v10 offset:8680
	ds_read_b32 v98, v10 offset:16872
	ds_read_b32 v99, v10 offset:25064
	ds_read_b32 v100, v10 offset:33256
	s_waitcnt vmcnt(15) lgkmcnt(0)
	v_fmac_f32_e32 v12, v96, v84
	v_fmac_f32_e32 v13, v96, v85
	v_fmac_f32_e32 v14, v96, v86
	v_fmac_f32_e32 v15, v96, v87
	v_fmac_f32_e32 v16, v97, v84
	v_fmac_f32_e32 v17, v97, v85
	v_fmac_f32_e32 v18, v97, v86
	v_fmac_f32_e32 v19, v97, v87
	v_fmac_f32_e32 v20, v98, v84
	v_fmac_f32_e32 v21, v98, v85
	v_fmac_f32_e32 v22, v98, v86
	v_fmac_f32_e32 v23, v98, v87
	v_fmac_f32_e32 v24, v99, v84
	v_fmac_f32_e32 v25, v99, v85
	v_fmac_f32_e32 v26, v99, v86
	v_fmac_f32_e32 v27, v99, v87
	v_fmac_f32_e32 v28, v100, v84
	v_fmac_f32_e32 v29, v100, v85
	v_fmac_f32_e32 v30, v100, v86
	v_fmac_f32_e32 v31, v100, v87
	global_load_dwordx4 v[84:87], v11, s[10:11]
	s_add_u32 s10, s10, 0x18000
	s_addc_u32 s11, s11, 0
	ds_read_b32 v96, v10 offset:496
	ds_read_b32 v97, v10 offset:8688
	ds_read_b32 v98, v10 offset:16880
	ds_read_b32 v99, v10 offset:25072
	ds_read_b32 v100, v10 offset:33264
	s_waitcnt vmcnt(15) lgkmcnt(0)
	v_fmac_f32_e32 v12, v96, v88
	v_fmac_f32_e32 v13, v96, v89
	v_fmac_f32_e32 v14, v96, v90
	v_fmac_f32_e32 v15, v96, v91
	v_fmac_f32_e32 v16, v97, v88
	v_fmac_f32_e32 v17, v97, v89
	v_fmac_f32_e32 v18, v97, v90
	v_fmac_f32_e32 v19, v97, v91
	v_fmac_f32_e32 v20, v98, v88
	v_fmac_f32_e32 v21, v98, v89
	v_fmac_f32_e32 v22, v98, v90
	v_fmac_f32_e32 v23, v98, v91
	v_fmac_f32_e32 v24, v99, v88
	v_fmac_f32_e32 v25, v99, v89
	v_fmac_f32_e32 v26, v99, v90
	v_fmac_f32_e32 v27, v99, v91
	v_fmac_f32_e32 v28, v100, v88
	v_fmac_f32_e32 v29, v100, v89
	v_fmac_f32_e32 v30, v100, v90
	v_fmac_f32_e32 v31, v100, v91
	global_load_dwordx4 v[88:91], v11, s[10:11]
	s_add_u32 s10, s10, 0x18000
	s_addc_u32 s11, s11, 0
	ds_read_b32 v96, v10 offset:504
	ds_read_b32 v97, v10 offset:8696
	ds_read_b32 v98, v10 offset:16888
	ds_read_b32 v99, v10 offset:25080
	ds_read_b32 v100, v10 offset:33272
	s_waitcnt vmcnt(15) lgkmcnt(0)
	v_fmac_f32_e32 v12, v96, v92
	v_fmac_f32_e32 v13, v96, v93
	v_fmac_f32_e32 v14, v96, v94
	v_fmac_f32_e32 v15, v96, v95
	v_fmac_f32_e32 v16, v97, v92
	v_fmac_f32_e32 v17, v97, v93
	v_fmac_f32_e32 v18, v97, v94
	v_fmac_f32_e32 v19, v97, v95
	v_fmac_f32_e32 v20, v98, v92
	v_fmac_f32_e32 v21, v98, v93
	v_fmac_f32_e32 v22, v98, v94
	v_fmac_f32_e32 v23, v98, v95
	v_fmac_f32_e32 v24, v99, v92
	v_fmac_f32_e32 v25, v99, v93
	v_fmac_f32_e32 v26, v99, v94
	v_fmac_f32_e32 v27, v99, v95
	v_fmac_f32_e32 v28, v100, v92
	v_fmac_f32_e32 v29, v100, v93
	v_fmac_f32_e32 v30, v100, v94
	v_fmac_f32_e32 v31, v100, v95
	global_load_dwordx4 v[92:95], v11, s[10:11]
	s_add_u32 s10, s10, 0x18000
	s_addc_u32 s11, s11, 0
	ds_read_b32 v96, v10 offset:512
	ds_read_b32 v97, v10 offset:8704
	ds_read_b32 v98, v10 offset:16896
	ds_read_b32 v99, v10 offset:25088
	ds_read_b32 v100, v10 offset:33280
	s_waitcnt vmcnt(15) lgkmcnt(0)
	v_fmac_f32_e32 v12, v96, v32
	v_fmac_f32_e32 v13, v96, v33
	v_fmac_f32_e32 v14, v96, v34
	v_fmac_f32_e32 v15, v96, v35
	v_fmac_f32_e32 v16, v97, v32
	v_fmac_f32_e32 v17, v97, v33
	v_fmac_f32_e32 v18, v97, v34
	v_fmac_f32_e32 v19, v97, v35
	v_fmac_f32_e32 v20, v98, v32
	v_fmac_f32_e32 v21, v98, v33
	v_fmac_f32_e32 v22, v98, v34
	v_fmac_f32_e32 v23, v98, v35
	v_fmac_f32_e32 v24, v99, v32
	v_fmac_f32_e32 v25, v99, v33
	v_fmac_f32_e32 v26, v99, v34
	v_fmac_f32_e32 v27, v99, v35
	v_fmac_f32_e32 v28, v100, v32
	v_fmac_f32_e32 v29, v100, v33
	v_fmac_f32_e32 v30, v100, v34
	v_fmac_f32_e32 v31, v100, v35
	global_load_dwordx4 v[32:35], v11, s[10:11]
	s_add_u32 s10, s10, 0x18000
	s_addc_u32 s11, s11, 0
	ds_read_b32 v96, v10 offset:520
	ds_read_b32 v97, v10 offset:8712
	ds_read_b32 v98, v10 offset:16904
	ds_read_b32 v99, v10 offset:25096
	ds_read_b32 v100, v10 offset:33288
	s_waitcnt vmcnt(15) lgkmcnt(0)
	v_fmac_f32_e32 v12, v96, v36
	v_fmac_f32_e32 v13, v96, v37
	v_fmac_f32_e32 v14, v96, v38
	v_fmac_f32_e32 v15, v96, v39
	v_fmac_f32_e32 v16, v97, v36
	v_fmac_f32_e32 v17, v97, v37
	v_fmac_f32_e32 v18, v97, v38
	v_fmac_f32_e32 v19, v97, v39
	v_fmac_f32_e32 v20, v98, v36
	v_fmac_f32_e32 v21, v98, v37
	v_fmac_f32_e32 v22, v98, v38
	v_fmac_f32_e32 v23, v98, v39
	v_fmac_f32_e32 v24, v99, v36
	v_fmac_f32_e32 v25, v99, v37
	v_fmac_f32_e32 v26, v99, v38
	v_fmac_f32_e32 v27, v99, v39
	v_fmac_f32_e32 v28, v100, v36
	v_fmac_f32_e32 v29, v100, v37
	v_fmac_f32_e32 v30, v100, v38
	v_fmac_f32_e32 v31, v100, v39
	global_load_dwordx4 v[36:39], v11, s[10:11]
	s_add_u32 s10, s10, 0x18000
	s_addc_u32 s11, s11, 0
	ds_read_b32 v96, v10 offset:528
	ds_read_b32 v97, v10 offset:8720
	ds_read_b32 v98, v10 offset:16912
	ds_read_b32 v99, v10 offset:25104
	ds_read_b32 v100, v10 offset:33296
	s_waitcnt vmcnt(15) lgkmcnt(0)
	v_fmac_f32_e32 v12, v96, v40
	v_fmac_f32_e32 v13, v96, v41
	v_fmac_f32_e32 v14, v96, v42
	v_fmac_f32_e32 v15, v96, v43
	v_fmac_f32_e32 v16, v97, v40
	v_fmac_f32_e32 v17, v97, v41
	v_fmac_f32_e32 v18, v97, v42
	v_fmac_f32_e32 v19, v97, v43
	v_fmac_f32_e32 v20, v98, v40
	v_fmac_f32_e32 v21, v98, v41
	v_fmac_f32_e32 v22, v98, v42
	v_fmac_f32_e32 v23, v98, v43
	v_fmac_f32_e32 v24, v99, v40
	v_fmac_f32_e32 v25, v99, v41
	v_fmac_f32_e32 v26, v99, v42
	v_fmac_f32_e32 v27, v99, v43
	v_fmac_f32_e32 v28, v100, v40
	v_fmac_f32_e32 v29, v100, v41
	v_fmac_f32_e32 v30, v100, v42
	v_fmac_f32_e32 v31, v100, v43
	global_load_dwordx4 v[40:43], v11, s[10:11]
	s_add_u32 s10, s10, 0x18000
	s_addc_u32 s11, s11, 0
	ds_read_b32 v96, v10 offset:536
	ds_read_b32 v97, v10 offset:8728
	ds_read_b32 v98, v10 offset:16920
	ds_read_b32 v99, v10 offset:25112
	ds_read_b32 v100, v10 offset:33304
	s_waitcnt vmcnt(15) lgkmcnt(0)
	v_fmac_f32_e32 v12, v96, v44
	v_fmac_f32_e32 v13, v96, v45
	v_fmac_f32_e32 v14, v96, v46
	v_fmac_f32_e32 v15, v96, v47
	v_fmac_f32_e32 v16, v97, v44
	v_fmac_f32_e32 v17, v97, v45
	v_fmac_f32_e32 v18, v97, v46
	v_fmac_f32_e32 v19, v97, v47
	v_fmac_f32_e32 v20, v98, v44
	v_fmac_f32_e32 v21, v98, v45
	v_fmac_f32_e32 v22, v98, v46
	v_fmac_f32_e32 v23, v98, v47
	v_fmac_f32_e32 v24, v99, v44
	v_fmac_f32_e32 v25, v99, v45
	v_fmac_f32_e32 v26, v99, v46
	v_fmac_f32_e32 v27, v99, v47
	v_fmac_f32_e32 v28, v100, v44
	v_fmac_f32_e32 v29, v100, v45
	v_fmac_f32_e32 v30, v100, v46
	v_fmac_f32_e32 v31, v100, v47
	global_load_dwordx4 v[44:47], v11, s[10:11]
	s_add_u32 s10, s10, 0x18000
	s_addc_u32 s11, s11, 0
	ds_read_b32 v96, v10 offset:544
	ds_read_b32 v97, v10 offset:8736
	ds_read_b32 v98, v10 offset:16928
	ds_read_b32 v99, v10 offset:25120
	ds_read_b32 v100, v10 offset:33312
	s_waitcnt vmcnt(15) lgkmcnt(0)
	v_fmac_f32_e32 v12, v96, v48
	v_fmac_f32_e32 v13, v96, v49
	v_fmac_f32_e32 v14, v96, v50
	v_fmac_f32_e32 v15, v96, v51
	v_fmac_f32_e32 v16, v97, v48
	v_fmac_f32_e32 v17, v97, v49
	v_fmac_f32_e32 v18, v97, v50
	v_fmac_f32_e32 v19, v97, v51
	v_fmac_f32_e32 v20, v98, v48
	v_fmac_f32_e32 v21, v98, v49
	v_fmac_f32_e32 v22, v98, v50
	v_fmac_f32_e32 v23, v98, v51
	v_fmac_f32_e32 v24, v99, v48
	v_fmac_f32_e32 v25, v99, v49
	v_fmac_f32_e32 v26, v99, v50
	v_fmac_f32_e32 v27, v99, v51
	v_fmac_f32_e32 v28, v100, v48
	v_fmac_f32_e32 v29, v100, v49
	v_fmac_f32_e32 v30, v100, v50
	v_fmac_f32_e32 v31, v100, v51
	global_load_dwordx4 v[48:51], v11, s[10:11]
	s_add_u32 s10, s10, 0x18000
	s_addc_u32 s11, s11, 0
	ds_read_b32 v96, v10 offset:552
	ds_read_b32 v97, v10 offset:8744
	ds_read_b32 v98, v10 offset:16936
	ds_read_b32 v99, v10 offset:25128
	ds_read_b32 v100, v10 offset:33320
	s_waitcnt vmcnt(15) lgkmcnt(0)
	v_fmac_f32_e32 v12, v96, v52
	v_fmac_f32_e32 v13, v96, v53
	v_fmac_f32_e32 v14, v96, v54
	v_fmac_f32_e32 v15, v96, v55
	v_fmac_f32_e32 v16, v97, v52
	v_fmac_f32_e32 v17, v97, v53
	v_fmac_f32_e32 v18, v97, v54
	v_fmac_f32_e32 v19, v97, v55
	v_fmac_f32_e32 v20, v98, v52
	v_fmac_f32_e32 v21, v98, v53
	v_fmac_f32_e32 v22, v98, v54
	v_fmac_f32_e32 v23, v98, v55
	v_fmac_f32_e32 v24, v99, v52
	v_fmac_f32_e32 v25, v99, v53
	v_fmac_f32_e32 v26, v99, v54
	v_fmac_f32_e32 v27, v99, v55
	v_fmac_f32_e32 v28, v100, v52
	v_fmac_f32_e32 v29, v100, v53
	v_fmac_f32_e32 v30, v100, v54
	v_fmac_f32_e32 v31, v100, v55
	global_load_dwordx4 v[52:55], v11, s[10:11]
	s_add_u32 s10, s10, 0x18000
	s_addc_u32 s11, s11, 0
	ds_read_b32 v96, v10 offset:560
	ds_read_b32 v97, v10 offset:8752
	ds_read_b32 v98, v10 offset:16944
	ds_read_b32 v99, v10 offset:25136
	ds_read_b32 v100, v10 offset:33328
	s_waitcnt vmcnt(15) lgkmcnt(0)
	v_fmac_f32_e32 v12, v96, v56
	v_fmac_f32_e32 v13, v96, v57
	v_fmac_f32_e32 v14, v96, v58
	v_fmac_f32_e32 v15, v96, v59
	v_fmac_f32_e32 v16, v97, v56
	v_fmac_f32_e32 v17, v97, v57
	v_fmac_f32_e32 v18, v97, v58
	v_fmac_f32_e32 v19, v97, v59
	v_fmac_f32_e32 v20, v98, v56
	v_fmac_f32_e32 v21, v98, v57
	v_fmac_f32_e32 v22, v98, v58
	v_fmac_f32_e32 v23, v98, v59
	v_fmac_f32_e32 v24, v99, v56
	v_fmac_f32_e32 v25, v99, v57
	v_fmac_f32_e32 v26, v99, v58
	v_fmac_f32_e32 v27, v99, v59
	v_fmac_f32_e32 v28, v100, v56
	v_fmac_f32_e32 v29, v100, v57
	v_fmac_f32_e32 v30, v100, v58
	v_fmac_f32_e32 v31, v100, v59
	global_load_dwordx4 v[56:59], v11, s[10:11]
	s_add_u32 s10, s10, 0x18000
	s_addc_u32 s11, s11, 0
	ds_read_b32 v96, v10 offset:568
	ds_read_b32 v97, v10 offset:8760
	ds_read_b32 v98, v10 offset:16952
	ds_read_b32 v99, v10 offset:25144
	ds_read_b32 v100, v10 offset:33336
	s_waitcnt vmcnt(15) lgkmcnt(0)
	v_fmac_f32_e32 v12, v96, v60
	v_fmac_f32_e32 v13, v96, v61
	v_fmac_f32_e32 v14, v96, v62
	v_fmac_f32_e32 v15, v96, v63
	v_fmac_f32_e32 v16, v97, v60
	v_fmac_f32_e32 v17, v97, v61
	v_fmac_f32_e32 v18, v97, v62
	v_fmac_f32_e32 v19, v97, v63
	v_fmac_f32_e32 v20, v98, v60
	v_fmac_f32_e32 v21, v98, v61
	v_fmac_f32_e32 v22, v98, v62
	v_fmac_f32_e32 v23, v98, v63
	v_fmac_f32_e32 v24, v99, v60
	v_fmac_f32_e32 v25, v99, v61
	v_fmac_f32_e32 v26, v99, v62
	v_fmac_f32_e32 v27, v99, v63
	v_fmac_f32_e32 v28, v100, v60
	v_fmac_f32_e32 v29, v100, v61
	v_fmac_f32_e32 v30, v100, v62
	v_fmac_f32_e32 v31, v100, v63
	global_load_dwordx4 v[60:63], v11, s[10:11]
	s_add_u32 s10, s10, 0x18000
	s_addc_u32 s11, s11, 0
	ds_read_b32 v96, v10 offset:576
	ds_read_b32 v97, v10 offset:8768
	ds_read_b32 v98, v10 offset:16960
	ds_read_b32 v99, v10 offset:25152
	ds_read_b32 v100, v10 offset:33344
	s_waitcnt vmcnt(15) lgkmcnt(0)
	v_fmac_f32_e32 v12, v96, v64
	v_fmac_f32_e32 v13, v96, v65
	v_fmac_f32_e32 v14, v96, v66
	v_fmac_f32_e32 v15, v96, v67
	v_fmac_f32_e32 v16, v97, v64
	v_fmac_f32_e32 v17, v97, v65
	v_fmac_f32_e32 v18, v97, v66
	v_fmac_f32_e32 v19, v97, v67
	v_fmac_f32_e32 v20, v98, v64
	v_fmac_f32_e32 v21, v98, v65
	v_fmac_f32_e32 v22, v98, v66
	v_fmac_f32_e32 v23, v98, v67
	v_fmac_f32_e32 v24, v99, v64
	v_fmac_f32_e32 v25, v99, v65
	v_fmac_f32_e32 v26, v99, v66
	v_fmac_f32_e32 v27, v99, v67
	v_fmac_f32_e32 v28, v100, v64
	v_fmac_f32_e32 v29, v100, v65
	v_fmac_f32_e32 v30, v100, v66
	v_fmac_f32_e32 v31, v100, v67
	global_load_dwordx4 v[64:67], v11, s[10:11]
	s_add_u32 s10, s10, 0x18000
	s_addc_u32 s11, s11, 0
	ds_read_b32 v96, v10 offset:584
	ds_read_b32 v97, v10 offset:8776
	ds_read_b32 v98, v10 offset:16968
	ds_read_b32 v99, v10 offset:25160
	ds_read_b32 v100, v10 offset:33352
	s_waitcnt vmcnt(15) lgkmcnt(0)
	v_fmac_f32_e32 v12, v96, v68
	v_fmac_f32_e32 v13, v96, v69
	v_fmac_f32_e32 v14, v96, v70
	v_fmac_f32_e32 v15, v96, v71
	v_fmac_f32_e32 v16, v97, v68
	v_fmac_f32_e32 v17, v97, v69
	v_fmac_f32_e32 v18, v97, v70
	v_fmac_f32_e32 v19, v97, v71
	v_fmac_f32_e32 v20, v98, v68
	v_fmac_f32_e32 v21, v98, v69
	v_fmac_f32_e32 v22, v98, v70
	v_fmac_f32_e32 v23, v98, v71
	v_fmac_f32_e32 v24, v99, v68
	v_fmac_f32_e32 v25, v99, v69
	v_fmac_f32_e32 v26, v99, v70
	v_fmac_f32_e32 v27, v99, v71
	v_fmac_f32_e32 v28, v100, v68
	v_fmac_f32_e32 v29, v100, v69
	v_fmac_f32_e32 v30, v100, v70
	v_fmac_f32_e32 v31, v100, v71
	global_load_dwordx4 v[68:71], v11, s[10:11]
	s_add_u32 s10, s10, 0x18000
	s_addc_u32 s11, s11, 0
	ds_read_b32 v96, v10 offset:592
	ds_read_b32 v97, v10 offset:8784
	ds_read_b32 v98, v10 offset:16976
	ds_read_b32 v99, v10 offset:25168
	ds_read_b32 v100, v10 offset:33360
	s_waitcnt vmcnt(15) lgkmcnt(0)
	v_fmac_f32_e32 v12, v96, v72
	v_fmac_f32_e32 v13, v96, v73
	v_fmac_f32_e32 v14, v96, v74
	v_fmac_f32_e32 v15, v96, v75
	v_fmac_f32_e32 v16, v97, v72
	v_fmac_f32_e32 v17, v97, v73
	v_fmac_f32_e32 v18, v97, v74
	v_fmac_f32_e32 v19, v97, v75
	v_fmac_f32_e32 v20, v98, v72
	v_fmac_f32_e32 v21, v98, v73
	v_fmac_f32_e32 v22, v98, v74
	v_fmac_f32_e32 v23, v98, v75
	v_fmac_f32_e32 v24, v99, v72
	v_fmac_f32_e32 v25, v99, v73
	v_fmac_f32_e32 v26, v99, v74
	v_fmac_f32_e32 v27, v99, v75
	v_fmac_f32_e32 v28, v100, v72
	v_fmac_f32_e32 v29, v100, v73
	v_fmac_f32_e32 v30, v100, v74
	v_fmac_f32_e32 v31, v100, v75
	global_load_dwordx4 v[72:75], v11, s[10:11]
	s_add_u32 s10, s10, 0x18000
	s_addc_u32 s11, s11, 0
	ds_read_b32 v96, v10 offset:600
	ds_read_b32 v97, v10 offset:8792
	ds_read_b32 v98, v10 offset:16984
	ds_read_b32 v99, v10 offset:25176
	ds_read_b32 v100, v10 offset:33368
	s_waitcnt vmcnt(15) lgkmcnt(0)
	v_fmac_f32_e32 v12, v96, v76
	v_fmac_f32_e32 v13, v96, v77
	v_fmac_f32_e32 v14, v96, v78
	v_fmac_f32_e32 v15, v96, v79
	v_fmac_f32_e32 v16, v97, v76
	v_fmac_f32_e32 v17, v97, v77
	v_fmac_f32_e32 v18, v97, v78
	v_fmac_f32_e32 v19, v97, v79
	v_fmac_f32_e32 v20, v98, v76
	v_fmac_f32_e32 v21, v98, v77
	v_fmac_f32_e32 v22, v98, v78
	v_fmac_f32_e32 v23, v98, v79
	v_fmac_f32_e32 v24, v99, v76
	v_fmac_f32_e32 v25, v99, v77
	v_fmac_f32_e32 v26, v99, v78
	v_fmac_f32_e32 v27, v99, v79
	v_fmac_f32_e32 v28, v100, v76
	v_fmac_f32_e32 v29, v100, v77
	v_fmac_f32_e32 v30, v100, v78
	v_fmac_f32_e32 v31, v100, v79
	global_load_dwordx4 v[76:79], v11, s[10:11]
	s_add_u32 s10, s10, 0x18000
	s_addc_u32 s11, s11, 0
	ds_read_b32 v96, v10 offset:608
	ds_read_b32 v97, v10 offset:8800
	ds_read_b32 v98, v10 offset:16992
	ds_read_b32 v99, v10 offset:25184
	ds_read_b32 v100, v10 offset:33376
	s_waitcnt vmcnt(15) lgkmcnt(0)
	v_fmac_f32_e32 v12, v96, v80
	v_fmac_f32_e32 v13, v96, v81
	v_fmac_f32_e32 v14, v96, v82
	v_fmac_f32_e32 v15, v96, v83
	v_fmac_f32_e32 v16, v97, v80
	v_fmac_f32_e32 v17, v97, v81
	v_fmac_f32_e32 v18, v97, v82
	v_fmac_f32_e32 v19, v97, v83
	v_fmac_f32_e32 v20, v98, v80
	v_fmac_f32_e32 v21, v98, v81
	v_fmac_f32_e32 v22, v98, v82
	v_fmac_f32_e32 v23, v98, v83
	v_fmac_f32_e32 v24, v99, v80
	v_fmac_f32_e32 v25, v99, v81
	v_fmac_f32_e32 v26, v99, v82
	v_fmac_f32_e32 v27, v99, v83
	v_fmac_f32_e32 v28, v100, v80
	v_fmac_f32_e32 v29, v100, v81
	v_fmac_f32_e32 v30, v100, v82
	v_fmac_f32_e32 v31, v100, v83
	global_load_dwordx4 v[80:83], v11, s[10:11]
	s_add_u32 s10, s10, 0x18000
	s_addc_u32 s11, s11, 0
	ds_read_b32 v96, v10 offset:616
	ds_read_b32 v97, v10 offset:8808
	ds_read_b32 v98, v10 offset:17000
	ds_read_b32 v99, v10 offset:25192
	ds_read_b32 v100, v10 offset:33384
	s_waitcnt vmcnt(15) lgkmcnt(0)
	v_fmac_f32_e32 v12, v96, v84
	v_fmac_f32_e32 v13, v96, v85
	v_fmac_f32_e32 v14, v96, v86
	v_fmac_f32_e32 v15, v96, v87
	v_fmac_f32_e32 v16, v97, v84
	v_fmac_f32_e32 v17, v97, v85
	v_fmac_f32_e32 v18, v97, v86
	v_fmac_f32_e32 v19, v97, v87
	v_fmac_f32_e32 v20, v98, v84
	v_fmac_f32_e32 v21, v98, v85
	v_fmac_f32_e32 v22, v98, v86
	v_fmac_f32_e32 v23, v98, v87
	v_fmac_f32_e32 v24, v99, v84
	v_fmac_f32_e32 v25, v99, v85
	v_fmac_f32_e32 v26, v99, v86
	v_fmac_f32_e32 v27, v99, v87
	v_fmac_f32_e32 v28, v100, v84
	v_fmac_f32_e32 v29, v100, v85
	v_fmac_f32_e32 v30, v100, v86
	v_fmac_f32_e32 v31, v100, v87
	global_load_dwordx4 v[84:87], v11, s[10:11]
	s_add_u32 s10, s10, 0x18000
	s_addc_u32 s11, s11, 0
	ds_read_b32 v96, v10 offset:624
	ds_read_b32 v97, v10 offset:8816
	ds_read_b32 v98, v10 offset:17008
	ds_read_b32 v99, v10 offset:25200
	ds_read_b32 v100, v10 offset:33392
	s_waitcnt vmcnt(15) lgkmcnt(0)
	v_fmac_f32_e32 v12, v96, v88
	v_fmac_f32_e32 v13, v96, v89
	v_fmac_f32_e32 v14, v96, v90
	v_fmac_f32_e32 v15, v96, v91
	v_fmac_f32_e32 v16, v97, v88
	v_fmac_f32_e32 v17, v97, v89
	v_fmac_f32_e32 v18, v97, v90
	v_fmac_f32_e32 v19, v97, v91
	v_fmac_f32_e32 v20, v98, v88
	v_fmac_f32_e32 v21, v98, v89
	v_fmac_f32_e32 v22, v98, v90
	v_fmac_f32_e32 v23, v98, v91
	v_fmac_f32_e32 v24, v99, v88
	v_fmac_f32_e32 v25, v99, v89
	v_fmac_f32_e32 v26, v99, v90
	v_fmac_f32_e32 v27, v99, v91
	v_fmac_f32_e32 v28, v100, v88
	v_fmac_f32_e32 v29, v100, v89
	v_fmac_f32_e32 v30, v100, v90
	v_fmac_f32_e32 v31, v100, v91
	global_load_dwordx4 v[88:91], v11, s[10:11]
	s_add_u32 s10, s10, 0x18000
	s_addc_u32 s11, s11, 0
	ds_read_b32 v96, v10 offset:632
	ds_read_b32 v97, v10 offset:8824
	ds_read_b32 v98, v10 offset:17016
	ds_read_b32 v99, v10 offset:25208
	ds_read_b32 v100, v10 offset:33400
	s_waitcnt vmcnt(15) lgkmcnt(0)
	v_fmac_f32_e32 v12, v96, v92
	v_fmac_f32_e32 v13, v96, v93
	v_fmac_f32_e32 v14, v96, v94
	v_fmac_f32_e32 v15, v96, v95
	v_fmac_f32_e32 v16, v97, v92
	v_fmac_f32_e32 v17, v97, v93
	v_fmac_f32_e32 v18, v97, v94
	v_fmac_f32_e32 v19, v97, v95
	v_fmac_f32_e32 v20, v98, v92
	v_fmac_f32_e32 v21, v98, v93
	v_fmac_f32_e32 v22, v98, v94
	v_fmac_f32_e32 v23, v98, v95
	v_fmac_f32_e32 v24, v99, v92
	v_fmac_f32_e32 v25, v99, v93
	v_fmac_f32_e32 v26, v99, v94
	v_fmac_f32_e32 v27, v99, v95
	v_fmac_f32_e32 v28, v100, v92
	v_fmac_f32_e32 v29, v100, v93
	v_fmac_f32_e32 v30, v100, v94
	v_fmac_f32_e32 v31, v100, v95
	global_load_dwordx4 v[92:95], v11, s[10:11]
	s_add_u32 s10, s10, 0x18000
	s_addc_u32 s11, s11, 0
	ds_read_b32 v96, v10 offset:640
	ds_read_b32 v97, v10 offset:8832
	ds_read_b32 v98, v10 offset:17024
	ds_read_b32 v99, v10 offset:25216
	ds_read_b32 v100, v10 offset:33408
	s_waitcnt vmcnt(15) lgkmcnt(0)
	v_fmac_f32_e32 v12, v96, v32
	v_fmac_f32_e32 v13, v96, v33
	v_fmac_f32_e32 v14, v96, v34
	v_fmac_f32_e32 v15, v96, v35
	v_fmac_f32_e32 v16, v97, v32
	v_fmac_f32_e32 v17, v97, v33
	v_fmac_f32_e32 v18, v97, v34
	v_fmac_f32_e32 v19, v97, v35
	v_fmac_f32_e32 v20, v98, v32
	v_fmac_f32_e32 v21, v98, v33
	v_fmac_f32_e32 v22, v98, v34
	v_fmac_f32_e32 v23, v98, v35
	v_fmac_f32_e32 v24, v99, v32
	v_fmac_f32_e32 v25, v99, v33
	v_fmac_f32_e32 v26, v99, v34
	v_fmac_f32_e32 v27, v99, v35
	v_fmac_f32_e32 v28, v100, v32
	v_fmac_f32_e32 v29, v100, v33
	v_fmac_f32_e32 v30, v100, v34
	v_fmac_f32_e32 v31, v100, v35
	global_load_dwordx4 v[32:35], v11, s[10:11]
	s_add_u32 s10, s10, 0x18000
	s_addc_u32 s11, s11, 0
	ds_read_b32 v96, v10 offset:648
	ds_read_b32 v97, v10 offset:8840
	ds_read_b32 v98, v10 offset:17032
	ds_read_b32 v99, v10 offset:25224
	ds_read_b32 v100, v10 offset:33416
	s_waitcnt vmcnt(15) lgkmcnt(0)
	v_fmac_f32_e32 v12, v96, v36
	v_fmac_f32_e32 v13, v96, v37
	v_fmac_f32_e32 v14, v96, v38
	v_fmac_f32_e32 v15, v96, v39
	v_fmac_f32_e32 v16, v97, v36
	v_fmac_f32_e32 v17, v97, v37
	v_fmac_f32_e32 v18, v97, v38
	v_fmac_f32_e32 v19, v97, v39
	v_fmac_f32_e32 v20, v98, v36
	v_fmac_f32_e32 v21, v98, v37
	v_fmac_f32_e32 v22, v98, v38
	v_fmac_f32_e32 v23, v98, v39
	v_fmac_f32_e32 v24, v99, v36
	v_fmac_f32_e32 v25, v99, v37
	v_fmac_f32_e32 v26, v99, v38
	v_fmac_f32_e32 v27, v99, v39
	v_fmac_f32_e32 v28, v100, v36
	v_fmac_f32_e32 v29, v100, v37
	v_fmac_f32_e32 v30, v100, v38
	v_fmac_f32_e32 v31, v100, v39
	global_load_dwordx4 v[36:39], v11, s[10:11]
	s_add_u32 s10, s10, 0x18000
	s_addc_u32 s11, s11, 0
	ds_read_b32 v96, v10 offset:656
	ds_read_b32 v97, v10 offset:8848
	ds_read_b32 v98, v10 offset:17040
	ds_read_b32 v99, v10 offset:25232
	ds_read_b32 v100, v10 offset:33424
	s_waitcnt vmcnt(15) lgkmcnt(0)
	v_fmac_f32_e32 v12, v96, v40
	v_fmac_f32_e32 v13, v96, v41
	v_fmac_f32_e32 v14, v96, v42
	v_fmac_f32_e32 v15, v96, v43
	v_fmac_f32_e32 v16, v97, v40
	v_fmac_f32_e32 v17, v97, v41
	v_fmac_f32_e32 v18, v97, v42
	v_fmac_f32_e32 v19, v97, v43
	v_fmac_f32_e32 v20, v98, v40
	v_fmac_f32_e32 v21, v98, v41
	v_fmac_f32_e32 v22, v98, v42
	v_fmac_f32_e32 v23, v98, v43
	v_fmac_f32_e32 v24, v99, v40
	v_fmac_f32_e32 v25, v99, v41
	v_fmac_f32_e32 v26, v99, v42
	v_fmac_f32_e32 v27, v99, v43
	v_fmac_f32_e32 v28, v100, v40
	v_fmac_f32_e32 v29, v100, v41
	v_fmac_f32_e32 v30, v100, v42
	v_fmac_f32_e32 v31, v100, v43
	global_load_dwordx4 v[40:43], v11, s[10:11]
	s_add_u32 s10, s10, 0x18000
	s_addc_u32 s11, s11, 0
	ds_read_b32 v96, v10 offset:664
	ds_read_b32 v97, v10 offset:8856
	ds_read_b32 v98, v10 offset:17048
	ds_read_b32 v99, v10 offset:25240
	ds_read_b32 v100, v10 offset:33432
	s_waitcnt vmcnt(15) lgkmcnt(0)
	v_fmac_f32_e32 v12, v96, v44
	v_fmac_f32_e32 v13, v96, v45
	v_fmac_f32_e32 v14, v96, v46
	v_fmac_f32_e32 v15, v96, v47
	v_fmac_f32_e32 v16, v97, v44
	v_fmac_f32_e32 v17, v97, v45
	v_fmac_f32_e32 v18, v97, v46
	v_fmac_f32_e32 v19, v97, v47
	v_fmac_f32_e32 v20, v98, v44
	v_fmac_f32_e32 v21, v98, v45
	v_fmac_f32_e32 v22, v98, v46
	v_fmac_f32_e32 v23, v98, v47
	v_fmac_f32_e32 v24, v99, v44
	v_fmac_f32_e32 v25, v99, v45
	v_fmac_f32_e32 v26, v99, v46
	v_fmac_f32_e32 v27, v99, v47
	v_fmac_f32_e32 v28, v100, v44
	v_fmac_f32_e32 v29, v100, v45
	v_fmac_f32_e32 v30, v100, v46
	v_fmac_f32_e32 v31, v100, v47
	global_load_dwordx4 v[44:47], v11, s[10:11]
	s_add_u32 s10, s10, 0x18000
	s_addc_u32 s11, s11, 0
	ds_read_b32 v96, v10 offset:672
	ds_read_b32 v97, v10 offset:8864
	ds_read_b32 v98, v10 offset:17056
	ds_read_b32 v99, v10 offset:25248
	ds_read_b32 v100, v10 offset:33440
	s_waitcnt vmcnt(15) lgkmcnt(0)
	v_fmac_f32_e32 v12, v96, v48
	v_fmac_f32_e32 v13, v96, v49
	v_fmac_f32_e32 v14, v96, v50
	v_fmac_f32_e32 v15, v96, v51
	v_fmac_f32_e32 v16, v97, v48
	v_fmac_f32_e32 v17, v97, v49
	v_fmac_f32_e32 v18, v97, v50
	v_fmac_f32_e32 v19, v97, v51
	v_fmac_f32_e32 v20, v98, v48
	v_fmac_f32_e32 v21, v98, v49
	v_fmac_f32_e32 v22, v98, v50
	v_fmac_f32_e32 v23, v98, v51
	v_fmac_f32_e32 v24, v99, v48
	v_fmac_f32_e32 v25, v99, v49
	v_fmac_f32_e32 v26, v99, v50
	v_fmac_f32_e32 v27, v99, v51
	v_fmac_f32_e32 v28, v100, v48
	v_fmac_f32_e32 v29, v100, v49
	v_fmac_f32_e32 v30, v100, v50
	v_fmac_f32_e32 v31, v100, v51
	global_load_dwordx4 v[48:51], v11, s[10:11]
	s_add_u32 s10, s10, 0x18000
	s_addc_u32 s11, s11, 0
	ds_read_b32 v96, v10 offset:680
	ds_read_b32 v97, v10 offset:8872
	ds_read_b32 v98, v10 offset:17064
	ds_read_b32 v99, v10 offset:25256
	ds_read_b32 v100, v10 offset:33448
	s_waitcnt vmcnt(15) lgkmcnt(0)
	v_fmac_f32_e32 v12, v96, v52
	v_fmac_f32_e32 v13, v96, v53
	v_fmac_f32_e32 v14, v96, v54
	v_fmac_f32_e32 v15, v96, v55
	v_fmac_f32_e32 v16, v97, v52
	v_fmac_f32_e32 v17, v97, v53
	v_fmac_f32_e32 v18, v97, v54
	v_fmac_f32_e32 v19, v97, v55
	v_fmac_f32_e32 v20, v98, v52
	v_fmac_f32_e32 v21, v98, v53
	v_fmac_f32_e32 v22, v98, v54
	v_fmac_f32_e32 v23, v98, v55
	v_fmac_f32_e32 v24, v99, v52
	v_fmac_f32_e32 v25, v99, v53
	v_fmac_f32_e32 v26, v99, v54
	v_fmac_f32_e32 v27, v99, v55
	v_fmac_f32_e32 v28, v100, v52
	v_fmac_f32_e32 v29, v100, v53
	v_fmac_f32_e32 v30, v100, v54
	v_fmac_f32_e32 v31, v100, v55
	global_load_dwordx4 v[52:55], v11, s[10:11]
	s_add_u32 s10, s10, 0x18000
	s_addc_u32 s11, s11, 0
	ds_read_b32 v96, v10 offset:688
	ds_read_b32 v97, v10 offset:8880
	ds_read_b32 v98, v10 offset:17072
	ds_read_b32 v99, v10 offset:25264
	ds_read_b32 v100, v10 offset:33456
	s_waitcnt vmcnt(15) lgkmcnt(0)
	v_fmac_f32_e32 v12, v96, v56
	v_fmac_f32_e32 v13, v96, v57
	v_fmac_f32_e32 v14, v96, v58
	v_fmac_f32_e32 v15, v96, v59
	v_fmac_f32_e32 v16, v97, v56
	v_fmac_f32_e32 v17, v97, v57
	v_fmac_f32_e32 v18, v97, v58
	v_fmac_f32_e32 v19, v97, v59
	v_fmac_f32_e32 v20, v98, v56
	v_fmac_f32_e32 v21, v98, v57
	v_fmac_f32_e32 v22, v98, v58
	v_fmac_f32_e32 v23, v98, v59
	v_fmac_f32_e32 v24, v99, v56
	v_fmac_f32_e32 v25, v99, v57
	v_fmac_f32_e32 v26, v99, v58
	v_fmac_f32_e32 v27, v99, v59
	v_fmac_f32_e32 v28, v100, v56
	v_fmac_f32_e32 v29, v100, v57
	v_fmac_f32_e32 v30, v100, v58
	v_fmac_f32_e32 v31, v100, v59
	global_load_dwordx4 v[56:59], v11, s[10:11]
	s_add_u32 s10, s10, 0x18000
	s_addc_u32 s11, s11, 0
	ds_read_b32 v96, v10 offset:696
	ds_read_b32 v97, v10 offset:8888
	ds_read_b32 v98, v10 offset:17080
	ds_read_b32 v99, v10 offset:25272
	ds_read_b32 v100, v10 offset:33464
	s_waitcnt vmcnt(15) lgkmcnt(0)
	v_fmac_f32_e32 v12, v96, v60
	v_fmac_f32_e32 v13, v96, v61
	v_fmac_f32_e32 v14, v96, v62
	v_fmac_f32_e32 v15, v96, v63
	v_fmac_f32_e32 v16, v97, v60
	v_fmac_f32_e32 v17, v97, v61
	v_fmac_f32_e32 v18, v97, v62
	v_fmac_f32_e32 v19, v97, v63
	v_fmac_f32_e32 v20, v98, v60
	v_fmac_f32_e32 v21, v98, v61
	v_fmac_f32_e32 v22, v98, v62
	v_fmac_f32_e32 v23, v98, v63
	v_fmac_f32_e32 v24, v99, v60
	v_fmac_f32_e32 v25, v99, v61
	v_fmac_f32_e32 v26, v99, v62
	v_fmac_f32_e32 v27, v99, v63
	v_fmac_f32_e32 v28, v100, v60
	v_fmac_f32_e32 v29, v100, v61
	v_fmac_f32_e32 v30, v100, v62
	v_fmac_f32_e32 v31, v100, v63
	global_load_dwordx4 v[60:63], v11, s[10:11]
	s_add_u32 s10, s10, 0x18000
	s_addc_u32 s11, s11, 0
	ds_read_b32 v96, v10 offset:704
	ds_read_b32 v97, v10 offset:8896
	ds_read_b32 v98, v10 offset:17088
	ds_read_b32 v99, v10 offset:25280
	ds_read_b32 v100, v10 offset:33472
	s_waitcnt vmcnt(15) lgkmcnt(0)
	v_fmac_f32_e32 v12, v96, v64
	v_fmac_f32_e32 v13, v96, v65
	v_fmac_f32_e32 v14, v96, v66
	v_fmac_f32_e32 v15, v96, v67
	v_fmac_f32_e32 v16, v97, v64
	v_fmac_f32_e32 v17, v97, v65
	v_fmac_f32_e32 v18, v97, v66
	v_fmac_f32_e32 v19, v97, v67
	v_fmac_f32_e32 v20, v98, v64
	v_fmac_f32_e32 v21, v98, v65
	v_fmac_f32_e32 v22, v98, v66
	v_fmac_f32_e32 v23, v98, v67
	v_fmac_f32_e32 v24, v99, v64
	v_fmac_f32_e32 v25, v99, v65
	v_fmac_f32_e32 v26, v99, v66
	v_fmac_f32_e32 v27, v99, v67
	v_fmac_f32_e32 v28, v100, v64
	v_fmac_f32_e32 v29, v100, v65
	v_fmac_f32_e32 v30, v100, v66
	v_fmac_f32_e32 v31, v100, v67
	global_load_dwordx4 v[64:67], v11, s[10:11]
	s_add_u32 s10, s10, 0x18000
	s_addc_u32 s11, s11, 0
	ds_read_b32 v96, v10 offset:712
	ds_read_b32 v97, v10 offset:8904
	ds_read_b32 v98, v10 offset:17096
	ds_read_b32 v99, v10 offset:25288
	ds_read_b32 v100, v10 offset:33480
	s_waitcnt vmcnt(15) lgkmcnt(0)
	v_fmac_f32_e32 v12, v96, v68
	v_fmac_f32_e32 v13, v96, v69
	v_fmac_f32_e32 v14, v96, v70
	v_fmac_f32_e32 v15, v96, v71
	v_fmac_f32_e32 v16, v97, v68
	v_fmac_f32_e32 v17, v97, v69
	v_fmac_f32_e32 v18, v97, v70
	v_fmac_f32_e32 v19, v97, v71
	v_fmac_f32_e32 v20, v98, v68
	v_fmac_f32_e32 v21, v98, v69
	v_fmac_f32_e32 v22, v98, v70
	v_fmac_f32_e32 v23, v98, v71
	v_fmac_f32_e32 v24, v99, v68
	v_fmac_f32_e32 v25, v99, v69
	v_fmac_f32_e32 v26, v99, v70
	v_fmac_f32_e32 v27, v99, v71
	v_fmac_f32_e32 v28, v100, v68
	v_fmac_f32_e32 v29, v100, v69
	v_fmac_f32_e32 v30, v100, v70
	v_fmac_f32_e32 v31, v100, v71
	global_load_dwordx4 v[68:71], v11, s[10:11]
	s_add_u32 s10, s10, 0x18000
	s_addc_u32 s11, s11, 0
	ds_read_b32 v96, v10 offset:720
	ds_read_b32 v97, v10 offset:8912
	ds_read_b32 v98, v10 offset:17104
	ds_read_b32 v99, v10 offset:25296
	ds_read_b32 v100, v10 offset:33488
	s_waitcnt vmcnt(15) lgkmcnt(0)
	v_fmac_f32_e32 v12, v96, v72
	v_fmac_f32_e32 v13, v96, v73
	v_fmac_f32_e32 v14, v96, v74
	v_fmac_f32_e32 v15, v96, v75
	v_fmac_f32_e32 v16, v97, v72
	v_fmac_f32_e32 v17, v97, v73
	v_fmac_f32_e32 v18, v97, v74
	v_fmac_f32_e32 v19, v97, v75
	v_fmac_f32_e32 v20, v98, v72
	v_fmac_f32_e32 v21, v98, v73
	v_fmac_f32_e32 v22, v98, v74
	v_fmac_f32_e32 v23, v98, v75
	v_fmac_f32_e32 v24, v99, v72
	v_fmac_f32_e32 v25, v99, v73
	v_fmac_f32_e32 v26, v99, v74
	v_fmac_f32_e32 v27, v99, v75
	v_fmac_f32_e32 v28, v100, v72
	v_fmac_f32_e32 v29, v100, v73
	v_fmac_f32_e32 v30, v100, v74
	v_fmac_f32_e32 v31, v100, v75
	global_load_dwordx4 v[72:75], v11, s[10:11]
	s_add_u32 s10, s10, 0x18000
	s_addc_u32 s11, s11, 0
	ds_read_b32 v96, v10 offset:728
	ds_read_b32 v97, v10 offset:8920
	ds_read_b32 v98, v10 offset:17112
	ds_read_b32 v99, v10 offset:25304
	ds_read_b32 v100, v10 offset:33496
	s_waitcnt vmcnt(15) lgkmcnt(0)
	v_fmac_f32_e32 v12, v96, v76
	v_fmac_f32_e32 v13, v96, v77
	v_fmac_f32_e32 v14, v96, v78
	v_fmac_f32_e32 v15, v96, v79
	v_fmac_f32_e32 v16, v97, v76
	v_fmac_f32_e32 v17, v97, v77
	v_fmac_f32_e32 v18, v97, v78
	v_fmac_f32_e32 v19, v97, v79
	v_fmac_f32_e32 v20, v98, v76
	v_fmac_f32_e32 v21, v98, v77
	v_fmac_f32_e32 v22, v98, v78
	v_fmac_f32_e32 v23, v98, v79
	v_fmac_f32_e32 v24, v99, v76
	v_fmac_f32_e32 v25, v99, v77
	v_fmac_f32_e32 v26, v99, v78
	v_fmac_f32_e32 v27, v99, v79
	v_fmac_f32_e32 v28, v100, v76
	v_fmac_f32_e32 v29, v100, v77
	v_fmac_f32_e32 v30, v100, v78
	v_fmac_f32_e32 v31, v100, v79
	global_load_dwordx4 v[76:79], v11, s[10:11]
	s_add_u32 s10, s10, 0x18000
	s_addc_u32 s11, s11, 0
	ds_read_b32 v96, v10 offset:736
	ds_read_b32 v97, v10 offset:8928
	ds_read_b32 v98, v10 offset:17120
	ds_read_b32 v99, v10 offset:25312
	ds_read_b32 v100, v10 offset:33504
	s_waitcnt vmcnt(15) lgkmcnt(0)
	v_fmac_f32_e32 v12, v96, v80
	v_fmac_f32_e32 v13, v96, v81
	v_fmac_f32_e32 v14, v96, v82
	v_fmac_f32_e32 v15, v96, v83
	v_fmac_f32_e32 v16, v97, v80
	v_fmac_f32_e32 v17, v97, v81
	v_fmac_f32_e32 v18, v97, v82
	v_fmac_f32_e32 v19, v97, v83
	v_fmac_f32_e32 v20, v98, v80
	v_fmac_f32_e32 v21, v98, v81
	v_fmac_f32_e32 v22, v98, v82
	v_fmac_f32_e32 v23, v98, v83
	v_fmac_f32_e32 v24, v99, v80
	v_fmac_f32_e32 v25, v99, v81
	v_fmac_f32_e32 v26, v99, v82
	v_fmac_f32_e32 v27, v99, v83
	v_fmac_f32_e32 v28, v100, v80
	v_fmac_f32_e32 v29, v100, v81
	v_fmac_f32_e32 v30, v100, v82
	v_fmac_f32_e32 v31, v100, v83
	global_load_dwordx4 v[80:83], v11, s[10:11]
	s_add_u32 s10, s10, 0x18000
	s_addc_u32 s11, s11, 0
	ds_read_b32 v96, v10 offset:744
	ds_read_b32 v97, v10 offset:8936
	ds_read_b32 v98, v10 offset:17128
	ds_read_b32 v99, v10 offset:25320
	ds_read_b32 v100, v10 offset:33512
	s_waitcnt vmcnt(15) lgkmcnt(0)
	v_fmac_f32_e32 v12, v96, v84
	v_fmac_f32_e32 v13, v96, v85
	v_fmac_f32_e32 v14, v96, v86
	v_fmac_f32_e32 v15, v96, v87
	v_fmac_f32_e32 v16, v97, v84
	v_fmac_f32_e32 v17, v97, v85
	v_fmac_f32_e32 v18, v97, v86
	v_fmac_f32_e32 v19, v97, v87
	v_fmac_f32_e32 v20, v98, v84
	v_fmac_f32_e32 v21, v98, v85
	v_fmac_f32_e32 v22, v98, v86
	v_fmac_f32_e32 v23, v98, v87
	v_fmac_f32_e32 v24, v99, v84
	v_fmac_f32_e32 v25, v99, v85
	v_fmac_f32_e32 v26, v99, v86
	v_fmac_f32_e32 v27, v99, v87
	v_fmac_f32_e32 v28, v100, v84
	v_fmac_f32_e32 v29, v100, v85
	v_fmac_f32_e32 v30, v100, v86
	v_fmac_f32_e32 v31, v100, v87
	global_load_dwordx4 v[84:87], v11, s[10:11]
	s_add_u32 s10, s10, 0x18000
	s_addc_u32 s11, s11, 0
	ds_read_b32 v96, v10 offset:752
	ds_read_b32 v97, v10 offset:8944
	ds_read_b32 v98, v10 offset:17136
	ds_read_b32 v99, v10 offset:25328
	ds_read_b32 v100, v10 offset:33520
	s_waitcnt vmcnt(15) lgkmcnt(0)
	v_fmac_f32_e32 v12, v96, v88
	v_fmac_f32_e32 v13, v96, v89
	v_fmac_f32_e32 v14, v96, v90
	v_fmac_f32_e32 v15, v96, v91
	v_fmac_f32_e32 v16, v97, v88
	v_fmac_f32_e32 v17, v97, v89
	v_fmac_f32_e32 v18, v97, v90
	v_fmac_f32_e32 v19, v97, v91
	v_fmac_f32_e32 v20, v98, v88
	v_fmac_f32_e32 v21, v98, v89
	v_fmac_f32_e32 v22, v98, v90
	v_fmac_f32_e32 v23, v98, v91
	v_fmac_f32_e32 v24, v99, v88
	v_fmac_f32_e32 v25, v99, v89
	v_fmac_f32_e32 v26, v99, v90
	v_fmac_f32_e32 v27, v99, v91
	v_fmac_f32_e32 v28, v100, v88
	v_fmac_f32_e32 v29, v100, v89
	v_fmac_f32_e32 v30, v100, v90
	v_fmac_f32_e32 v31, v100, v91
	global_load_dwordx4 v[88:91], v11, s[10:11]
	s_add_u32 s10, s10, 0x18000
	s_addc_u32 s11, s11, 0
	ds_read_b32 v96, v10 offset:760
	ds_read_b32 v97, v10 offset:8952
	ds_read_b32 v98, v10 offset:17144
	ds_read_b32 v99, v10 offset:25336
	ds_read_b32 v100, v10 offset:33528
	s_waitcnt vmcnt(15) lgkmcnt(0)
	v_fmac_f32_e32 v12, v96, v92
	v_fmac_f32_e32 v13, v96, v93
	v_fmac_f32_e32 v14, v96, v94
	v_fmac_f32_e32 v15, v96, v95
	v_fmac_f32_e32 v16, v97, v92
	v_fmac_f32_e32 v17, v97, v93
	v_fmac_f32_e32 v18, v97, v94
	v_fmac_f32_e32 v19, v97, v95
	v_fmac_f32_e32 v20, v98, v92
	v_fmac_f32_e32 v21, v98, v93
	v_fmac_f32_e32 v22, v98, v94
	v_fmac_f32_e32 v23, v98, v95
	v_fmac_f32_e32 v24, v99, v92
	v_fmac_f32_e32 v25, v99, v93
	v_fmac_f32_e32 v26, v99, v94
	v_fmac_f32_e32 v27, v99, v95
	v_fmac_f32_e32 v28, v100, v92
	v_fmac_f32_e32 v29, v100, v93
	v_fmac_f32_e32 v30, v100, v94
	v_fmac_f32_e32 v31, v100, v95
	global_load_dwordx4 v[92:95], v11, s[10:11]
	s_add_u32 s10, s10, 0x18000
	s_addc_u32 s11, s11, 0
	ds_read_b32 v96, v10 offset:768
	ds_read_b32 v97, v10 offset:8960
	ds_read_b32 v98, v10 offset:17152
	ds_read_b32 v99, v10 offset:25344
	ds_read_b32 v100, v10 offset:33536
	s_waitcnt vmcnt(15) lgkmcnt(0)
	v_fmac_f32_e32 v12, v96, v32
	v_fmac_f32_e32 v13, v96, v33
	v_fmac_f32_e32 v14, v96, v34
	v_fmac_f32_e32 v15, v96, v35
	v_fmac_f32_e32 v16, v97, v32
	v_fmac_f32_e32 v17, v97, v33
	v_fmac_f32_e32 v18, v97, v34
	v_fmac_f32_e32 v19, v97, v35
	v_fmac_f32_e32 v20, v98, v32
	v_fmac_f32_e32 v21, v98, v33
	v_fmac_f32_e32 v22, v98, v34
	v_fmac_f32_e32 v23, v98, v35
	v_fmac_f32_e32 v24, v99, v32
	v_fmac_f32_e32 v25, v99, v33
	v_fmac_f32_e32 v26, v99, v34
	v_fmac_f32_e32 v27, v99, v35
	v_fmac_f32_e32 v28, v100, v32
	v_fmac_f32_e32 v29, v100, v33
	v_fmac_f32_e32 v30, v100, v34
	v_fmac_f32_e32 v31, v100, v35
	global_load_dwordx4 v[32:35], v11, s[10:11]
	s_add_u32 s10, s10, 0x18000
	s_addc_u32 s11, s11, 0
	ds_read_b32 v96, v10 offset:776
	ds_read_b32 v97, v10 offset:8968
	ds_read_b32 v98, v10 offset:17160
	ds_read_b32 v99, v10 offset:25352
	ds_read_b32 v100, v10 offset:33544
	s_waitcnt vmcnt(15) lgkmcnt(0)
	v_fmac_f32_e32 v12, v96, v36
	v_fmac_f32_e32 v13, v96, v37
	v_fmac_f32_e32 v14, v96, v38
	v_fmac_f32_e32 v15, v96, v39
	v_fmac_f32_e32 v16, v97, v36
	v_fmac_f32_e32 v17, v97, v37
	v_fmac_f32_e32 v18, v97, v38
	v_fmac_f32_e32 v19, v97, v39
	v_fmac_f32_e32 v20, v98, v36
	v_fmac_f32_e32 v21, v98, v37
	v_fmac_f32_e32 v22, v98, v38
	v_fmac_f32_e32 v23, v98, v39
	v_fmac_f32_e32 v24, v99, v36
	v_fmac_f32_e32 v25, v99, v37
	v_fmac_f32_e32 v26, v99, v38
	v_fmac_f32_e32 v27, v99, v39
	v_fmac_f32_e32 v28, v100, v36
	v_fmac_f32_e32 v29, v100, v37
	v_fmac_f32_e32 v30, v100, v38
	v_fmac_f32_e32 v31, v100, v39
	global_load_dwordx4 v[36:39], v11, s[10:11]
	s_add_u32 s10, s10, 0x18000
	s_addc_u32 s11, s11, 0
	ds_read_b32 v96, v10 offset:784
	ds_read_b32 v97, v10 offset:8976
	ds_read_b32 v98, v10 offset:17168
	ds_read_b32 v99, v10 offset:25360
	ds_read_b32 v100, v10 offset:33552
	s_waitcnt vmcnt(15) lgkmcnt(0)
	v_fmac_f32_e32 v12, v96, v40
	v_fmac_f32_e32 v13, v96, v41
	v_fmac_f32_e32 v14, v96, v42
	v_fmac_f32_e32 v15, v96, v43
	v_fmac_f32_e32 v16, v97, v40
	v_fmac_f32_e32 v17, v97, v41
	v_fmac_f32_e32 v18, v97, v42
	v_fmac_f32_e32 v19, v97, v43
	v_fmac_f32_e32 v20, v98, v40
	v_fmac_f32_e32 v21, v98, v41
	v_fmac_f32_e32 v22, v98, v42
	v_fmac_f32_e32 v23, v98, v43
	v_fmac_f32_e32 v24, v99, v40
	v_fmac_f32_e32 v25, v99, v41
	v_fmac_f32_e32 v26, v99, v42
	v_fmac_f32_e32 v27, v99, v43
	v_fmac_f32_e32 v28, v100, v40
	v_fmac_f32_e32 v29, v100, v41
	v_fmac_f32_e32 v30, v100, v42
	v_fmac_f32_e32 v31, v100, v43
	global_load_dwordx4 v[40:43], v11, s[10:11]
	s_add_u32 s10, s10, 0x18000
	s_addc_u32 s11, s11, 0
	ds_read_b32 v96, v10 offset:792
	ds_read_b32 v97, v10 offset:8984
	ds_read_b32 v98, v10 offset:17176
	ds_read_b32 v99, v10 offset:25368
	ds_read_b32 v100, v10 offset:33560
	s_waitcnt vmcnt(15) lgkmcnt(0)
	v_fmac_f32_e32 v12, v96, v44
	v_fmac_f32_e32 v13, v96, v45
	v_fmac_f32_e32 v14, v96, v46
	v_fmac_f32_e32 v15, v96, v47
	v_fmac_f32_e32 v16, v97, v44
	v_fmac_f32_e32 v17, v97, v45
	v_fmac_f32_e32 v18, v97, v46
	v_fmac_f32_e32 v19, v97, v47
	v_fmac_f32_e32 v20, v98, v44
	v_fmac_f32_e32 v21, v98, v45
	v_fmac_f32_e32 v22, v98, v46
	v_fmac_f32_e32 v23, v98, v47
	v_fmac_f32_e32 v24, v99, v44
	v_fmac_f32_e32 v25, v99, v45
	v_fmac_f32_e32 v26, v99, v46
	v_fmac_f32_e32 v27, v99, v47
	v_fmac_f32_e32 v28, v100, v44
	v_fmac_f32_e32 v29, v100, v45
	v_fmac_f32_e32 v30, v100, v46
	v_fmac_f32_e32 v31, v100, v47
	global_load_dwordx4 v[44:47], v11, s[10:11]
	s_add_u32 s10, s10, 0x18000
	s_addc_u32 s11, s11, 0
	ds_read_b32 v96, v10 offset:800
	ds_read_b32 v97, v10 offset:8992
	ds_read_b32 v98, v10 offset:17184
	ds_read_b32 v99, v10 offset:25376
	ds_read_b32 v100, v10 offset:33568
	s_waitcnt vmcnt(15) lgkmcnt(0)
	v_fmac_f32_e32 v12, v96, v48
	v_fmac_f32_e32 v13, v96, v49
	v_fmac_f32_e32 v14, v96, v50
	v_fmac_f32_e32 v15, v96, v51
	v_fmac_f32_e32 v16, v97, v48
	v_fmac_f32_e32 v17, v97, v49
	v_fmac_f32_e32 v18, v97, v50
	v_fmac_f32_e32 v19, v97, v51
	v_fmac_f32_e32 v20, v98, v48
	v_fmac_f32_e32 v21, v98, v49
	v_fmac_f32_e32 v22, v98, v50
	v_fmac_f32_e32 v23, v98, v51
	v_fmac_f32_e32 v24, v99, v48
	v_fmac_f32_e32 v25, v99, v49
	v_fmac_f32_e32 v26, v99, v50
	v_fmac_f32_e32 v27, v99, v51
	v_fmac_f32_e32 v28, v100, v48
	v_fmac_f32_e32 v29, v100, v49
	v_fmac_f32_e32 v30, v100, v50
	v_fmac_f32_e32 v31, v100, v51
	global_load_dwordx4 v[48:51], v11, s[10:11]
	s_add_u32 s10, s10, 0x18000
	s_addc_u32 s11, s11, 0
	ds_read_b32 v96, v10 offset:808
	ds_read_b32 v97, v10 offset:9000
	ds_read_b32 v98, v10 offset:17192
	ds_read_b32 v99, v10 offset:25384
	ds_read_b32 v100, v10 offset:33576
	s_waitcnt vmcnt(15) lgkmcnt(0)
	v_fmac_f32_e32 v12, v96, v52
	v_fmac_f32_e32 v13, v96, v53
	v_fmac_f32_e32 v14, v96, v54
	v_fmac_f32_e32 v15, v96, v55
	v_fmac_f32_e32 v16, v97, v52
	v_fmac_f32_e32 v17, v97, v53
	v_fmac_f32_e32 v18, v97, v54
	v_fmac_f32_e32 v19, v97, v55
	v_fmac_f32_e32 v20, v98, v52
	v_fmac_f32_e32 v21, v98, v53
	v_fmac_f32_e32 v22, v98, v54
	v_fmac_f32_e32 v23, v98, v55
	v_fmac_f32_e32 v24, v99, v52
	v_fmac_f32_e32 v25, v99, v53
	v_fmac_f32_e32 v26, v99, v54
	v_fmac_f32_e32 v27, v99, v55
	v_fmac_f32_e32 v28, v100, v52
	v_fmac_f32_e32 v29, v100, v53
	v_fmac_f32_e32 v30, v100, v54
	v_fmac_f32_e32 v31, v100, v55
	global_load_dwordx4 v[52:55], v11, s[10:11]
	s_add_u32 s10, s10, 0x18000
	s_addc_u32 s11, s11, 0
	ds_read_b32 v96, v10 offset:816
	ds_read_b32 v97, v10 offset:9008
	ds_read_b32 v98, v10 offset:17200
	ds_read_b32 v99, v10 offset:25392
	ds_read_b32 v100, v10 offset:33584
	s_waitcnt vmcnt(15) lgkmcnt(0)
	v_fmac_f32_e32 v12, v96, v56
	v_fmac_f32_e32 v13, v96, v57
	v_fmac_f32_e32 v14, v96, v58
	v_fmac_f32_e32 v15, v96, v59
	v_fmac_f32_e32 v16, v97, v56
	v_fmac_f32_e32 v17, v97, v57
	v_fmac_f32_e32 v18, v97, v58
	v_fmac_f32_e32 v19, v97, v59
	v_fmac_f32_e32 v20, v98, v56
	v_fmac_f32_e32 v21, v98, v57
	v_fmac_f32_e32 v22, v98, v58
	v_fmac_f32_e32 v23, v98, v59
	v_fmac_f32_e32 v24, v99, v56
	v_fmac_f32_e32 v25, v99, v57
	v_fmac_f32_e32 v26, v99, v58
	v_fmac_f32_e32 v27, v99, v59
	v_fmac_f32_e32 v28, v100, v56
	v_fmac_f32_e32 v29, v100, v57
	v_fmac_f32_e32 v30, v100, v58
	v_fmac_f32_e32 v31, v100, v59
	global_load_dwordx4 v[56:59], v11, s[10:11]
	s_add_u32 s10, s10, 0x18000
	s_addc_u32 s11, s11, 0
	ds_read_b32 v96, v10 offset:824
	ds_read_b32 v97, v10 offset:9016
	ds_read_b32 v98, v10 offset:17208
	ds_read_b32 v99, v10 offset:25400
	ds_read_b32 v100, v10 offset:33592
	s_waitcnt vmcnt(15) lgkmcnt(0)
	v_fmac_f32_e32 v12, v96, v60
	v_fmac_f32_e32 v13, v96, v61
	v_fmac_f32_e32 v14, v96, v62
	v_fmac_f32_e32 v15, v96, v63
	v_fmac_f32_e32 v16, v97, v60
	v_fmac_f32_e32 v17, v97, v61
	v_fmac_f32_e32 v18, v97, v62
	v_fmac_f32_e32 v19, v97, v63
	v_fmac_f32_e32 v20, v98, v60
	v_fmac_f32_e32 v21, v98, v61
	v_fmac_f32_e32 v22, v98, v62
	v_fmac_f32_e32 v23, v98, v63
	v_fmac_f32_e32 v24, v99, v60
	v_fmac_f32_e32 v25, v99, v61
	v_fmac_f32_e32 v26, v99, v62
	v_fmac_f32_e32 v27, v99, v63
	v_fmac_f32_e32 v28, v100, v60
	v_fmac_f32_e32 v29, v100, v61
	v_fmac_f32_e32 v30, v100, v62
	v_fmac_f32_e32 v31, v100, v63
	global_load_dwordx4 v[60:63], v11, s[10:11]
	s_add_u32 s10, s10, 0x18000
	s_addc_u32 s11, s11, 0
	ds_read_b32 v96, v10 offset:832
	ds_read_b32 v97, v10 offset:9024
	ds_read_b32 v98, v10 offset:17216
	ds_read_b32 v99, v10 offset:25408
	ds_read_b32 v100, v10 offset:33600
	s_waitcnt vmcnt(15) lgkmcnt(0)
	v_fmac_f32_e32 v12, v96, v64
	v_fmac_f32_e32 v13, v96, v65
	v_fmac_f32_e32 v14, v96, v66
	v_fmac_f32_e32 v15, v96, v67
	v_fmac_f32_e32 v16, v97, v64
	v_fmac_f32_e32 v17, v97, v65
	v_fmac_f32_e32 v18, v97, v66
	v_fmac_f32_e32 v19, v97, v67
	v_fmac_f32_e32 v20, v98, v64
	v_fmac_f32_e32 v21, v98, v65
	v_fmac_f32_e32 v22, v98, v66
	v_fmac_f32_e32 v23, v98, v67
	v_fmac_f32_e32 v24, v99, v64
	v_fmac_f32_e32 v25, v99, v65
	v_fmac_f32_e32 v26, v99, v66
	v_fmac_f32_e32 v27, v99, v67
	v_fmac_f32_e32 v28, v100, v64
	v_fmac_f32_e32 v29, v100, v65
	v_fmac_f32_e32 v30, v100, v66
	v_fmac_f32_e32 v31, v100, v67
	global_load_dwordx4 v[64:67], v11, s[10:11]
	s_add_u32 s10, s10, 0x18000
	s_addc_u32 s11, s11, 0
	ds_read_b32 v96, v10 offset:840
	ds_read_b32 v97, v10 offset:9032
	ds_read_b32 v98, v10 offset:17224
	ds_read_b32 v99, v10 offset:25416
	ds_read_b32 v100, v10 offset:33608
	s_waitcnt vmcnt(15) lgkmcnt(0)
	v_fmac_f32_e32 v12, v96, v68
	v_fmac_f32_e32 v13, v96, v69
	v_fmac_f32_e32 v14, v96, v70
	v_fmac_f32_e32 v15, v96, v71
	v_fmac_f32_e32 v16, v97, v68
	v_fmac_f32_e32 v17, v97, v69
	v_fmac_f32_e32 v18, v97, v70
	v_fmac_f32_e32 v19, v97, v71
	v_fmac_f32_e32 v20, v98, v68
	v_fmac_f32_e32 v21, v98, v69
	v_fmac_f32_e32 v22, v98, v70
	v_fmac_f32_e32 v23, v98, v71
	v_fmac_f32_e32 v24, v99, v68
	v_fmac_f32_e32 v25, v99, v69
	v_fmac_f32_e32 v26, v99, v70
	v_fmac_f32_e32 v27, v99, v71
	v_fmac_f32_e32 v28, v100, v68
	v_fmac_f32_e32 v29, v100, v69
	v_fmac_f32_e32 v30, v100, v70
	v_fmac_f32_e32 v31, v100, v71
	global_load_dwordx4 v[68:71], v11, s[10:11]
	s_add_u32 s10, s10, 0x18000
	s_addc_u32 s11, s11, 0
	ds_read_b32 v96, v10 offset:848
	ds_read_b32 v97, v10 offset:9040
	ds_read_b32 v98, v10 offset:17232
	ds_read_b32 v99, v10 offset:25424
	ds_read_b32 v100, v10 offset:33616
	s_waitcnt vmcnt(15) lgkmcnt(0)
	v_fmac_f32_e32 v12, v96, v72
	v_fmac_f32_e32 v13, v96, v73
	v_fmac_f32_e32 v14, v96, v74
	v_fmac_f32_e32 v15, v96, v75
	v_fmac_f32_e32 v16, v97, v72
	v_fmac_f32_e32 v17, v97, v73
	v_fmac_f32_e32 v18, v97, v74
	v_fmac_f32_e32 v19, v97, v75
	v_fmac_f32_e32 v20, v98, v72
	v_fmac_f32_e32 v21, v98, v73
	v_fmac_f32_e32 v22, v98, v74
	v_fmac_f32_e32 v23, v98, v75
	v_fmac_f32_e32 v24, v99, v72
	v_fmac_f32_e32 v25, v99, v73
	v_fmac_f32_e32 v26, v99, v74
	v_fmac_f32_e32 v27, v99, v75
	v_fmac_f32_e32 v28, v100, v72
	v_fmac_f32_e32 v29, v100, v73
	v_fmac_f32_e32 v30, v100, v74
	v_fmac_f32_e32 v31, v100, v75
	global_load_dwordx4 v[72:75], v11, s[10:11]
	s_add_u32 s10, s10, 0x18000
	s_addc_u32 s11, s11, 0
	ds_read_b32 v96, v10 offset:856
	ds_read_b32 v97, v10 offset:9048
	ds_read_b32 v98, v10 offset:17240
	ds_read_b32 v99, v10 offset:25432
	ds_read_b32 v100, v10 offset:33624
	s_waitcnt vmcnt(15) lgkmcnt(0)
	v_fmac_f32_e32 v12, v96, v76
	v_fmac_f32_e32 v13, v96, v77
	v_fmac_f32_e32 v14, v96, v78
	v_fmac_f32_e32 v15, v96, v79
	v_fmac_f32_e32 v16, v97, v76
	v_fmac_f32_e32 v17, v97, v77
	v_fmac_f32_e32 v18, v97, v78
	v_fmac_f32_e32 v19, v97, v79
	v_fmac_f32_e32 v20, v98, v76
	v_fmac_f32_e32 v21, v98, v77
	v_fmac_f32_e32 v22, v98, v78
	v_fmac_f32_e32 v23, v98, v79
	v_fmac_f32_e32 v24, v99, v76
	v_fmac_f32_e32 v25, v99, v77
	v_fmac_f32_e32 v26, v99, v78
	v_fmac_f32_e32 v27, v99, v79
	v_fmac_f32_e32 v28, v100, v76
	v_fmac_f32_e32 v29, v100, v77
	v_fmac_f32_e32 v30, v100, v78
	v_fmac_f32_e32 v31, v100, v79
	global_load_dwordx4 v[76:79], v11, s[10:11]
	s_add_u32 s10, s10, 0x18000
	s_addc_u32 s11, s11, 0
	ds_read_b32 v96, v10 offset:864
	ds_read_b32 v97, v10 offset:9056
	ds_read_b32 v98, v10 offset:17248
	ds_read_b32 v99, v10 offset:25440
	ds_read_b32 v100, v10 offset:33632
	s_waitcnt vmcnt(15) lgkmcnt(0)
	v_fmac_f32_e32 v12, v96, v80
	v_fmac_f32_e32 v13, v96, v81
	v_fmac_f32_e32 v14, v96, v82
	v_fmac_f32_e32 v15, v96, v83
	v_fmac_f32_e32 v16, v97, v80
	v_fmac_f32_e32 v17, v97, v81
	v_fmac_f32_e32 v18, v97, v82
	v_fmac_f32_e32 v19, v97, v83
	v_fmac_f32_e32 v20, v98, v80
	v_fmac_f32_e32 v21, v98, v81
	v_fmac_f32_e32 v22, v98, v82
	v_fmac_f32_e32 v23, v98, v83
	v_fmac_f32_e32 v24, v99, v80
	v_fmac_f32_e32 v25, v99, v81
	v_fmac_f32_e32 v26, v99, v82
	v_fmac_f32_e32 v27, v99, v83
	v_fmac_f32_e32 v28, v100, v80
	v_fmac_f32_e32 v29, v100, v81
	v_fmac_f32_e32 v30, v100, v82
	v_fmac_f32_e32 v31, v100, v83
	global_load_dwordx4 v[80:83], v11, s[10:11]
	s_add_u32 s10, s10, 0x18000
	s_addc_u32 s11, s11, 0
	ds_read_b32 v96, v10 offset:872
	ds_read_b32 v97, v10 offset:9064
	ds_read_b32 v98, v10 offset:17256
	ds_read_b32 v99, v10 offset:25448
	ds_read_b32 v100, v10 offset:33640
	s_waitcnt vmcnt(15) lgkmcnt(0)
	v_fmac_f32_e32 v12, v96, v84
	v_fmac_f32_e32 v13, v96, v85
	v_fmac_f32_e32 v14, v96, v86
	v_fmac_f32_e32 v15, v96, v87
	v_fmac_f32_e32 v16, v97, v84
	v_fmac_f32_e32 v17, v97, v85
	v_fmac_f32_e32 v18, v97, v86
	v_fmac_f32_e32 v19, v97, v87
	v_fmac_f32_e32 v20, v98, v84
	v_fmac_f32_e32 v21, v98, v85
	v_fmac_f32_e32 v22, v98, v86
	v_fmac_f32_e32 v23, v98, v87
	v_fmac_f32_e32 v24, v99, v84
	v_fmac_f32_e32 v25, v99, v85
	v_fmac_f32_e32 v26, v99, v86
	v_fmac_f32_e32 v27, v99, v87
	v_fmac_f32_e32 v28, v100, v84
	v_fmac_f32_e32 v29, v100, v85
	v_fmac_f32_e32 v30, v100, v86
	v_fmac_f32_e32 v31, v100, v87
	global_load_dwordx4 v[84:87], v11, s[10:11]
	s_add_u32 s10, s10, 0x18000
	s_addc_u32 s11, s11, 0
	ds_read_b32 v96, v10 offset:880
	ds_read_b32 v97, v10 offset:9072
	ds_read_b32 v98, v10 offset:17264
	ds_read_b32 v99, v10 offset:25456
	ds_read_b32 v100, v10 offset:33648
	s_waitcnt vmcnt(15) lgkmcnt(0)
	v_fmac_f32_e32 v12, v96, v88
	v_fmac_f32_e32 v13, v96, v89
	v_fmac_f32_e32 v14, v96, v90
	v_fmac_f32_e32 v15, v96, v91
	v_fmac_f32_e32 v16, v97, v88
	v_fmac_f32_e32 v17, v97, v89
	v_fmac_f32_e32 v18, v97, v90
	v_fmac_f32_e32 v19, v97, v91
	v_fmac_f32_e32 v20, v98, v88
	v_fmac_f32_e32 v21, v98, v89
	v_fmac_f32_e32 v22, v98, v90
	v_fmac_f32_e32 v23, v98, v91
	v_fmac_f32_e32 v24, v99, v88
	v_fmac_f32_e32 v25, v99, v89
	v_fmac_f32_e32 v26, v99, v90
	v_fmac_f32_e32 v27, v99, v91
	v_fmac_f32_e32 v28, v100, v88
	v_fmac_f32_e32 v29, v100, v89
	v_fmac_f32_e32 v30, v100, v90
	v_fmac_f32_e32 v31, v100, v91
	global_load_dwordx4 v[88:91], v11, s[10:11]
	s_add_u32 s10, s10, 0x18000
	s_addc_u32 s11, s11, 0
	ds_read_b32 v96, v10 offset:888
	ds_read_b32 v97, v10 offset:9080
	ds_read_b32 v98, v10 offset:17272
	ds_read_b32 v99, v10 offset:25464
	ds_read_b32 v100, v10 offset:33656
	s_waitcnt vmcnt(15) lgkmcnt(0)
	v_fmac_f32_e32 v12, v96, v92
	v_fmac_f32_e32 v13, v96, v93
	v_fmac_f32_e32 v14, v96, v94
	v_fmac_f32_e32 v15, v96, v95
	v_fmac_f32_e32 v16, v97, v92
	v_fmac_f32_e32 v17, v97, v93
	v_fmac_f32_e32 v18, v97, v94
	v_fmac_f32_e32 v19, v97, v95
	v_fmac_f32_e32 v20, v98, v92
	v_fmac_f32_e32 v21, v98, v93
	v_fmac_f32_e32 v22, v98, v94
	v_fmac_f32_e32 v23, v98, v95
	v_fmac_f32_e32 v24, v99, v92
	v_fmac_f32_e32 v25, v99, v93
	v_fmac_f32_e32 v26, v99, v94
	v_fmac_f32_e32 v27, v99, v95
	v_fmac_f32_e32 v28, v100, v92
	v_fmac_f32_e32 v29, v100, v93
	v_fmac_f32_e32 v30, v100, v94
	v_fmac_f32_e32 v31, v100, v95
	global_load_dwordx4 v[92:95], v11, s[10:11]
	s_add_u32 s10, s10, 0x18000
	s_addc_u32 s11, s11, 0
	ds_read_b32 v96, v10 offset:896
	ds_read_b32 v97, v10 offset:9088
	ds_read_b32 v98, v10 offset:17280
	ds_read_b32 v99, v10 offset:25472
	ds_read_b32 v100, v10 offset:33664
	s_waitcnt vmcnt(15) lgkmcnt(0)
	v_fmac_f32_e32 v12, v96, v32
	v_fmac_f32_e32 v13, v96, v33
	v_fmac_f32_e32 v14, v96, v34
	v_fmac_f32_e32 v15, v96, v35
	v_fmac_f32_e32 v16, v97, v32
	v_fmac_f32_e32 v17, v97, v33
	v_fmac_f32_e32 v18, v97, v34
	v_fmac_f32_e32 v19, v97, v35
	v_fmac_f32_e32 v20, v98, v32
	v_fmac_f32_e32 v21, v98, v33
	v_fmac_f32_e32 v22, v98, v34
	v_fmac_f32_e32 v23, v98, v35
	v_fmac_f32_e32 v24, v99, v32
	v_fmac_f32_e32 v25, v99, v33
	v_fmac_f32_e32 v26, v99, v34
	v_fmac_f32_e32 v27, v99, v35
	v_fmac_f32_e32 v28, v100, v32
	v_fmac_f32_e32 v29, v100, v33
	v_fmac_f32_e32 v30, v100, v34
	v_fmac_f32_e32 v31, v100, v35
	ds_read_b32 v96, v10 offset:904
	ds_read_b32 v97, v10 offset:9096
	ds_read_b32 v98, v10 offset:17288
	ds_read_b32 v99, v10 offset:25480
	ds_read_b32 v100, v10 offset:33672
	s_waitcnt vmcnt(14) lgkmcnt(0)
	v_fmac_f32_e32 v12, v96, v36
	v_fmac_f32_e32 v13, v96, v37
	v_fmac_f32_e32 v14, v96, v38
	v_fmac_f32_e32 v15, v96, v39
	v_fmac_f32_e32 v16, v97, v36
	v_fmac_f32_e32 v17, v97, v37
	v_fmac_f32_e32 v18, v97, v38
	v_fmac_f32_e32 v19, v97, v39
	v_fmac_f32_e32 v20, v98, v36
	v_fmac_f32_e32 v21, v98, v37
	v_fmac_f32_e32 v22, v98, v38
	v_fmac_f32_e32 v23, v98, v39
	v_fmac_f32_e32 v24, v99, v36
	v_fmac_f32_e32 v25, v99, v37
	v_fmac_f32_e32 v26, v99, v38
	v_fmac_f32_e32 v27, v99, v39
	v_fmac_f32_e32 v28, v100, v36
	v_fmac_f32_e32 v29, v100, v37
	v_fmac_f32_e32 v30, v100, v38
	v_fmac_f32_e32 v31, v100, v39
	ds_read_b32 v96, v10 offset:912
	ds_read_b32 v97, v10 offset:9104
	ds_read_b32 v98, v10 offset:17296
	ds_read_b32 v99, v10 offset:25488
	ds_read_b32 v100, v10 offset:33680
	s_waitcnt vmcnt(13) lgkmcnt(0)
	v_fmac_f32_e32 v12, v96, v40
	v_fmac_f32_e32 v13, v96, v41
	v_fmac_f32_e32 v14, v96, v42
	v_fmac_f32_e32 v15, v96, v43
	v_fmac_f32_e32 v16, v97, v40
	v_fmac_f32_e32 v17, v97, v41
	v_fmac_f32_e32 v18, v97, v42
	v_fmac_f32_e32 v19, v97, v43
	v_fmac_f32_e32 v20, v98, v40
	v_fmac_f32_e32 v21, v98, v41
	v_fmac_f32_e32 v22, v98, v42
	v_fmac_f32_e32 v23, v98, v43
	v_fmac_f32_e32 v24, v99, v40
	v_fmac_f32_e32 v25, v99, v41
	v_fmac_f32_e32 v26, v99, v42
	v_fmac_f32_e32 v27, v99, v43
	v_fmac_f32_e32 v28, v100, v40
	v_fmac_f32_e32 v29, v100, v41
	v_fmac_f32_e32 v30, v100, v42
	v_fmac_f32_e32 v31, v100, v43
	ds_read_b32 v96, v10 offset:920
	ds_read_b32 v97, v10 offset:9112
	ds_read_b32 v98, v10 offset:17304
	ds_read_b32 v99, v10 offset:25496
	ds_read_b32 v100, v10 offset:33688
	s_waitcnt vmcnt(12) lgkmcnt(0)
	v_fmac_f32_e32 v12, v96, v44
	v_fmac_f32_e32 v13, v96, v45
	v_fmac_f32_e32 v14, v96, v46
	v_fmac_f32_e32 v15, v96, v47
	v_fmac_f32_e32 v16, v97, v44
	v_fmac_f32_e32 v17, v97, v45
	v_fmac_f32_e32 v18, v97, v46
	v_fmac_f32_e32 v19, v97, v47
	v_fmac_f32_e32 v20, v98, v44
	v_fmac_f32_e32 v21, v98, v45
	v_fmac_f32_e32 v22, v98, v46
	v_fmac_f32_e32 v23, v98, v47
	v_fmac_f32_e32 v24, v99, v44
	v_fmac_f32_e32 v25, v99, v45
	v_fmac_f32_e32 v26, v99, v46
	v_fmac_f32_e32 v27, v99, v47
	v_fmac_f32_e32 v28, v100, v44
	v_fmac_f32_e32 v29, v100, v45
	v_fmac_f32_e32 v30, v100, v46
	v_fmac_f32_e32 v31, v100, v47
	ds_read_b32 v96, v10 offset:928
	ds_read_b32 v97, v10 offset:9120
	ds_read_b32 v98, v10 offset:17312
	ds_read_b32 v99, v10 offset:25504
	ds_read_b32 v100, v10 offset:33696
	s_waitcnt vmcnt(11) lgkmcnt(0)
	v_fmac_f32_e32 v12, v96, v48
	v_fmac_f32_e32 v13, v96, v49
	v_fmac_f32_e32 v14, v96, v50
	v_fmac_f32_e32 v15, v96, v51
	v_fmac_f32_e32 v16, v97, v48
	v_fmac_f32_e32 v17, v97, v49
	v_fmac_f32_e32 v18, v97, v50
	v_fmac_f32_e32 v19, v97, v51
	v_fmac_f32_e32 v20, v98, v48
	v_fmac_f32_e32 v21, v98, v49
	v_fmac_f32_e32 v22, v98, v50
	v_fmac_f32_e32 v23, v98, v51
	v_fmac_f32_e32 v24, v99, v48
	v_fmac_f32_e32 v25, v99, v49
	v_fmac_f32_e32 v26, v99, v50
	v_fmac_f32_e32 v27, v99, v51
	v_fmac_f32_e32 v28, v100, v48
	v_fmac_f32_e32 v29, v100, v49
	v_fmac_f32_e32 v30, v100, v50
	v_fmac_f32_e32 v31, v100, v51
	ds_read_b32 v96, v10 offset:936
	ds_read_b32 v97, v10 offset:9128
	ds_read_b32 v98, v10 offset:17320
	ds_read_b32 v99, v10 offset:25512
	ds_read_b32 v100, v10 offset:33704
	s_waitcnt vmcnt(10) lgkmcnt(0)
	v_fmac_f32_e32 v12, v96, v52
	v_fmac_f32_e32 v13, v96, v53
	v_fmac_f32_e32 v14, v96, v54
	v_fmac_f32_e32 v15, v96, v55
	v_fmac_f32_e32 v16, v97, v52
	v_fmac_f32_e32 v17, v97, v53
	v_fmac_f32_e32 v18, v97, v54
	v_fmac_f32_e32 v19, v97, v55
	v_fmac_f32_e32 v20, v98, v52
	v_fmac_f32_e32 v21, v98, v53
	v_fmac_f32_e32 v22, v98, v54
	v_fmac_f32_e32 v23, v98, v55
	v_fmac_f32_e32 v24, v99, v52
	v_fmac_f32_e32 v25, v99, v53
	v_fmac_f32_e32 v26, v99, v54
	v_fmac_f32_e32 v27, v99, v55
	v_fmac_f32_e32 v28, v100, v52
	v_fmac_f32_e32 v29, v100, v53
	v_fmac_f32_e32 v30, v100, v54
	v_fmac_f32_e32 v31, v100, v55
	ds_read_b32 v96, v10 offset:944
	ds_read_b32 v97, v10 offset:9136
	ds_read_b32 v98, v10 offset:17328
	ds_read_b32 v99, v10 offset:25520
	ds_read_b32 v100, v10 offset:33712
	s_waitcnt vmcnt(9) lgkmcnt(0)
	v_fmac_f32_e32 v12, v96, v56
	v_fmac_f32_e32 v13, v96, v57
	v_fmac_f32_e32 v14, v96, v58
	v_fmac_f32_e32 v15, v96, v59
	v_fmac_f32_e32 v16, v97, v56
	v_fmac_f32_e32 v17, v97, v57
	v_fmac_f32_e32 v18, v97, v58
	v_fmac_f32_e32 v19, v97, v59
	v_fmac_f32_e32 v20, v98, v56
	v_fmac_f32_e32 v21, v98, v57
	v_fmac_f32_e32 v22, v98, v58
	v_fmac_f32_e32 v23, v98, v59
	v_fmac_f32_e32 v24, v99, v56
	v_fmac_f32_e32 v25, v99, v57
	v_fmac_f32_e32 v26, v99, v58
	v_fmac_f32_e32 v27, v99, v59
	v_fmac_f32_e32 v28, v100, v56
	v_fmac_f32_e32 v29, v100, v57
	v_fmac_f32_e32 v30, v100, v58
	v_fmac_f32_e32 v31, v100, v59
	ds_read_b32 v96, v10 offset:952
	ds_read_b32 v97, v10 offset:9144
	ds_read_b32 v98, v10 offset:17336
	ds_read_b32 v99, v10 offset:25528
	ds_read_b32 v100, v10 offset:33720
	s_waitcnt vmcnt(8) lgkmcnt(0)
	v_fmac_f32_e32 v12, v96, v60
	v_fmac_f32_e32 v13, v96, v61
	v_fmac_f32_e32 v14, v96, v62
	v_fmac_f32_e32 v15, v96, v63
	v_fmac_f32_e32 v16, v97, v60
	v_fmac_f32_e32 v17, v97, v61
	v_fmac_f32_e32 v18, v97, v62
	v_fmac_f32_e32 v19, v97, v63
	v_fmac_f32_e32 v20, v98, v60
	v_fmac_f32_e32 v21, v98, v61
	v_fmac_f32_e32 v22, v98, v62
	v_fmac_f32_e32 v23, v98, v63
	v_fmac_f32_e32 v24, v99, v60
	v_fmac_f32_e32 v25, v99, v61
	v_fmac_f32_e32 v26, v99, v62
	v_fmac_f32_e32 v27, v99, v63
	v_fmac_f32_e32 v28, v100, v60
	v_fmac_f32_e32 v29, v100, v61
	v_fmac_f32_e32 v30, v100, v62
	v_fmac_f32_e32 v31, v100, v63
	ds_read_b32 v96, v10 offset:960
	ds_read_b32 v97, v10 offset:9152
	ds_read_b32 v98, v10 offset:17344
	ds_read_b32 v99, v10 offset:25536
	ds_read_b32 v100, v10 offset:33728
	s_waitcnt vmcnt(7) lgkmcnt(0)
	v_fmac_f32_e32 v12, v96, v64
	v_fmac_f32_e32 v13, v96, v65
	v_fmac_f32_e32 v14, v96, v66
	v_fmac_f32_e32 v15, v96, v67
	v_fmac_f32_e32 v16, v97, v64
	v_fmac_f32_e32 v17, v97, v65
	v_fmac_f32_e32 v18, v97, v66
	v_fmac_f32_e32 v19, v97, v67
	v_fmac_f32_e32 v20, v98, v64
	v_fmac_f32_e32 v21, v98, v65
	v_fmac_f32_e32 v22, v98, v66
	v_fmac_f32_e32 v23, v98, v67
	v_fmac_f32_e32 v24, v99, v64
	v_fmac_f32_e32 v25, v99, v65
	v_fmac_f32_e32 v26, v99, v66
	v_fmac_f32_e32 v27, v99, v67
	v_fmac_f32_e32 v28, v100, v64
	v_fmac_f32_e32 v29, v100, v65
	v_fmac_f32_e32 v30, v100, v66
	v_fmac_f32_e32 v31, v100, v67
	ds_read_b32 v96, v10 offset:968
	ds_read_b32 v97, v10 offset:9160
	ds_read_b32 v98, v10 offset:17352
	ds_read_b32 v99, v10 offset:25544
	ds_read_b32 v100, v10 offset:33736
	s_waitcnt vmcnt(6) lgkmcnt(0)
	v_fmac_f32_e32 v12, v96, v68
	v_fmac_f32_e32 v13, v96, v69
	v_fmac_f32_e32 v14, v96, v70
	v_fmac_f32_e32 v15, v96, v71
	v_fmac_f32_e32 v16, v97, v68
	v_fmac_f32_e32 v17, v97, v69
	v_fmac_f32_e32 v18, v97, v70
	v_fmac_f32_e32 v19, v97, v71
	v_fmac_f32_e32 v20, v98, v68
	v_fmac_f32_e32 v21, v98, v69
	v_fmac_f32_e32 v22, v98, v70
	v_fmac_f32_e32 v23, v98, v71
	v_fmac_f32_e32 v24, v99, v68
	v_fmac_f32_e32 v25, v99, v69
	v_fmac_f32_e32 v26, v99, v70
	v_fmac_f32_e32 v27, v99, v71
	v_fmac_f32_e32 v28, v100, v68
	v_fmac_f32_e32 v29, v100, v69
	v_fmac_f32_e32 v30, v100, v70
	v_fmac_f32_e32 v31, v100, v71
	ds_read_b32 v96, v10 offset:976
	ds_read_b32 v97, v10 offset:9168
	ds_read_b32 v98, v10 offset:17360
	ds_read_b32 v99, v10 offset:25552
	ds_read_b32 v100, v10 offset:33744
	s_waitcnt vmcnt(5) lgkmcnt(0)
	v_fmac_f32_e32 v12, v96, v72
	v_fmac_f32_e32 v13, v96, v73
	v_fmac_f32_e32 v14, v96, v74
	v_fmac_f32_e32 v15, v96, v75
	v_fmac_f32_e32 v16, v97, v72
	v_fmac_f32_e32 v17, v97, v73
	v_fmac_f32_e32 v18, v97, v74
	v_fmac_f32_e32 v19, v97, v75
	v_fmac_f32_e32 v20, v98, v72
	v_fmac_f32_e32 v21, v98, v73
	v_fmac_f32_e32 v22, v98, v74
	v_fmac_f32_e32 v23, v98, v75
	v_fmac_f32_e32 v24, v99, v72
	v_fmac_f32_e32 v25, v99, v73
	v_fmac_f32_e32 v26, v99, v74
	v_fmac_f32_e32 v27, v99, v75
	v_fmac_f32_e32 v28, v100, v72
	v_fmac_f32_e32 v29, v100, v73
	v_fmac_f32_e32 v30, v100, v74
	v_fmac_f32_e32 v31, v100, v75
	ds_read_b32 v96, v10 offset:984
	ds_read_b32 v97, v10 offset:9176
	ds_read_b32 v98, v10 offset:17368
	ds_read_b32 v99, v10 offset:25560
	ds_read_b32 v100, v10 offset:33752
	s_waitcnt vmcnt(4) lgkmcnt(0)
	v_fmac_f32_e32 v12, v96, v76
	v_fmac_f32_e32 v13, v96, v77
	v_fmac_f32_e32 v14, v96, v78
	v_fmac_f32_e32 v15, v96, v79
	v_fmac_f32_e32 v16, v97, v76
	v_fmac_f32_e32 v17, v97, v77
	v_fmac_f32_e32 v18, v97, v78
	v_fmac_f32_e32 v19, v97, v79
	v_fmac_f32_e32 v20, v98, v76
	v_fmac_f32_e32 v21, v98, v77
	v_fmac_f32_e32 v22, v98, v78
	v_fmac_f32_e32 v23, v98, v79
	v_fmac_f32_e32 v24, v99, v76
	v_fmac_f32_e32 v25, v99, v77
	v_fmac_f32_e32 v26, v99, v78
	v_fmac_f32_e32 v27, v99, v79
	v_fmac_f32_e32 v28, v100, v76
	v_fmac_f32_e32 v29, v100, v77
	v_fmac_f32_e32 v30, v100, v78
	v_fmac_f32_e32 v31, v100, v79
	ds_read_b32 v96, v10 offset:992
	ds_read_b32 v97, v10 offset:9184
	ds_read_b32 v98, v10 offset:17376
	ds_read_b32 v99, v10 offset:25568
	ds_read_b32 v100, v10 offset:33760
	s_waitcnt vmcnt(3) lgkmcnt(0)
	v_fmac_f32_e32 v12, v96, v80
	v_fmac_f32_e32 v13, v96, v81
	v_fmac_f32_e32 v14, v96, v82
	v_fmac_f32_e32 v15, v96, v83
	v_fmac_f32_e32 v16, v97, v80
	v_fmac_f32_e32 v17, v97, v81
	v_fmac_f32_e32 v18, v97, v82
	v_fmac_f32_e32 v19, v97, v83
	v_fmac_f32_e32 v20, v98, v80
	v_fmac_f32_e32 v21, v98, v81
	v_fmac_f32_e32 v22, v98, v82
	v_fmac_f32_e32 v23, v98, v83
	v_fmac_f32_e32 v24, v99, v80
	v_fmac_f32_e32 v25, v99, v81
	v_fmac_f32_e32 v26, v99, v82
	v_fmac_f32_e32 v27, v99, v83
	v_fmac_f32_e32 v28, v100, v80
	v_fmac_f32_e32 v29, v100, v81
	v_fmac_f32_e32 v30, v100, v82
	v_fmac_f32_e32 v31, v100, v83
	ds_read_b32 v96, v10 offset:1000
	ds_read_b32 v97, v10 offset:9192
	ds_read_b32 v98, v10 offset:17384
	ds_read_b32 v99, v10 offset:25576
	ds_read_b32 v100, v10 offset:33768
	s_waitcnt vmcnt(2) lgkmcnt(0)
	v_fmac_f32_e32 v12, v96, v84
	v_fmac_f32_e32 v13, v96, v85
	v_fmac_f32_e32 v14, v96, v86
	v_fmac_f32_e32 v15, v96, v87
	v_fmac_f32_e32 v16, v97, v84
	v_fmac_f32_e32 v17, v97, v85
	v_fmac_f32_e32 v18, v97, v86
	v_fmac_f32_e32 v19, v97, v87
	v_fmac_f32_e32 v20, v98, v84
	v_fmac_f32_e32 v21, v98, v85
	v_fmac_f32_e32 v22, v98, v86
	v_fmac_f32_e32 v23, v98, v87
	v_fmac_f32_e32 v24, v99, v84
	v_fmac_f32_e32 v25, v99, v85
	v_fmac_f32_e32 v26, v99, v86
	v_fmac_f32_e32 v27, v99, v87
	v_fmac_f32_e32 v28, v100, v84
	v_fmac_f32_e32 v29, v100, v85
	v_fmac_f32_e32 v30, v100, v86
	v_fmac_f32_e32 v31, v100, v87
	ds_read_b32 v96, v10 offset:1008
	ds_read_b32 v97, v10 offset:9200
	ds_read_b32 v98, v10 offset:17392
	ds_read_b32 v99, v10 offset:25584
	ds_read_b32 v100, v10 offset:33776
	s_waitcnt vmcnt(1) lgkmcnt(0)
	v_fmac_f32_e32 v12, v96, v88
	v_fmac_f32_e32 v13, v96, v89
	v_fmac_f32_e32 v14, v96, v90
	v_fmac_f32_e32 v15, v96, v91
	v_fmac_f32_e32 v16, v97, v88
	v_fmac_f32_e32 v17, v97, v89
	v_fmac_f32_e32 v18, v97, v90
	v_fmac_f32_e32 v19, v97, v91
	v_fmac_f32_e32 v20, v98, v88
	v_fmac_f32_e32 v21, v98, v89
	v_fmac_f32_e32 v22, v98, v90
	v_fmac_f32_e32 v23, v98, v91
	v_fmac_f32_e32 v24, v99, v88
	v_fmac_f32_e32 v25, v99, v89
	v_fmac_f32_e32 v26, v99, v90
	v_fmac_f32_e32 v27, v99, v91
	v_fmac_f32_e32 v28, v100, v88
	v_fmac_f32_e32 v29, v100, v89
	v_fmac_f32_e32 v30, v100, v90
	v_fmac_f32_e32 v31, v100, v91
	ds_read_b32 v96, v10 offset:1016
	ds_read_b32 v97, v10 offset:9208
	ds_read_b32 v98, v10 offset:17400
	ds_read_b32 v99, v10 offset:25592
	ds_read_b32 v100, v10 offset:33784
	s_waitcnt vmcnt(0) lgkmcnt(0)
	v_fmac_f32_e32 v12, v96, v92
	v_fmac_f32_e32 v13, v96, v93
	v_fmac_f32_e32 v14, v96, v94
	v_fmac_f32_e32 v15, v96, v95
	v_fmac_f32_e32 v16, v97, v92
	v_fmac_f32_e32 v17, v97, v93
	v_fmac_f32_e32 v18, v97, v94
	v_fmac_f32_e32 v19, v97, v95
	v_fmac_f32_e32 v20, v98, v92
	v_fmac_f32_e32 v21, v98, v93
	v_fmac_f32_e32 v22, v98, v94
	v_fmac_f32_e32 v23, v98, v95
	v_fmac_f32_e32 v24, v99, v92
	v_fmac_f32_e32 v25, v99, v93
	v_fmac_f32_e32 v26, v99, v94
	v_fmac_f32_e32 v27, v99, v95
	v_fmac_f32_e32 v28, v100, v92
	v_fmac_f32_e32 v29, v100, v93
	v_fmac_f32_e32 v30, v100, v94
	v_fmac_f32_e32 v31, v100, v95
	v_lshl_add_u32 v5, v4, 1, v2
	v_mul_u32_u24_e32 v5, 24, v5
	v_add_u32_e32 v5, v5, v3
	v_mul_u32_u24_e32 v5, 80, v5
	v_add_u32_e32 v5, 0xa000, v5
	ds_write_b128 v5, v[12:15] offset:0
	ds_write_b128 v5, v[16:19] offset:16
	ds_write_b128 v5, v[20:23] offset:32
	ds_write_b128 v5, v[24:27] offset:48
	ds_write_b128 v5, v[28:31] offset:64
	s_mov_b64 exec, s[20:21]
	s_waitcnt lgkmcnt(0)
	s_barrier
	v_cmp_gt_u32_e32 vcc, 480, v154
	s_and_saveexec_b64 s[20:21], vcc
	v_mul_u32_u24_e32 v1, 0xccd, v154
	v_lshrrev_b32_e32 v1, 16, v1
	v_mul_u32_u24_e32 v2, 20, v1
	v_sub_u32_e32 v2, v154, v2
	v_mul_u32_u24_e32 v3, 80, v1
	v_lshl_add_u32 v3, v2, 2, v3
	v_add_u32_e32 v3, 0xa000, v3
	ds_read_b32 v32, v3 offset:0
	ds_read_b32 v33, v3 offset:1920
	ds_read_b32 v34, v3 offset:3840
	ds_read_b32 v35, v3 offset:5760
	ds_read_b32 v36, v3 offset:7680
	ds_read_b32 v37, v3 offset:9600
	ds_read_b32 v38, v3 offset:11520
	ds_read_b32 v39, v3 offset:13440
	ds_read_b32 v40, v3 offset:15360
	ds_read_b32 v41, v3 offset:17280
	ds_read_b32 v42, v3 offset:19200
	ds_read_b32 v43, v3 offset:21120
	ds_read_b32 v44, v3 offset:23040
	ds_read_b32 v45, v3 offset:24960
	ds_read_b32 v46, v3 offset:26880
	ds_read_b32 v47, v3 offset:28800
	v_lshrrev_b32_e32 v4, 2, v2
	v_and_b32_e32 v5, 3, v2
	v_lshl_add_u32 v5, v1, 2, v5
	v_add_u32_e32 v5, s9, v5
	s_mul_i32 s12, s8, 12288
	v_add_u32_e32 v6, s12, v5
	v_lshlrev_b32_e32 v6, 2, v6
	global_load_dword v7, v6, s[2:3]
	s_mul_i32 s12, s8, 5
	v_add_u32_e32 v4, s12, v4
	v_mul_u32_u24_e32 v4, 12288, v4
	v_add_u32_e32 v4, v4, v5
	v_lshlrev_b32_e32 v4, 2, v4
	s_add_u32 s12, s90, 0x10400000
	s_addc_u32 s13, s91, 0
	s_waitcnt lgkmcnt(0)
	v_mov_b32_e32 v8, 0
	v_add_f32_e32 v8, v8, v32
	v_add_f32_e32 v8, v8, v33
	v_add_f32_e32 v8, v8, v34
	v_add_f32_e32 v8, v8, v35
	v_add_f32_e32 v8, v8, v36
	v_add_f32_e32 v8, v8, v37
	v_add_f32_e32 v8, v8, v38
	v_add_f32_e32 v8, v8, v39
	v_add_f32_e32 v8, v8, v40
	v_add_f32_e32 v8, v8, v41
	v_add_f32_e32 v8, v8, v42
	v_add_f32_e32 v8, v8, v43
	v_add_f32_e32 v8, v8, v44
	v_add_f32_e32 v8, v8, v45
	v_add_f32_e32 v8, v8, v46
	v_add_f32_e32 v8, v8, v47
	s_waitcnt vmcnt(0)
	v_add_f32_e32 v8, v8, v7
	global_store_dword v4, v8, s[12:13]
	s_or_b64 exec, exec, s[20:21]
	s_waitcnt vmcnt(0)
	s_barrier
	v_mov_b32_e32 v22, v154
	s_branch .Lmix0_moddone
.Lmix0_moddone:
	s_load_dwordx2 s[0:1], s[92:93], 0x58
	s_load_dwordx2 s[2:3], s[92:93], 0xb8
	s_load_dwordx2 s[4:5], s[92:93], 0xc0
	s_load_dwordx2 s[6:7], s[92:93], 0xc8
	s_load_dwordx2 s[8:9], s[92:93], 0xd0
	s_load_dwordx2 s[10:11], s[92:93], 0xe8
	v_and_b32_e32 v74, 63, v154
	v_lshrrev_b32_e32 v75, 6, v154
	v_mul_u32_u24_e32 v75, 0x2100, v75
	v_lshrrev_b32_e32 v3, 5, v74
	v_and_b32_e32 v4, 31, v74
	v_lshlrev_b32_e32 v4, 2, v4
	v_lshrrev_b32_e32 v5, 3, v74
	v_and_b32_e32 v6, 7, v74
	v_mul_u32_u24_e32 v2, 264, v6
	v_add_u32_e32 v2, v2, v5
	v_lshl_add_u32 v2, v2, 2, v75
	v_lshlrev_b32_e32 v6, 4, v6
	v_mul_u32_u24_e32 v1, 132, v5
	v_add3_u32 v1, v1, v6, v75
	v_readfirstlane_b32 s13, v154
	s_lshr_b32 s13, s13, 6
	s_lshl_b32 s26, s96, 3
	s_add_u32 s13, s13, s26
	s_sub_u32 s12, s13, 1024
	s_add_u32 s12, s12, 12288
	s_waitcnt lgkmcnt(0)
	s_cmp_ge_u32 s12, 33280
	s_cbranch_scc1 .Ltrm_done
	s_cmp_ge_u32 s12, 33280
	s_cselect_b32 s41, 1, 0
	s_cselect_b32 s26, 33280, 0
	s_sub_u32 s42, s12, s26
	s_cmp_ge_u32 s42, 12288
	s_cbranch_scc1 .Ltrm_m2
	s_mul_i32 s43, s42, 43691
	s_lshr_b32 s43, s43, 24
	s_mul_i32 s26, s43, 384
	s_sub_u32 s44, s42, s26
	s_mov_b32 s14, s0
	s_mov_b32 s15, s1
	s_mov_b32 s36, 0xc000
	s_mov_b32 s37, 0x6000000
	s_mov_b32 s38, 0x0
	s_mov_b32 s39, 0x3000000
	s_mov_b32 s40, 0x1000
	s_branch .Ltrm_dec_done1
